# speedup vs baseline: 1.0035x; 1.0035x over previous
; #define STAGE(P, RS, SOFF, OFF, kt) do { const int _so = (SOFF) + (kt) * (BK * 2); \
;     _Pragma("unroll") for (int _i = 0; _i < 2; ++_i) { \
;       __builtin_amdgcn_raw_ptr_buffer_load_lds(RS, (__attribute__((address_space(3))) void*)((P) + wave * 1024 + _i * 8192), 16, OFF[_i], _so, 0, 0); } } while (0)
; #define LDA(dst, b, h) _Pragma("unroll") for (int m = 0; m < 4; ++m) _Pragma("unroll") for (int k = 0; k < 2; ++k) \
;     dst[m][k] = *reinterpret_cast<const bf16x8*>(SA(b, h) + lds_byte(wr * 64 + m * 16 + fr, k * 32 + fq * 8))
; #define LDB(dst, b, h) _Pragma("unroll") for (int n = 0; n < 2; ++n) _Pragma("unroll") for (int k = 0; k < 2; ++k) \
;     dst[n][k] = *reinterpret_cast<const bf16x8*>(SB(b, h) + lds_byte(wc * 32 + n * 16 + fr, k * 32 + fq * 8))
; #define WAIT_V(n) asm volatile("s_waitcnt vmcnt(" #n ")" ::: "memory")
; #define WAIT_L(n) asm volatile("s_waitcnt lgkmcnt(" #n ")" ::: "memory")
; #define BAR __builtin_amdgcn_s_barrier()
; #define SCHED __builtin_amdgcn_sched_barrier(0)
;     ...
;     for (int t = 0; t < nt - 2; t += 2) {
;       LDB(B0, 0, 0); SCHED; LDA(At, 0, 0); STAGE(SA(1, 1), rsA, sA1, offA, t + 1);
;       WAIT_L(8); BAR; WAIT_L(0); MMA(0, 0, At, B0); BAR; SCHED;
;       LDB(B1, 0, 1); STAGE(SB(0, 0), rsB, sB0, offB, t + 2);
;       BAR; WAIT_L(0); MMA(0, 1, At, B1); BAR;
;       LDA(At, 0, 1); STAGE(SA(0, 0), rsA, sA0, offA, t + 2);
;       BAR; WAIT_L(0); MMA(1, 0, At, B0); BAR; SCHED;
;       STAGE(SB(0, 1), rsB, sB1, offB, t + 2);
;       WAIT_V(6); BAR; MMA(1, 1, At, B1); BAR;
.LBB0_95:
	ds_read_b128 v[154:157], v149
	ds_read_b128 v[158:161], v150
	ds_read_b128 v[162:165], v151
	ds_read_b128 v[166:169], v152
	s_add_i32 s43, s37, s15
	s_add_i32 s10, s43, 0x80
	s_mov_b32 m0, s30
	ds_read_b128 v[170:173], v131
	ds_read_b128 v[174:177], v131 offset:1024
	ds_read_b128 v[178:181], v134
	ds_read_b128 v[182:185], v134 offset:1024
	ds_read_b128 v[186:189], v133
	ds_read_b128 v[190:193], v133 offset:1024
	ds_read_b128 v[194:197], v132
	ds_read_b128 v[198:201], v132 offset:1024
	buffer_load_dwordx4 v143, s[4:7], s10 offen lds
	s_mov_b32 m0, s31
	s_nop 0
	buffer_load_dwordx4 v144, s[4:7], s10 offen lds
	s_waitcnt lgkmcnt(8)
	s_barrier
	s_waitcnt lgkmcnt(0)
	v_mfma_f32_16x16x32_bf16 v[124:127], v[154:157], v[170:173], v[124:127]
	v_mfma_f32_16x16x32_bf16 v[120:123], v[162:165], v[170:173], v[120:123]
	v_mfma_f32_16x16x32_bf16 v[116:119], v[154:157], v[178:181], v[116:119]
	v_mfma_f32_16x16x32_bf16 v[112:115], v[162:165], v[178:181], v[112:115]
	v_mfma_f32_16x16x32_bf16 v[108:111], v[154:157], v[186:189], v[108:111]
	v_mfma_f32_16x16x32_bf16 v[104:107], v[162:165], v[186:189], v[104:107]
	v_mfma_f32_16x16x32_bf16 v[100:103], v[154:157], v[194:197], v[100:103]
	v_mfma_f32_16x16x32_bf16 v[96:99], v[162:165], v[194:197], v[96:99]
	v_mfma_f32_16x16x32_bf16 v[124:127], v[158:161], v[174:177], v[124:127]
	v_mfma_f32_16x16x32_bf16 v[120:123], v[166:169], v[174:177], v[120:123]
	v_mfma_f32_16x16x32_bf16 v[116:119], v[158:161], v[182:185], v[116:119]
	v_mfma_f32_16x16x32_bf16 v[112:115], v[166:169], v[182:185], v[112:115]
	v_mfma_f32_16x16x32_bf16 v[108:111], v[158:161], v[190:193], v[108:111]
	v_mfma_f32_16x16x32_bf16 v[104:107], v[166:169], v[190:193], v[104:107]
	v_mfma_f32_16x16x32_bf16 v[100:103], v[158:161], v[198:201], v[100:103]
	v_mfma_f32_16x16x32_bf16 v[96:99], v[166:169], v[198:201], v[96:99]
	s_barrier
	s_add_i32 s44, s39, s15
	s_add_i32 s45, s44, 0x100
	s_mov_b32 s10, s6
	s_mov_b32 s11, s7
	s_mov_b32 m0, s1
	ds_read_b128 v[202:205], v145
	ds_read_b128 v[206:209], v146
	ds_read_b128 v[210:213], v147
	ds_read_b128 v[214:217], v148
	buffer_load_dwordx4 v143, s[8:11], s45 offen lds
	s_mov_b32 m0, s3
	s_nop 0
	buffer_load_dwordx4 v144, s[8:11], s45 offen lds
	s_barrier
	s_waitcnt lgkmcnt(0)
	v_mfma_f32_16x16x32_bf16 v[92:95], v[202:205], v[170:173], v[92:95]
	v_mfma_f32_16x16x32_bf16 v[88:91], v[210:213], v[170:173], v[88:91]
	v_mfma_f32_16x16x32_bf16 v[84:87], v[202:205], v[178:181], v[84:87]
	v_mfma_f32_16x16x32_bf16 v[80:83], v[210:213], v[178:181], v[80:83]
	v_mfma_f32_16x16x32_bf16 v[76:79], v[202:205], v[186:189], v[76:79]
	v_mfma_f32_16x16x32_bf16 v[72:75], v[210:213], v[186:189], v[72:75]
	v_mfma_f32_16x16x32_bf16 v[68:71], v[202:205], v[194:197], v[68:71]
	v_mfma_f32_16x16x32_bf16 v[64:67], v[210:213], v[194:197], v[64:67]
	v_mfma_f32_16x16x32_bf16 v[92:95], v[206:209], v[174:177], v[92:95]
	v_mfma_f32_16x16x32_bf16 v[88:91], v[214:217], v[174:177], v[88:91]
	v_mfma_f32_16x16x32_bf16 v[84:87], v[206:209], v[182:185], v[84:87]
	v_mfma_f32_16x16x32_bf16 v[80:83], v[214:217], v[182:185], v[80:83]
	v_mfma_f32_16x16x32_bf16 v[76:79], v[206:209], v[190:193], v[76:79]
	v_mfma_f32_16x16x32_bf16 v[72:75], v[214:217], v[190:193], v[72:75]
	v_mfma_f32_16x16x32_bf16 v[68:71], v[206:209], v[198:201], v[68:71]
	v_mfma_f32_16x16x32_bf16 v[64:67], v[214:217], v[198:201], v[64:67]
	s_barrier
	s_add_i32 s45, s38, s15
	s_add_i32 s46, s45, 0x100
	s_mov_b32 m0, s0
	ds_read_b128 v[170:173], v131 offset:16384
	ds_read_b128 v[174:177], v131 offset:17408
	ds_read_b128 v[178:181], v134 offset:16384
	ds_read_b128 v[182:185], v134 offset:17408
	ds_read_b128 v[186:189], v133 offset:16384
	ds_read_b128 v[190:193], v133 offset:17408
	ds_read_b128 v[194:197], v132 offset:16384
	ds_read_b128 v[198:201], v132 offset:17408
	buffer_load_dwordx4 v143, s[4:7], s46 offen lds
	s_mov_b32 m0, s18
	s_nop 0
	buffer_load_dwordx4 v144, s[4:7], s46 offen lds
	s_barrier
	s_waitcnt lgkmcnt(0)
	v_mfma_f32_16x16x32_bf16 v[60:63], v[154:157], v[170:173], v[60:63]
	v_mfma_f32_16x16x32_bf16 v[56:59], v[162:165], v[170:173], v[56:59]
	v_mfma_f32_16x16x32_bf16 v[52:55], v[154:157], v[178:181], v[52:55]
	v_mfma_f32_16x16x32_bf16 v[48:51], v[162:165], v[178:181], v[48:51]
	v_mfma_f32_16x16x32_bf16 v[44:47], v[154:157], v[186:189], v[44:47]
	v_mfma_f32_16x16x32_bf16 v[40:43], v[162:165], v[186:189], v[40:43]
	v_mfma_f32_16x16x32_bf16 v[36:39], v[154:157], v[194:197], v[36:39]
	v_mfma_f32_16x16x32_bf16 v[32:35], v[162:165], v[194:197], v[32:35]
	v_mfma_f32_16x16x32_bf16 v[60:63], v[158:161], v[174:177], v[60:63]
	v_mfma_f32_16x16x32_bf16 v[56:59], v[166:169], v[174:177], v[56:59]
	v_mfma_f32_16x16x32_bf16 v[52:55], v[158:161], v[182:185], v[52:55]
	v_mfma_f32_16x16x32_bf16 v[48:51], v[166:169], v[182:185], v[48:51]
	v_mfma_f32_16x16x32_bf16 v[44:47], v[158:161], v[190:193], v[44:47]
	v_mfma_f32_16x16x32_bf16 v[40:43], v[166:169], v[190:193], v[40:43]
	v_mfma_f32_16x16x32_bf16 v[36:39], v[158:161], v[198:201], v[36:39]
	v_mfma_f32_16x16x32_bf16 v[32:35], v[166:169], v[198:201], v[32:35]
	s_barrier
	s_add_i32 s46, s40, s15
	s_add_i32 s47, s46, 0x100
	s_mov_b32 m0, s19
	s_nop 0
	buffer_load_dwordx4 v143, s[8:11], s47 offen lds
	s_mov_b32 m0, s20
	s_nop 0
	buffer_load_dwordx4 v144, s[8:11], s47 offen lds
	s_waitcnt vmcnt(6)
	s_barrier
; #define STAGE(P, RS, SOFF, OFF, kt) do { const int _so = (SOFF) + (kt) * (BK * 2); \
;     _Pragma("unroll") for (int _i = 0; _i < 2; ++_i) { \
;       __builtin_amdgcn_raw_ptr_buffer_load_lds(RS, (__attribute__((address_space(3))) void*)((P) + wave * 1024 + _i * 8192), 16, OFF[_i], _so, 0, 0); } } while (0)
; #define LDA(dst, b, h) _Pragma("unroll") for (int m = 0; m < 4; ++m) _Pragma("unroll") for (int k = 0; k < 2; ++k) \
;     dst[m][k] = *reinterpret_cast<const bf16x8*>(SA(b, h) + lds_byte(wr * 64 + m * 16 + fr, k * 32 + fq * 8))
; #define LDB(dst, b, h) _Pragma("unroll") for (int n = 0; n < 2; ++n) _Pragma("unroll") for (int k = 0; k < 2; ++k) \
;     dst[n][k] = *reinterpret_cast<const bf16x8*>(SB(b, h) + lds_byte(wc * 32 + n * 16 + fr, k * 32 + fq * 8))
; #define WAIT_V(n) asm volatile("s_waitcnt vmcnt(" #n ")" ::: "memory")
; #define WAIT_L(n) asm volatile("s_waitcnt lgkmcnt(" #n ")" ::: "memory")
; #define BAR __builtin_amdgcn_s_barrier()
; #define SCHED __builtin_amdgcn_sched_barrier(0)
;     ...
;       WAIT_V(6); BAR; MMA(1, 1, At, B1); BAR;
;       LDB(B0, 1, 0); SCHED; LDA(At, 1, 0); STAGE(SA(0, 1), rsA, sA1, offA, t + 2);
;       WAIT_L(8); BAR; WAIT_L(0); MMA(0, 0, At, B0); BAR; SCHED;
;       LDB(B1, 1, 1); STAGE(SB(1, 0), rsB, sB0, offB, t + 3);
;       BAR; WAIT_L(0); MMA(0, 1, At, B1); BAR;
;       LDA(At, 1, 1); STAGE(SA(1, 0), rsA, sA0, offA, t + 3);
;       BAR; WAIT_L(0); MMA(1, 0, At, B0); BAR; SCHED;
;       STAGE(SB(1, 1), rsB, sB1, offB, t + 3);
;       WAIT_V(6); BAR; MMA(1, 1, At, B1); BAR;
	v_mfma_f32_16x16x32_bf16 v[28:31], v[202:205], v[170:173], v[28:31]
	v_mfma_f32_16x16x32_bf16 v[24:27], v[210:213], v[170:173], v[24:27]
	v_mfma_f32_16x16x32_bf16 v[20:23], v[202:205], v[178:181], v[20:23]
	v_mfma_f32_16x16x32_bf16 v[16:19], v[210:213], v[178:181], v[16:19]
	v_mfma_f32_16x16x32_bf16 v[12:15], v[202:205], v[186:189], v[12:15]
	v_mfma_f32_16x16x32_bf16 v[8:11], v[210:213], v[186:189], v[8:11]
	v_mfma_f32_16x16x32_bf16 v[4:7], v[202:205], v[194:197], v[4:7]
	v_mfma_f32_16x16x32_bf16 v[0:3], v[210:213], v[194:197], v[0:3]
	v_mfma_f32_16x16x32_bf16 v[28:31], v[206:209], v[174:177], v[28:31]
	v_mfma_f32_16x16x32_bf16 v[24:27], v[214:217], v[174:177], v[24:27]
	v_mfma_f32_16x16x32_bf16 v[20:23], v[206:209], v[182:185], v[20:23]
	v_mfma_f32_16x16x32_bf16 v[16:19], v[214:217], v[182:185], v[16:19]
	v_mfma_f32_16x16x32_bf16 v[12:15], v[206:209], v[190:193], v[12:15]
	v_mfma_f32_16x16x32_bf16 v[8:11], v[214:217], v[190:193], v[8:11]
	v_mfma_f32_16x16x32_bf16 v[4:7], v[206:209], v[198:201], v[4:7]
	v_mfma_f32_16x16x32_bf16 v[0:3], v[214:217], v[198:201], v[0:3]
	s_barrier
	ds_read_b128 v[154:157], v139
	ds_read_b128 v[158:161], v140
	ds_read_b128 v[162:165], v141
	ds_read_b128 v[166:169], v142
	s_addk_i32 s43, 0x100
	s_mov_b32 m0, s21
	ds_read_b128 v[170:173], v131 offset:32768
	ds_read_b128 v[174:177], v131 offset:33792
	ds_read_b128 v[178:181], v134 offset:32768
	ds_read_b128 v[182:185], v134 offset:33792
	ds_read_b128 v[186:189], v133 offset:32768
	ds_read_b128 v[190:193], v133 offset:33792
	ds_read_b128 v[194:197], v132 offset:32768
	ds_read_b128 v[198:201], v132 offset:33792
	buffer_load_dwordx4 v143, s[4:7], s43 offen lds
	s_mov_b32 m0, s22
	s_nop 0
	buffer_load_dwordx4 v144, s[4:7], s43 offen lds
	s_waitcnt lgkmcnt(8)
	s_barrier
	s_waitcnt lgkmcnt(0)
	v_mfma_f32_16x16x32_bf16 v[124:127], v[154:157], v[170:173], v[124:127]
	v_mfma_f32_16x16x32_bf16 v[120:123], v[162:165], v[170:173], v[120:123]
	v_mfma_f32_16x16x32_bf16 v[116:119], v[154:157], v[178:181], v[116:119]
	v_mfma_f32_16x16x32_bf16 v[112:115], v[162:165], v[178:181], v[112:115]
	v_mfma_f32_16x16x32_bf16 v[108:111], v[154:157], v[186:189], v[108:111]
	v_mfma_f32_16x16x32_bf16 v[104:107], v[162:165], v[186:189], v[104:107]
	v_mfma_f32_16x16x32_bf16 v[100:103], v[154:157], v[194:197], v[100:103]
	v_mfma_f32_16x16x32_bf16 v[96:99], v[162:165], v[194:197], v[96:99]
	v_mfma_f32_16x16x32_bf16 v[124:127], v[158:161], v[174:177], v[124:127]
	v_mfma_f32_16x16x32_bf16 v[120:123], v[166:169], v[174:177], v[120:123]
	v_mfma_f32_16x16x32_bf16 v[116:119], v[158:161], v[182:185], v[116:119]
	v_mfma_f32_16x16x32_bf16 v[112:115], v[166:169], v[182:185], v[112:115]
	v_mfma_f32_16x16x32_bf16 v[108:111], v[158:161], v[190:193], v[108:111]
	v_mfma_f32_16x16x32_bf16 v[104:107], v[166:169], v[190:193], v[104:107]
	v_mfma_f32_16x16x32_bf16 v[100:103], v[158:161], v[198:201], v[100:103]
	v_mfma_f32_16x16x32_bf16 v[96:99], v[166:169], v[198:201], v[96:99]
	s_barrier
	s_addk_i32 s44, 0x180
	s_mov_b32 m0, s23
	ds_read_b128 v[202:205], v135
	ds_read_b128 v[206:209], v136
	ds_read_b128 v[210:213], v137
	ds_read_b128 v[214:217], v138
	buffer_load_dwordx4 v143, s[8:11], s44 offen lds
	s_mov_b32 m0, s24
	s_nop 0
	buffer_load_dwordx4 v144, s[8:11], s44 offen lds
	s_barrier
	s_waitcnt lgkmcnt(0)
	v_mfma_f32_16x16x32_bf16 v[92:95], v[202:205], v[170:173], v[92:95]
	v_mfma_f32_16x16x32_bf16 v[88:91], v[210:213], v[170:173], v[88:91]
	v_mfma_f32_16x16x32_bf16 v[84:87], v[202:205], v[178:181], v[84:87]
	v_mfma_f32_16x16x32_bf16 v[80:83], v[210:213], v[178:181], v[80:83]
	v_mfma_f32_16x16x32_bf16 v[76:79], v[202:205], v[186:189], v[76:79]
	v_mfma_f32_16x16x32_bf16 v[72:75], v[210:213], v[186:189], v[72:75]
	v_mfma_f32_16x16x32_bf16 v[68:71], v[202:205], v[194:197], v[68:71]
	v_mfma_f32_16x16x32_bf16 v[64:67], v[210:213], v[194:197], v[64:67]
	v_mfma_f32_16x16x32_bf16 v[92:95], v[206:209], v[174:177], v[92:95]
	v_mfma_f32_16x16x32_bf16 v[88:91], v[214:217], v[174:177], v[88:91]
	v_mfma_f32_16x16x32_bf16 v[84:87], v[206:209], v[182:185], v[84:87]
	v_mfma_f32_16x16x32_bf16 v[80:83], v[214:217], v[182:185], v[80:83]
	v_mfma_f32_16x16x32_bf16 v[76:79], v[206:209], v[190:193], v[76:79]
	v_mfma_f32_16x16x32_bf16 v[72:75], v[214:217], v[190:193], v[72:75]
	v_mfma_f32_16x16x32_bf16 v[68:71], v[206:209], v[198:201], v[68:71]
	v_mfma_f32_16x16x32_bf16 v[64:67], v[214:217], v[198:201], v[64:67]
	s_barrier
	s_addk_i32 s45, 0x180
	s_mov_b32 m0, s25
	ds_read_b128 v[170:173], v131 offset:49152
	ds_read_b128 v[174:177], v131 offset:50176
	ds_read_b128 v[178:181], v134 offset:49152
	ds_read_b128 v[182:185], v134 offset:50176
	ds_read_b128 v[186:189], v133 offset:49152
	ds_read_b128 v[190:193], v133 offset:50176
	ds_read_b128 v[194:197], v132 offset:49152
	ds_read_b128 v[198:201], v132 offset:50176
	buffer_load_dwordx4 v143, s[4:7], s45 offen lds
	s_mov_b32 m0, s26
	s_nop 0
	buffer_load_dwordx4 v144, s[4:7], s45 offen lds
	s_barrier
	s_waitcnt lgkmcnt(0)
	v_mfma_f32_16x16x32_bf16 v[60:63], v[154:157], v[170:173], v[60:63]
	v_mfma_f32_16x16x32_bf16 v[56:59], v[162:165], v[170:173], v[56:59]
	v_mfma_f32_16x16x32_bf16 v[52:55], v[154:157], v[178:181], v[52:55]
	v_mfma_f32_16x16x32_bf16 v[48:51], v[162:165], v[178:181], v[48:51]
	v_mfma_f32_16x16x32_bf16 v[44:47], v[154:157], v[186:189], v[44:47]
	v_mfma_f32_16x16x32_bf16 v[40:43], v[162:165], v[186:189], v[40:43]
	v_mfma_f32_16x16x32_bf16 v[36:39], v[154:157], v[194:197], v[36:39]
	v_mfma_f32_16x16x32_bf16 v[32:35], v[162:165], v[194:197], v[32:35]
	v_mfma_f32_16x16x32_bf16 v[60:63], v[158:161], v[174:177], v[60:63]
	v_mfma_f32_16x16x32_bf16 v[56:59], v[166:169], v[174:177], v[56:59]
	v_mfma_f32_16x16x32_bf16 v[52:55], v[158:161], v[182:185], v[52:55]
	v_mfma_f32_16x16x32_bf16 v[48:51], v[166:169], v[182:185], v[48:51]
	v_mfma_f32_16x16x32_bf16 v[44:47], v[158:161], v[190:193], v[44:47]
	v_mfma_f32_16x16x32_bf16 v[40:43], v[166:169], v[190:193], v[40:43]
	v_mfma_f32_16x16x32_bf16 v[36:39], v[158:161], v[198:201], v[36:39]
	v_mfma_f32_16x16x32_bf16 v[32:35], v[166:169], v[198:201], v[32:35]
	s_barrier
; #define STAGE(P, RS, SOFF, OFF, kt) do { const int _so = (SOFF) + (kt) * (BK * 2); \
;     _Pragma("unroll") for (int _i = 0; _i < 2; ++_i) { \
;       __builtin_amdgcn_raw_ptr_buffer_load_lds(RS, (__attribute__((address_space(3))) void*)((P) + wave * 1024 + _i * 8192), 16, OFF[_i], _so, 0, 0); } } while (0)
; #define LDA(dst, b, h) _Pragma("unroll") for (int m = 0; m < 4; ++m) _Pragma("unroll") for (int k = 0; k < 2; ++k) \
;     dst[m][k] = *reinterpret_cast<const bf16x8*>(SA(b, h) + lds_byte(wr * 64 + m * 16 + fr, k * 32 + fq * 8))
; #define LDB(dst, b, h) _Pragma("unroll") for (int n = 0; n < 2; ++n) _Pragma("unroll") for (int k = 0; k < 2; ++k) \
;     dst[n][k] = *reinterpret_cast<const bf16x8*>(SB(b, h) + lds_byte(wc * 32 + n * 16 + fr, k * 32 + fq * 8))
; #define WAIT_V(n) asm volatile("s_waitcnt vmcnt(" #n ")" ::: "memory")
; #define WAIT_L(n) asm volatile("s_waitcnt lgkmcnt(" #n ")" ::: "memory")
; #define BAR __builtin_amdgcn_s_barrier()
;     ...
;       WAIT_V(6); BAR; MMA(1, 1, At, B1); BAR;
;     }
;     { LDB(B0, 0, 0); LDA(At, 0, 0); STAGE(SA(1, 1), rsA, sA1, offA, nt - 1);
;       BAR; WAIT_L(0); MMA(0, 0, At, B0); BAR;
;       LDB(B1, 0, 1); BAR; WAIT_L(0); MMA(0, 1, At, B1); BAR;
;       LDA(At, 0, 1); WAIT_V(4); BAR; WAIT_L(0); MMA(1, 0, At, B0); MMA(1, 1, At, B1); BAR; }
	s_addk_i32 s46, 0x180
	s_mov_b32 m0, s27
	s_nop 0
	buffer_load_dwordx4 v143, s[8:11], s46 offen lds
	s_mov_b32 m0, s28
	s_nop 0
	buffer_load_dwordx4 v144, s[8:11], s46 offen lds
	s_add_i32 s14, s14, 2
	s_addk_i32 s15, 0x100
	s_cmp_gt_u32 s14, 27
	s_waitcnt vmcnt(6)
	s_barrier
	v_mfma_f32_16x16x32_bf16 v[28:31], v[202:205], v[170:173], v[28:31]
	v_mfma_f32_16x16x32_bf16 v[24:27], v[210:213], v[170:173], v[24:27]
	v_mfma_f32_16x16x32_bf16 v[20:23], v[202:205], v[178:181], v[20:23]
	v_mfma_f32_16x16x32_bf16 v[16:19], v[210:213], v[178:181], v[16:19]
	v_mfma_f32_16x16x32_bf16 v[12:15], v[202:205], v[186:189], v[12:15]
	v_mfma_f32_16x16x32_bf16 v[8:11], v[210:213], v[186:189], v[8:11]
	v_mfma_f32_16x16x32_bf16 v[4:7], v[202:205], v[194:197], v[4:7]
	v_mfma_f32_16x16x32_bf16 v[0:3], v[210:213], v[194:197], v[0:3]
	v_mfma_f32_16x16x32_bf16 v[28:31], v[206:209], v[174:177], v[28:31]
	v_mfma_f32_16x16x32_bf16 v[24:27], v[214:217], v[174:177], v[24:27]
	v_mfma_f32_16x16x32_bf16 v[20:23], v[206:209], v[182:185], v[20:23]
	v_mfma_f32_16x16x32_bf16 v[16:19], v[214:217], v[182:185], v[16:19]
	v_mfma_f32_16x16x32_bf16 v[12:15], v[206:209], v[190:193], v[12:15]
	v_mfma_f32_16x16x32_bf16 v[8:11], v[214:217], v[190:193], v[8:11]
	v_mfma_f32_16x16x32_bf16 v[4:7], v[206:209], v[198:201], v[4:7]
	v_mfma_f32_16x16x32_bf16 v[0:3], v[214:217], v[198:201], v[0:3]
	s_barrier
	s_cbranch_scc0 .LBB0_95
	s_add_i32 s10, s37, 0xf80
	s_mov_b32 m0, s30
	ds_read_b128 v[154:157], v149
	ds_read_b128 v[158:161], v150
	ds_read_b128 v[162:165], v151
	ds_read_b128 v[150:153], v152
	ds_read_b128 v[166:169], v131
	ds_read_b128 v[170:173], v131 offset:1024
	ds_read_b128 v[174:177], v134
	ds_read_b128 v[178:181], v134 offset:1024
	ds_read_b128 v[182:185], v133
	ds_read_b128 v[186:189], v133 offset:1024
	ds_read_b128 v[190:193], v132
	ds_read_b128 v[194:197], v132 offset:1024
	buffer_load_dwordx4 v143, s[4:7], s10 offen lds
	s_mov_b32 m0, s31
	s_nop 0
	buffer_load_dwordx4 v144, s[4:7], s10 offen lds
	s_barrier
	s_waitcnt lgkmcnt(0)
	v_mfma_f32_16x16x32_bf16 v[124:127], v[154:157], v[166:169], v[124:127]
	v_mfma_f32_16x16x32_bf16 v[120:123], v[162:165], v[166:169], v[120:123]
	v_mfma_f32_16x16x32_bf16 v[116:119], v[154:157], v[174:177], v[116:119]
	v_mfma_f32_16x16x32_bf16 v[112:115], v[162:165], v[174:177], v[112:115]
	v_mfma_f32_16x16x32_bf16 v[108:111], v[154:157], v[182:185], v[108:111]
	v_mfma_f32_16x16x32_bf16 v[104:107], v[162:165], v[182:185], v[104:107]
	v_mfma_f32_16x16x32_bf16 v[100:103], v[154:157], v[190:193], v[100:103]
	v_mfma_f32_16x16x32_bf16 v[96:99], v[162:165], v[190:193], v[96:99]
	v_mfma_f32_16x16x32_bf16 v[124:127], v[158:161], v[170:173], v[124:127]
	v_mfma_f32_16x16x32_bf16 v[120:123], v[150:153], v[170:173], v[120:123]
	v_mfma_f32_16x16x32_bf16 v[116:119], v[158:161], v[178:181], v[116:119]
	v_mfma_f32_16x16x32_bf16 v[112:115], v[150:153], v[178:181], v[112:115]
	v_mfma_f32_16x16x32_bf16 v[108:111], v[158:161], v[186:189], v[108:111]
	v_mfma_f32_16x16x32_bf16 v[104:107], v[150:153], v[186:189], v[104:107]
	v_mfma_f32_16x16x32_bf16 v[100:103], v[158:161], v[194:197], v[100:103]
	v_mfma_f32_16x16x32_bf16 v[96:99], v[150:153], v[194:197], v[96:99]
	s_barrier
	ds_read_b128 v[198:201], v145
	ds_read_b128 v[202:205], v146
	ds_read_b128 v[144:147], v147
	ds_read_b128 v[206:209], v148
	s_barrier
	s_waitcnt lgkmcnt(0)
	v_mfma_f32_16x16x32_bf16 v[92:95], v[198:201], v[166:169], v[92:95]
	v_mfma_f32_16x16x32_bf16 v[84:87], v[198:201], v[174:177], v[84:87]
	v_mfma_f32_16x16x32_bf16 v[76:79], v[198:201], v[182:185], v[76:79]
	v_mfma_f32_16x16x32_bf16 v[68:71], v[198:201], v[190:193], v[68:71]
	v_mfma_f32_16x16x32_bf16 v[88:91], v[144:147], v[166:169], v[88:91]
	v_mfma_f32_16x16x32_bf16 v[80:83], v[144:147], v[174:177], v[80:83]
	v_mfma_f32_16x16x32_bf16 v[72:75], v[144:147], v[182:185], v[72:75]
	v_mfma_f32_16x16x32_bf16 v[64:67], v[144:147], v[190:193], v[64:67]
	v_mfma_f32_16x16x32_bf16 v[92:95], v[202:205], v[170:173], v[92:95]
	v_mfma_f32_16x16x32_bf16 v[84:87], v[202:205], v[178:181], v[84:87]
	v_mfma_f32_16x16x32_bf16 v[76:79], v[202:205], v[186:189], v[76:79]
	v_mfma_f32_16x16x32_bf16 v[68:71], v[202:205], v[194:197], v[68:71]
	v_mfma_f32_16x16x32_bf16 v[166:169], v[206:209], v[170:173], v[88:91]
	v_mfma_f32_16x16x32_bf16 v[170:173], v[206:209], v[178:181], v[80:83]
	v_mfma_f32_16x16x32_bf16 v[174:177], v[206:209], v[186:189], v[72:75]
	v_mfma_f32_16x16x32_bf16 v[178:181], v[206:209], v[194:197], v[64:67]
	s_barrier
	s_nop 0
	ds_read_b128 v[64:67], v131 offset:16384
	ds_read_b128 v[72:75], v131 offset:17408
	ds_read_b128 v[80:83], v134 offset:16384
	ds_read_b128 v[88:91], v134 offset:17408
	ds_read_b128 v[182:185], v133 offset:16384
	ds_read_b128 v[186:189], v133 offset:17408
	ds_read_b128 v[190:193], v132 offset:16384
	ds_read_b128 v[194:197], v132 offset:17408
	s_waitcnt vmcnt(4)
	s_barrier
; #define LDA(dst, b, h) _Pragma("unroll") for (int m = 0; m < 4; ++m) _Pragma("unroll") for (int k = 0; k < 2; ++k) \
;     dst[m][k] = *reinterpret_cast<const bf16x8*>(SA(b, h) + lds_byte(wr * 64 + m * 16 + fr, k * 32 + fq * 8))
; #define LDB(dst, b, h) _Pragma("unroll") for (int n = 0; n < 2; ++n) _Pragma("unroll") for (int k = 0; k < 2; ++k) \
;     dst[n][k] = *reinterpret_cast<const bf16x8*>(SB(b, h) + lds_byte(wc * 32 + n * 16 + fr, k * 32 + fq * 8))
; #define WAIT_V(n) asm volatile("s_waitcnt vmcnt(" #n ")" ::: "memory")
; #define WAIT_L(n) asm volatile("s_waitcnt lgkmcnt(" #n ")" ::: "memory")
; #define BAR __builtin_amdgcn_s_barrier()
;     ...
;       LDA(At, 0, 1); WAIT_V(4); BAR; WAIT_L(0); MMA(1, 0, At, B0); MMA(1, 1, At, B1); BAR; }
;     { LDB(B0, 1, 0); LDA(At, 1, 0); WAIT_V(2); BAR; WAIT_L(0); MMA(0, 0, At, B0); BAR;
;       LDB(B1, 1, 1); WAIT_V(0); BAR; WAIT_L(0); MMA(0, 1, At, B1); BAR;
	s_waitcnt lgkmcnt(0)
	v_mfma_f32_16x16x32_bf16 v[60:63], v[154:157], v[64:67], v[60:63]
	v_mfma_f32_16x16x32_bf16 v[56:59], v[162:165], v[64:67], v[56:59]
	v_mfma_f32_16x16x32_bf16 v[52:55], v[154:157], v[80:83], v[52:55]
	v_mfma_f32_16x16x32_bf16 v[48:51], v[162:165], v[80:83], v[48:51]
	v_mfma_f32_16x16x32_bf16 v[44:47], v[154:157], v[182:185], v[44:47]
	v_mfma_f32_16x16x32_bf16 v[40:43], v[162:165], v[182:185], v[40:43]
	v_mfma_f32_16x16x32_bf16 v[36:39], v[154:157], v[190:193], v[36:39]
	v_mfma_f32_16x16x32_bf16 v[32:35], v[162:165], v[190:193], v[32:35]
	v_mfma_f32_16x16x32_bf16 v[60:63], v[158:161], v[72:75], v[60:63]
	v_mfma_f32_16x16x32_bf16 v[56:59], v[150:153], v[72:75], v[56:59]
	v_mfma_f32_16x16x32_bf16 v[52:55], v[158:161], v[88:91], v[52:55]
	v_mfma_f32_16x16x32_bf16 v[48:51], v[150:153], v[88:91], v[48:51]
	v_mfma_f32_16x16x32_bf16 v[44:47], v[158:161], v[186:189], v[44:47]
	v_mfma_f32_16x16x32_bf16 v[40:43], v[150:153], v[186:189], v[40:43]
	v_mfma_f32_16x16x32_bf16 v[36:39], v[158:161], v[194:197], v[36:39]
	v_mfma_f32_16x16x32_bf16 v[32:35], v[150:153], v[194:197], v[32:35]
	v_mfma_f32_16x16x32_bf16 v[28:31], v[198:201], v[64:67], v[28:31]
	v_mfma_f32_16x16x32_bf16 v[20:23], v[198:201], v[80:83], v[20:23]
	v_mfma_f32_16x16x32_bf16 v[12:15], v[198:201], v[182:185], v[12:15]
	v_mfma_f32_16x16x32_bf16 v[4:7], v[198:201], v[190:193], v[4:7]
	v_mfma_f32_16x16x32_bf16 v[24:27], v[144:147], v[64:67], v[24:27]
	v_mfma_f32_16x16x32_bf16 v[16:19], v[144:147], v[80:83], v[16:19]
	v_mfma_f32_16x16x32_bf16 v[8:11], v[144:147], v[182:185], v[8:11]
	v_mfma_f32_16x16x32_bf16 v[0:3], v[144:147], v[190:193], v[0:3]
	v_mfma_f32_16x16x32_bf16 v[28:31], v[202:205], v[72:75], v[28:31]
	v_mfma_f32_16x16x32_bf16 v[20:23], v[202:205], v[88:91], v[20:23]
	v_mfma_f32_16x16x32_bf16 v[12:15], v[202:205], v[186:189], v[12:15]
	v_mfma_f32_16x16x32_bf16 v[4:7], v[202:205], v[194:197], v[4:7]
	v_mfma_f32_16x16x32_bf16 v[144:147], v[206:209], v[72:75], v[24:27]
	v_mfma_f32_16x16x32_bf16 v[148:151], v[206:209], v[88:91], v[16:19]
	v_mfma_f32_16x16x32_bf16 v[152:155], v[206:209], v[186:189], v[8:11]
	v_mfma_f32_16x16x32_bf16 v[156:159], v[206:209], v[194:197], v[0:3]
	s_barrier
	s_nop 0
	ds_read_b128 v[0:3], v139
	ds_read_b128 v[8:11], v140
	ds_read_b128 v[16:19], v141
	ds_read_b128 v[140:143], v142
	ds_read_b128 v[24:27], v131 offset:32768
	ds_read_b128 v[160:163], v131 offset:33792
	ds_read_b128 v[182:185], v134 offset:32768
	ds_read_b128 v[186:189], v134 offset:33792
	ds_read_b128 v[190:193], v133 offset:32768
	ds_read_b128 v[194:197], v133 offset:33792
	ds_read_b128 v[198:201], v132 offset:32768
	ds_read_b128 v[202:205], v132 offset:33792
	s_waitcnt vmcnt(2)
	s_barrier
	s_waitcnt lgkmcnt(0)
	v_mfma_f32_16x16x32_bf16 v[64:67], v[0:3], v[24:27], v[124:127]
	v_mfma_f32_16x16x32_bf16 v[72:75], v[16:19], v[24:27], v[120:123]
	v_mfma_f32_16x16x32_bf16 v[80:83], v[0:3], v[182:185], v[116:119]
	v_mfma_f32_16x16x32_bf16 v[88:91], v[16:19], v[182:185], v[112:115]
	v_mfma_f32_16x16x32_bf16 v[108:111], v[0:3], v[190:193], v[108:111]
	v_mfma_f32_16x16x32_bf16 v[116:119], v[16:19], v[190:193], v[104:107]
	v_mfma_f32_16x16x32_bf16 v[100:103], v[0:3], v[198:201], v[100:103]
	v_mfma_f32_16x16x32_bf16 v[124:127], v[16:19], v[198:201], v[96:99]
	v_mfma_f32_16x16x32_bf16 v[120:123], v[8:11], v[160:163], v[64:67]
	v_mfma_f32_16x16x32_bf16 v[112:115], v[140:143], v[160:163], v[72:75]
	v_mfma_f32_16x16x32_bf16 v[104:107], v[8:11], v[186:189], v[80:83]
	v_mfma_f32_16x16x32_bf16 v[96:99], v[140:143], v[186:189], v[88:91]
	v_mfma_f32_16x16x32_bf16 v[88:91], v[8:11], v[194:197], v[108:111]
	v_mfma_f32_16x16x32_bf16 v[80:83], v[140:143], v[194:197], v[116:119]
	v_mfma_f32_16x16x32_bf16 v[72:75], v[8:11], v[202:205], v[100:103]
	v_mfma_f32_16x16x32_bf16 v[64:67], v[140:143], v[202:205], v[124:127]
	s_barrier
	ds_read_b128 v[206:209], v135
	ds_read_b128 v[210:213], v136
	ds_read_b128 v[214:217], v137
	ds_read_b128 v[136:139], v138
	s_waitcnt vmcnt(0)
	s_barrier
; #define LDA(dst, b, h) _Pragma("unroll") for (int m = 0; m < 4; ++m) _Pragma("unroll") for (int k = 0; k < 2; ++k) \
;     dst[m][k] = *reinterpret_cast<const bf16x8*>(SA(b, h) + lds_byte(wr * 64 + m * 16 + fr, k * 32 + fq * 8))
; #define LDB(dst, b, h) _Pragma("unroll") for (int n = 0; n < 2; ++n) _Pragma("unroll") for (int k = 0; k < 2; ++k) \
;     dst[n][k] = *reinterpret_cast<const bf16x8*>(SB(b, h) + lds_byte(wc * 32 + n * 16 + fr, k * 32 + fq * 8))
; #define WAIT_V(n) asm volatile("s_waitcnt vmcnt(" #n ")" ::: "memory")
; #define WAIT_L(n) asm volatile("s_waitcnt lgkmcnt(" #n ")" ::: "memory")
; #define BAR __builtin_amdgcn_s_barrier()
;     ...
;       LDB(B1, 1, 1); WAIT_V(0); BAR; WAIT_L(0); MMA(0, 1, At, B1); BAR;
;       LDA(At, 1, 1); BAR; WAIT_L(0); MMA(1, 0, At, B0); MMA(1, 1, At, B1); BAR; }
;     if (wr == 0) BAR;
	s_waitcnt lgkmcnt(0)
	v_mfma_f32_16x16x32_bf16 v[92:95], v[206:209], v[24:27], v[92:95]
	v_mfma_f32_16x16x32_bf16 v[24:27], v[214:217], v[24:27], v[166:169]
	v_mfma_f32_16x16x32_bf16 v[84:87], v[206:209], v[182:185], v[84:87]
	v_mfma_f32_16x16x32_bf16 v[100:103], v[214:217], v[182:185], v[170:173]
	v_mfma_f32_16x16x32_bf16 v[76:79], v[206:209], v[190:193], v[76:79]
	v_mfma_f32_16x16x32_bf16 v[164:167], v[214:217], v[190:193], v[174:177]
	v_mfma_f32_16x16x32_bf16 v[68:71], v[206:209], v[198:201], v[68:71]
	v_mfma_f32_16x16x32_bf16 v[168:171], v[214:217], v[198:201], v[178:181]
	v_mfma_f32_16x16x32_bf16 v[124:127], v[210:213], v[160:163], v[92:95]
	v_mfma_f32_16x16x32_bf16 v[116:119], v[136:139], v[160:163], v[24:27]
	v_mfma_f32_16x16x32_bf16 v[108:111], v[210:213], v[186:189], v[84:87]
	v_mfma_f32_16x16x32_bf16 v[100:103], v[136:139], v[186:189], v[100:103]
	v_mfma_f32_16x16x32_bf16 v[92:95], v[210:213], v[194:197], v[76:79]
	v_mfma_f32_16x16x32_bf16 v[84:87], v[136:139], v[194:197], v[164:167]
	v_mfma_f32_16x16x32_bf16 v[76:79], v[210:213], v[202:205], v[68:71]
	v_mfma_f32_16x16x32_bf16 v[68:71], v[136:139], v[202:205], v[168:171]
	s_barrier
	ds_read_b128 v[160:163], v131 offset:49152
	ds_read_b128 v[164:167], v131 offset:50176
	ds_read_b128 v[168:171], v134 offset:49152
	ds_read_b128 v[172:175], v134 offset:50176
	ds_read_b128 v[176:179], v133 offset:49152
	ds_read_b128 v[180:183], v133 offset:50176
	ds_read_b128 v[184:187], v132 offset:49152
	ds_read_b128 v[132:135], v132 offset:50176
	s_barrier
	s_waitcnt lgkmcnt(0)
	v_mfma_f32_16x16x32_bf16 v[24:27], v[0:3], v[160:163], v[60:63]
	v_mfma_f32_16x16x32_bf16 v[60:63], v[16:19], v[160:163], v[56:59]
	v_mfma_f32_16x16x32_bf16 v[52:55], v[0:3], v[168:171], v[52:55]
	v_mfma_f32_16x16x32_bf16 v[188:191], v[16:19], v[168:171], v[48:51]
	v_mfma_f32_16x16x32_bf16 v[44:47], v[0:3], v[176:179], v[44:47]
	v_mfma_f32_16x16x32_bf16 v[192:195], v[16:19], v[176:179], v[40:43]
	v_mfma_f32_16x16x32_bf16 v[0:3], v[0:3], v[184:187], v[36:39]
	v_mfma_f32_16x16x32_bf16 v[36:39], v[16:19], v[184:187], v[32:35]
	v_mfma_f32_16x16x32_bf16 v[56:59], v[8:11], v[164:167], v[24:27]
	v_mfma_f32_16x16x32_bf16 v[48:51], v[140:143], v[164:167], v[60:63]
	v_mfma_f32_16x16x32_bf16 v[40:43], v[8:11], v[172:175], v[52:55]
	v_mfma_f32_16x16x32_bf16 v[32:35], v[140:143], v[172:175], v[188:191]
	v_mfma_f32_16x16x32_bf16 v[24:27], v[8:11], v[180:183], v[44:47]
	v_mfma_f32_16x16x32_bf16 v[16:19], v[140:143], v[180:183], v[192:195]
	v_mfma_f32_16x16x32_bf16 v[8:11], v[8:11], v[132:135], v[0:3]
	v_mfma_f32_16x16x32_bf16 v[0:3], v[140:143], v[132:135], v[36:39]
	v_mfma_f32_16x16x32_bf16 v[28:31], v[206:209], v[160:163], v[28:31]
	v_mfma_f32_16x16x32_bf16 v[36:39], v[214:217], v[160:163], v[144:147]
	v_mfma_f32_16x16x32_bf16 v[20:23], v[206:209], v[168:171], v[20:23]
	v_mfma_f32_16x16x32_bf16 v[140:143], v[214:217], v[168:171], v[148:151]
	v_mfma_f32_16x16x32_bf16 v[12:15], v[206:209], v[176:179], v[12:15]
	v_mfma_f32_16x16x32_bf16 v[144:147], v[214:217], v[176:179], v[152:155]
	v_mfma_f32_16x16x32_bf16 v[4:7], v[206:209], v[184:187], v[4:7]
	v_mfma_f32_16x16x32_bf16 v[148:151], v[214:217], v[184:187], v[156:159]
	v_mfma_f32_16x16x32_bf16 v[60:63], v[210:213], v[164:167], v[28:31]
	v_mfma_f32_16x16x32_bf16 v[52:55], v[136:139], v[164:167], v[36:39]
	v_mfma_f32_16x16x32_bf16 v[44:47], v[210:213], v[172:175], v[20:23]
	v_mfma_f32_16x16x32_bf16 v[36:39], v[136:139], v[172:175], v[140:143]
	v_mfma_f32_16x16x32_bf16 v[28:31], v[210:213], v[180:183], v[12:15]
	v_mfma_f32_16x16x32_bf16 v[20:23], v[136:139], v[180:183], v[144:147]
	v_mfma_f32_16x16x32_bf16 v[12:15], v[210:213], v[132:135], v[4:7]
	v_mfma_f32_16x16x32_bf16 v[4:7], v[136:139], v[132:135], v[148:151]
	v_cmp_gt_u32_e32 vcc, s35, v130
	s_barrier
	s_and_saveexec_b64 s[10:11], vcc
	s_cbranch_execz .LBB0_98
	s_barrier

; #define STAGE(P, RS, SOFF, OFF, kt) do { const int _so = (SOFF) + (kt) * (BK * 2); \
;     _Pragma("unroll") for (int _i = 0; _i < 2; ++_i) { \
;       __builtin_amdgcn_raw_ptr_buffer_load_lds(RS, (__attribute__((address_space(3))) void*)((P) + wave * 1024 + _i * 8192), 16, OFF[_i], _so, 0, 0); } } while (0)
; #define LDA(dst, b, h) _Pragma("unroll") for (int m = 0; m < 4; ++m) _Pragma("unroll") for (int k = 0; k < 2; ++k) \
;     dst[m][k] = *reinterpret_cast<const bf16x8*>(SA(b, h) + lds_byte(wr * 64 + m * 16 + fr, k * 32 + fq * 8))
; #define LDB(dst, b, h) _Pragma("unroll") for (int n = 0; n < 2; ++n) _Pragma("unroll") for (int k = 0; k < 2; ++k) \
;     dst[n][k] = *reinterpret_cast<const bf16x8*>(SB(b, h) + lds_byte(wc * 32 + n * 16 + fr, k * 32 + fq * 8))
; #define WAIT_V(n) asm volatile("s_waitcnt vmcnt(" #n ")" ::: "memory")
; #define WAIT_L(n) asm volatile("s_waitcnt lgkmcnt(" #n ")" ::: "memory")
; #define BAR __builtin_amdgcn_s_barrier()
; #define SCHED __builtin_amdgcn_sched_barrier(0)
;     ...
;     for (int t = 0; t < nt - 2; t += 2) {
;       LDB(B0, 0, 0); SCHED; LDA(At, 0, 0); STAGE(SA(1, 1), rsA, sA1, offA, t + 1);
;       WAIT_L(8); BAR; WAIT_L(0); MMA(0, 0, At, B0); BAR; SCHED;
;       LDB(B1, 0, 1); STAGE(SB(0, 0), rsB, sB0, offB, t + 2);
;       BAR; WAIT_L(0); MMA(0, 1, At, B1); BAR;
;       LDA(At, 0, 1); STAGE(SA(0, 0), rsA, sA0, offA, t + 2);
;       BAR; WAIT_L(0); MMA(1, 0, At, B0); BAR; SCHED;
;       STAGE(SB(0, 1), rsB, sB1, offB, t + 2);
;       WAIT_V(6); BAR; MMA(1, 1, At, B1); BAR;
.LBB0_110:
	ds_read_b128 v[156:159], v151
	ds_read_b128 v[160:163], v152
	ds_read_b128 v[164:167], v153
	ds_read_b128 v[168:171], v154
	s_add_i32 s44, s38, s17
	s_add_i32 s10, s44, 0x80
	s_mov_b32 m0, s31
	ds_read_b128 v[172:175], v131
	ds_read_b128 v[176:179], v131 offset:1024
	ds_read_b128 v[180:183], v138
	ds_read_b128 v[184:187], v138 offset:1024
	ds_read_b128 v[188:191], v137
	ds_read_b128 v[192:195], v137 offset:1024
	ds_read_b128 v[196:199], v135
	ds_read_b128 v[200:203], v135 offset:1024
	buffer_load_dwordx4 v128, s[4:7], s10 offen lds
	s_mov_b32 m0, s33
	s_nop 0
	buffer_load_dwordx4 v132, s[4:7], s10 offen lds
	s_waitcnt lgkmcnt(8)
	s_barrier
	s_waitcnt lgkmcnt(0)
	v_mfma_f32_16x16x32_bf16 v[124:127], v[156:159], v[172:175], v[124:127]
	v_mfma_f32_16x16x32_bf16 v[120:123], v[164:167], v[172:175], v[120:123]
	v_mfma_f32_16x16x32_bf16 v[116:119], v[156:159], v[180:183], v[116:119]
	v_mfma_f32_16x16x32_bf16 v[112:115], v[164:167], v[180:183], v[112:115]
	v_mfma_f32_16x16x32_bf16 v[108:111], v[156:159], v[188:191], v[108:111]
	v_mfma_f32_16x16x32_bf16 v[104:107], v[164:167], v[188:191], v[104:107]
	v_mfma_f32_16x16x32_bf16 v[100:103], v[156:159], v[196:199], v[100:103]
	v_mfma_f32_16x16x32_bf16 v[96:99], v[164:167], v[196:199], v[96:99]
	v_mfma_f32_16x16x32_bf16 v[124:127], v[160:163], v[176:179], v[124:127]
	v_mfma_f32_16x16x32_bf16 v[120:123], v[168:171], v[176:179], v[120:123]
	v_mfma_f32_16x16x32_bf16 v[116:119], v[160:163], v[184:187], v[116:119]
	v_mfma_f32_16x16x32_bf16 v[112:115], v[168:171], v[184:187], v[112:115]
	v_mfma_f32_16x16x32_bf16 v[108:111], v[160:163], v[192:195], v[108:111]
	v_mfma_f32_16x16x32_bf16 v[104:107], v[168:171], v[192:195], v[104:107]
	v_mfma_f32_16x16x32_bf16 v[100:103], v[160:163], v[200:203], v[100:103]
	v_mfma_f32_16x16x32_bf16 v[96:99], v[168:171], v[200:203], v[96:99]
	s_barrier
	s_add_i32 s45, s40, s17
	s_add_i32 s46, s45, 0x100
	s_mov_b32 s10, s6
	s_mov_b32 s11, s7
	s_mov_b32 m0, s3
	ds_read_b128 v[204:207], v147
	ds_read_b128 v[208:211], v148
	ds_read_b128 v[212:215], v149
	ds_read_b128 v[216:219], v150
	buffer_load_dwordx4 v130, s[8:11], s46 offen lds
	s_mov_b32 m0, s18
	s_nop 0
	buffer_load_dwordx4 v134, s[8:11], s46 offen lds
	s_barrier
	s_waitcnt lgkmcnt(0)
	v_mfma_f32_16x16x32_bf16 v[92:95], v[204:207], v[172:175], v[92:95]
	v_mfma_f32_16x16x32_bf16 v[88:91], v[212:215], v[172:175], v[88:91]
	v_mfma_f32_16x16x32_bf16 v[84:87], v[204:207], v[180:183], v[84:87]
	v_mfma_f32_16x16x32_bf16 v[80:83], v[212:215], v[180:183], v[80:83]
	v_mfma_f32_16x16x32_bf16 v[76:79], v[204:207], v[188:191], v[76:79]
	v_mfma_f32_16x16x32_bf16 v[72:75], v[212:215], v[188:191], v[72:75]
	v_mfma_f32_16x16x32_bf16 v[68:71], v[204:207], v[196:199], v[68:71]
	v_mfma_f32_16x16x32_bf16 v[64:67], v[212:215], v[196:199], v[64:67]
	v_mfma_f32_16x16x32_bf16 v[92:95], v[208:211], v[176:179], v[92:95]
	v_mfma_f32_16x16x32_bf16 v[88:91], v[216:219], v[176:179], v[88:91]
	v_mfma_f32_16x16x32_bf16 v[84:87], v[208:211], v[184:187], v[84:87]
	v_mfma_f32_16x16x32_bf16 v[80:83], v[216:219], v[184:187], v[80:83]
	v_mfma_f32_16x16x32_bf16 v[76:79], v[208:211], v[192:195], v[76:79]
	v_mfma_f32_16x16x32_bf16 v[72:75], v[216:219], v[192:195], v[72:75]
	v_mfma_f32_16x16x32_bf16 v[68:71], v[208:211], v[200:203], v[68:71]
	v_mfma_f32_16x16x32_bf16 v[64:67], v[216:219], v[200:203], v[64:67]
	s_barrier
	s_add_i32 s46, s39, s17
	s_add_i32 s47, s46, 0x100
	s_mov_b32 m0, s0
	ds_read_b128 v[172:175], v131 offset:16384
	ds_read_b128 v[176:179], v131 offset:17408
	ds_read_b128 v[180:183], v138 offset:16384
	ds_read_b128 v[184:187], v138 offset:17408
	ds_read_b128 v[188:191], v137 offset:16384
	ds_read_b128 v[192:195], v137 offset:17408
	ds_read_b128 v[196:199], v135 offset:16384
	ds_read_b128 v[200:203], v135 offset:17408
	buffer_load_dwordx4 v128, s[4:7], s47 offen lds
	s_mov_b32 m0, s19
	s_nop 0
	buffer_load_dwordx4 v132, s[4:7], s47 offen lds
	s_barrier
	s_waitcnt lgkmcnt(0)
	v_mfma_f32_16x16x32_bf16 v[60:63], v[156:159], v[172:175], v[60:63]
	v_mfma_f32_16x16x32_bf16 v[56:59], v[164:167], v[172:175], v[56:59]
	v_mfma_f32_16x16x32_bf16 v[52:55], v[156:159], v[180:183], v[52:55]
	v_mfma_f32_16x16x32_bf16 v[48:51], v[164:167], v[180:183], v[48:51]
	v_mfma_f32_16x16x32_bf16 v[44:47], v[156:159], v[188:191], v[44:47]
	v_mfma_f32_16x16x32_bf16 v[40:43], v[164:167], v[188:191], v[40:43]
	v_mfma_f32_16x16x32_bf16 v[36:39], v[156:159], v[196:199], v[36:39]
	v_mfma_f32_16x16x32_bf16 v[32:35], v[164:167], v[196:199], v[32:35]
	v_mfma_f32_16x16x32_bf16 v[60:63], v[160:163], v[176:179], v[60:63]
	v_mfma_f32_16x16x32_bf16 v[56:59], v[168:171], v[176:179], v[56:59]
	v_mfma_f32_16x16x32_bf16 v[52:55], v[160:163], v[184:187], v[52:55]
	v_mfma_f32_16x16x32_bf16 v[48:51], v[168:171], v[184:187], v[48:51]
	v_mfma_f32_16x16x32_bf16 v[44:47], v[160:163], v[192:195], v[44:47]
	v_mfma_f32_16x16x32_bf16 v[40:43], v[168:171], v[192:195], v[40:43]
	v_mfma_f32_16x16x32_bf16 v[36:39], v[160:163], v[200:203], v[36:39]
	v_mfma_f32_16x16x32_bf16 v[32:35], v[168:171], v[200:203], v[32:35]
	s_barrier
	s_add_i32 s47, s41, s17
	s_add_i32 s48, s47, 0x100
	s_mov_b32 m0, s20
	s_nop 0
	buffer_load_dwordx4 v130, s[8:11], s48 offen lds
	s_mov_b32 m0, s21
	s_nop 0
	buffer_load_dwordx4 v134, s[8:11], s48 offen lds
	s_waitcnt vmcnt(6)
	s_barrier
; #define STAGE(P, RS, SOFF, OFF, kt) do { const int _so = (SOFF) + (kt) * (BK * 2); \
;     _Pragma("unroll") for (int _i = 0; _i < 2; ++_i) { \
;       __builtin_amdgcn_raw_ptr_buffer_load_lds(RS, (__attribute__((address_space(3))) void*)((P) + wave * 1024 + _i * 8192), 16, OFF[_i], _so, 0, 0); } } while (0)
; #define LDA(dst, b, h) _Pragma("unroll") for (int m = 0; m < 4; ++m) _Pragma("unroll") for (int k = 0; k < 2; ++k) \
;     dst[m][k] = *reinterpret_cast<const bf16x8*>(SA(b, h) + lds_byte(wr * 64 + m * 16 + fr, k * 32 + fq * 8))
; #define LDB(dst, b, h) _Pragma("unroll") for (int n = 0; n < 2; ++n) _Pragma("unroll") for (int k = 0; k < 2; ++k) \
;     dst[n][k] = *reinterpret_cast<const bf16x8*>(SB(b, h) + lds_byte(wc * 32 + n * 16 + fr, k * 32 + fq * 8))
; #define WAIT_V(n) asm volatile("s_waitcnt vmcnt(" #n ")" ::: "memory")
; #define WAIT_L(n) asm volatile("s_waitcnt lgkmcnt(" #n ")" ::: "memory")
; #define BAR __builtin_amdgcn_s_barrier()
; #define SCHED __builtin_amdgcn_sched_barrier(0)
;     ...
;       WAIT_V(6); BAR; MMA(1, 1, At, B1); BAR;
;       LDB(B0, 1, 0); SCHED; LDA(At, 1, 0); STAGE(SA(0, 1), rsA, sA1, offA, t + 2);
;       WAIT_L(8); BAR; WAIT_L(0); MMA(0, 0, At, B0); BAR; SCHED;
;       LDB(B1, 1, 1); STAGE(SB(1, 0), rsB, sB0, offB, t + 3);
;       BAR; WAIT_L(0); MMA(0, 1, At, B1); BAR;
;       LDA(At, 1, 1); STAGE(SA(1, 0), rsA, sA0, offA, t + 3);
;       BAR; WAIT_L(0); MMA(1, 0, At, B0); BAR; SCHED;
;       STAGE(SB(1, 1), rsB, sB1, offB, t + 3);
;       WAIT_V(6); BAR; MMA(1, 1, At, B1); BAR;
	v_mfma_f32_16x16x32_bf16 v[28:31], v[204:207], v[172:175], v[28:31]
	v_mfma_f32_16x16x32_bf16 v[24:27], v[212:215], v[172:175], v[24:27]
	v_mfma_f32_16x16x32_bf16 v[20:23], v[204:207], v[180:183], v[20:23]
	v_mfma_f32_16x16x32_bf16 v[16:19], v[212:215], v[180:183], v[16:19]
	v_mfma_f32_16x16x32_bf16 v[12:15], v[204:207], v[188:191], v[12:15]
	v_mfma_f32_16x16x32_bf16 v[8:11], v[212:215], v[188:191], v[8:11]
	v_mfma_f32_16x16x32_bf16 v[4:7], v[204:207], v[196:199], v[4:7]
	v_mfma_f32_16x16x32_bf16 v[0:3], v[212:215], v[196:199], v[0:3]
	v_mfma_f32_16x16x32_bf16 v[28:31], v[208:211], v[176:179], v[28:31]
	v_mfma_f32_16x16x32_bf16 v[24:27], v[216:219], v[176:179], v[24:27]
	v_mfma_f32_16x16x32_bf16 v[20:23], v[208:211], v[184:187], v[20:23]
	v_mfma_f32_16x16x32_bf16 v[16:19], v[216:219], v[184:187], v[16:19]
	v_mfma_f32_16x16x32_bf16 v[12:15], v[208:211], v[192:195], v[12:15]
	v_mfma_f32_16x16x32_bf16 v[8:11], v[216:219], v[192:195], v[8:11]
	v_mfma_f32_16x16x32_bf16 v[4:7], v[208:211], v[200:203], v[4:7]
	v_mfma_f32_16x16x32_bf16 v[0:3], v[216:219], v[200:203], v[0:3]
	s_barrier
	ds_read_b128 v[156:159], v143
	ds_read_b128 v[160:163], v144
	ds_read_b128 v[164:167], v145
	ds_read_b128 v[168:171], v146
	s_addk_i32 s44, 0x100
	s_mov_b32 m0, s22
	ds_read_b128 v[172:175], v131 offset:32768
	ds_read_b128 v[176:179], v131 offset:33792
	ds_read_b128 v[180:183], v138 offset:32768
	ds_read_b128 v[184:187], v138 offset:33792
	ds_read_b128 v[188:191], v137 offset:32768
	ds_read_b128 v[192:195], v137 offset:33792
	ds_read_b128 v[196:199], v135 offset:32768
	ds_read_b128 v[200:203], v135 offset:33792
	buffer_load_dwordx4 v128, s[4:7], s44 offen lds
	s_mov_b32 m0, s23
	s_nop 0
	buffer_load_dwordx4 v132, s[4:7], s44 offen lds
	s_waitcnt lgkmcnt(8)
	s_barrier
	s_waitcnt lgkmcnt(0)
	v_mfma_f32_16x16x32_bf16 v[124:127], v[156:159], v[172:175], v[124:127]
	v_mfma_f32_16x16x32_bf16 v[120:123], v[164:167], v[172:175], v[120:123]
	v_mfma_f32_16x16x32_bf16 v[116:119], v[156:159], v[180:183], v[116:119]
	v_mfma_f32_16x16x32_bf16 v[112:115], v[164:167], v[180:183], v[112:115]
	v_mfma_f32_16x16x32_bf16 v[108:111], v[156:159], v[188:191], v[108:111]
	v_mfma_f32_16x16x32_bf16 v[104:107], v[164:167], v[188:191], v[104:107]
	v_mfma_f32_16x16x32_bf16 v[100:103], v[156:159], v[196:199], v[100:103]
	v_mfma_f32_16x16x32_bf16 v[96:99], v[164:167], v[196:199], v[96:99]
	v_mfma_f32_16x16x32_bf16 v[124:127], v[160:163], v[176:179], v[124:127]
	v_mfma_f32_16x16x32_bf16 v[120:123], v[168:171], v[176:179], v[120:123]
	v_mfma_f32_16x16x32_bf16 v[116:119], v[160:163], v[184:187], v[116:119]
	v_mfma_f32_16x16x32_bf16 v[112:115], v[168:171], v[184:187], v[112:115]
	v_mfma_f32_16x16x32_bf16 v[108:111], v[160:163], v[192:195], v[108:111]
	v_mfma_f32_16x16x32_bf16 v[104:107], v[168:171], v[192:195], v[104:107]
	v_mfma_f32_16x16x32_bf16 v[100:103], v[160:163], v[200:203], v[100:103]
	v_mfma_f32_16x16x32_bf16 v[96:99], v[168:171], v[200:203], v[96:99]
	s_barrier
	s_addk_i32 s45, 0x180
	s_mov_b32 m0, s24
	ds_read_b128 v[204:207], v139
	ds_read_b128 v[208:211], v140
	ds_read_b128 v[212:215], v141
	ds_read_b128 v[216:219], v142
	buffer_load_dwordx4 v130, s[8:11], s45 offen lds
	s_mov_b32 m0, s25
	s_nop 0
	buffer_load_dwordx4 v134, s[8:11], s45 offen lds
	s_barrier
	s_waitcnt lgkmcnt(0)
	v_mfma_f32_16x16x32_bf16 v[92:95], v[204:207], v[172:175], v[92:95]
	v_mfma_f32_16x16x32_bf16 v[88:91], v[212:215], v[172:175], v[88:91]
	v_mfma_f32_16x16x32_bf16 v[84:87], v[204:207], v[180:183], v[84:87]
	v_mfma_f32_16x16x32_bf16 v[80:83], v[212:215], v[180:183], v[80:83]
	v_mfma_f32_16x16x32_bf16 v[76:79], v[204:207], v[188:191], v[76:79]
	v_mfma_f32_16x16x32_bf16 v[72:75], v[212:215], v[188:191], v[72:75]
	v_mfma_f32_16x16x32_bf16 v[68:71], v[204:207], v[196:199], v[68:71]
	v_mfma_f32_16x16x32_bf16 v[64:67], v[212:215], v[196:199], v[64:67]
	v_mfma_f32_16x16x32_bf16 v[92:95], v[208:211], v[176:179], v[92:95]
	v_mfma_f32_16x16x32_bf16 v[88:91], v[216:219], v[176:179], v[88:91]
	v_mfma_f32_16x16x32_bf16 v[84:87], v[208:211], v[184:187], v[84:87]
	v_mfma_f32_16x16x32_bf16 v[80:83], v[216:219], v[184:187], v[80:83]
	v_mfma_f32_16x16x32_bf16 v[76:79], v[208:211], v[192:195], v[76:79]
	v_mfma_f32_16x16x32_bf16 v[72:75], v[216:219], v[192:195], v[72:75]
	v_mfma_f32_16x16x32_bf16 v[68:71], v[208:211], v[200:203], v[68:71]
	v_mfma_f32_16x16x32_bf16 v[64:67], v[216:219], v[200:203], v[64:67]
	s_barrier
	s_addk_i32 s46, 0x180
	s_mov_b32 m0, s26
	ds_read_b128 v[172:175], v131 offset:49152
	ds_read_b128 v[176:179], v131 offset:50176
	ds_read_b128 v[180:183], v138 offset:49152
	ds_read_b128 v[184:187], v138 offset:50176
	ds_read_b128 v[188:191], v137 offset:49152
	ds_read_b128 v[192:195], v137 offset:50176
	ds_read_b128 v[196:199], v135 offset:49152
	ds_read_b128 v[200:203], v135 offset:50176
	buffer_load_dwordx4 v128, s[4:7], s46 offen lds
	s_mov_b32 m0, s27
	s_nop 0
	buffer_load_dwordx4 v132, s[4:7], s46 offen lds
	s_barrier
	s_waitcnt lgkmcnt(0)
	v_mfma_f32_16x16x32_bf16 v[60:63], v[156:159], v[172:175], v[60:63]
	v_mfma_f32_16x16x32_bf16 v[56:59], v[164:167], v[172:175], v[56:59]
	v_mfma_f32_16x16x32_bf16 v[52:55], v[156:159], v[180:183], v[52:55]
	v_mfma_f32_16x16x32_bf16 v[48:51], v[164:167], v[180:183], v[48:51]
	v_mfma_f32_16x16x32_bf16 v[44:47], v[156:159], v[188:191], v[44:47]
	v_mfma_f32_16x16x32_bf16 v[40:43], v[164:167], v[188:191], v[40:43]
	v_mfma_f32_16x16x32_bf16 v[36:39], v[156:159], v[196:199], v[36:39]
	v_mfma_f32_16x16x32_bf16 v[32:35], v[164:167], v[196:199], v[32:35]
	v_mfma_f32_16x16x32_bf16 v[60:63], v[160:163], v[176:179], v[60:63]
	v_mfma_f32_16x16x32_bf16 v[56:59], v[168:171], v[176:179], v[56:59]
	v_mfma_f32_16x16x32_bf16 v[52:55], v[160:163], v[184:187], v[52:55]
	v_mfma_f32_16x16x32_bf16 v[48:51], v[168:171], v[184:187], v[48:51]
	v_mfma_f32_16x16x32_bf16 v[44:47], v[160:163], v[192:195], v[44:47]
	v_mfma_f32_16x16x32_bf16 v[40:43], v[168:171], v[192:195], v[40:43]
	v_mfma_f32_16x16x32_bf16 v[36:39], v[160:163], v[200:203], v[36:39]
	v_mfma_f32_16x16x32_bf16 v[32:35], v[168:171], v[200:203], v[32:35]
	s_barrier
; #define STAGE(P, RS, SOFF, OFF, kt) do { const int _so = (SOFF) + (kt) * (BK * 2); \
;     _Pragma("unroll") for (int _i = 0; _i < 2; ++_i) { \
;       __builtin_amdgcn_raw_ptr_buffer_load_lds(RS, (__attribute__((address_space(3))) void*)((P) + wave * 1024 + _i * 8192), 16, OFF[_i], _so, 0, 0); } } while (0)
; #define LDA(dst, b, h) _Pragma("unroll") for (int m = 0; m < 4; ++m) _Pragma("unroll") for (int k = 0; k < 2; ++k) \
;     dst[m][k] = *reinterpret_cast<const bf16x8*>(SA(b, h) + lds_byte(wr * 64 + m * 16 + fr, k * 32 + fq * 8))
; #define LDB(dst, b, h) _Pragma("unroll") for (int n = 0; n < 2; ++n) _Pragma("unroll") for (int k = 0; k < 2; ++k) \
;     dst[n][k] = *reinterpret_cast<const bf16x8*>(SB(b, h) + lds_byte(wc * 32 + n * 16 + fr, k * 32 + fq * 8))
; #define WAIT_V(n) asm volatile("s_waitcnt vmcnt(" #n ")" ::: "memory")
; #define WAIT_L(n) asm volatile("s_waitcnt lgkmcnt(" #n ")" ::: "memory")
; #define BAR __builtin_amdgcn_s_barrier()
;     ...
;       WAIT_V(6); BAR; MMA(1, 1, At, B1); BAR;
;     }
;     { LDB(B0, 0, 0); LDA(At, 0, 0); STAGE(SA(1, 1), rsA, sA1, offA, nt - 1);
;       BAR; WAIT_L(0); MMA(0, 0, At, B0); BAR;
;       LDB(B1, 0, 1); BAR; WAIT_L(0); MMA(0, 1, At, B1); BAR;
;       LDA(At, 0, 1); WAIT_V(4); BAR; WAIT_L(0); MMA(1, 0, At, B0); MMA(1, 1, At, B1); BAR; }
	s_addk_i32 s47, 0x180
	s_mov_b32 m0, s28
	s_nop 0
	buffer_load_dwordx4 v130, s[8:11], s47 offen lds
	s_mov_b32 m0, s29
	s_nop 0
	buffer_load_dwordx4 v134, s[8:11], s47 offen lds
	s_add_i32 s16, s16, 2
	s_addk_i32 s17, 0x100
	s_cmp_gt_u32 s16, 3
	s_waitcnt vmcnt(6)
	s_barrier
	v_mfma_f32_16x16x32_bf16 v[28:31], v[204:207], v[172:175], v[28:31]
	v_mfma_f32_16x16x32_bf16 v[24:27], v[212:215], v[172:175], v[24:27]
	v_mfma_f32_16x16x32_bf16 v[20:23], v[204:207], v[180:183], v[20:23]
	v_mfma_f32_16x16x32_bf16 v[16:19], v[212:215], v[180:183], v[16:19]
	v_mfma_f32_16x16x32_bf16 v[12:15], v[204:207], v[188:191], v[12:15]
	v_mfma_f32_16x16x32_bf16 v[8:11], v[212:215], v[188:191], v[8:11]
	v_mfma_f32_16x16x32_bf16 v[4:7], v[204:207], v[196:199], v[4:7]
	v_mfma_f32_16x16x32_bf16 v[0:3], v[212:215], v[196:199], v[0:3]
	v_mfma_f32_16x16x32_bf16 v[28:31], v[208:211], v[176:179], v[28:31]
	v_mfma_f32_16x16x32_bf16 v[24:27], v[216:219], v[176:179], v[24:27]
	v_mfma_f32_16x16x32_bf16 v[20:23], v[208:211], v[184:187], v[20:23]
	v_mfma_f32_16x16x32_bf16 v[16:19], v[216:219], v[184:187], v[16:19]
	v_mfma_f32_16x16x32_bf16 v[12:15], v[208:211], v[192:195], v[12:15]
	v_mfma_f32_16x16x32_bf16 v[8:11], v[216:219], v[192:195], v[8:11]
	v_mfma_f32_16x16x32_bf16 v[4:7], v[208:211], v[200:203], v[4:7]
	v_mfma_f32_16x16x32_bf16 v[0:3], v[216:219], v[200:203], v[0:3]
	s_barrier
	s_cbranch_scc0 .LBB0_110
	s_add_i32 s10, s38, 0x380
	s_mov_b32 m0, s31
	ds_read_b128 v[156:159], v151
	ds_read_b128 v[160:163], v152
	ds_read_b128 v[164:167], v153
	ds_read_b128 v[152:155], v154
	ds_read_b128 v[168:171], v131
	ds_read_b128 v[172:175], v131 offset:1024
	ds_read_b128 v[176:179], v138
	ds_read_b128 v[180:183], v138 offset:1024
	ds_read_b128 v[184:187], v137
	ds_read_b128 v[188:191], v137 offset:1024
	ds_read_b128 v[192:195], v135
	ds_read_b128 v[196:199], v135 offset:1024
	buffer_load_dwordx4 v128, s[4:7], s10 offen lds
	s_mov_b32 m0, s33
	s_nop 0
	buffer_load_dwordx4 v132, s[4:7], s10 offen lds
	s_barrier
	s_waitcnt lgkmcnt(0)
	v_mfma_f32_16x16x32_bf16 v[124:127], v[156:159], v[168:171], v[124:127]
	v_mfma_f32_16x16x32_bf16 v[120:123], v[164:167], v[168:171], v[120:123]
	v_mfma_f32_16x16x32_bf16 v[116:119], v[156:159], v[176:179], v[116:119]
	v_mfma_f32_16x16x32_bf16 v[112:115], v[164:167], v[176:179], v[112:115]
	v_mfma_f32_16x16x32_bf16 v[108:111], v[156:159], v[184:187], v[108:111]
	v_mfma_f32_16x16x32_bf16 v[104:107], v[164:167], v[184:187], v[104:107]
	v_mfma_f32_16x16x32_bf16 v[100:103], v[156:159], v[192:195], v[100:103]
	v_mfma_f32_16x16x32_bf16 v[96:99], v[164:167], v[192:195], v[96:99]
	v_mfma_f32_16x16x32_bf16 v[124:127], v[160:163], v[172:175], v[124:127]
	v_mfma_f32_16x16x32_bf16 v[120:123], v[152:155], v[172:175], v[120:123]
	v_mfma_f32_16x16x32_bf16 v[116:119], v[160:163], v[180:183], v[116:119]
	v_mfma_f32_16x16x32_bf16 v[112:115], v[152:155], v[180:183], v[112:115]
	v_mfma_f32_16x16x32_bf16 v[108:111], v[160:163], v[188:191], v[108:111]
	v_mfma_f32_16x16x32_bf16 v[104:107], v[152:155], v[188:191], v[104:107]
	v_mfma_f32_16x16x32_bf16 v[100:103], v[160:163], v[196:199], v[100:103]
	v_mfma_f32_16x16x32_bf16 v[96:99], v[152:155], v[196:199], v[96:99]
	s_barrier
	ds_read_b128 v[200:203], v147
	ds_read_b128 v[204:207], v148
	ds_read_b128 v[208:211], v149
	ds_read_b128 v[148:151], v150
	s_barrier
	s_waitcnt lgkmcnt(0)
	v_mfma_f32_16x16x32_bf16 v[92:95], v[200:203], v[168:171], v[92:95]
	v_mfma_f32_16x16x32_bf16 v[88:91], v[208:211], v[168:171], v[88:91]
	v_mfma_f32_16x16x32_bf16 v[84:87], v[200:203], v[176:179], v[84:87]
	v_mfma_f32_16x16x32_bf16 v[80:83], v[208:211], v[176:179], v[80:83]
	v_mfma_f32_16x16x32_bf16 v[76:79], v[200:203], v[184:187], v[76:79]
	v_mfma_f32_16x16x32_bf16 v[72:75], v[208:211], v[184:187], v[72:75]
	v_mfma_f32_16x16x32_bf16 v[68:71], v[200:203], v[192:195], v[68:71]
	v_mfma_f32_16x16x32_bf16 v[64:67], v[208:211], v[192:195], v[64:67]
	v_mfma_f32_16x16x32_bf16 v[92:95], v[204:207], v[172:175], v[92:95]
	v_mfma_f32_16x16x32_bf16 v[88:91], v[148:151], v[172:175], v[88:91]
	v_mfma_f32_16x16x32_bf16 v[84:87], v[204:207], v[180:183], v[84:87]
	v_mfma_f32_16x16x32_bf16 v[80:83], v[148:151], v[180:183], v[80:83]
	v_mfma_f32_16x16x32_bf16 v[76:79], v[204:207], v[188:191], v[76:79]
	v_mfma_f32_16x16x32_bf16 v[72:75], v[148:151], v[188:191], v[72:75]
	v_mfma_f32_16x16x32_bf16 v[68:71], v[204:207], v[196:199], v[68:71]
	v_mfma_f32_16x16x32_bf16 v[64:67], v[148:151], v[196:199], v[64:67]
	s_barrier
	ds_read_b128 v[168:171], v131 offset:16384
	ds_read_b128 v[172:175], v131 offset:17408
	ds_read_b128 v[176:179], v138 offset:16384
	ds_read_b128 v[180:183], v138 offset:17408
	ds_read_b128 v[184:187], v137 offset:16384
	ds_read_b128 v[188:191], v137 offset:17408
	ds_read_b128 v[192:195], v135 offset:16384
	ds_read_b128 v[196:199], v135 offset:17408
	s_waitcnt vmcnt(4)
	s_barrier
; #define LDA(dst, b, h) _Pragma("unroll") for (int m = 0; m < 4; ++m) _Pragma("unroll") for (int k = 0; k < 2; ++k) \
;     dst[m][k] = *reinterpret_cast<const bf16x8*>(SA(b, h) + lds_byte(wr * 64 + m * 16 + fr, k * 32 + fq * 8))
; #define LDB(dst, b, h) _Pragma("unroll") for (int n = 0; n < 2; ++n) _Pragma("unroll") for (int k = 0; k < 2; ++k) \
;     dst[n][k] = *reinterpret_cast<const bf16x8*>(SB(b, h) + lds_byte(wc * 32 + n * 16 + fr, k * 32 + fq * 8))
; #define WAIT_V(n) asm volatile("s_waitcnt vmcnt(" #n ")" ::: "memory")
; #define WAIT_L(n) asm volatile("s_waitcnt lgkmcnt(" #n ")" ::: "memory")
; #define BAR __builtin_amdgcn_s_barrier()
;     ...
;       LDA(At, 0, 1); WAIT_V(4); BAR; WAIT_L(0); MMA(1, 0, At, B0); MMA(1, 1, At, B1); BAR; }
;     { LDB(B0, 1, 0); LDA(At, 1, 0); WAIT_V(2); BAR; WAIT_L(0); MMA(0, 0, At, B0); BAR;
	s_waitcnt lgkmcnt(0)
	v_mfma_f32_16x16x32_bf16 v[60:63], v[156:159], v[168:171], v[60:63]
	v_mfma_f32_16x16x32_bf16 v[56:59], v[164:167], v[168:171], v[56:59]
	v_mfma_f32_16x16x32_bf16 v[52:55], v[156:159], v[176:179], v[52:55]
	v_mfma_f32_16x16x32_bf16 v[48:51], v[164:167], v[176:179], v[48:51]
	v_mfma_f32_16x16x32_bf16 v[44:47], v[156:159], v[184:187], v[44:47]
	v_mfma_f32_16x16x32_bf16 v[40:43], v[164:167], v[184:187], v[40:43]
	v_mfma_f32_16x16x32_bf16 v[36:39], v[156:159], v[192:195], v[36:39]
	v_mfma_f32_16x16x32_bf16 v[32:35], v[164:167], v[192:195], v[32:35]
	v_mfma_f32_16x16x32_bf16 v[60:63], v[160:163], v[172:175], v[60:63]
	v_mfma_f32_16x16x32_bf16 v[56:59], v[152:155], v[172:175], v[56:59]
	v_mfma_f32_16x16x32_bf16 v[52:55], v[160:163], v[180:183], v[52:55]
	v_mfma_f32_16x16x32_bf16 v[48:51], v[152:155], v[180:183], v[48:51]
	v_mfma_f32_16x16x32_bf16 v[44:47], v[160:163], v[188:191], v[44:47]
	v_mfma_f32_16x16x32_bf16 v[40:43], v[152:155], v[188:191], v[40:43]
	v_mfma_f32_16x16x32_bf16 v[36:39], v[160:163], v[196:199], v[36:39]
	v_mfma_f32_16x16x32_bf16 v[32:35], v[152:155], v[196:199], v[32:35]
	v_mfma_f32_16x16x32_bf16 v[28:31], v[200:203], v[168:171], v[28:31]
	v_mfma_f32_16x16x32_bf16 v[24:27], v[208:211], v[168:171], v[24:27]
	v_mfma_f32_16x16x32_bf16 v[20:23], v[200:203], v[176:179], v[20:23]
	v_mfma_f32_16x16x32_bf16 v[16:19], v[208:211], v[176:179], v[16:19]
	v_mfma_f32_16x16x32_bf16 v[12:15], v[200:203], v[184:187], v[12:15]
	v_mfma_f32_16x16x32_bf16 v[8:11], v[208:211], v[184:187], v[8:11]
	v_mfma_f32_16x16x32_bf16 v[4:7], v[200:203], v[192:195], v[4:7]
	v_mfma_f32_16x16x32_bf16 v[0:3], v[208:211], v[192:195], v[0:3]
	v_mfma_f32_16x16x32_bf16 v[28:31], v[204:207], v[172:175], v[28:31]
	v_mfma_f32_16x16x32_bf16 v[24:27], v[148:151], v[172:175], v[24:27]
	v_mfma_f32_16x16x32_bf16 v[20:23], v[204:207], v[180:183], v[20:23]
	v_mfma_f32_16x16x32_bf16 v[16:19], v[148:151], v[180:183], v[16:19]
	v_mfma_f32_16x16x32_bf16 v[12:15], v[204:207], v[188:191], v[12:15]
	v_mfma_f32_16x16x32_bf16 v[8:11], v[148:151], v[188:191], v[8:11]
	v_mfma_f32_16x16x32_bf16 v[4:7], v[204:207], v[196:199], v[4:7]
	v_mfma_f32_16x16x32_bf16 v[0:3], v[148:151], v[196:199], v[0:3]
	s_barrier
	ds_read_b128 v[148:151], v143
	ds_read_b128 v[152:155], v144
	ds_read_b128 v[156:159], v145
	ds_read_b128 v[144:147], v146
	ds_read_b128 v[160:163], v131 offset:32768
	ds_read_b128 v[164:167], v131 offset:33792
	ds_read_b128 v[168:171], v138 offset:32768
	ds_read_b128 v[172:175], v138 offset:33792
	ds_read_b128 v[176:179], v137 offset:32768
	ds_read_b128 v[180:183], v137 offset:33792
	ds_read_b128 v[184:187], v135 offset:32768
	ds_read_b128 v[188:191], v135 offset:33792
	s_waitcnt vmcnt(2)
	s_barrier
	s_waitcnt lgkmcnt(0)
	v_mfma_f32_16x16x32_bf16 v[124:127], v[148:151], v[160:163], v[124:127]
	v_mfma_f32_16x16x32_bf16 v[120:123], v[156:159], v[160:163], v[120:123]
	v_mfma_f32_16x16x32_bf16 v[116:119], v[148:151], v[168:171], v[116:119]
	v_mfma_f32_16x16x32_bf16 v[112:115], v[156:159], v[168:171], v[112:115]
	v_mfma_f32_16x16x32_bf16 v[108:111], v[148:151], v[176:179], v[108:111]
	v_mfma_f32_16x16x32_bf16 v[104:107], v[156:159], v[176:179], v[104:107]
	v_mfma_f32_16x16x32_bf16 v[100:103], v[148:151], v[184:187], v[100:103]
	v_mfma_f32_16x16x32_bf16 v[96:99], v[156:159], v[184:187], v[96:99]
	v_mfma_f32_16x16x32_bf16 v[124:127], v[152:155], v[164:167], v[124:127]
	v_mfma_f32_16x16x32_bf16 v[120:123], v[144:147], v[164:167], v[120:123]
	v_mfma_f32_16x16x32_bf16 v[116:119], v[152:155], v[172:175], v[116:119]
	v_mfma_f32_16x16x32_bf16 v[112:115], v[144:147], v[172:175], v[112:115]
	v_mfma_f32_16x16x32_bf16 v[108:111], v[152:155], v[180:183], v[108:111]
	v_mfma_f32_16x16x32_bf16 v[104:107], v[144:147], v[180:183], v[104:107]
	v_mfma_f32_16x16x32_bf16 v[100:103], v[152:155], v[188:191], v[100:103]
	v_mfma_f32_16x16x32_bf16 v[96:99], v[144:147], v[188:191], v[96:99]
	s_barrier
; #define LDA(dst, b, h) _Pragma("unroll") for (int m = 0; m < 4; ++m) _Pragma("unroll") for (int k = 0; k < 2; ++k) \
;     dst[m][k] = *reinterpret_cast<const bf16x8*>(SA(b, h) + lds_byte(wr * 64 + m * 16 + fr, k * 32 + fq * 8))
; #define LDB(dst, b, h) _Pragma("unroll") for (int n = 0; n < 2; ++n) _Pragma("unroll") for (int k = 0; k < 2; ++k) \
;     dst[n][k] = *reinterpret_cast<const bf16x8*>(SB(b, h) + lds_byte(wc * 32 + n * 16 + fr, k * 32 + fq * 8))
; #define WAIT_V(n) asm volatile("s_waitcnt vmcnt(" #n ")" ::: "memory")
; #define WAIT_L(n) asm volatile("s_waitcnt lgkmcnt(" #n ")" ::: "memory")
; #define BAR __builtin_amdgcn_s_barrier()
;     ...
;       LDB(B1, 1, 1); WAIT_V(0); BAR; WAIT_L(0); MMA(0, 1, At, B1); BAR;
;       LDA(At, 1, 1); BAR; WAIT_L(0); MMA(1, 0, At, B0); MMA(1, 1, At, B1); BAR; }
;     if (wr == 0) BAR;
	ds_read_b128 v[192:195], v139
	ds_read_b128 v[196:199], v140
	ds_read_b128 v[200:203], v141
	ds_read_b128 v[140:143], v142
	s_waitcnt vmcnt(0)
	s_barrier
	s_waitcnt lgkmcnt(0)
	v_mfma_f32_16x16x32_bf16 v[92:95], v[192:195], v[160:163], v[92:95]
	v_mfma_f32_16x16x32_bf16 v[88:91], v[200:203], v[160:163], v[88:91]
	v_mfma_f32_16x16x32_bf16 v[84:87], v[192:195], v[168:171], v[84:87]
	v_mfma_f32_16x16x32_bf16 v[80:83], v[200:203], v[168:171], v[80:83]
	v_mfma_f32_16x16x32_bf16 v[76:79], v[192:195], v[176:179], v[76:79]
	v_mfma_f32_16x16x32_bf16 v[72:75], v[200:203], v[176:179], v[72:75]
	v_mfma_f32_16x16x32_bf16 v[68:71], v[192:195], v[184:187], v[68:71]
	v_mfma_f32_16x16x32_bf16 v[64:67], v[200:203], v[184:187], v[64:67]
	v_mfma_f32_16x16x32_bf16 v[92:95], v[196:199], v[164:167], v[92:95]
	v_mfma_f32_16x16x32_bf16 v[88:91], v[140:143], v[164:167], v[88:91]
	v_mfma_f32_16x16x32_bf16 v[84:87], v[196:199], v[172:175], v[84:87]
	v_mfma_f32_16x16x32_bf16 v[80:83], v[140:143], v[172:175], v[80:83]
	v_mfma_f32_16x16x32_bf16 v[76:79], v[196:199], v[180:183], v[76:79]
	v_mfma_f32_16x16x32_bf16 v[72:75], v[140:143], v[180:183], v[72:75]
	v_mfma_f32_16x16x32_bf16 v[68:71], v[196:199], v[188:191], v[68:71]
	v_mfma_f32_16x16x32_bf16 v[64:67], v[140:143], v[188:191], v[64:67]
	s_barrier
	ds_read_b128 v[160:163], v131 offset:49152
	ds_read_b128 v[164:167], v131 offset:50176
	ds_read_b128 v[168:171], v138 offset:49152
	ds_read_b128 v[172:175], v138 offset:50176
	ds_read_b128 v[176:179], v137 offset:49152
	ds_read_b128 v[180:183], v137 offset:50176
	ds_read_b128 v[184:187], v135 offset:49152
	ds_read_b128 v[188:191], v135 offset:50176
	s_barrier
	s_waitcnt lgkmcnt(0)
	v_mfma_f32_16x16x32_bf16 v[60:63], v[148:151], v[160:163], v[60:63]
	v_mfma_f32_16x16x32_bf16 v[56:59], v[156:159], v[160:163], v[56:59]
	v_mfma_f32_16x16x32_bf16 v[52:55], v[148:151], v[168:171], v[52:55]
	v_mfma_f32_16x16x32_bf16 v[48:51], v[156:159], v[168:171], v[48:51]
	v_mfma_f32_16x16x32_bf16 v[44:47], v[148:151], v[176:179], v[44:47]
	v_mfma_f32_16x16x32_bf16 v[40:43], v[156:159], v[176:179], v[40:43]
	v_mfma_f32_16x16x32_bf16 v[36:39], v[148:151], v[184:187], v[36:39]
	v_mfma_f32_16x16x32_bf16 v[32:35], v[156:159], v[184:187], v[32:35]
	v_mfma_f32_16x16x32_bf16 v[60:63], v[152:155], v[164:167], v[60:63]
	v_mfma_f32_16x16x32_bf16 v[56:59], v[144:147], v[164:167], v[56:59]
	v_mfma_f32_16x16x32_bf16 v[52:55], v[152:155], v[172:175], v[52:55]
	v_mfma_f32_16x16x32_bf16 v[48:51], v[144:147], v[172:175], v[48:51]
	v_mfma_f32_16x16x32_bf16 v[44:47], v[152:155], v[180:183], v[44:47]
	v_mfma_f32_16x16x32_bf16 v[40:43], v[144:147], v[180:183], v[40:43]
	v_mfma_f32_16x16x32_bf16 v[36:39], v[152:155], v[188:191], v[36:39]
	v_mfma_f32_16x16x32_bf16 v[32:35], v[144:147], v[188:191], v[32:35]
	v_mfma_f32_16x16x32_bf16 v[28:31], v[192:195], v[160:163], v[28:31]
	v_mfma_f32_16x16x32_bf16 v[24:27], v[200:203], v[160:163], v[24:27]
	v_mfma_f32_16x16x32_bf16 v[20:23], v[192:195], v[168:171], v[20:23]
	v_mfma_f32_16x16x32_bf16 v[16:19], v[200:203], v[168:171], v[16:19]
	v_mfma_f32_16x16x32_bf16 v[12:15], v[192:195], v[176:179], v[12:15]
	v_mfma_f32_16x16x32_bf16 v[8:11], v[200:203], v[176:179], v[8:11]
	v_mfma_f32_16x16x32_bf16 v[4:7], v[192:195], v[184:187], v[4:7]
	v_mfma_f32_16x16x32_bf16 v[0:3], v[200:203], v[184:187], v[0:3]
	v_mfma_f32_16x16x32_bf16 v[28:31], v[196:199], v[164:167], v[28:31]
	v_mfma_f32_16x16x32_bf16 v[24:27], v[140:143], v[164:167], v[24:27]
	v_mfma_f32_16x16x32_bf16 v[20:23], v[196:199], v[172:175], v[20:23]
	v_mfma_f32_16x16x32_bf16 v[16:19], v[140:143], v[172:175], v[16:19]
	v_mfma_f32_16x16x32_bf16 v[12:15], v[196:199], v[180:183], v[12:15]
	v_mfma_f32_16x16x32_bf16 v[8:11], v[140:143], v[180:183], v[8:11]
	v_mfma_f32_16x16x32_bf16 v[4:7], v[196:199], v[188:191], v[4:7]
	v_mfma_f32_16x16x32_bf16 v[0:3], v[140:143], v[188:191], v[0:3]
	v_cmp_gt_u32_e32 vcc, s36, v136
	s_barrier
	s_and_saveexec_b64 s[10:11], vcc
	s_cbranch_execz .LBB0_113
	s_barrier

; #define STAGE(P, RS, SOFF, OFF, kt) do { const int _so = (SOFF) + (kt) * (BK * 2); \
;     _Pragma("unroll") for (int _i = 0; _i < 2; ++_i) { \
;       __builtin_amdgcn_raw_ptr_buffer_load_lds(RS, (__attribute__((address_space(3))) void*)((P) + wave * 1024 + _i * 8192), 16, OFF[_i], _so, 0, 0); } } while (0)
; #define LDA(dst, b, h) _Pragma("unroll") for (int m = 0; m < 4; ++m) _Pragma("unroll") for (int k = 0; k < 2; ++k) \
;     dst[m][k] = *reinterpret_cast<const bf16x8*>(SA(b, h) + lds_byte(wr * 64 + m * 16 + fr, k * 32 + fq * 8))
; #define LDB(dst, b, h) _Pragma("unroll") for (int n = 0; n < 2; ++n) _Pragma("unroll") for (int k = 0; k < 2; ++k) \
;     dst[n][k] = *reinterpret_cast<const bf16x8*>(SB(b, h) + lds_byte(wc * 32 + n * 16 + fr, k * 32 + fq * 8))
; #define WAIT_V(n) asm volatile("s_waitcnt vmcnt(" #n ")" ::: "memory")
; #define WAIT_L(n) asm volatile("s_waitcnt lgkmcnt(" #n ")" ::: "memory")
; #define BAR __builtin_amdgcn_s_barrier()
; #define SCHED __builtin_amdgcn_sched_barrier(0)
;     ...
;     for (int t = 0; t < nt - 2; t += 2) {
;       LDB(B0, 0, 0); SCHED; LDA(At, 0, 0); STAGE(SA(1, 1), rsA, sA1, offA, t + 1);
;       WAIT_L(8); BAR; WAIT_L(0); MMA(0, 0, At, B0); BAR; SCHED;
;       LDB(B1, 0, 1); STAGE(SB(0, 0), rsB, sB0, offB, t + 2);
;       BAR; WAIT_L(0); MMA(0, 1, At, B1); BAR;
;       LDA(At, 0, 1); STAGE(SA(0, 0), rsA, sA0, offA, t + 2);
;       BAR; WAIT_L(0); MMA(1, 0, At, B0); BAR; SCHED;
;       STAGE(SB(0, 1), rsB, sB1, offB, t + 2);
;       WAIT_V(6); BAR; MMA(1, 1, At, B1); BAR;
.LBB0_148:
	ds_read_b128 v[152:155], v147
	ds_read_b128 v[156:159], v148
	ds_read_b128 v[160:163], v149
	ds_read_b128 v[164:167], v150
	s_add_i32 s4, s82, s3
	s_add_i32 s5, s4, 0x80
	s_mov_b32 m0, s31
	ds_read_b128 v[168:171], v129
	ds_read_b128 v[172:175], v129 offset:1024
	ds_read_b128 v[176:179], v132
	ds_read_b128 v[180:183], v132 offset:1024
	ds_read_b128 v[184:187], v131
	ds_read_b128 v[188:191], v131 offset:1024
	ds_read_b128 v[192:195], v130
	ds_read_b128 v[196:199], v130 offset:1024
	buffer_load_dwordx4 v141, s[8:11], s5 offen lds
	s_mov_b32 m0, s58
	s_nop 0
	buffer_load_dwordx4 v142, s[8:11], s5 offen lds
	s_waitcnt lgkmcnt(8)
	s_barrier
	s_waitcnt lgkmcnt(0)
	v_mfma_f32_16x16x32_bf16 v[124:127], v[152:155], v[168:171], v[124:127]
	v_mfma_f32_16x16x32_bf16 v[120:123], v[160:163], v[168:171], v[120:123]
	v_mfma_f32_16x16x32_bf16 v[116:119], v[152:155], v[176:179], v[116:119]
	v_mfma_f32_16x16x32_bf16 v[112:115], v[160:163], v[176:179], v[112:115]
	v_mfma_f32_16x16x32_bf16 v[108:111], v[152:155], v[184:187], v[108:111]
	v_mfma_f32_16x16x32_bf16 v[104:107], v[160:163], v[184:187], v[104:107]
	v_mfma_f32_16x16x32_bf16 v[100:103], v[152:155], v[192:195], v[100:103]
	v_mfma_f32_16x16x32_bf16 v[96:99], v[160:163], v[192:195], v[96:99]
	v_mfma_f32_16x16x32_bf16 v[124:127], v[156:159], v[172:175], v[124:127]
	v_mfma_f32_16x16x32_bf16 v[120:123], v[164:167], v[172:175], v[120:123]
	v_mfma_f32_16x16x32_bf16 v[116:119], v[156:159], v[180:183], v[116:119]
	v_mfma_f32_16x16x32_bf16 v[112:115], v[164:167], v[180:183], v[112:115]
	v_mfma_f32_16x16x32_bf16 v[108:111], v[156:159], v[188:191], v[108:111]
	v_mfma_f32_16x16x32_bf16 v[104:107], v[164:167], v[188:191], v[104:107]
	v_mfma_f32_16x16x32_bf16 v[100:103], v[156:159], v[196:199], v[100:103]
	v_mfma_f32_16x16x32_bf16 v[96:99], v[164:167], v[196:199], v[96:99]
	s_barrier
	s_add_i32 s5, s84, s3
	s_add_i32 s6, s5, 0x100
	s_mov_b32 s14, s10
	s_mov_b32 s15, s11
	s_mov_b32 m0, s34
	ds_read_b128 v[200:203], v143
	ds_read_b128 v[204:207], v144
	ds_read_b128 v[208:211], v145
	ds_read_b128 v[212:215], v146
	buffer_load_dwordx4 v141, s[12:15], s6 offen lds
	s_mov_b32 m0, s43
	s_nop 0
	buffer_load_dwordx4 v142, s[12:15], s6 offen lds
	s_barrier
	s_waitcnt lgkmcnt(0)
	v_mfma_f32_16x16x32_bf16 v[92:95], v[200:203], v[168:171], v[92:95]
	v_mfma_f32_16x16x32_bf16 v[88:91], v[208:211], v[168:171], v[88:91]
	v_mfma_f32_16x16x32_bf16 v[80:83], v[200:203], v[176:179], v[80:83]
	v_mfma_f32_16x16x32_bf16 v[68:71], v[208:211], v[176:179], v[68:71]
	v_mfma_f32_16x16x32_bf16 v[60:63], v[200:203], v[184:187], v[60:63]
	v_mfma_f32_16x16x32_bf16 v[56:59], v[208:211], v[184:187], v[56:59]
	v_mfma_f32_16x16x32_bf16 v[52:55], v[200:203], v[192:195], v[52:55]
	v_mfma_f32_16x16x32_bf16 v[48:51], v[208:211], v[192:195], v[48:51]
	v_mfma_f32_16x16x32_bf16 v[92:95], v[204:207], v[172:175], v[92:95]
	v_mfma_f32_16x16x32_bf16 v[88:91], v[212:215], v[172:175], v[88:91]
	v_mfma_f32_16x16x32_bf16 v[80:83], v[204:207], v[180:183], v[80:83]
	v_mfma_f32_16x16x32_bf16 v[68:71], v[212:215], v[180:183], v[68:71]
	v_mfma_f32_16x16x32_bf16 v[60:63], v[204:207], v[188:191], v[60:63]
	v_mfma_f32_16x16x32_bf16 v[56:59], v[212:215], v[188:191], v[56:59]
	v_mfma_f32_16x16x32_bf16 v[52:55], v[204:207], v[196:199], v[52:55]
	v_mfma_f32_16x16x32_bf16 v[48:51], v[212:215], v[196:199], v[48:51]
	s_barrier
	s_add_i32 s6, s83, s3
	s_add_i32 s7, s6, 0x100
	s_mov_b32 m0, s30
	ds_read_b128 v[168:171], v129 offset:16384
	ds_read_b128 v[172:175], v129 offset:17408
	ds_read_b128 v[176:179], v132 offset:16384
	ds_read_b128 v[180:183], v132 offset:17408
	ds_read_b128 v[184:187], v131 offset:16384
	ds_read_b128 v[188:191], v131 offset:17408
	ds_read_b128 v[192:195], v130 offset:16384
	ds_read_b128 v[196:199], v130 offset:17408
	buffer_load_dwordx4 v141, s[8:11], s7 offen lds
	s_mov_b32 m0, s44
	s_nop 0
	buffer_load_dwordx4 v142, s[8:11], s7 offen lds
	s_barrier
	s_waitcnt lgkmcnt(0)
	v_mfma_f32_16x16x32_bf16 v[44:47], v[152:155], v[168:171], v[44:47]
	v_mfma_f32_16x16x32_bf16 v[40:43], v[160:163], v[168:171], v[40:43]
	v_mfma_f32_16x16x32_bf16 v[36:39], v[152:155], v[176:179], v[36:39]
	v_mfma_f32_16x16x32_bf16 v[32:35], v[160:163], v[176:179], v[32:35]
	v_mfma_f32_16x16x32_bf16 v[28:31], v[152:155], v[184:187], v[28:31]
	v_mfma_f32_16x16x32_bf16 v[24:27], v[160:163], v[184:187], v[24:27]
	v_mfma_f32_16x16x32_bf16 v[20:23], v[152:155], v[192:195], v[20:23]
	v_mfma_f32_16x16x32_bf16 v[16:19], v[160:163], v[192:195], v[16:19]
	v_mfma_f32_16x16x32_bf16 v[44:47], v[156:159], v[172:175], v[44:47]
	v_mfma_f32_16x16x32_bf16 v[40:43], v[164:167], v[172:175], v[40:43]
	v_mfma_f32_16x16x32_bf16 v[36:39], v[156:159], v[180:183], v[36:39]
	v_mfma_f32_16x16x32_bf16 v[32:35], v[164:167], v[180:183], v[32:35]
	v_mfma_f32_16x16x32_bf16 v[28:31], v[156:159], v[188:191], v[28:31]
	v_mfma_f32_16x16x32_bf16 v[24:27], v[164:167], v[188:191], v[24:27]
	v_mfma_f32_16x16x32_bf16 v[20:23], v[156:159], v[196:199], v[20:23]
	v_mfma_f32_16x16x32_bf16 v[16:19], v[164:167], v[196:199], v[16:19]
	s_barrier
	s_add_i32 s7, s85, s3
	s_add_i32 s19, s7, 0x100
	s_mov_b32 m0, s35
	s_nop 0
	buffer_load_dwordx4 v141, s[12:15], s19 offen lds
	s_mov_b32 m0, s45
	s_nop 0
	buffer_load_dwordx4 v142, s[12:15], s19 offen lds
	s_waitcnt vmcnt(6)
	s_barrier
; #define STAGE(P, RS, SOFF, OFF, kt) do { const int _so = (SOFF) + (kt) * (BK * 2); \
;     _Pragma("unroll") for (int _i = 0; _i < 2; ++_i) { \
;       __builtin_amdgcn_raw_ptr_buffer_load_lds(RS, (__attribute__((address_space(3))) void*)((P) + wave * 1024 + _i * 8192), 16, OFF[_i], _so, 0, 0); } } while (0)
; #define LDA(dst, b, h) _Pragma("unroll") for (int m = 0; m < 4; ++m) _Pragma("unroll") for (int k = 0; k < 2; ++k) \
;     dst[m][k] = *reinterpret_cast<const bf16x8*>(SA(b, h) + lds_byte(wr * 64 + m * 16 + fr, k * 32 + fq * 8))
; #define LDB(dst, b, h) _Pragma("unroll") for (int n = 0; n < 2; ++n) _Pragma("unroll") for (int k = 0; k < 2; ++k) \
;     dst[n][k] = *reinterpret_cast<const bf16x8*>(SB(b, h) + lds_byte(wc * 32 + n * 16 + fr, k * 32 + fq * 8))
; #define WAIT_V(n) asm volatile("s_waitcnt vmcnt(" #n ")" ::: "memory")
; #define WAIT_L(n) asm volatile("s_waitcnt lgkmcnt(" #n ")" ::: "memory")
; #define BAR __builtin_amdgcn_s_barrier()
; #define SCHED __builtin_amdgcn_sched_barrier(0)
;     ...
;       WAIT_V(6); BAR; MMA(1, 1, At, B1); BAR;
;       LDB(B0, 1, 0); SCHED; LDA(At, 1, 0); STAGE(SA(0, 1), rsA, sA1, offA, t + 2);
;       WAIT_L(8); BAR; WAIT_L(0); MMA(0, 0, At, B0); BAR; SCHED;
;       LDB(B1, 1, 1); STAGE(SB(1, 0), rsB, sB0, offB, t + 3);
;       BAR; WAIT_L(0); MMA(0, 1, At, B1); BAR;
;       LDA(At, 1, 1); STAGE(SA(1, 0), rsA, sA0, offA, t + 3);
;       BAR; WAIT_L(0); MMA(1, 0, At, B0); BAR; SCHED;
;       STAGE(SB(1, 1), rsB, sB1, offB, t + 3);
;       WAIT_V(6); BAR; MMA(1, 1, At, B1); BAR;
	v_mfma_f32_16x16x32_bf16 v[12:15], v[200:203], v[168:171], v[12:15]
	v_mfma_f32_16x16x32_bf16 v[8:11], v[208:211], v[168:171], v[8:11]
	v_mfma_f32_16x16x32_bf16 v[4:7], v[200:203], v[176:179], v[4:7]
	v_mfma_f32_16x16x32_bf16 v[0:3], v[208:211], v[176:179], v[0:3]
	v_mfma_f32_16x16x32_bf16 v[64:67], v[200:203], v[184:187], v[64:67]
	v_mfma_f32_16x16x32_bf16 v[72:75], v[208:211], v[184:187], v[72:75]
	v_mfma_f32_16x16x32_bf16 v[76:79], v[200:203], v[192:195], v[76:79]
	v_mfma_f32_16x16x32_bf16 v[84:87], v[208:211], v[192:195], v[84:87]
	v_mfma_f32_16x16x32_bf16 v[12:15], v[204:207], v[172:175], v[12:15]
	v_mfma_f32_16x16x32_bf16 v[8:11], v[212:215], v[172:175], v[8:11]
	v_mfma_f32_16x16x32_bf16 v[4:7], v[204:207], v[180:183], v[4:7]
	v_mfma_f32_16x16x32_bf16 v[0:3], v[212:215], v[180:183], v[0:3]
	v_mfma_f32_16x16x32_bf16 v[64:67], v[204:207], v[188:191], v[64:67]
	v_mfma_f32_16x16x32_bf16 v[72:75], v[212:215], v[188:191], v[72:75]
	v_mfma_f32_16x16x32_bf16 v[76:79], v[204:207], v[196:199], v[76:79]
	v_mfma_f32_16x16x32_bf16 v[84:87], v[212:215], v[196:199], v[84:87]
	s_barrier
	ds_read_b128 v[152:155], v137
	ds_read_b128 v[156:159], v138
	ds_read_b128 v[160:163], v139
	ds_read_b128 v[164:167], v140
	s_addk_i32 s4, 0x100
	s_mov_b32 m0, s36
	ds_read_b128 v[168:171], v129 offset:32768
	ds_read_b128 v[172:175], v129 offset:33792
	ds_read_b128 v[176:179], v132 offset:32768
	ds_read_b128 v[180:183], v132 offset:33792
	ds_read_b128 v[184:187], v131 offset:32768
	ds_read_b128 v[188:191], v131 offset:33792
	ds_read_b128 v[192:195], v130 offset:32768
	ds_read_b128 v[196:199], v130 offset:33792
	buffer_load_dwordx4 v141, s[8:11], s4 offen lds
	s_mov_b32 m0, s48
	s_nop 0
	buffer_load_dwordx4 v142, s[8:11], s4 offen lds
	s_waitcnt lgkmcnt(8)
	s_barrier
	s_waitcnt lgkmcnt(0)
	v_mfma_f32_16x16x32_bf16 v[124:127], v[152:155], v[168:171], v[124:127]
	v_mfma_f32_16x16x32_bf16 v[120:123], v[160:163], v[168:171], v[120:123]
	v_mfma_f32_16x16x32_bf16 v[116:119], v[152:155], v[176:179], v[116:119]
	v_mfma_f32_16x16x32_bf16 v[112:115], v[160:163], v[176:179], v[112:115]
	v_mfma_f32_16x16x32_bf16 v[108:111], v[152:155], v[184:187], v[108:111]
	v_mfma_f32_16x16x32_bf16 v[104:107], v[160:163], v[184:187], v[104:107]
	v_mfma_f32_16x16x32_bf16 v[100:103], v[152:155], v[192:195], v[100:103]
	v_mfma_f32_16x16x32_bf16 v[96:99], v[160:163], v[192:195], v[96:99]
	v_mfma_f32_16x16x32_bf16 v[124:127], v[156:159], v[172:175], v[124:127]
	v_mfma_f32_16x16x32_bf16 v[120:123], v[164:167], v[172:175], v[120:123]
	v_mfma_f32_16x16x32_bf16 v[116:119], v[156:159], v[180:183], v[116:119]
	v_mfma_f32_16x16x32_bf16 v[112:115], v[164:167], v[180:183], v[112:115]
	v_mfma_f32_16x16x32_bf16 v[108:111], v[156:159], v[188:191], v[108:111]
	v_mfma_f32_16x16x32_bf16 v[104:107], v[164:167], v[188:191], v[104:107]
	v_mfma_f32_16x16x32_bf16 v[100:103], v[156:159], v[196:199], v[100:103]
	v_mfma_f32_16x16x32_bf16 v[96:99], v[164:167], v[196:199], v[96:99]
	s_barrier
	s_addk_i32 s5, 0x180
	s_mov_b32 m0, s37
	ds_read_b128 v[200:203], v133
	ds_read_b128 v[204:207], v134
	ds_read_b128 v[208:211], v135
	ds_read_b128 v[212:215], v136
	buffer_load_dwordx4 v141, s[12:15], s5 offen lds
	s_mov_b32 m0, s49
	s_nop 0
	buffer_load_dwordx4 v142, s[12:15], s5 offen lds
	s_barrier
	s_waitcnt lgkmcnt(0)
	v_mfma_f32_16x16x32_bf16 v[92:95], v[200:203], v[168:171], v[92:95]
	v_mfma_f32_16x16x32_bf16 v[88:91], v[208:211], v[168:171], v[88:91]
	v_mfma_f32_16x16x32_bf16 v[80:83], v[200:203], v[176:179], v[80:83]
	v_mfma_f32_16x16x32_bf16 v[68:71], v[208:211], v[176:179], v[68:71]
	v_mfma_f32_16x16x32_bf16 v[60:63], v[200:203], v[184:187], v[60:63]
	v_mfma_f32_16x16x32_bf16 v[56:59], v[208:211], v[184:187], v[56:59]
	v_mfma_f32_16x16x32_bf16 v[52:55], v[200:203], v[192:195], v[52:55]
	v_mfma_f32_16x16x32_bf16 v[48:51], v[208:211], v[192:195], v[48:51]
	v_mfma_f32_16x16x32_bf16 v[92:95], v[204:207], v[172:175], v[92:95]
	v_mfma_f32_16x16x32_bf16 v[88:91], v[212:215], v[172:175], v[88:91]
	v_mfma_f32_16x16x32_bf16 v[80:83], v[204:207], v[180:183], v[80:83]
	v_mfma_f32_16x16x32_bf16 v[68:71], v[212:215], v[180:183], v[68:71]
	v_mfma_f32_16x16x32_bf16 v[60:63], v[204:207], v[188:191], v[60:63]
	v_mfma_f32_16x16x32_bf16 v[56:59], v[212:215], v[188:191], v[56:59]
	v_mfma_f32_16x16x32_bf16 v[52:55], v[204:207], v[196:199], v[52:55]
	v_mfma_f32_16x16x32_bf16 v[48:51], v[212:215], v[196:199], v[48:51]
	s_barrier
	s_addk_i32 s6, 0x180
	s_mov_b32 m0, s38
	ds_read_b128 v[168:171], v129 offset:49152
	ds_read_b128 v[172:175], v129 offset:50176
	ds_read_b128 v[176:179], v132 offset:49152
	ds_read_b128 v[180:183], v132 offset:50176
	ds_read_b128 v[184:187], v131 offset:49152
	ds_read_b128 v[188:191], v131 offset:50176
	ds_read_b128 v[192:195], v130 offset:49152
	ds_read_b128 v[196:199], v130 offset:50176
	buffer_load_dwordx4 v141, s[8:11], s6 offen lds
	s_mov_b32 m0, s54
	s_nop 0
	buffer_load_dwordx4 v142, s[8:11], s6 offen lds
	s_barrier
	s_waitcnt lgkmcnt(0)
	v_mfma_f32_16x16x32_bf16 v[44:47], v[152:155], v[168:171], v[44:47]
	v_mfma_f32_16x16x32_bf16 v[40:43], v[160:163], v[168:171], v[40:43]
	v_mfma_f32_16x16x32_bf16 v[36:39], v[152:155], v[176:179], v[36:39]
	v_mfma_f32_16x16x32_bf16 v[32:35], v[160:163], v[176:179], v[32:35]
	v_mfma_f32_16x16x32_bf16 v[28:31], v[152:155], v[184:187], v[28:31]
	v_mfma_f32_16x16x32_bf16 v[24:27], v[160:163], v[184:187], v[24:27]
	v_mfma_f32_16x16x32_bf16 v[20:23], v[152:155], v[192:195], v[20:23]
	v_mfma_f32_16x16x32_bf16 v[16:19], v[160:163], v[192:195], v[16:19]
	v_mfma_f32_16x16x32_bf16 v[44:47], v[156:159], v[172:175], v[44:47]
	v_mfma_f32_16x16x32_bf16 v[40:43], v[164:167], v[172:175], v[40:43]
	v_mfma_f32_16x16x32_bf16 v[36:39], v[156:159], v[180:183], v[36:39]
	v_mfma_f32_16x16x32_bf16 v[32:35], v[164:167], v[180:183], v[32:35]
	v_mfma_f32_16x16x32_bf16 v[28:31], v[156:159], v[188:191], v[28:31]
	v_mfma_f32_16x16x32_bf16 v[24:27], v[164:167], v[188:191], v[24:27]
	v_mfma_f32_16x16x32_bf16 v[20:23], v[156:159], v[196:199], v[20:23]
	v_mfma_f32_16x16x32_bf16 v[16:19], v[164:167], v[196:199], v[16:19]
	s_barrier
; #define STAGE(P, RS, SOFF, OFF, kt) do { const int _so = (SOFF) + (kt) * (BK * 2); \
;     _Pragma("unroll") for (int _i = 0; _i < 2; ++_i) { \
;       __builtin_amdgcn_raw_ptr_buffer_load_lds(RS, (__attribute__((address_space(3))) void*)((P) + wave * 1024 + _i * 8192), 16, OFF[_i], _so, 0, 0); } } while (0)
; #define LDA(dst, b, h) _Pragma("unroll") for (int m = 0; m < 4; ++m) _Pragma("unroll") for (int k = 0; k < 2; ++k) \
;     dst[m][k] = *reinterpret_cast<const bf16x8*>(SA(b, h) + lds_byte(wr * 64 + m * 16 + fr, k * 32 + fq * 8))
; #define LDB(dst, b, h) _Pragma("unroll") for (int n = 0; n < 2; ++n) _Pragma("unroll") for (int k = 0; k < 2; ++k) \
;     dst[n][k] = *reinterpret_cast<const bf16x8*>(SB(b, h) + lds_byte(wc * 32 + n * 16 + fr, k * 32 + fq * 8))
; #define WAIT_V(n) asm volatile("s_waitcnt vmcnt(" #n ")" ::: "memory")
; #define WAIT_L(n) asm volatile("s_waitcnt lgkmcnt(" #n ")" ::: "memory")
; #define BAR __builtin_amdgcn_s_barrier()
;     ...
;       WAIT_V(6); BAR; MMA(1, 1, At, B1); BAR;
;     }
;     { LDB(B0, 0, 0); LDA(At, 0, 0); STAGE(SA(1, 1), rsA, sA1, offA, nt - 1);
;       BAR; WAIT_L(0); MMA(0, 0, At, B0); BAR;
;       LDB(B1, 0, 1); BAR; WAIT_L(0); MMA(0, 1, At, B1); BAR;
;       LDA(At, 0, 1); WAIT_V(4); BAR; WAIT_L(0); MMA(1, 0, At, B0); MMA(1, 1, At, B1); BAR; }
	s_addk_i32 s7, 0x180
	s_mov_b32 m0, s39
	s_nop 0
	buffer_load_dwordx4 v141, s[12:15], s7 offen lds
	s_mov_b32 m0, s55
	s_nop 0
	buffer_load_dwordx4 v142, s[12:15], s7 offen lds
	s_add_i32 s1, s1, 2
	s_addk_i32 s3, 0x100
	s_cmp_gt_u32 s1, 59
	s_waitcnt vmcnt(6)
	s_barrier
	v_mfma_f32_16x16x32_bf16 v[12:15], v[200:203], v[168:171], v[12:15]
	v_mfma_f32_16x16x32_bf16 v[8:11], v[208:211], v[168:171], v[8:11]
	v_mfma_f32_16x16x32_bf16 v[4:7], v[200:203], v[176:179], v[4:7]
	v_mfma_f32_16x16x32_bf16 v[0:3], v[208:211], v[176:179], v[0:3]
	v_mfma_f32_16x16x32_bf16 v[64:67], v[200:203], v[184:187], v[64:67]
	v_mfma_f32_16x16x32_bf16 v[72:75], v[208:211], v[184:187], v[72:75]
	v_mfma_f32_16x16x32_bf16 v[76:79], v[200:203], v[192:195], v[76:79]
	v_mfma_f32_16x16x32_bf16 v[84:87], v[208:211], v[192:195], v[84:87]
	v_mfma_f32_16x16x32_bf16 v[12:15], v[204:207], v[172:175], v[12:15]
	v_mfma_f32_16x16x32_bf16 v[8:11], v[212:215], v[172:175], v[8:11]
	v_mfma_f32_16x16x32_bf16 v[4:7], v[204:207], v[180:183], v[4:7]
	v_mfma_f32_16x16x32_bf16 v[0:3], v[212:215], v[180:183], v[0:3]
	v_mfma_f32_16x16x32_bf16 v[64:67], v[204:207], v[188:191], v[64:67]
	v_mfma_f32_16x16x32_bf16 v[72:75], v[212:215], v[188:191], v[72:75]
	v_mfma_f32_16x16x32_bf16 v[76:79], v[204:207], v[196:199], v[76:79]
	v_mfma_f32_16x16x32_bf16 v[84:87], v[212:215], v[196:199], v[84:87]
	s_barrier
	s_cbranch_scc0 .LBB0_148
	s_add_i32 s1, s82, 0x1f80
	s_mov_b32 m0, s31
	ds_read_b128 v[152:155], v147
	ds_read_b128 v[156:159], v148
	ds_read_b128 v[160:163], v149
	ds_read_b128 v[148:151], v150
	ds_read_b128 v[164:167], v129
	ds_read_b128 v[168:171], v129 offset:1024
	ds_read_b128 v[172:175], v132
	ds_read_b128 v[176:179], v132 offset:1024
	ds_read_b128 v[180:183], v131
	ds_read_b128 v[184:187], v131 offset:1024
	ds_read_b128 v[188:191], v130
	ds_read_b128 v[192:195], v130 offset:1024
	buffer_load_dwordx4 v141, s[8:11], s1 offen lds
	s_mov_b32 m0, s58
	s_nop 0
	buffer_load_dwordx4 v142, s[8:11], s1 offen lds
	s_barrier
	s_waitcnt lgkmcnt(0)
	v_mfma_f32_16x16x32_bf16 v[124:127], v[152:155], v[164:167], v[124:127]
	v_mfma_f32_16x16x32_bf16 v[120:123], v[160:163], v[164:167], v[120:123]
	v_mfma_f32_16x16x32_bf16 v[116:119], v[152:155], v[172:175], v[116:119]
	v_mfma_f32_16x16x32_bf16 v[112:115], v[160:163], v[172:175], v[112:115]
	v_mfma_f32_16x16x32_bf16 v[108:111], v[152:155], v[180:183], v[108:111]
	v_mfma_f32_16x16x32_bf16 v[104:107], v[160:163], v[180:183], v[104:107]
	v_mfma_f32_16x16x32_bf16 v[100:103], v[152:155], v[188:191], v[100:103]
	v_mfma_f32_16x16x32_bf16 v[96:99], v[160:163], v[188:191], v[96:99]
	v_mfma_f32_16x16x32_bf16 v[124:127], v[156:159], v[168:171], v[124:127]
	v_mfma_f32_16x16x32_bf16 v[120:123], v[148:151], v[168:171], v[120:123]
	v_mfma_f32_16x16x32_bf16 v[116:119], v[156:159], v[176:179], v[116:119]
	v_mfma_f32_16x16x32_bf16 v[112:115], v[148:151], v[176:179], v[112:115]
	v_mfma_f32_16x16x32_bf16 v[108:111], v[156:159], v[184:187], v[108:111]
	v_mfma_f32_16x16x32_bf16 v[104:107], v[148:151], v[184:187], v[104:107]
	v_mfma_f32_16x16x32_bf16 v[100:103], v[156:159], v[192:195], v[100:103]
	v_mfma_f32_16x16x32_bf16 v[96:99], v[148:151], v[192:195], v[96:99]
	s_barrier
	ds_read_b128 v[196:199], v143
	ds_read_b128 v[200:203], v144
	ds_read_b128 v[142:145], v145
	ds_read_b128 v[204:207], v146
	s_barrier
	s_waitcnt lgkmcnt(0)
	v_mfma_f32_16x16x32_bf16 v[88:91], v[142:145], v[164:167], v[88:91]
	v_mfma_f32_16x16x32_bf16 v[80:83], v[196:199], v[172:175], v[80:83]
	v_mfma_f32_16x16x32_bf16 v[60:63], v[196:199], v[180:183], v[60:63]
	v_mfma_f32_16x16x32_bf16 v[56:59], v[142:145], v[180:183], v[56:59]
	v_mfma_f32_16x16x32_bf16 v[52:55], v[196:199], v[188:191], v[52:55]
	v_mfma_f32_16x16x32_bf16 v[48:51], v[142:145], v[188:191], v[48:51]
	v_mfma_f32_16x16x32_bf16 v[92:95], v[196:199], v[164:167], v[92:95]
	v_mfma_f32_16x16x32_bf16 v[68:71], v[142:145], v[172:175], v[68:71]
	v_mfma_f32_16x16x32_bf16 v[88:91], v[204:207], v[168:171], v[88:91]
	v_mfma_f32_16x16x32_bf16 v[80:83], v[200:203], v[176:179], v[80:83]
	v_mfma_f32_16x16x32_bf16 v[60:63], v[200:203], v[184:187], v[60:63]
	v_mfma_f32_16x16x32_bf16 v[56:59], v[204:207], v[184:187], v[56:59]
	v_mfma_f32_16x16x32_bf16 v[52:55], v[200:203], v[192:195], v[52:55]
	v_mfma_f32_16x16x32_bf16 v[48:51], v[204:207], v[192:195], v[48:51]
	v_mfma_f32_16x16x32_bf16 v[164:167], v[200:203], v[168:171], v[92:95]
	v_mfma_f32_16x16x32_bf16 v[168:171], v[204:207], v[176:179], v[68:71]
	s_barrier
	s_nop 0
	ds_read_b128 v[68:71], v129 offset:16384
	ds_read_b128 v[92:95], v129 offset:17408
	ds_read_b128 v[172:175], v132 offset:16384
	ds_read_b128 v[176:179], v132 offset:17408
	ds_read_b128 v[180:183], v131 offset:16384
	ds_read_b128 v[184:187], v131 offset:17408
	ds_read_b128 v[188:191], v130 offset:16384
	ds_read_b128 v[192:195], v130 offset:17408
	s_waitcnt vmcnt(4)
	s_barrier
; #define LDA(dst, b, h) _Pragma("unroll") for (int m = 0; m < 4; ++m) _Pragma("unroll") for (int k = 0; k < 2; ++k) \
;     dst[m][k] = *reinterpret_cast<const bf16x8*>(SA(b, h) + lds_byte(wr * 64 + m * 16 + fr, k * 32 + fq * 8))
; #define LDB(dst, b, h) _Pragma("unroll") for (int n = 0; n < 2; ++n) _Pragma("unroll") for (int k = 0; k < 2; ++k) \
;     dst[n][k] = *reinterpret_cast<const bf16x8*>(SB(b, h) + lds_byte(wc * 32 + n * 16 + fr, k * 32 + fq * 8))
; #define WAIT_V(n) asm volatile("s_waitcnt vmcnt(" #n ")" ::: "memory")
; #define WAIT_L(n) asm volatile("s_waitcnt lgkmcnt(" #n ")" ::: "memory")
; #define BAR __builtin_amdgcn_s_barrier()
;     ...
;       LDA(At, 0, 1); WAIT_V(4); BAR; WAIT_L(0); MMA(1, 0, At, B0); MMA(1, 1, At, B1); BAR; }
;     { LDB(B0, 1, 0); LDA(At, 1, 0); WAIT_V(2); BAR; WAIT_L(0); MMA(0, 0, At, B0); BAR;
	s_waitcnt lgkmcnt(0)
	v_mfma_f32_16x16x32_bf16 v[44:47], v[152:155], v[68:71], v[44:47]
	v_mfma_f32_16x16x32_bf16 v[40:43], v[160:163], v[68:71], v[40:43]
	v_mfma_f32_16x16x32_bf16 v[36:39], v[152:155], v[172:175], v[36:39]
	v_mfma_f32_16x16x32_bf16 v[32:35], v[160:163], v[172:175], v[32:35]
	v_mfma_f32_16x16x32_bf16 v[28:31], v[152:155], v[180:183], v[28:31]
	v_mfma_f32_16x16x32_bf16 v[24:27], v[160:163], v[180:183], v[24:27]
	v_mfma_f32_16x16x32_bf16 v[20:23], v[152:155], v[188:191], v[20:23]
	v_mfma_f32_16x16x32_bf16 v[16:19], v[160:163], v[188:191], v[16:19]
	v_mfma_f32_16x16x32_bf16 v[44:47], v[156:159], v[92:95], v[44:47]
	v_mfma_f32_16x16x32_bf16 v[40:43], v[148:151], v[92:95], v[40:43]
	v_mfma_f32_16x16x32_bf16 v[36:39], v[156:159], v[176:179], v[36:39]
	v_mfma_f32_16x16x32_bf16 v[32:35], v[148:151], v[176:179], v[32:35]
	v_mfma_f32_16x16x32_bf16 v[28:31], v[156:159], v[184:187], v[28:31]
	v_mfma_f32_16x16x32_bf16 v[24:27], v[148:151], v[184:187], v[24:27]
	v_mfma_f32_16x16x32_bf16 v[20:23], v[156:159], v[192:195], v[20:23]
	v_mfma_f32_16x16x32_bf16 v[16:19], v[148:151], v[192:195], v[16:19]
	v_mfma_f32_16x16x32_bf16 v[8:11], v[142:145], v[68:71], v[8:11]
	v_mfma_f32_16x16x32_bf16 v[0:3], v[142:145], v[172:175], v[0:3]
	v_mfma_f32_16x16x32_bf16 v[12:15], v[196:199], v[68:71], v[12:15]
	v_mfma_f32_16x16x32_bf16 v[4:7], v[196:199], v[172:175], v[4:7]
	v_mfma_f32_16x16x32_bf16 v[64:67], v[196:199], v[180:183], v[64:67]
	v_mfma_f32_16x16x32_bf16 v[68:71], v[142:145], v[180:183], v[72:75]
	v_mfma_f32_16x16x32_bf16 v[72:75], v[196:199], v[188:191], v[76:79]
	v_mfma_f32_16x16x32_bf16 v[76:79], v[142:145], v[188:191], v[84:87]
	v_mfma_f32_16x16x32_bf16 v[8:11], v[204:207], v[92:95], v[8:11]
	v_mfma_f32_16x16x32_bf16 v[0:3], v[204:207], v[176:179], v[0:3]
	v_mfma_f32_16x16x32_bf16 v[160:163], v[200:203], v[92:95], v[12:15]
	v_mfma_f32_16x16x32_bf16 v[172:175], v[200:203], v[176:179], v[4:7]
	v_mfma_f32_16x16x32_bf16 v[176:179], v[200:203], v[184:187], v[64:67]
	v_mfma_f32_16x16x32_bf16 v[180:183], v[204:207], v[184:187], v[68:71]
	v_mfma_f32_16x16x32_bf16 v[184:187], v[200:203], v[192:195], v[72:75]
	v_mfma_f32_16x16x32_bf16 v[188:191], v[204:207], v[192:195], v[76:79]
	s_barrier
	ds_read_b128 v[4:7], v137
	ds_read_b128 v[12:15], v138
	ds_read_b128 v[192:195], v139
	ds_read_b128 v[138:141], v140
	ds_read_b128 v[72:75], v129 offset:32768
	ds_read_b128 v[142:145], v129 offset:33792
	ds_read_b128 v[76:79], v132 offset:32768
	ds_read_b128 v[196:199], v132 offset:33792
	ds_read_b128 v[152:155], v131 offset:32768
	ds_read_b128 v[200:203], v131 offset:33792
	ds_read_b128 v[204:207], v130 offset:32768
	ds_read_b128 v[208:211], v130 offset:33792
	s_waitcnt vmcnt(2)
	s_barrier
	s_waitcnt lgkmcnt(0)
	v_mfma_f32_16x16x32_bf16 v[64:67], v[4:7], v[72:75], v[124:127]
	v_mfma_f32_16x16x32_bf16 v[84:87], v[192:195], v[72:75], v[120:123]
	v_mfma_f32_16x16x32_bf16 v[92:95], v[4:7], v[76:79], v[116:119]
	v_mfma_f32_16x16x32_bf16 v[112:115], v[192:195], v[76:79], v[112:115]
	v_mfma_f32_16x16x32_bf16 v[108:111], v[4:7], v[152:155], v[108:111]
	v_mfma_f32_16x16x32_bf16 v[104:107], v[192:195], v[152:155], v[104:107]
	v_mfma_f32_16x16x32_bf16 v[100:103], v[4:7], v[204:207], v[100:103]
	v_mfma_f32_16x16x32_bf16 v[96:99], v[192:195], v[204:207], v[96:99]
	v_mfma_f32_16x16x32_bf16 v[68:71], v[12:15], v[142:145], v[64:67]
	v_mfma_f32_16x16x32_bf16 v[64:67], v[138:141], v[142:145], v[84:87]
	v_mfma_f32_16x16x32_bf16 v[156:159], v[12:15], v[196:199], v[92:95]
	v_mfma_f32_16x16x32_bf16 v[148:151], v[138:141], v[196:199], v[112:115]
	v_mfma_f32_16x16x32_bf16 v[124:127], v[12:15], v[200:203], v[108:111]
	v_mfma_f32_16x16x32_bf16 v[116:119], v[138:141], v[200:203], v[104:107]
	v_mfma_f32_16x16x32_bf16 v[92:95], v[12:15], v[208:211], v[100:103]
	v_mfma_f32_16x16x32_bf16 v[84:87], v[138:141], v[208:211], v[96:99]
	s_barrier
; #define LDA(dst, b, h) _Pragma("unroll") for (int m = 0; m < 4; ++m) _Pragma("unroll") for (int k = 0; k < 2; ++k) \
;     dst[m][k] = *reinterpret_cast<const bf16x8*>(SA(b, h) + lds_byte(wr * 64 + m * 16 + fr, k * 32 + fq * 8))
; #define LDB(dst, b, h) _Pragma("unroll") for (int n = 0; n < 2; ++n) _Pragma("unroll") for (int k = 0; k < 2; ++k) \
;     dst[n][k] = *reinterpret_cast<const bf16x8*>(SB(b, h) + lds_byte(wc * 32 + n * 16 + fr, k * 32 + fq * 8))
; #define WAIT_V(n) asm volatile("s_waitcnt vmcnt(" #n ")" ::: "memory")
; #define WAIT_L(n) asm volatile("s_waitcnt lgkmcnt(" #n ")" ::: "memory")
; #define BAR __builtin_amdgcn_s_barrier()
;     ...
;       LDB(B1, 1, 1); WAIT_V(0); BAR; WAIT_L(0); MMA(0, 1, At, B1); BAR;
;       LDA(At, 1, 1); BAR; WAIT_L(0); MMA(1, 0, At, B0); MMA(1, 1, At, B1); BAR; }
;     if (wr == 0) BAR;
	s_nop 0
	ds_read_b128 v[96:99], v133
	ds_read_b128 v[100:103], v134
	ds_read_b128 v[104:107], v135
	ds_read_b128 v[108:111], v136
	s_waitcnt vmcnt(0)
	s_barrier
	s_waitcnt lgkmcnt(0)
	v_mfma_f32_16x16x32_bf16 v[112:115], v[96:99], v[72:75], v[164:167]
	v_mfma_f32_16x16x32_bf16 v[72:75], v[104:107], v[72:75], v[88:91]
	v_mfma_f32_16x16x32_bf16 v[80:83], v[96:99], v[76:79], v[80:83]
	v_mfma_f32_16x16x32_bf16 v[88:91], v[104:107], v[76:79], v[168:171]
	v_mfma_f32_16x16x32_bf16 v[60:63], v[96:99], v[152:155], v[60:63]
	v_mfma_f32_16x16x32_bf16 v[56:59], v[104:107], v[152:155], v[56:59]
	v_mfma_f32_16x16x32_bf16 v[52:55], v[96:99], v[204:207], v[52:55]
	v_mfma_f32_16x16x32_bf16 v[48:51], v[104:107], v[204:207], v[48:51]
	v_mfma_f32_16x16x32_bf16 v[76:79], v[100:103], v[142:145], v[112:115]
	v_mfma_f32_16x16x32_bf16 v[72:75], v[108:111], v[142:145], v[72:75]
	v_mfma_f32_16x16x32_bf16 v[152:155], v[100:103], v[196:199], v[80:83]
	v_mfma_f32_16x16x32_bf16 v[144:147], v[108:111], v[196:199], v[88:91]
	v_mfma_f32_16x16x32_bf16 v[120:123], v[100:103], v[200:203], v[60:63]
	v_mfma_f32_16x16x32_bf16 v[112:115], v[108:111], v[200:203], v[56:59]
	v_mfma_f32_16x16x32_bf16 v[88:91], v[100:103], v[208:211], v[52:55]
	v_mfma_f32_16x16x32_bf16 v[80:83], v[108:111], v[208:211], v[48:51]
	s_barrier
	s_nop 0
	ds_read_b128 v[48:51], v129 offset:49152
	ds_read_b128 v[134:137], v129 offset:50176
	ds_read_b128 v[56:59], v132 offset:49152
	ds_read_b128 v[164:167], v132 offset:50176
	ds_read_b128 v[168:171], v131 offset:49152
	ds_read_b128 v[196:199], v131 offset:50176
	ds_read_b128 v[200:203], v130 offset:49152
	ds_read_b128 v[130:133], v130 offset:50176
	s_barrier
	s_waitcnt lgkmcnt(0)
	v_mfma_f32_16x16x32_bf16 v[44:47], v[4:7], v[48:51], v[44:47]
	v_mfma_f32_16x16x32_bf16 v[40:43], v[192:195], v[48:51], v[40:43]
	v_mfma_f32_16x16x32_bf16 v[36:39], v[4:7], v[56:59], v[36:39]
	v_mfma_f32_16x16x32_bf16 v[32:35], v[192:195], v[56:59], v[32:35]
	v_mfma_f32_16x16x32_bf16 v[28:31], v[4:7], v[168:171], v[28:31]
	v_mfma_f32_16x16x32_bf16 v[24:27], v[192:195], v[168:171], v[24:27]
	v_mfma_f32_16x16x32_bf16 v[4:7], v[4:7], v[200:203], v[20:23]
	v_mfma_f32_16x16x32_bf16 v[16:19], v[192:195], v[200:203], v[16:19]
	v_mfma_f32_16x16x32_bf16 v[60:63], v[12:15], v[134:137], v[44:47]
	v_mfma_f32_16x16x32_bf16 v[52:55], v[138:141], v[134:137], v[40:43]
	v_mfma_f32_16x16x32_bf16 v[44:47], v[12:15], v[164:167], v[36:39]
	v_mfma_f32_16x16x32_bf16 v[36:39], v[138:141], v[164:167], v[32:35]
	v_mfma_f32_16x16x32_bf16 v[28:31], v[12:15], v[196:199], v[28:31]
	v_mfma_f32_16x16x32_bf16 v[20:23], v[138:141], v[196:199], v[24:27]
	v_mfma_f32_16x16x32_bf16 v[12:15], v[12:15], v[130:133], v[4:7]
	v_mfma_f32_16x16x32_bf16 v[4:7], v[138:141], v[130:133], v[16:19]
	v_mfma_f32_16x16x32_bf16 v[16:19], v[96:99], v[48:51], v[160:163]
	v_mfma_f32_16x16x32_bf16 v[8:11], v[104:107], v[48:51], v[8:11]
	v_mfma_f32_16x16x32_bf16 v[24:27], v[96:99], v[56:59], v[172:175]
	v_mfma_f32_16x16x32_bf16 v[0:3], v[104:107], v[56:59], v[0:3]
	v_mfma_f32_16x16x32_bf16 v[138:141], v[96:99], v[168:171], v[176:179]
	v_mfma_f32_16x16x32_bf16 v[160:163], v[104:107], v[168:171], v[180:183]
	v_mfma_f32_16x16x32_bf16 v[96:99], v[96:99], v[200:203], v[184:187]
	v_mfma_f32_16x16x32_bf16 v[104:107], v[104:107], v[200:203], v[188:191]
	v_mfma_f32_16x16x32_bf16 v[56:59], v[100:103], v[134:137], v[16:19]
	v_mfma_f32_16x16x32_bf16 v[48:51], v[108:111], v[134:137], v[8:11]
	v_mfma_f32_16x16x32_bf16 v[40:43], v[100:103], v[164:167], v[24:27]
	v_mfma_f32_16x16x32_bf16 v[32:35], v[108:111], v[164:167], v[0:3]
	v_mfma_f32_16x16x32_bf16 v[24:27], v[100:103], v[196:199], v[138:141]
	v_mfma_f32_16x16x32_bf16 v[16:19], v[108:111], v[196:199], v[160:163]
	v_mfma_f32_16x16x32_bf16 v[8:11], v[100:103], v[130:133], v[96:99]
	v_mfma_f32_16x16x32_bf16 v[0:3], v[108:111], v[130:133], v[104:107]
	v_cmp_gt_u32_e32 vcc, s60, v128
	s_barrier
	s_and_saveexec_b64 s[4:5], vcc
	s_cbranch_execz .LBB0_151
	s_barrier

; #define STAGE(P, RS, SOFF, OFF, kt) do { const int _so = (SOFF) + (kt) * (BK * 2); \
;     _Pragma("unroll") for (int _i = 0; _i < 2; ++_i) { \
;       __builtin_amdgcn_raw_ptr_buffer_load_lds(RS, (__attribute__((address_space(3))) void*)((P) + wave * 1024 + _i * 8192), 16, OFF[_i], _so, 0, 0); } } while (0)
; #define LDA(dst, b, h) _Pragma("unroll") for (int m = 0; m < 4; ++m) _Pragma("unroll") for (int k = 0; k < 2; ++k) \
;     dst[m][k] = *reinterpret_cast<const bf16x8*>(SA(b, h) + lds_byte(wr * 64 + m * 16 + fr, k * 32 + fq * 8))
; #define LDB(dst, b, h) _Pragma("unroll") for (int n = 0; n < 2; ++n) _Pragma("unroll") for (int k = 0; k < 2; ++k) \
;     dst[n][k] = *reinterpret_cast<const bf16x8*>(SB(b, h) + lds_byte(wc * 32 + n * 16 + fr, k * 32 + fq * 8))
; #define WAIT_V(n) asm volatile("s_waitcnt vmcnt(" #n ")" ::: "memory")
; #define WAIT_L(n) asm volatile("s_waitcnt lgkmcnt(" #n ")" ::: "memory")
; #define BAR __builtin_amdgcn_s_barrier()
; #define SCHED __builtin_amdgcn_sched_barrier(0)
;     ...
;       LDB(B0, 0, 0); SCHED; LDA(At, 0, 0); STAGE(SA(1, 1), rsA, sA1, offA, t + 1);
;       WAIT_L(8); BAR; WAIT_L(0); MMA(0, 0, At, B0); BAR; SCHED;
;       LDB(B1, 0, 1); STAGE(SB(0, 0), rsB, sB0, offB, t + 2);
;       BAR; WAIT_L(0); MMA(0, 1, At, B1); BAR;
;       LDA(At, 0, 1); STAGE(SA(0, 0), rsA, sA0, offA, t + 2);
;       BAR; WAIT_L(0); MMA(1, 0, At, B0); BAR; SCHED;
;       STAGE(SB(0, 1), rsB, sB1, offB, t + 2);
;       WAIT_V(6); BAR; MMA(1, 1, At, B1); BAR;
.LBB0_210:
	ds_read_b128 v[154:157], v149
	ds_read_b128 v[158:161], v150
	ds_read_b128 v[162:165], v151
	ds_read_b128 v[166:169], v152
	s_add_i32 s44, s38, s17
	s_add_i32 s10, s44, 0x80
	s_mov_b32 m0, s30
	ds_read_b128 v[170:173], v131
	ds_read_b128 v[174:177], v131 offset:1024
	ds_read_b128 v[178:181], v134
	ds_read_b128 v[182:185], v134 offset:1024
	ds_read_b128 v[186:189], v133
	ds_read_b128 v[190:193], v133 offset:1024
	ds_read_b128 v[194:197], v132
	ds_read_b128 v[198:201], v132 offset:1024
	buffer_load_dwordx4 v143, s[4:7], s10 offen lds
	s_mov_b32 m0, s31
	s_nop 0
	buffer_load_dwordx4 v144, s[4:7], s10 offen lds
	s_waitcnt lgkmcnt(8)
	s_barrier
	s_waitcnt lgkmcnt(0)
	v_mfma_f32_16x16x32_bf16 v[124:127], v[154:157], v[170:173], v[124:127]
	v_mfma_f32_16x16x32_bf16 v[120:123], v[162:165], v[170:173], v[120:123]
	v_mfma_f32_16x16x32_bf16 v[116:119], v[154:157], v[178:181], v[116:119]
	v_mfma_f32_16x16x32_bf16 v[112:115], v[162:165], v[178:181], v[112:115]
	v_mfma_f32_16x16x32_bf16 v[108:111], v[154:157], v[186:189], v[108:111]
	v_mfma_f32_16x16x32_bf16 v[104:107], v[162:165], v[186:189], v[104:107]
	v_mfma_f32_16x16x32_bf16 v[100:103], v[154:157], v[194:197], v[100:103]
	v_mfma_f32_16x16x32_bf16 v[96:99], v[162:165], v[194:197], v[96:99]
	v_mfma_f32_16x16x32_bf16 v[124:127], v[158:161], v[174:177], v[124:127]
	v_mfma_f32_16x16x32_bf16 v[120:123], v[166:169], v[174:177], v[120:123]
	v_mfma_f32_16x16x32_bf16 v[116:119], v[158:161], v[182:185], v[116:119]
	v_mfma_f32_16x16x32_bf16 v[112:115], v[166:169], v[182:185], v[112:115]
	v_mfma_f32_16x16x32_bf16 v[108:111], v[158:161], v[190:193], v[108:111]
	v_mfma_f32_16x16x32_bf16 v[104:107], v[166:169], v[190:193], v[104:107]
	v_mfma_f32_16x16x32_bf16 v[100:103], v[158:161], v[198:201], v[100:103]
	v_mfma_f32_16x16x32_bf16 v[96:99], v[166:169], v[198:201], v[96:99]
	s_barrier
	s_add_i32 s45, s40, s17
	s_add_i32 s46, s45, 0x100
	s_mov_b32 s10, s6
	s_mov_b32 s11, s7
	s_mov_b32 m0, s1
	ds_read_b128 v[202:205], v145
	ds_read_b128 v[206:209], v146
	ds_read_b128 v[210:213], v147
	ds_read_b128 v[214:217], v148
	buffer_load_dwordx4 v143, s[8:11], s46 offen lds
	s_mov_b32 m0, s3
	s_nop 0
	buffer_load_dwordx4 v144, s[8:11], s46 offen lds
	s_barrier
	s_waitcnt lgkmcnt(0)
	v_mfma_f32_16x16x32_bf16 v[92:95], v[202:205], v[170:173], v[92:95]
	v_mfma_f32_16x16x32_bf16 v[88:91], v[210:213], v[170:173], v[88:91]
	v_mfma_f32_16x16x32_bf16 v[84:87], v[202:205], v[178:181], v[84:87]
	v_mfma_f32_16x16x32_bf16 v[80:83], v[210:213], v[178:181], v[80:83]
	v_mfma_f32_16x16x32_bf16 v[76:79], v[202:205], v[186:189], v[76:79]
	v_mfma_f32_16x16x32_bf16 v[72:75], v[210:213], v[186:189], v[72:75]
	v_mfma_f32_16x16x32_bf16 v[68:71], v[202:205], v[194:197], v[68:71]
	v_mfma_f32_16x16x32_bf16 v[64:67], v[210:213], v[194:197], v[64:67]
	v_mfma_f32_16x16x32_bf16 v[92:95], v[206:209], v[174:177], v[92:95]
	v_mfma_f32_16x16x32_bf16 v[88:91], v[214:217], v[174:177], v[88:91]
	v_mfma_f32_16x16x32_bf16 v[84:87], v[206:209], v[182:185], v[84:87]
	v_mfma_f32_16x16x32_bf16 v[80:83], v[214:217], v[182:185], v[80:83]
	v_mfma_f32_16x16x32_bf16 v[76:79], v[206:209], v[190:193], v[76:79]
	v_mfma_f32_16x16x32_bf16 v[72:75], v[214:217], v[190:193], v[72:75]
	v_mfma_f32_16x16x32_bf16 v[68:71], v[206:209], v[198:201], v[68:71]
	v_mfma_f32_16x16x32_bf16 v[64:67], v[214:217], v[198:201], v[64:67]
	s_barrier
	s_add_i32 s46, s39, s17
	s_add_i32 s47, s46, 0x100
	s_mov_b32 m0, s0
	ds_read_b128 v[170:173], v131 offset:16384
	ds_read_b128 v[174:177], v131 offset:17408
	ds_read_b128 v[178:181], v134 offset:16384
	ds_read_b128 v[182:185], v134 offset:17408
	ds_read_b128 v[186:189], v133 offset:16384
	ds_read_b128 v[190:193], v133 offset:17408
	ds_read_b128 v[194:197], v132 offset:16384
	ds_read_b128 v[198:201], v132 offset:17408
	buffer_load_dwordx4 v143, s[4:7], s47 offen lds
	s_mov_b32 m0, s18
	s_nop 0
	buffer_load_dwordx4 v144, s[4:7], s47 offen lds
	s_barrier
	s_waitcnt lgkmcnt(0)
	v_mfma_f32_16x16x32_bf16 v[60:63], v[154:157], v[170:173], v[60:63]
	v_mfma_f32_16x16x32_bf16 v[56:59], v[162:165], v[170:173], v[56:59]
	v_mfma_f32_16x16x32_bf16 v[52:55], v[154:157], v[178:181], v[52:55]
	v_mfma_f32_16x16x32_bf16 v[48:51], v[162:165], v[178:181], v[48:51]
	v_mfma_f32_16x16x32_bf16 v[44:47], v[154:157], v[186:189], v[44:47]
	v_mfma_f32_16x16x32_bf16 v[40:43], v[162:165], v[186:189], v[40:43]
	v_mfma_f32_16x16x32_bf16 v[36:39], v[154:157], v[194:197], v[36:39]
	v_mfma_f32_16x16x32_bf16 v[32:35], v[162:165], v[194:197], v[32:35]
	v_mfma_f32_16x16x32_bf16 v[60:63], v[158:161], v[174:177], v[60:63]
	v_mfma_f32_16x16x32_bf16 v[56:59], v[166:169], v[174:177], v[56:59]
	v_mfma_f32_16x16x32_bf16 v[52:55], v[158:161], v[182:185], v[52:55]
	v_mfma_f32_16x16x32_bf16 v[48:51], v[166:169], v[182:185], v[48:51]
	v_mfma_f32_16x16x32_bf16 v[44:47], v[158:161], v[190:193], v[44:47]
	v_mfma_f32_16x16x32_bf16 v[40:43], v[166:169], v[190:193], v[40:43]
	v_mfma_f32_16x16x32_bf16 v[36:39], v[158:161], v[198:201], v[36:39]
	v_mfma_f32_16x16x32_bf16 v[32:35], v[166:169], v[198:201], v[32:35]
	s_barrier
	s_add_i32 s47, s41, s17
	s_add_i32 s48, s47, 0x100
	s_mov_b32 m0, s19
	s_nop 0
	buffer_load_dwordx4 v143, s[8:11], s48 offen lds
	s_mov_b32 m0, s20
	s_nop 0
	buffer_load_dwordx4 v144, s[8:11], s48 offen lds
	s_waitcnt vmcnt(6)
	s_barrier
; #define STAGE(P, RS, SOFF, OFF, kt) do { const int _so = (SOFF) + (kt) * (BK * 2); \
;     _Pragma("unroll") for (int _i = 0; _i < 2; ++_i) { \
;       __builtin_amdgcn_raw_ptr_buffer_load_lds(RS, (__attribute__((address_space(3))) void*)((P) + wave * 1024 + _i * 8192), 16, OFF[_i], _so, 0, 0); } } while (0)
; #define LDA(dst, b, h) _Pragma("unroll") for (int m = 0; m < 4; ++m) _Pragma("unroll") for (int k = 0; k < 2; ++k) \
;     dst[m][k] = *reinterpret_cast<const bf16x8*>(SA(b, h) + lds_byte(wr * 64 + m * 16 + fr, k * 32 + fq * 8))
; #define LDB(dst, b, h) _Pragma("unroll") for (int n = 0; n < 2; ++n) _Pragma("unroll") for (int k = 0; k < 2; ++k) \
;     dst[n][k] = *reinterpret_cast<const bf16x8*>(SB(b, h) + lds_byte(wc * 32 + n * 16 + fr, k * 32 + fq * 8))
; #define WAIT_V(n) asm volatile("s_waitcnt vmcnt(" #n ")" ::: "memory")
; #define WAIT_L(n) asm volatile("s_waitcnt lgkmcnt(" #n ")" ::: "memory")
; #define BAR __builtin_amdgcn_s_barrier()
; #define SCHED __builtin_amdgcn_sched_barrier(0)
;     ...
;       WAIT_V(6); BAR; MMA(1, 1, At, B1); BAR;
;       LDB(B0, 1, 0); SCHED; LDA(At, 1, 0); STAGE(SA(0, 1), rsA, sA1, offA, t + 2);
;       WAIT_L(8); BAR; WAIT_L(0); MMA(0, 0, At, B0); BAR; SCHED;
;       LDB(B1, 1, 1); STAGE(SB(1, 0), rsB, sB0, offB, t + 3);
;       BAR; WAIT_L(0); MMA(0, 1, At, B1); BAR;
;       LDA(At, 1, 1); STAGE(SA(1, 0), rsA, sA0, offA, t + 3);
;       BAR; WAIT_L(0); MMA(1, 0, At, B0); BAR; SCHED;
	v_mfma_f32_16x16x32_bf16 v[28:31], v[202:205], v[170:173], v[28:31]
	v_mfma_f32_16x16x32_bf16 v[24:27], v[210:213], v[170:173], v[24:27]
	v_mfma_f32_16x16x32_bf16 v[20:23], v[202:205], v[178:181], v[20:23]
	v_mfma_f32_16x16x32_bf16 v[16:19], v[210:213], v[178:181], v[16:19]
	v_mfma_f32_16x16x32_bf16 v[12:15], v[202:205], v[186:189], v[12:15]
	v_mfma_f32_16x16x32_bf16 v[8:11], v[210:213], v[186:189], v[8:11]
	v_mfma_f32_16x16x32_bf16 v[4:7], v[202:205], v[194:197], v[4:7]
	v_mfma_f32_16x16x32_bf16 v[0:3], v[210:213], v[194:197], v[0:3]
	v_mfma_f32_16x16x32_bf16 v[28:31], v[206:209], v[174:177], v[28:31]
	v_mfma_f32_16x16x32_bf16 v[24:27], v[214:217], v[174:177], v[24:27]
	v_mfma_f32_16x16x32_bf16 v[20:23], v[206:209], v[182:185], v[20:23]
	v_mfma_f32_16x16x32_bf16 v[16:19], v[214:217], v[182:185], v[16:19]
	v_mfma_f32_16x16x32_bf16 v[12:15], v[206:209], v[190:193], v[12:15]
	v_mfma_f32_16x16x32_bf16 v[8:11], v[214:217], v[190:193], v[8:11]
	v_mfma_f32_16x16x32_bf16 v[4:7], v[206:209], v[198:201], v[4:7]
	v_mfma_f32_16x16x32_bf16 v[0:3], v[214:217], v[198:201], v[0:3]
	s_barrier
	ds_read_b128 v[154:157], v139
	ds_read_b128 v[158:161], v140
	ds_read_b128 v[162:165], v141
	ds_read_b128 v[166:169], v142
	s_addk_i32 s44, 0x100
	s_mov_b32 m0, s21
	ds_read_b128 v[170:173], v131 offset:32768
	ds_read_b128 v[174:177], v131 offset:33792
	ds_read_b128 v[178:181], v134 offset:32768
	ds_read_b128 v[182:185], v134 offset:33792
	ds_read_b128 v[186:189], v133 offset:32768
	ds_read_b128 v[190:193], v133 offset:33792
	ds_read_b128 v[194:197], v132 offset:32768
	ds_read_b128 v[198:201], v132 offset:33792
	buffer_load_dwordx4 v143, s[4:7], s44 offen lds
	s_mov_b32 m0, s22
	s_nop 0
	buffer_load_dwordx4 v144, s[4:7], s44 offen lds
	s_waitcnt lgkmcnt(8)
	s_barrier
	s_waitcnt lgkmcnt(0)
	v_mfma_f32_16x16x32_bf16 v[124:127], v[154:157], v[170:173], v[124:127]
	v_mfma_f32_16x16x32_bf16 v[120:123], v[162:165], v[170:173], v[120:123]
	v_mfma_f32_16x16x32_bf16 v[116:119], v[154:157], v[178:181], v[116:119]
	v_mfma_f32_16x16x32_bf16 v[112:115], v[162:165], v[178:181], v[112:115]
	v_mfma_f32_16x16x32_bf16 v[108:111], v[154:157], v[186:189], v[108:111]
	v_mfma_f32_16x16x32_bf16 v[104:107], v[162:165], v[186:189], v[104:107]
	v_mfma_f32_16x16x32_bf16 v[100:103], v[154:157], v[194:197], v[100:103]
	v_mfma_f32_16x16x32_bf16 v[96:99], v[162:165], v[194:197], v[96:99]
	v_mfma_f32_16x16x32_bf16 v[124:127], v[158:161], v[174:177], v[124:127]
	v_mfma_f32_16x16x32_bf16 v[120:123], v[166:169], v[174:177], v[120:123]
	v_mfma_f32_16x16x32_bf16 v[116:119], v[158:161], v[182:185], v[116:119]
	v_mfma_f32_16x16x32_bf16 v[112:115], v[166:169], v[182:185], v[112:115]
	v_mfma_f32_16x16x32_bf16 v[108:111], v[158:161], v[190:193], v[108:111]
	v_mfma_f32_16x16x32_bf16 v[104:107], v[166:169], v[190:193], v[104:107]
	v_mfma_f32_16x16x32_bf16 v[100:103], v[158:161], v[198:201], v[100:103]
	v_mfma_f32_16x16x32_bf16 v[96:99], v[166:169], v[198:201], v[96:99]
	s_barrier
	s_addk_i32 s45, 0x180
	s_mov_b32 m0, s23
	ds_read_b128 v[202:205], v135
	ds_read_b128 v[206:209], v136
	ds_read_b128 v[210:213], v137
	ds_read_b128 v[214:217], v138
	buffer_load_dwordx4 v143, s[8:11], s45 offen lds
	s_mov_b32 m0, s24
	s_nop 0
	buffer_load_dwordx4 v144, s[8:11], s45 offen lds
	s_barrier
	s_waitcnt lgkmcnt(0)
	v_mfma_f32_16x16x32_bf16 v[92:95], v[202:205], v[170:173], v[92:95]
	v_mfma_f32_16x16x32_bf16 v[88:91], v[210:213], v[170:173], v[88:91]
	v_mfma_f32_16x16x32_bf16 v[84:87], v[202:205], v[178:181], v[84:87]
	v_mfma_f32_16x16x32_bf16 v[80:83], v[210:213], v[178:181], v[80:83]
	v_mfma_f32_16x16x32_bf16 v[76:79], v[202:205], v[186:189], v[76:79]
	v_mfma_f32_16x16x32_bf16 v[72:75], v[210:213], v[186:189], v[72:75]
	v_mfma_f32_16x16x32_bf16 v[68:71], v[202:205], v[194:197], v[68:71]
	v_mfma_f32_16x16x32_bf16 v[64:67], v[210:213], v[194:197], v[64:67]
	v_mfma_f32_16x16x32_bf16 v[92:95], v[206:209], v[174:177], v[92:95]
	v_mfma_f32_16x16x32_bf16 v[88:91], v[214:217], v[174:177], v[88:91]
	v_mfma_f32_16x16x32_bf16 v[84:87], v[206:209], v[182:185], v[84:87]
	v_mfma_f32_16x16x32_bf16 v[80:83], v[214:217], v[182:185], v[80:83]
	v_mfma_f32_16x16x32_bf16 v[76:79], v[206:209], v[190:193], v[76:79]
	v_mfma_f32_16x16x32_bf16 v[72:75], v[214:217], v[190:193], v[72:75]
	v_mfma_f32_16x16x32_bf16 v[68:71], v[206:209], v[198:201], v[68:71]
	v_mfma_f32_16x16x32_bf16 v[64:67], v[214:217], v[198:201], v[64:67]
	s_barrier
	s_addk_i32 s46, 0x180
	s_mov_b32 m0, s25
	ds_read_b128 v[170:173], v131 offset:49152
	ds_read_b128 v[174:177], v131 offset:50176
	ds_read_b128 v[178:181], v134 offset:49152
	ds_read_b128 v[182:185], v134 offset:50176
	ds_read_b128 v[186:189], v133 offset:49152
	ds_read_b128 v[190:193], v133 offset:50176
	ds_read_b128 v[194:197], v132 offset:49152
	ds_read_b128 v[198:201], v132 offset:50176
	buffer_load_dwordx4 v143, s[4:7], s46 offen lds
	s_mov_b32 m0, s26
	s_nop 0
	buffer_load_dwordx4 v144, s[4:7], s46 offen lds
	s_barrier
	s_waitcnt lgkmcnt(0)
	v_mfma_f32_16x16x32_bf16 v[60:63], v[154:157], v[170:173], v[60:63]
	v_mfma_f32_16x16x32_bf16 v[56:59], v[162:165], v[170:173], v[56:59]
	v_mfma_f32_16x16x32_bf16 v[52:55], v[154:157], v[178:181], v[52:55]
	v_mfma_f32_16x16x32_bf16 v[48:51], v[162:165], v[178:181], v[48:51]
	v_mfma_f32_16x16x32_bf16 v[44:47], v[154:157], v[186:189], v[44:47]
	v_mfma_f32_16x16x32_bf16 v[40:43], v[162:165], v[186:189], v[40:43]
	v_mfma_f32_16x16x32_bf16 v[36:39], v[154:157], v[194:197], v[36:39]
	v_mfma_f32_16x16x32_bf16 v[32:35], v[162:165], v[194:197], v[32:35]
	v_mfma_f32_16x16x32_bf16 v[60:63], v[158:161], v[174:177], v[60:63]
	v_mfma_f32_16x16x32_bf16 v[56:59], v[166:169], v[174:177], v[56:59]
	v_mfma_f32_16x16x32_bf16 v[52:55], v[158:161], v[182:185], v[52:55]
	v_mfma_f32_16x16x32_bf16 v[48:51], v[166:169], v[182:185], v[48:51]
	v_mfma_f32_16x16x32_bf16 v[44:47], v[158:161], v[190:193], v[44:47]
	v_mfma_f32_16x16x32_bf16 v[40:43], v[166:169], v[190:193], v[40:43]
	v_mfma_f32_16x16x32_bf16 v[36:39], v[158:161], v[198:201], v[36:39]
	v_mfma_f32_16x16x32_bf16 v[32:35], v[166:169], v[198:201], v[32:35]
	s_barrier
; #define STAGE(P, RS, SOFF, OFF, kt) do { const int _so = (SOFF) + (kt) * (BK * 2); \
;     _Pragma("unroll") for (int _i = 0; _i < 2; ++_i) { \
;       __builtin_amdgcn_raw_ptr_buffer_load_lds(RS, (__attribute__((address_space(3))) void*)((P) + wave * 1024 + _i * 8192), 16, OFF[_i], _so, 0, 0); } } while (0)
; #define LDA(dst, b, h) _Pragma("unroll") for (int m = 0; m < 4; ++m) _Pragma("unroll") for (int k = 0; k < 2; ++k) \
;     dst[m][k] = *reinterpret_cast<const bf16x8*>(SA(b, h) + lds_byte(wr * 64 + m * 16 + fr, k * 32 + fq * 8))
; #define LDB(dst, b, h) _Pragma("unroll") for (int n = 0; n < 2; ++n) _Pragma("unroll") for (int k = 0; k < 2; ++k) \
;     dst[n][k] = *reinterpret_cast<const bf16x8*>(SB(b, h) + lds_byte(wc * 32 + n * 16 + fr, k * 32 + fq * 8))
; #define WAIT_V(n) asm volatile("s_waitcnt vmcnt(" #n ")" ::: "memory")
; #define WAIT_L(n) asm volatile("s_waitcnt lgkmcnt(" #n ")" ::: "memory")
; #define BAR __builtin_amdgcn_s_barrier()
;     ...
;       STAGE(SB(1, 1), rsB, sB1, offB, t + 3);
;       WAIT_V(6); BAR; MMA(1, 1, At, B1); BAR;
;     }
;     { LDB(B0, 0, 0); LDA(At, 0, 0); STAGE(SA(1, 1), rsA, sA1, offA, nt - 1);
;       BAR; WAIT_L(0); MMA(0, 0, At, B0); BAR;
;       LDB(B1, 0, 1); BAR; WAIT_L(0); MMA(0, 1, At, B1); BAR;
;       LDA(At, 0, 1); WAIT_V(4); BAR; WAIT_L(0); MMA(1, 0, At, B0); MMA(1, 1, At, B1); BAR; }
	s_addk_i32 s47, 0x180
	s_mov_b32 m0, s27
	s_nop 0
	buffer_load_dwordx4 v143, s[8:11], s47 offen lds
	s_mov_b32 m0, s28
	s_nop 0
	buffer_load_dwordx4 v144, s[8:11], s47 offen lds
	s_add_i32 s16, s16, 2
	s_addk_i32 s17, 0x100
	s_cmp_gt_u32 s16, 27
	s_waitcnt vmcnt(6)
	s_barrier
	v_mfma_f32_16x16x32_bf16 v[28:31], v[202:205], v[170:173], v[28:31]
	v_mfma_f32_16x16x32_bf16 v[24:27], v[210:213], v[170:173], v[24:27]
	v_mfma_f32_16x16x32_bf16 v[20:23], v[202:205], v[178:181], v[20:23]
	v_mfma_f32_16x16x32_bf16 v[16:19], v[210:213], v[178:181], v[16:19]
	v_mfma_f32_16x16x32_bf16 v[12:15], v[202:205], v[186:189], v[12:15]
	v_mfma_f32_16x16x32_bf16 v[8:11], v[210:213], v[186:189], v[8:11]
	v_mfma_f32_16x16x32_bf16 v[4:7], v[202:205], v[194:197], v[4:7]
	v_mfma_f32_16x16x32_bf16 v[0:3], v[210:213], v[194:197], v[0:3]
	v_mfma_f32_16x16x32_bf16 v[28:31], v[206:209], v[174:177], v[28:31]
	v_mfma_f32_16x16x32_bf16 v[24:27], v[214:217], v[174:177], v[24:27]
	v_mfma_f32_16x16x32_bf16 v[20:23], v[206:209], v[182:185], v[20:23]
	v_mfma_f32_16x16x32_bf16 v[16:19], v[214:217], v[182:185], v[16:19]
	v_mfma_f32_16x16x32_bf16 v[12:15], v[206:209], v[190:193], v[12:15]
	v_mfma_f32_16x16x32_bf16 v[8:11], v[214:217], v[190:193], v[8:11]
	v_mfma_f32_16x16x32_bf16 v[4:7], v[206:209], v[198:201], v[4:7]
	v_mfma_f32_16x16x32_bf16 v[0:3], v[214:217], v[198:201], v[0:3]
	s_barrier
	s_cbranch_scc0 .LBB0_210
	s_add_i32 s10, s38, 0xf80
	s_mov_b32 m0, s30
	ds_read_b128 v[154:157], v149
	ds_read_b128 v[158:161], v150
	ds_read_b128 v[162:165], v151
	ds_read_b128 v[150:153], v152
	ds_read_b128 v[166:169], v131
	ds_read_b128 v[170:173], v131 offset:1024
	ds_read_b128 v[174:177], v134
	ds_read_b128 v[178:181], v134 offset:1024
	ds_read_b128 v[182:185], v133
	ds_read_b128 v[186:189], v133 offset:1024
	ds_read_b128 v[190:193], v132
	ds_read_b128 v[194:197], v132 offset:1024
	buffer_load_dwordx4 v143, s[4:7], s10 offen lds
	s_mov_b32 m0, s31
	s_nop 0
	buffer_load_dwordx4 v144, s[4:7], s10 offen lds
	s_barrier
	s_waitcnt lgkmcnt(0)
	v_mfma_f32_16x16x32_bf16 v[124:127], v[154:157], v[166:169], v[124:127]
	v_mfma_f32_16x16x32_bf16 v[120:123], v[162:165], v[166:169], v[120:123]
	v_mfma_f32_16x16x32_bf16 v[116:119], v[154:157], v[174:177], v[116:119]
	v_mfma_f32_16x16x32_bf16 v[112:115], v[162:165], v[174:177], v[112:115]
	v_mfma_f32_16x16x32_bf16 v[108:111], v[154:157], v[182:185], v[108:111]
	v_mfma_f32_16x16x32_bf16 v[104:107], v[162:165], v[182:185], v[104:107]
	v_mfma_f32_16x16x32_bf16 v[100:103], v[154:157], v[190:193], v[100:103]
	v_mfma_f32_16x16x32_bf16 v[96:99], v[162:165], v[190:193], v[96:99]
	v_mfma_f32_16x16x32_bf16 v[124:127], v[158:161], v[170:173], v[124:127]
	v_mfma_f32_16x16x32_bf16 v[120:123], v[150:153], v[170:173], v[120:123]
	v_mfma_f32_16x16x32_bf16 v[116:119], v[158:161], v[178:181], v[116:119]
	v_mfma_f32_16x16x32_bf16 v[112:115], v[150:153], v[178:181], v[112:115]
	v_mfma_f32_16x16x32_bf16 v[108:111], v[158:161], v[186:189], v[108:111]
	v_mfma_f32_16x16x32_bf16 v[104:107], v[150:153], v[186:189], v[104:107]
	v_mfma_f32_16x16x32_bf16 v[100:103], v[158:161], v[194:197], v[100:103]
	v_mfma_f32_16x16x32_bf16 v[96:99], v[150:153], v[194:197], v[96:99]
	s_barrier
	ds_read_b128 v[198:201], v145
	ds_read_b128 v[202:205], v146
	ds_read_b128 v[144:147], v147
	ds_read_b128 v[206:209], v148
	s_barrier
	s_waitcnt lgkmcnt(0)
	v_mfma_f32_16x16x32_bf16 v[92:95], v[198:201], v[166:169], v[92:95]
	v_mfma_f32_16x16x32_bf16 v[88:91], v[144:147], v[166:169], v[88:91]
	v_mfma_f32_16x16x32_bf16 v[84:87], v[198:201], v[174:177], v[84:87]
	v_mfma_f32_16x16x32_bf16 v[80:83], v[144:147], v[174:177], v[80:83]
	v_mfma_f32_16x16x32_bf16 v[76:79], v[198:201], v[182:185], v[76:79]
	v_mfma_f32_16x16x32_bf16 v[72:75], v[144:147], v[182:185], v[72:75]
	v_mfma_f32_16x16x32_bf16 v[68:71], v[198:201], v[190:193], v[68:71]
	v_mfma_f32_16x16x32_bf16 v[64:67], v[144:147], v[190:193], v[64:67]
	v_mfma_f32_16x16x32_bf16 v[92:95], v[202:205], v[170:173], v[92:95]
	v_mfma_f32_16x16x32_bf16 v[88:91], v[206:209], v[170:173], v[88:91]
	v_mfma_f32_16x16x32_bf16 v[84:87], v[202:205], v[178:181], v[84:87]
	v_mfma_f32_16x16x32_bf16 v[80:83], v[206:209], v[178:181], v[80:83]
	v_mfma_f32_16x16x32_bf16 v[76:79], v[202:205], v[186:189], v[76:79]
	v_mfma_f32_16x16x32_bf16 v[72:75], v[206:209], v[186:189], v[72:75]
	v_mfma_f32_16x16x32_bf16 v[68:71], v[202:205], v[194:197], v[68:71]
	v_mfma_f32_16x16x32_bf16 v[64:67], v[206:209], v[194:197], v[64:67]
	s_barrier
	ds_read_b128 v[166:169], v131 offset:16384
	ds_read_b128 v[170:173], v131 offset:17408
	ds_read_b128 v[174:177], v134 offset:16384
	ds_read_b128 v[178:181], v134 offset:17408
	ds_read_b128 v[182:185], v133 offset:16384
	ds_read_b128 v[186:189], v133 offset:17408
	ds_read_b128 v[190:193], v132 offset:16384
	ds_read_b128 v[194:197], v132 offset:17408
	s_waitcnt vmcnt(4)
	s_barrier
; #define LDA(dst, b, h) _Pragma("unroll") for (int m = 0; m < 4; ++m) _Pragma("unroll") for (int k = 0; k < 2; ++k) \
;     dst[m][k] = *reinterpret_cast<const bf16x8*>(SA(b, h) + lds_byte(wr * 64 + m * 16 + fr, k * 32 + fq * 8))
; #define LDB(dst, b, h) _Pragma("unroll") for (int n = 0; n < 2; ++n) _Pragma("unroll") for (int k = 0; k < 2; ++k) \
;     dst[n][k] = *reinterpret_cast<const bf16x8*>(SB(b, h) + lds_byte(wc * 32 + n * 16 + fr, k * 32 + fq * 8))
; #define WAIT_V(n) asm volatile("s_waitcnt vmcnt(" #n ")" ::: "memory")
; #define WAIT_L(n) asm volatile("s_waitcnt lgkmcnt(" #n ")" ::: "memory")
; #define BAR __builtin_amdgcn_s_barrier()
;     ...
;       LDA(At, 0, 1); WAIT_V(4); BAR; WAIT_L(0); MMA(1, 0, At, B0); MMA(1, 1, At, B1); BAR; }
;     { LDB(B0, 1, 0); LDA(At, 1, 0); WAIT_V(2); BAR; WAIT_L(0); MMA(0, 0, At, B0); BAR;
	s_waitcnt lgkmcnt(0)
	v_mfma_f32_16x16x32_bf16 v[60:63], v[154:157], v[166:169], v[60:63]
	v_mfma_f32_16x16x32_bf16 v[56:59], v[162:165], v[166:169], v[56:59]
	v_mfma_f32_16x16x32_bf16 v[52:55], v[154:157], v[174:177], v[52:55]
	v_mfma_f32_16x16x32_bf16 v[48:51], v[162:165], v[174:177], v[48:51]
	v_mfma_f32_16x16x32_bf16 v[44:47], v[154:157], v[182:185], v[44:47]
	v_mfma_f32_16x16x32_bf16 v[40:43], v[162:165], v[182:185], v[40:43]
	v_mfma_f32_16x16x32_bf16 v[36:39], v[154:157], v[190:193], v[36:39]
	v_mfma_f32_16x16x32_bf16 v[32:35], v[162:165], v[190:193], v[32:35]
	v_mfma_f32_16x16x32_bf16 v[60:63], v[158:161], v[170:173], v[60:63]
	v_mfma_f32_16x16x32_bf16 v[56:59], v[150:153], v[170:173], v[56:59]
	v_mfma_f32_16x16x32_bf16 v[52:55], v[158:161], v[178:181], v[52:55]
	v_mfma_f32_16x16x32_bf16 v[48:51], v[150:153], v[178:181], v[48:51]
	v_mfma_f32_16x16x32_bf16 v[44:47], v[158:161], v[186:189], v[44:47]
	v_mfma_f32_16x16x32_bf16 v[40:43], v[150:153], v[186:189], v[40:43]
	v_mfma_f32_16x16x32_bf16 v[36:39], v[158:161], v[194:197], v[36:39]
	v_mfma_f32_16x16x32_bf16 v[32:35], v[150:153], v[194:197], v[32:35]
	v_mfma_f32_16x16x32_bf16 v[28:31], v[198:201], v[166:169], v[28:31]
	v_mfma_f32_16x16x32_bf16 v[24:27], v[144:147], v[166:169], v[24:27]
	v_mfma_f32_16x16x32_bf16 v[20:23], v[198:201], v[174:177], v[20:23]
	v_mfma_f32_16x16x32_bf16 v[16:19], v[144:147], v[174:177], v[16:19]
	v_mfma_f32_16x16x32_bf16 v[12:15], v[198:201], v[182:185], v[12:15]
	v_mfma_f32_16x16x32_bf16 v[8:11], v[144:147], v[182:185], v[8:11]
	v_mfma_f32_16x16x32_bf16 v[4:7], v[198:201], v[190:193], v[4:7]
	v_mfma_f32_16x16x32_bf16 v[0:3], v[144:147], v[190:193], v[0:3]
	v_mfma_f32_16x16x32_bf16 v[28:31], v[202:205], v[170:173], v[28:31]
	v_mfma_f32_16x16x32_bf16 v[24:27], v[206:209], v[170:173], v[24:27]
	v_mfma_f32_16x16x32_bf16 v[20:23], v[202:205], v[178:181], v[20:23]
	v_mfma_f32_16x16x32_bf16 v[16:19], v[206:209], v[178:181], v[16:19]
	v_mfma_f32_16x16x32_bf16 v[12:15], v[202:205], v[186:189], v[12:15]
	v_mfma_f32_16x16x32_bf16 v[8:11], v[206:209], v[186:189], v[8:11]
	v_mfma_f32_16x16x32_bf16 v[4:7], v[202:205], v[194:197], v[4:7]
	v_mfma_f32_16x16x32_bf16 v[0:3], v[206:209], v[194:197], v[0:3]
	s_barrier
	ds_read_b128 v[144:147], v139
	ds_read_b128 v[148:151], v140
	ds_read_b128 v[152:155], v141
	ds_read_b128 v[140:143], v142
	ds_read_b128 v[156:159], v131 offset:32768
	ds_read_b128 v[160:163], v131 offset:33792
	ds_read_b128 v[164:167], v134 offset:32768
	ds_read_b128 v[168:171], v134 offset:33792
	ds_read_b128 v[172:175], v133 offset:32768
	ds_read_b128 v[176:179], v133 offset:33792
	ds_read_b128 v[180:183], v132 offset:32768
	ds_read_b128 v[184:187], v132 offset:33792
	s_waitcnt vmcnt(2)
	s_barrier
	s_waitcnt lgkmcnt(0)
	v_mfma_f32_16x16x32_bf16 v[124:127], v[144:147], v[156:159], v[124:127]
	v_mfma_f32_16x16x32_bf16 v[120:123], v[152:155], v[156:159], v[120:123]
	v_mfma_f32_16x16x32_bf16 v[116:119], v[144:147], v[164:167], v[116:119]
	v_mfma_f32_16x16x32_bf16 v[112:115], v[152:155], v[164:167], v[112:115]
	v_mfma_f32_16x16x32_bf16 v[108:111], v[144:147], v[172:175], v[108:111]
	v_mfma_f32_16x16x32_bf16 v[104:107], v[152:155], v[172:175], v[104:107]
	v_mfma_f32_16x16x32_bf16 v[100:103], v[144:147], v[180:183], v[100:103]
	v_mfma_f32_16x16x32_bf16 v[96:99], v[152:155], v[180:183], v[96:99]
	v_mfma_f32_16x16x32_bf16 v[124:127], v[148:151], v[160:163], v[124:127]
	v_mfma_f32_16x16x32_bf16 v[120:123], v[140:143], v[160:163], v[120:123]
	v_mfma_f32_16x16x32_bf16 v[116:119], v[148:151], v[168:171], v[116:119]
	v_mfma_f32_16x16x32_bf16 v[112:115], v[140:143], v[168:171], v[112:115]
	v_mfma_f32_16x16x32_bf16 v[108:111], v[148:151], v[176:179], v[108:111]
	v_mfma_f32_16x16x32_bf16 v[104:107], v[140:143], v[176:179], v[104:107]
	v_mfma_f32_16x16x32_bf16 v[100:103], v[148:151], v[184:187], v[100:103]
	v_mfma_f32_16x16x32_bf16 v[96:99], v[140:143], v[184:187], v[96:99]
	s_barrier
; #define LDA(dst, b, h) _Pragma("unroll") for (int m = 0; m < 4; ++m) _Pragma("unroll") for (int k = 0; k < 2; ++k) \
;     dst[m][k] = *reinterpret_cast<const bf16x8*>(SA(b, h) + lds_byte(wr * 64 + m * 16 + fr, k * 32 + fq * 8))
; #define LDB(dst, b, h) _Pragma("unroll") for (int n = 0; n < 2; ++n) _Pragma("unroll") for (int k = 0; k < 2; ++k) \
;     dst[n][k] = *reinterpret_cast<const bf16x8*>(SB(b, h) + lds_byte(wc * 32 + n * 16 + fr, k * 32 + fq * 8))
; #define WAIT_V(n) asm volatile("s_waitcnt vmcnt(" #n ")" ::: "memory")
; #define WAIT_L(n) asm volatile("s_waitcnt lgkmcnt(" #n ")" ::: "memory")
; #define BAR __builtin_amdgcn_s_barrier()
;     ...
;       LDB(B1, 1, 1); WAIT_V(0); BAR; WAIT_L(0); MMA(0, 1, At, B1); BAR;
;       LDA(At, 1, 1); BAR; WAIT_L(0); MMA(1, 0, At, B0); MMA(1, 1, At, B1); BAR; }
;     if (wr == 0) BAR;
	ds_read_b128 v[188:191], v135
	ds_read_b128 v[192:195], v136
	ds_read_b128 v[196:199], v137
	ds_read_b128 v[136:139], v138
	s_waitcnt vmcnt(0)
	s_barrier
	s_waitcnt lgkmcnt(0)
	v_mfma_f32_16x16x32_bf16 v[92:95], v[188:191], v[156:159], v[92:95]
	v_mfma_f32_16x16x32_bf16 v[88:91], v[196:199], v[156:159], v[88:91]
	v_mfma_f32_16x16x32_bf16 v[84:87], v[188:191], v[164:167], v[84:87]
	v_mfma_f32_16x16x32_bf16 v[80:83], v[196:199], v[164:167], v[80:83]
	v_mfma_f32_16x16x32_bf16 v[76:79], v[188:191], v[172:175], v[76:79]
	v_mfma_f32_16x16x32_bf16 v[72:75], v[196:199], v[172:175], v[72:75]
	v_mfma_f32_16x16x32_bf16 v[68:71], v[188:191], v[180:183], v[68:71]
	v_mfma_f32_16x16x32_bf16 v[64:67], v[196:199], v[180:183], v[64:67]
	v_mfma_f32_16x16x32_bf16 v[92:95], v[192:195], v[160:163], v[92:95]
	v_mfma_f32_16x16x32_bf16 v[88:91], v[136:139], v[160:163], v[88:91]
	v_mfma_f32_16x16x32_bf16 v[84:87], v[192:195], v[168:171], v[84:87]
	v_mfma_f32_16x16x32_bf16 v[80:83], v[136:139], v[168:171], v[80:83]
	v_mfma_f32_16x16x32_bf16 v[76:79], v[192:195], v[176:179], v[76:79]
	v_mfma_f32_16x16x32_bf16 v[72:75], v[136:139], v[176:179], v[72:75]
	v_mfma_f32_16x16x32_bf16 v[68:71], v[192:195], v[184:187], v[68:71]
	v_mfma_f32_16x16x32_bf16 v[64:67], v[136:139], v[184:187], v[64:67]
	s_barrier
	ds_read_b128 v[156:159], v131 offset:49152
	ds_read_b128 v[160:163], v131 offset:50176
	ds_read_b128 v[164:167], v134 offset:49152
	ds_read_b128 v[168:171], v134 offset:50176
	ds_read_b128 v[172:175], v133 offset:49152
	ds_read_b128 v[176:179], v133 offset:50176
	ds_read_b128 v[180:183], v132 offset:49152
	ds_read_b128 v[132:135], v132 offset:50176
	s_barrier
	s_waitcnt lgkmcnt(0)
	v_mfma_f32_16x16x32_bf16 v[60:63], v[144:147], v[156:159], v[60:63]
	v_mfma_f32_16x16x32_bf16 v[56:59], v[152:155], v[156:159], v[56:59]
	v_mfma_f32_16x16x32_bf16 v[52:55], v[144:147], v[164:167], v[52:55]
	v_mfma_f32_16x16x32_bf16 v[48:51], v[152:155], v[164:167], v[48:51]
	v_mfma_f32_16x16x32_bf16 v[44:47], v[144:147], v[172:175], v[44:47]
	v_mfma_f32_16x16x32_bf16 v[40:43], v[152:155], v[172:175], v[40:43]
	v_mfma_f32_16x16x32_bf16 v[36:39], v[144:147], v[180:183], v[36:39]
	v_mfma_f32_16x16x32_bf16 v[32:35], v[152:155], v[180:183], v[32:35]
	v_mfma_f32_16x16x32_bf16 v[60:63], v[148:151], v[160:163], v[60:63]
	v_mfma_f32_16x16x32_bf16 v[56:59], v[140:143], v[160:163], v[56:59]
	v_mfma_f32_16x16x32_bf16 v[52:55], v[148:151], v[168:171], v[52:55]
	v_mfma_f32_16x16x32_bf16 v[48:51], v[140:143], v[168:171], v[48:51]
	v_mfma_f32_16x16x32_bf16 v[44:47], v[148:151], v[176:179], v[44:47]
	v_mfma_f32_16x16x32_bf16 v[40:43], v[140:143], v[176:179], v[40:43]
	v_mfma_f32_16x16x32_bf16 v[36:39], v[148:151], v[132:135], v[36:39]
	v_mfma_f32_16x16x32_bf16 v[32:35], v[140:143], v[132:135], v[32:35]
	v_mfma_f32_16x16x32_bf16 v[28:31], v[188:191], v[156:159], v[28:31]
	v_mfma_f32_16x16x32_bf16 v[24:27], v[196:199], v[156:159], v[24:27]
	v_mfma_f32_16x16x32_bf16 v[20:23], v[188:191], v[164:167], v[20:23]
	v_mfma_f32_16x16x32_bf16 v[16:19], v[196:199], v[164:167], v[16:19]
	v_mfma_f32_16x16x32_bf16 v[12:15], v[188:191], v[172:175], v[12:15]
	v_mfma_f32_16x16x32_bf16 v[8:11], v[196:199], v[172:175], v[8:11]
	v_mfma_f32_16x16x32_bf16 v[4:7], v[188:191], v[180:183], v[4:7]
	v_mfma_f32_16x16x32_bf16 v[0:3], v[196:199], v[180:183], v[0:3]
	v_mfma_f32_16x16x32_bf16 v[28:31], v[192:195], v[160:163], v[28:31]
	v_mfma_f32_16x16x32_bf16 v[24:27], v[136:139], v[160:163], v[24:27]
	v_mfma_f32_16x16x32_bf16 v[20:23], v[192:195], v[168:171], v[20:23]
	v_mfma_f32_16x16x32_bf16 v[16:19], v[136:139], v[168:171], v[16:19]
	v_mfma_f32_16x16x32_bf16 v[12:15], v[192:195], v[176:179], v[12:15]
	v_mfma_f32_16x16x32_bf16 v[8:11], v[136:139], v[176:179], v[8:11]
	v_mfma_f32_16x16x32_bf16 v[4:7], v[192:195], v[132:135], v[4:7]
	v_mfma_f32_16x16x32_bf16 v[0:3], v[136:139], v[132:135], v[0:3]
	v_cmp_gt_u32_e32 vcc, s35, v130
	s_barrier
	s_and_saveexec_b64 s[10:11], vcc
	s_cbranch_execz .LBB0_213
	s_barrier

; #define STAGE(P, RS, SOFF, OFF, kt) do { const int _so = (SOFF) + (kt) * (BK * 2); \
;     _Pragma("unroll") for (int _i = 0; _i < 2; ++_i) { \
;       __builtin_amdgcn_raw_ptr_buffer_load_lds(RS, (__attribute__((address_space(3))) void*)((P) + wave * 1024 + _i * 8192), 16, OFF[_i], _so, 0, 0); } } while (0)
; #define LDA(dst, b, h) _Pragma("unroll") for (int m = 0; m < 4; ++m) _Pragma("unroll") for (int k = 0; k < 2; ++k) \
;     dst[m][k] = *reinterpret_cast<const bf16x8*>(SA(b, h) + lds_byte(wr * 64 + m * 16 + fr, k * 32 + fq * 8))
; #define LDB(dst, b, h) _Pragma("unroll") for (int n = 0; n < 2; ++n) _Pragma("unroll") for (int k = 0; k < 2; ++k) \
;     dst[n][k] = *reinterpret_cast<const bf16x8*>(SB(b, h) + lds_byte(wc * 32 + n * 16 + fr, k * 32 + fq * 8))
; #define WAIT_V(n) asm volatile("s_waitcnt vmcnt(" #n ")" ::: "memory")
; #define WAIT_L(n) asm volatile("s_waitcnt lgkmcnt(" #n ")" ::: "memory")
; #define BAR __builtin_amdgcn_s_barrier()
; #define SCHED __builtin_amdgcn_sched_barrier(0)
;     ...
;       LDB(B0, 0, 0); SCHED; LDA(At, 0, 0); STAGE(SA(1, 1), rsA, sA1, offA, t + 1);
;       WAIT_L(8); BAR; WAIT_L(0); MMA(0, 0, At, B0); BAR; SCHED;
;       LDB(B1, 0, 1); STAGE(SB(0, 0), rsB, sB0, offB, t + 2);
;       BAR; WAIT_L(0); MMA(0, 1, At, B1); BAR;
;       LDA(At, 0, 1); STAGE(SA(0, 0), rsA, sA0, offA, t + 2);
;       BAR; WAIT_L(0); MMA(1, 0, At, B0); BAR; SCHED;
;       STAGE(SB(0, 1), rsB, sB1, offB, t + 2);
;       WAIT_V(6); BAR; MMA(1, 1, At, B1); BAR;
.LBB0_225:
	ds_read_b128 v[152:155], v148
	ds_read_b128 v[156:159], v149
	ds_read_b128 v[160:163], v150
	ds_read_b128 v[164:167], v151
	s_add_i32 s18, s41, s17
	s_add_i32 s19, s18, 0x80
	s_mov_b32 m0, s33
	ds_read_b128 v[168:171], v130
	ds_read_b128 v[172:175], v130 offset:1024
	ds_read_b128 v[176:179], v133
	ds_read_b128 v[180:183], v133 offset:1024
	ds_read_b128 v[184:187], v132
	ds_read_b128 v[188:191], v132 offset:1024
	ds_read_b128 v[192:195], v131
	ds_read_b128 v[196:199], v131 offset:1024
	buffer_load_dwordx4 v142, s[4:7], s19 offen lds
	s_mov_b32 m0, s34
	s_nop 0
	buffer_load_dwordx4 v143, s[4:7], s19 offen lds
	s_waitcnt lgkmcnt(8)
	s_barrier
	s_waitcnt lgkmcnt(0)
	v_mfma_f32_16x16x32_bf16 v[124:127], v[168:171], v[152:155], v[124:127]
	v_mfma_f32_16x16x32_bf16 v[120:123], v[168:171], v[160:163], v[120:123]
	v_mfma_f32_16x16x32_bf16 v[116:119], v[176:179], v[152:155], v[116:119]
	v_mfma_f32_16x16x32_bf16 v[112:115], v[176:179], v[160:163], v[112:115]
	v_mfma_f32_16x16x32_bf16 v[108:111], v[184:187], v[152:155], v[108:111]
	v_mfma_f32_16x16x32_bf16 v[104:107], v[184:187], v[160:163], v[104:107]
	v_mfma_f32_16x16x32_bf16 v[100:103], v[192:195], v[152:155], v[100:103]
	v_mfma_f32_16x16x32_bf16 v[96:99], v[192:195], v[160:163], v[96:99]
	v_mfma_f32_16x16x32_bf16 v[124:127], v[172:175], v[156:159], v[124:127]
	v_mfma_f32_16x16x32_bf16 v[120:123], v[172:175], v[164:167], v[120:123]
	v_mfma_f32_16x16x32_bf16 v[116:119], v[180:183], v[156:159], v[116:119]
	v_mfma_f32_16x16x32_bf16 v[112:115], v[180:183], v[164:167], v[112:115]
	v_mfma_f32_16x16x32_bf16 v[108:111], v[188:191], v[156:159], v[108:111]
	v_mfma_f32_16x16x32_bf16 v[104:107], v[188:191], v[164:167], v[104:107]
	v_mfma_f32_16x16x32_bf16 v[100:103], v[196:199], v[156:159], v[100:103]
	v_mfma_f32_16x16x32_bf16 v[96:99], v[196:199], v[164:167], v[96:99]
	s_barrier
	s_add_i32 s19, s43, s17
	s_add_i32 s47, s19, 0x100
	s_mov_b32 m0, s1
	ds_read_b128 v[200:203], v144
	ds_read_b128 v[204:207], v145
	ds_read_b128 v[208:211], v146
	ds_read_b128 v[212:215], v147
	buffer_load_dwordx4 v142, s[8:11], s47 offen lds
	s_mov_b32 m0, s3
	s_nop 0
	buffer_load_dwordx4 v143, s[8:11], s47 offen lds
	s_barrier
	s_waitcnt lgkmcnt(0)
	v_mfma_f32_16x16x32_bf16 v[92:95], v[168:171], v[200:203], v[92:95]
	v_mfma_f32_16x16x32_bf16 v[88:91], v[168:171], v[208:211], v[88:91]
	v_mfma_f32_16x16x32_bf16 v[84:87], v[176:179], v[200:203], v[84:87]
	v_mfma_f32_16x16x32_bf16 v[80:83], v[176:179], v[208:211], v[80:83]
	v_mfma_f32_16x16x32_bf16 v[76:79], v[184:187], v[200:203], v[76:79]
	v_mfma_f32_16x16x32_bf16 v[72:75], v[184:187], v[208:211], v[72:75]
	v_mfma_f32_16x16x32_bf16 v[68:71], v[192:195], v[200:203], v[68:71]
	v_mfma_f32_16x16x32_bf16 v[64:67], v[192:195], v[208:211], v[64:67]
	v_mfma_f32_16x16x32_bf16 v[92:95], v[172:175], v[204:207], v[92:95]
	v_mfma_f32_16x16x32_bf16 v[88:91], v[172:175], v[212:215], v[88:91]
	v_mfma_f32_16x16x32_bf16 v[84:87], v[180:183], v[204:207], v[84:87]
	v_mfma_f32_16x16x32_bf16 v[80:83], v[180:183], v[212:215], v[80:83]
	v_mfma_f32_16x16x32_bf16 v[76:79], v[188:191], v[204:207], v[76:79]
	v_mfma_f32_16x16x32_bf16 v[72:75], v[188:191], v[212:215], v[72:75]
	v_mfma_f32_16x16x32_bf16 v[68:71], v[196:199], v[204:207], v[68:71]
	v_mfma_f32_16x16x32_bf16 v[64:67], v[196:199], v[212:215], v[64:67]
	s_barrier
	s_add_i32 s47, s42, s17
	s_add_i32 s48, s47, 0x100
	s_mov_b32 m0, s0
	ds_read_b128 v[168:171], v130 offset:16384
	ds_read_b128 v[172:175], v130 offset:17408
	ds_read_b128 v[176:179], v133 offset:16384
	ds_read_b128 v[180:183], v133 offset:17408
	ds_read_b128 v[184:187], v132 offset:16384
	ds_read_b128 v[188:191], v132 offset:17408
	ds_read_b128 v[192:195], v131 offset:16384
	ds_read_b128 v[196:199], v131 offset:17408
	buffer_load_dwordx4 v142, s[4:7], s48 offen lds
	s_mov_b32 m0, s20
	s_nop 0
	buffer_load_dwordx4 v143, s[4:7], s48 offen lds
	s_barrier
	s_waitcnt lgkmcnt(0)
	v_mfma_f32_16x16x32_bf16 v[60:63], v[168:171], v[152:155], v[60:63]
	v_mfma_f32_16x16x32_bf16 v[56:59], v[168:171], v[160:163], v[56:59]
	v_mfma_f32_16x16x32_bf16 v[52:55], v[176:179], v[152:155], v[52:55]
	v_mfma_f32_16x16x32_bf16 v[48:51], v[176:179], v[160:163], v[48:51]
	v_mfma_f32_16x16x32_bf16 v[44:47], v[184:187], v[152:155], v[44:47]
	v_mfma_f32_16x16x32_bf16 v[40:43], v[184:187], v[160:163], v[40:43]
	v_mfma_f32_16x16x32_bf16 v[36:39], v[192:195], v[152:155], v[36:39]
	v_mfma_f32_16x16x32_bf16 v[32:35], v[192:195], v[160:163], v[32:35]
	v_mfma_f32_16x16x32_bf16 v[60:63], v[172:175], v[156:159], v[60:63]
	v_mfma_f32_16x16x32_bf16 v[56:59], v[172:175], v[164:167], v[56:59]
	v_mfma_f32_16x16x32_bf16 v[52:55], v[180:183], v[156:159], v[52:55]
	v_mfma_f32_16x16x32_bf16 v[48:51], v[180:183], v[164:167], v[48:51]
	v_mfma_f32_16x16x32_bf16 v[44:47], v[188:191], v[156:159], v[44:47]
	v_mfma_f32_16x16x32_bf16 v[40:43], v[188:191], v[164:167], v[40:43]
	v_mfma_f32_16x16x32_bf16 v[36:39], v[196:199], v[156:159], v[36:39]
	v_mfma_f32_16x16x32_bf16 v[32:35], v[196:199], v[164:167], v[32:35]
	s_barrier
	s_add_i32 s48, s44, s17
	s_add_i32 s49, s48, 0x100
	s_mov_b32 m0, s21
	s_nop 0
	buffer_load_dwordx4 v142, s[8:11], s49 offen lds
	s_mov_b32 m0, s22
	s_nop 0
	buffer_load_dwordx4 v143, s[8:11], s49 offen lds
	s_waitcnt vmcnt(6)
	s_barrier
; #define STAGE(P, RS, SOFF, OFF, kt) do { const int _so = (SOFF) + (kt) * (BK * 2); \
;     _Pragma("unroll") for (int _i = 0; _i < 2; ++_i) { \
;       __builtin_amdgcn_raw_ptr_buffer_load_lds(RS, (__attribute__((address_space(3))) void*)((P) + wave * 1024 + _i * 8192), 16, OFF[_i], _so, 0, 0); } } while (0)
; #define LDA(dst, b, h) _Pragma("unroll") for (int m = 0; m < 4; ++m) _Pragma("unroll") for (int k = 0; k < 2; ++k) \
;     dst[m][k] = *reinterpret_cast<const bf16x8*>(SA(b, h) + lds_byte(wr * 64 + m * 16 + fr, k * 32 + fq * 8))
; #define LDB(dst, b, h) _Pragma("unroll") for (int n = 0; n < 2; ++n) _Pragma("unroll") for (int k = 0; k < 2; ++k) \
;     dst[n][k] = *reinterpret_cast<const bf16x8*>(SB(b, h) + lds_byte(wc * 32 + n * 16 + fr, k * 32 + fq * 8))
; #define WAIT_V(n) asm volatile("s_waitcnt vmcnt(" #n ")" ::: "memory")
; #define WAIT_L(n) asm volatile("s_waitcnt lgkmcnt(" #n ")" ::: "memory")
; #define BAR __builtin_amdgcn_s_barrier()
; #define SCHED __builtin_amdgcn_sched_barrier(0)
;     ...
;       WAIT_V(6); BAR; MMA(1, 1, At, B1); BAR;
;       LDB(B0, 1, 0); SCHED; LDA(At, 1, 0); STAGE(SA(0, 1), rsA, sA1, offA, t + 2);
;       WAIT_L(8); BAR; WAIT_L(0); MMA(0, 0, At, B0); BAR; SCHED;
;       LDB(B1, 1, 1); STAGE(SB(1, 0), rsB, sB0, offB, t + 3);
;       BAR; WAIT_L(0); MMA(0, 1, At, B1); BAR;
;       LDA(At, 1, 1); STAGE(SA(1, 0), rsA, sA0, offA, t + 3);
;       BAR; WAIT_L(0); MMA(1, 0, At, B0); BAR; SCHED;
	v_mfma_f32_16x16x32_bf16 v[28:31], v[168:171], v[200:203], v[28:31]
	v_mfma_f32_16x16x32_bf16 v[24:27], v[168:171], v[208:211], v[24:27]
	v_mfma_f32_16x16x32_bf16 v[20:23], v[176:179], v[200:203], v[20:23]
	v_mfma_f32_16x16x32_bf16 v[16:19], v[176:179], v[208:211], v[16:19]
	v_mfma_f32_16x16x32_bf16 v[12:15], v[184:187], v[200:203], v[12:15]
	v_mfma_f32_16x16x32_bf16 v[8:11], v[184:187], v[208:211], v[8:11]
	v_mfma_f32_16x16x32_bf16 v[4:7], v[192:195], v[200:203], v[4:7]
	v_mfma_f32_16x16x32_bf16 v[0:3], v[192:195], v[208:211], v[0:3]
	v_mfma_f32_16x16x32_bf16 v[28:31], v[172:175], v[204:207], v[28:31]
	v_mfma_f32_16x16x32_bf16 v[24:27], v[172:175], v[212:215], v[24:27]
	v_mfma_f32_16x16x32_bf16 v[20:23], v[180:183], v[204:207], v[20:23]
	v_mfma_f32_16x16x32_bf16 v[16:19], v[180:183], v[212:215], v[16:19]
	v_mfma_f32_16x16x32_bf16 v[12:15], v[188:191], v[204:207], v[12:15]
	v_mfma_f32_16x16x32_bf16 v[8:11], v[188:191], v[212:215], v[8:11]
	v_mfma_f32_16x16x32_bf16 v[4:7], v[196:199], v[204:207], v[4:7]
	v_mfma_f32_16x16x32_bf16 v[0:3], v[196:199], v[212:215], v[0:3]
	s_barrier
	ds_read_b128 v[152:155], v138
	ds_read_b128 v[156:159], v139
	ds_read_b128 v[160:163], v140
	ds_read_b128 v[164:167], v141
	s_addk_i32 s18, 0x100
	s_mov_b32 m0, s23
	ds_read_b128 v[168:171], v130 offset:32768
	ds_read_b128 v[172:175], v130 offset:33792
	ds_read_b128 v[176:179], v133 offset:32768
	ds_read_b128 v[180:183], v133 offset:33792
	ds_read_b128 v[184:187], v132 offset:32768
	ds_read_b128 v[188:191], v132 offset:33792
	ds_read_b128 v[192:195], v131 offset:32768
	ds_read_b128 v[196:199], v131 offset:33792
	buffer_load_dwordx4 v142, s[4:7], s18 offen lds
	s_mov_b32 m0, s24
	s_nop 0
	buffer_load_dwordx4 v143, s[4:7], s18 offen lds
	s_waitcnt lgkmcnt(8)
	s_barrier
	s_waitcnt lgkmcnt(0)
	v_mfma_f32_16x16x32_bf16 v[124:127], v[168:171], v[152:155], v[124:127]
	v_mfma_f32_16x16x32_bf16 v[120:123], v[168:171], v[160:163], v[120:123]
	v_mfma_f32_16x16x32_bf16 v[116:119], v[176:179], v[152:155], v[116:119]
	v_mfma_f32_16x16x32_bf16 v[112:115], v[176:179], v[160:163], v[112:115]
	v_mfma_f32_16x16x32_bf16 v[108:111], v[184:187], v[152:155], v[108:111]
	v_mfma_f32_16x16x32_bf16 v[104:107], v[184:187], v[160:163], v[104:107]
	v_mfma_f32_16x16x32_bf16 v[100:103], v[192:195], v[152:155], v[100:103]
	v_mfma_f32_16x16x32_bf16 v[96:99], v[192:195], v[160:163], v[96:99]
	v_mfma_f32_16x16x32_bf16 v[124:127], v[172:175], v[156:159], v[124:127]
	v_mfma_f32_16x16x32_bf16 v[120:123], v[172:175], v[164:167], v[120:123]
	v_mfma_f32_16x16x32_bf16 v[116:119], v[180:183], v[156:159], v[116:119]
	v_mfma_f32_16x16x32_bf16 v[112:115], v[180:183], v[164:167], v[112:115]
	v_mfma_f32_16x16x32_bf16 v[108:111], v[188:191], v[156:159], v[108:111]
	v_mfma_f32_16x16x32_bf16 v[104:107], v[188:191], v[164:167], v[104:107]
	v_mfma_f32_16x16x32_bf16 v[100:103], v[196:199], v[156:159], v[100:103]
	v_mfma_f32_16x16x32_bf16 v[96:99], v[196:199], v[164:167], v[96:99]
	s_barrier
	s_addk_i32 s19, 0x180
	s_mov_b32 m0, s25
	ds_read_b128 v[200:203], v134
	ds_read_b128 v[204:207], v135
	ds_read_b128 v[208:211], v136
	ds_read_b128 v[212:215], v137
	buffer_load_dwordx4 v142, s[8:11], s19 offen lds
	s_mov_b32 m0, s26
	s_nop 0
	buffer_load_dwordx4 v143, s[8:11], s19 offen lds
	s_barrier
	s_waitcnt lgkmcnt(0)
	v_mfma_f32_16x16x32_bf16 v[92:95], v[168:171], v[200:203], v[92:95]
	v_mfma_f32_16x16x32_bf16 v[88:91], v[168:171], v[208:211], v[88:91]
	v_mfma_f32_16x16x32_bf16 v[84:87], v[176:179], v[200:203], v[84:87]
	v_mfma_f32_16x16x32_bf16 v[80:83], v[176:179], v[208:211], v[80:83]
	v_mfma_f32_16x16x32_bf16 v[76:79], v[184:187], v[200:203], v[76:79]
	v_mfma_f32_16x16x32_bf16 v[72:75], v[184:187], v[208:211], v[72:75]
	v_mfma_f32_16x16x32_bf16 v[68:71], v[192:195], v[200:203], v[68:71]
	v_mfma_f32_16x16x32_bf16 v[64:67], v[192:195], v[208:211], v[64:67]
	v_mfma_f32_16x16x32_bf16 v[92:95], v[172:175], v[204:207], v[92:95]
	v_mfma_f32_16x16x32_bf16 v[88:91], v[172:175], v[212:215], v[88:91]
	v_mfma_f32_16x16x32_bf16 v[84:87], v[180:183], v[204:207], v[84:87]
	v_mfma_f32_16x16x32_bf16 v[80:83], v[180:183], v[212:215], v[80:83]
	v_mfma_f32_16x16x32_bf16 v[76:79], v[188:191], v[204:207], v[76:79]
	v_mfma_f32_16x16x32_bf16 v[72:75], v[188:191], v[212:215], v[72:75]
	v_mfma_f32_16x16x32_bf16 v[68:71], v[196:199], v[204:207], v[68:71]
	v_mfma_f32_16x16x32_bf16 v[64:67], v[196:199], v[212:215], v[64:67]
	s_barrier
	s_addk_i32 s47, 0x180
	s_mov_b32 m0, s27
	ds_read_b128 v[168:171], v130 offset:49152
	ds_read_b128 v[172:175], v130 offset:50176
	ds_read_b128 v[176:179], v133 offset:49152
	ds_read_b128 v[180:183], v133 offset:50176
	ds_read_b128 v[184:187], v132 offset:49152
	ds_read_b128 v[188:191], v132 offset:50176
	ds_read_b128 v[192:195], v131 offset:49152
	ds_read_b128 v[196:199], v131 offset:50176
	buffer_load_dwordx4 v142, s[4:7], s47 offen lds
	s_mov_b32 m0, s28
	s_nop 0
	buffer_load_dwordx4 v143, s[4:7], s47 offen lds
	s_barrier
	s_waitcnt lgkmcnt(0)
	v_mfma_f32_16x16x32_bf16 v[60:63], v[168:171], v[152:155], v[60:63]
	v_mfma_f32_16x16x32_bf16 v[56:59], v[168:171], v[160:163], v[56:59]
	v_mfma_f32_16x16x32_bf16 v[52:55], v[176:179], v[152:155], v[52:55]
	v_mfma_f32_16x16x32_bf16 v[48:51], v[176:179], v[160:163], v[48:51]
	v_mfma_f32_16x16x32_bf16 v[44:47], v[184:187], v[152:155], v[44:47]
	v_mfma_f32_16x16x32_bf16 v[40:43], v[184:187], v[160:163], v[40:43]
	v_mfma_f32_16x16x32_bf16 v[36:39], v[192:195], v[152:155], v[36:39]
	v_mfma_f32_16x16x32_bf16 v[32:35], v[192:195], v[160:163], v[32:35]
	v_mfma_f32_16x16x32_bf16 v[60:63], v[172:175], v[156:159], v[60:63]
	v_mfma_f32_16x16x32_bf16 v[56:59], v[172:175], v[164:167], v[56:59]
	v_mfma_f32_16x16x32_bf16 v[52:55], v[180:183], v[156:159], v[52:55]
	v_mfma_f32_16x16x32_bf16 v[48:51], v[180:183], v[164:167], v[48:51]
	v_mfma_f32_16x16x32_bf16 v[44:47], v[188:191], v[156:159], v[44:47]
	v_mfma_f32_16x16x32_bf16 v[40:43], v[188:191], v[164:167], v[40:43]
	v_mfma_f32_16x16x32_bf16 v[36:39], v[196:199], v[156:159], v[36:39]
	v_mfma_f32_16x16x32_bf16 v[32:35], v[196:199], v[164:167], v[32:35]
	s_barrier
; #define STAGE(P, RS, SOFF, OFF, kt) do { const int _so = (SOFF) + (kt) * (BK * 2); \
;     _Pragma("unroll") for (int _i = 0; _i < 2; ++_i) { \
;       __builtin_amdgcn_raw_ptr_buffer_load_lds(RS, (__attribute__((address_space(3))) void*)((P) + wave * 1024 + _i * 8192), 16, OFF[_i], _so, 0, 0); } } while (0)
; #define LDA(dst, b, h) _Pragma("unroll") for (int m = 0; m < 4; ++m) _Pragma("unroll") for (int k = 0; k < 2; ++k) \
;     dst[m][k] = *reinterpret_cast<const bf16x8*>(SA(b, h) + lds_byte(wr * 64 + m * 16 + fr, k * 32 + fq * 8))
; #define LDB(dst, b, h) _Pragma("unroll") for (int n = 0; n < 2; ++n) _Pragma("unroll") for (int k = 0; k < 2; ++k) \
;     dst[n][k] = *reinterpret_cast<const bf16x8*>(SB(b, h) + lds_byte(wc * 32 + n * 16 + fr, k * 32 + fq * 8))
; #define WAIT_V(n) asm volatile("s_waitcnt vmcnt(" #n ")" ::: "memory")
; #define WAIT_L(n) asm volatile("s_waitcnt lgkmcnt(" #n ")" ::: "memory")
; #define BAR __builtin_amdgcn_s_barrier()
;     ...
;       STAGE(SB(1, 1), rsB, sB1, offB, t + 3);
;       WAIT_V(6); BAR; MMA(1, 1, At, B1); BAR;
;     }
;     { LDB(B0, 0, 0); LDA(At, 0, 0); STAGE(SA(1, 1), rsA, sA1, offA, nt - 1);
;       BAR; WAIT_L(0); MMA(0, 0, At, B0); BAR;
;       LDB(B1, 0, 1); BAR; WAIT_L(0); MMA(0, 1, At, B1); BAR;
;       LDA(At, 0, 1); WAIT_V(4); BAR; WAIT_L(0); MMA(1, 0, At, B0); MMA(1, 1, At, B1); BAR; }
	s_addk_i32 s48, 0x180
	s_mov_b32 m0, s29
	s_nop 0
	buffer_load_dwordx4 v142, s[8:11], s48 offen lds
	s_mov_b32 m0, s30
	s_nop 0
	buffer_load_dwordx4 v143, s[8:11], s48 offen lds
	s_add_i32 s16, s16, 2
	s_addk_i32 s17, 0x100
	s_cmp_gt_u32 s16, 27
	s_waitcnt vmcnt(6)
	s_barrier
	v_mfma_f32_16x16x32_bf16 v[28:31], v[168:171], v[200:203], v[28:31]
	v_mfma_f32_16x16x32_bf16 v[24:27], v[168:171], v[208:211], v[24:27]
	v_mfma_f32_16x16x32_bf16 v[20:23], v[176:179], v[200:203], v[20:23]
	v_mfma_f32_16x16x32_bf16 v[16:19], v[176:179], v[208:211], v[16:19]
	v_mfma_f32_16x16x32_bf16 v[12:15], v[184:187], v[200:203], v[12:15]
	v_mfma_f32_16x16x32_bf16 v[8:11], v[184:187], v[208:211], v[8:11]
	v_mfma_f32_16x16x32_bf16 v[4:7], v[192:195], v[200:203], v[4:7]
	v_mfma_f32_16x16x32_bf16 v[0:3], v[192:195], v[208:211], v[0:3]
	v_mfma_f32_16x16x32_bf16 v[28:31], v[172:175], v[204:207], v[28:31]
	v_mfma_f32_16x16x32_bf16 v[24:27], v[172:175], v[212:215], v[24:27]
	v_mfma_f32_16x16x32_bf16 v[20:23], v[180:183], v[204:207], v[20:23]
	v_mfma_f32_16x16x32_bf16 v[16:19], v[180:183], v[212:215], v[16:19]
	v_mfma_f32_16x16x32_bf16 v[12:15], v[188:191], v[204:207], v[12:15]
	v_mfma_f32_16x16x32_bf16 v[8:11], v[188:191], v[212:215], v[8:11]
	v_mfma_f32_16x16x32_bf16 v[4:7], v[196:199], v[204:207], v[4:7]
	v_mfma_f32_16x16x32_bf16 v[0:3], v[196:199], v[212:215], v[0:3]
	s_barrier
	s_cbranch_scc0 .LBB0_225
	s_add_i32 s16, s41, 0xf80
	s_mov_b32 m0, s33
	ds_read_b128 v[152:155], v148
	ds_read_b128 v[156:159], v149
	ds_read_b128 v[160:163], v150
	ds_read_b128 v[148:151], v151
	ds_read_b128 v[164:167], v130
	ds_read_b128 v[168:171], v130 offset:1024
	ds_read_b128 v[172:175], v133
	ds_read_b128 v[176:179], v133 offset:1024
	ds_read_b128 v[180:183], v132
	ds_read_b128 v[184:187], v132 offset:1024
	ds_read_b128 v[188:191], v131
	ds_read_b128 v[192:195], v131 offset:1024
	buffer_load_dwordx4 v142, s[4:7], s16 offen lds
	s_mov_b32 m0, s34
	s_nop 0
	buffer_load_dwordx4 v143, s[4:7], s16 offen lds
	s_barrier
	s_waitcnt lgkmcnt(0)
	v_mfma_f32_16x16x32_bf16 v[124:127], v[164:167], v[152:155], v[124:127]
	v_mfma_f32_16x16x32_bf16 v[120:123], v[164:167], v[160:163], v[120:123]
	v_mfma_f32_16x16x32_bf16 v[116:119], v[172:175], v[152:155], v[116:119]
	v_mfma_f32_16x16x32_bf16 v[112:115], v[172:175], v[160:163], v[112:115]
	v_mfma_f32_16x16x32_bf16 v[108:111], v[180:183], v[152:155], v[108:111]
	v_mfma_f32_16x16x32_bf16 v[104:107], v[180:183], v[160:163], v[104:107]
	v_mfma_f32_16x16x32_bf16 v[100:103], v[188:191], v[152:155], v[100:103]
	v_mfma_f32_16x16x32_bf16 v[96:99], v[188:191], v[160:163], v[96:99]
	v_mfma_f32_16x16x32_bf16 v[124:127], v[168:171], v[156:159], v[124:127]
	v_mfma_f32_16x16x32_bf16 v[120:123], v[168:171], v[148:151], v[120:123]
	v_mfma_f32_16x16x32_bf16 v[116:119], v[176:179], v[156:159], v[116:119]
	v_mfma_f32_16x16x32_bf16 v[112:115], v[176:179], v[148:151], v[112:115]
	v_mfma_f32_16x16x32_bf16 v[108:111], v[184:187], v[156:159], v[108:111]
	v_mfma_f32_16x16x32_bf16 v[104:107], v[184:187], v[148:151], v[104:107]
	v_mfma_f32_16x16x32_bf16 v[100:103], v[192:195], v[156:159], v[100:103]
	v_mfma_f32_16x16x32_bf16 v[96:99], v[192:195], v[148:151], v[96:99]
	s_barrier
	ds_read_b128 v[196:199], v144
	ds_read_b128 v[142:145], v145
	ds_read_b128 v[200:203], v146
	ds_read_b128 v[204:207], v147
	s_barrier
	s_waitcnt lgkmcnt(0)
	v_mfma_f32_16x16x32_bf16 v[88:91], v[164:167], v[200:203], v[88:91]
	v_mfma_f32_16x16x32_bf16 v[84:87], v[172:175], v[196:199], v[84:87]
	v_mfma_f32_16x16x32_bf16 v[80:83], v[172:175], v[200:203], v[80:83]
	v_mfma_f32_16x16x32_bf16 v[76:79], v[180:183], v[196:199], v[76:79]
	v_mfma_f32_16x16x32_bf16 v[72:75], v[180:183], v[200:203], v[72:75]
	v_mfma_f32_16x16x32_bf16 v[68:71], v[188:191], v[196:199], v[68:71]
	v_mfma_f32_16x16x32_bf16 v[64:67], v[188:191], v[200:203], v[64:67]
	v_mfma_f32_16x16x32_bf16 v[92:95], v[164:167], v[196:199], v[92:95]
	v_mfma_f32_16x16x32_bf16 v[88:91], v[168:171], v[204:207], v[88:91]
	v_mfma_f32_16x16x32_bf16 v[84:87], v[176:179], v[142:145], v[84:87]
	v_mfma_f32_16x16x32_bf16 v[80:83], v[176:179], v[204:207], v[80:83]
	v_mfma_f32_16x16x32_bf16 v[76:79], v[184:187], v[142:145], v[76:79]
	v_mfma_f32_16x16x32_bf16 v[72:75], v[184:187], v[204:207], v[72:75]
	v_mfma_f32_16x16x32_bf16 v[68:71], v[192:195], v[142:145], v[68:71]
	v_mfma_f32_16x16x32_bf16 v[64:67], v[192:195], v[204:207], v[64:67]
	v_mfma_f32_16x16x32_bf16 v[164:167], v[168:171], v[142:145], v[92:95]
	s_barrier
	s_nop 0
	ds_read_b128 v[92:95], v130 offset:16384
	ds_read_b128 v[168:171], v130 offset:17408
	ds_read_b128 v[172:175], v133 offset:16384
	ds_read_b128 v[176:179], v133 offset:17408
	ds_read_b128 v[180:183], v132 offset:16384
	ds_read_b128 v[184:187], v132 offset:17408
	ds_read_b128 v[188:191], v131 offset:16384
	ds_read_b128 v[192:195], v131 offset:17408
	s_waitcnt vmcnt(4)
	s_barrier
; #define LDA(dst, b, h) _Pragma("unroll") for (int m = 0; m < 4; ++m) _Pragma("unroll") for (int k = 0; k < 2; ++k) \
;     dst[m][k] = *reinterpret_cast<const bf16x8*>(SA(b, h) + lds_byte(wr * 64 + m * 16 + fr, k * 32 + fq * 8))
; #define LDB(dst, b, h) _Pragma("unroll") for (int n = 0; n < 2; ++n) _Pragma("unroll") for (int k = 0; k < 2; ++k) \
;     dst[n][k] = *reinterpret_cast<const bf16x8*>(SB(b, h) + lds_byte(wc * 32 + n * 16 + fr, k * 32 + fq * 8))
; #define WAIT_V(n) asm volatile("s_waitcnt vmcnt(" #n ")" ::: "memory")
; #define WAIT_L(n) asm volatile("s_waitcnt lgkmcnt(" #n ")" ::: "memory")
; #define BAR __builtin_amdgcn_s_barrier()
;     ...
;       LDA(At, 0, 1); WAIT_V(4); BAR; WAIT_L(0); MMA(1, 0, At, B0); MMA(1, 1, At, B1); BAR; }
;     { LDB(B0, 1, 0); LDA(At, 1, 0); WAIT_V(2); BAR; WAIT_L(0); MMA(0, 0, At, B0); BAR;
	s_waitcnt lgkmcnt(0)
	v_mfma_f32_16x16x32_bf16 v[60:63], v[92:95], v[152:155], v[60:63]
	v_mfma_f32_16x16x32_bf16 v[56:59], v[92:95], v[160:163], v[56:59]
	v_mfma_f32_16x16x32_bf16 v[52:55], v[172:175], v[152:155], v[52:55]
	v_mfma_f32_16x16x32_bf16 v[48:51], v[172:175], v[160:163], v[48:51]
	v_mfma_f32_16x16x32_bf16 v[44:47], v[180:183], v[152:155], v[44:47]
	v_mfma_f32_16x16x32_bf16 v[40:43], v[180:183], v[160:163], v[40:43]
	v_mfma_f32_16x16x32_bf16 v[36:39], v[188:191], v[152:155], v[36:39]
	v_mfma_f32_16x16x32_bf16 v[32:35], v[188:191], v[160:163], v[32:35]
	v_mfma_f32_16x16x32_bf16 v[60:63], v[168:171], v[156:159], v[60:63]
	v_mfma_f32_16x16x32_bf16 v[56:59], v[168:171], v[148:151], v[56:59]
	v_mfma_f32_16x16x32_bf16 v[52:55], v[176:179], v[156:159], v[52:55]
	v_mfma_f32_16x16x32_bf16 v[48:51], v[176:179], v[148:151], v[48:51]
	v_mfma_f32_16x16x32_bf16 v[44:47], v[184:187], v[156:159], v[44:47]
	v_mfma_f32_16x16x32_bf16 v[40:43], v[184:187], v[148:151], v[40:43]
	v_mfma_f32_16x16x32_bf16 v[36:39], v[192:195], v[156:159], v[36:39]
	v_mfma_f32_16x16x32_bf16 v[32:35], v[192:195], v[148:151], v[32:35]
	v_mfma_f32_16x16x32_bf16 v[28:31], v[92:95], v[196:199], v[28:31]
	v_mfma_f32_16x16x32_bf16 v[24:27], v[92:95], v[200:203], v[24:27]
	v_mfma_f32_16x16x32_bf16 v[20:23], v[172:175], v[196:199], v[20:23]
	v_mfma_f32_16x16x32_bf16 v[16:19], v[172:175], v[200:203], v[16:19]
	v_mfma_f32_16x16x32_bf16 v[12:15], v[180:183], v[196:199], v[12:15]
	v_mfma_f32_16x16x32_bf16 v[8:11], v[180:183], v[200:203], v[8:11]
	v_mfma_f32_16x16x32_bf16 v[4:7], v[188:191], v[196:199], v[4:7]
	v_mfma_f32_16x16x32_bf16 v[0:3], v[188:191], v[200:203], v[0:3]
	v_mfma_f32_16x16x32_bf16 v[28:31], v[168:171], v[142:145], v[28:31]
	v_mfma_f32_16x16x32_bf16 v[24:27], v[168:171], v[204:207], v[24:27]
	v_mfma_f32_16x16x32_bf16 v[20:23], v[176:179], v[142:145], v[20:23]
	v_mfma_f32_16x16x32_bf16 v[16:19], v[176:179], v[204:207], v[16:19]
	v_mfma_f32_16x16x32_bf16 v[12:15], v[184:187], v[142:145], v[12:15]
	v_mfma_f32_16x16x32_bf16 v[8:11], v[184:187], v[204:207], v[8:11]
	v_mfma_f32_16x16x32_bf16 v[4:7], v[192:195], v[142:145], v[4:7]
	v_mfma_f32_16x16x32_bf16 v[0:3], v[192:195], v[204:207], v[0:3]
	s_barrier
	ds_read_b128 v[142:145], v138
	ds_read_b128 v[146:149], v139
	ds_read_b128 v[150:153], v140
	ds_read_b128 v[138:141], v141
	ds_read_b128 v[154:157], v130 offset:32768
	ds_read_b128 v[158:161], v130 offset:33792
	ds_read_b128 v[168:171], v133 offset:32768
	ds_read_b128 v[172:175], v133 offset:33792
	ds_read_b128 v[176:179], v132 offset:32768
	ds_read_b128 v[180:183], v132 offset:33792
	ds_read_b128 v[184:187], v131 offset:32768
	ds_read_b128 v[188:191], v131 offset:33792
	s_waitcnt vmcnt(2)
	s_barrier
	s_waitcnt lgkmcnt(0)
	v_mfma_f32_16x16x32_bf16 v[92:95], v[154:157], v[142:145], v[124:127]
	v_mfma_f32_16x16x32_bf16 v[120:123], v[154:157], v[150:153], v[120:123]
	v_mfma_f32_16x16x32_bf16 v[116:119], v[168:171], v[142:145], v[116:119]
	v_mfma_f32_16x16x32_bf16 v[112:115], v[168:171], v[150:153], v[112:115]
	v_mfma_f32_16x16x32_bf16 v[108:111], v[176:179], v[142:145], v[108:111]
	v_mfma_f32_16x16x32_bf16 v[104:107], v[176:179], v[150:153], v[104:107]
	v_mfma_f32_16x16x32_bf16 v[100:103], v[184:187], v[142:145], v[100:103]
	v_mfma_f32_16x16x32_bf16 v[96:99], v[184:187], v[150:153], v[96:99]
	v_mfma_f32_16x16x32_bf16 v[124:127], v[158:161], v[146:149], v[92:95]
	v_mfma_f32_16x16x32_bf16 v[120:123], v[158:161], v[138:141], v[120:123]
	v_mfma_f32_16x16x32_bf16 v[116:119], v[172:175], v[146:149], v[116:119]
	v_mfma_f32_16x16x32_bf16 v[112:115], v[172:175], v[138:141], v[112:115]
	v_mfma_f32_16x16x32_bf16 v[108:111], v[180:183], v[146:149], v[108:111]
	v_mfma_f32_16x16x32_bf16 v[104:107], v[180:183], v[138:141], v[104:107]
	v_mfma_f32_16x16x32_bf16 v[100:103], v[188:191], v[146:149], v[100:103]
	v_mfma_f32_16x16x32_bf16 v[92:95], v[188:191], v[138:141], v[96:99]
	s_barrier
; #define LDA(dst, b, h) _Pragma("unroll") for (int m = 0; m < 4; ++m) _Pragma("unroll") for (int k = 0; k < 2; ++k) \
;     dst[m][k] = *reinterpret_cast<const bf16x8*>(SA(b, h) + lds_byte(wr * 64 + m * 16 + fr, k * 32 + fq * 8))
; #define LDB(dst, b, h) _Pragma("unroll") for (int n = 0; n < 2; ++n) _Pragma("unroll") for (int k = 0; k < 2; ++k) \
;     dst[n][k] = *reinterpret_cast<const bf16x8*>(SB(b, h) + lds_byte(wc * 32 + n * 16 + fr, k * 32 + fq * 8))
; #define WAIT_V(n) asm volatile("s_waitcnt vmcnt(" #n ")" ::: "memory")
; #define WAIT_L(n) asm volatile("s_waitcnt lgkmcnt(" #n ")" ::: "memory")
; #define BAR __builtin_amdgcn_s_barrier()
;     ...
;       LDB(B1, 1, 1); WAIT_V(0); BAR; WAIT_L(0); MMA(0, 1, At, B1); BAR;
;       LDA(At, 1, 1); BAR; WAIT_L(0); MMA(1, 0, At, B0); MMA(1, 1, At, B1); BAR; }
;     if (wr == 0) BAR;
	ds_read_b128 v[192:195], v134
	ds_read_b128 v[196:199], v135
	ds_read_b128 v[200:203], v136
	ds_read_b128 v[134:137], v137
	s_waitcnt vmcnt(0)
	s_barrier
	s_waitcnt lgkmcnt(0)
	v_mfma_f32_16x16x32_bf16 v[96:99], v[154:157], v[192:195], v[164:167]
	v_mfma_f32_16x16x32_bf16 v[88:91], v[154:157], v[200:203], v[88:91]
	v_mfma_f32_16x16x32_bf16 v[84:87], v[168:171], v[192:195], v[84:87]
	v_mfma_f32_16x16x32_bf16 v[80:83], v[168:171], v[200:203], v[80:83]
	v_mfma_f32_16x16x32_bf16 v[76:79], v[176:179], v[192:195], v[76:79]
	v_mfma_f32_16x16x32_bf16 v[72:75], v[176:179], v[200:203], v[72:75]
	v_mfma_f32_16x16x32_bf16 v[68:71], v[184:187], v[192:195], v[68:71]
	v_mfma_f32_16x16x32_bf16 v[64:67], v[184:187], v[200:203], v[64:67]
	v_mfma_f32_16x16x32_bf16 v[96:99], v[158:161], v[196:199], v[96:99]
	v_mfma_f32_16x16x32_bf16 v[88:91], v[158:161], v[134:137], v[88:91]
	v_mfma_f32_16x16x32_bf16 v[84:87], v[172:175], v[196:199], v[84:87]
	v_mfma_f32_16x16x32_bf16 v[80:83], v[172:175], v[134:137], v[80:83]
	v_mfma_f32_16x16x32_bf16 v[76:79], v[180:183], v[196:199], v[76:79]
	v_mfma_f32_16x16x32_bf16 v[72:75], v[180:183], v[134:137], v[72:75]
	v_mfma_f32_16x16x32_bf16 v[68:71], v[188:191], v[196:199], v[68:71]
	v_mfma_f32_16x16x32_bf16 v[64:67], v[188:191], v[134:137], v[64:67]
	s_barrier
	ds_read_b128 v[154:157], v130 offset:49152
	ds_read_b128 v[158:161], v130 offset:50176
	ds_read_b128 v[162:165], v133 offset:49152
	ds_read_b128 v[166:169], v133 offset:50176
	ds_read_b128 v[170:173], v132 offset:49152
	ds_read_b128 v[174:177], v132 offset:50176
	ds_read_b128 v[178:181], v131 offset:49152
	ds_read_b128 v[130:133], v131 offset:50176
	s_barrier
	s_waitcnt lgkmcnt(0)
	v_mfma_f32_16x16x32_bf16 v[60:63], v[154:157], v[142:145], v[60:63]
	v_mfma_f32_16x16x32_bf16 v[56:59], v[154:157], v[150:153], v[56:59]
	v_mfma_f32_16x16x32_bf16 v[52:55], v[162:165], v[142:145], v[52:55]
	v_mfma_f32_16x16x32_bf16 v[48:51], v[162:165], v[150:153], v[48:51]
	v_mfma_f32_16x16x32_bf16 v[44:47], v[170:173], v[142:145], v[44:47]
	v_mfma_f32_16x16x32_bf16 v[40:43], v[170:173], v[150:153], v[40:43]
	v_mfma_f32_16x16x32_bf16 v[36:39], v[178:181], v[142:145], v[36:39]
	v_mfma_f32_16x16x32_bf16 v[32:35], v[178:181], v[150:153], v[32:35]
	v_mfma_f32_16x16x32_bf16 v[60:63], v[158:161], v[146:149], v[60:63]
	v_mfma_f32_16x16x32_bf16 v[56:59], v[158:161], v[138:141], v[56:59]
	v_mfma_f32_16x16x32_bf16 v[52:55], v[166:169], v[146:149], v[52:55]
	v_mfma_f32_16x16x32_bf16 v[48:51], v[166:169], v[138:141], v[48:51]
	v_mfma_f32_16x16x32_bf16 v[44:47], v[174:177], v[146:149], v[44:47]
	v_mfma_f32_16x16x32_bf16 v[40:43], v[174:177], v[138:141], v[40:43]
	v_mfma_f32_16x16x32_bf16 v[36:39], v[130:133], v[146:149], v[36:39]
	v_mfma_f32_16x16x32_bf16 v[32:35], v[130:133], v[138:141], v[32:35]
	v_mfma_f32_16x16x32_bf16 v[28:31], v[154:157], v[192:195], v[28:31]
	v_mfma_f32_16x16x32_bf16 v[24:27], v[154:157], v[200:203], v[24:27]
	v_mfma_f32_16x16x32_bf16 v[20:23], v[162:165], v[192:195], v[20:23]
	v_mfma_f32_16x16x32_bf16 v[16:19], v[162:165], v[200:203], v[16:19]
	v_mfma_f32_16x16x32_bf16 v[12:15], v[170:173], v[192:195], v[12:15]
	v_mfma_f32_16x16x32_bf16 v[8:11], v[170:173], v[200:203], v[8:11]
	v_mfma_f32_16x16x32_bf16 v[4:7], v[178:181], v[192:195], v[4:7]
	v_mfma_f32_16x16x32_bf16 v[0:3], v[178:181], v[200:203], v[0:3]
	v_mfma_f32_16x16x32_bf16 v[28:31], v[158:161], v[196:199], v[28:31]
	v_mfma_f32_16x16x32_bf16 v[24:27], v[158:161], v[134:137], v[24:27]
	v_mfma_f32_16x16x32_bf16 v[20:23], v[166:169], v[196:199], v[20:23]
	v_mfma_f32_16x16x32_bf16 v[16:19], v[166:169], v[134:137], v[16:19]
	v_mfma_f32_16x16x32_bf16 v[12:15], v[174:177], v[196:199], v[12:15]
	v_mfma_f32_16x16x32_bf16 v[8:11], v[174:177], v[134:137], v[8:11]
	v_mfma_f32_16x16x32_bf16 v[4:7], v[130:133], v[196:199], v[4:7]
	v_mfma_f32_16x16x32_bf16 v[0:3], v[130:133], v[134:137], v[0:3]
	v_cmp_gt_u32_e32 vcc, s37, v129
	s_barrier
	s_and_saveexec_b64 s[16:17], vcc
	s_cbranch_execz .LBB0_228
	s_barrier

; #define STAGE(P, RS, SOFF, OFF, kt) do { const int _so = (SOFF) + (kt) * (BK * 2); \
;     _Pragma("unroll") for (int _i = 0; _i < 2; ++_i) { \
;       __builtin_amdgcn_raw_ptr_buffer_load_lds(RS, (__attribute__((address_space(3))) void*)((P) + wave * 1024 + _i * 8192), 16, OFF[_i], _so, 0, 0); } } while (0)
; #define LDA(dst, b, h) _Pragma("unroll") for (int m = 0; m < 4; ++m) _Pragma("unroll") for (int k = 0; k < 2; ++k) \
;     dst[m][k] = *reinterpret_cast<const bf16x8*>(SA(b, h) + lds_byte(wr * 64 + m * 16 + fr, k * 32 + fq * 8))
; #define LDB(dst, b, h) _Pragma("unroll") for (int n = 0; n < 2; ++n) _Pragma("unroll") for (int k = 0; k < 2; ++k) \
;     dst[n][k] = *reinterpret_cast<const bf16x8*>(SB(b, h) + lds_byte(wc * 32 + n * 16 + fr, k * 32 + fq * 8))
; #define WAIT_V(n) asm volatile("s_waitcnt vmcnt(" #n ")" ::: "memory")
; #define WAIT_L(n) asm volatile("s_waitcnt lgkmcnt(" #n ")" ::: "memory")
; #define BAR __builtin_amdgcn_s_barrier()
; #define SCHED __builtin_amdgcn_sched_barrier(0)
;     ...
;       LDB(B0, 0, 0); SCHED; LDA(At, 0, 0); STAGE(SA(1, 1), rsA, sA1, offA, t + 1);
;       WAIT_L(8); BAR; WAIT_L(0); MMA(0, 0, At, B0); BAR; SCHED;
;       LDB(B1, 0, 1); STAGE(SB(0, 0), rsB, sB0, offB, t + 2);
;       BAR; WAIT_L(0); MMA(0, 1, At, B1); BAR;
;       LDA(At, 0, 1); STAGE(SA(0, 0), rsA, sA0, offA, t + 2);
;       BAR; WAIT_L(0); MMA(1, 0, At, B0); BAR; SCHED;
;       STAGE(SB(0, 1), rsB, sB1, offB, t + 2);
;       WAIT_V(6); BAR; MMA(1, 1, At, B1); BAR;
.LBB0_291:
	ds_read_b128 v[152:155], v147
	ds_read_b128 v[156:159], v148
	ds_read_b128 v[160:163], v149
	ds_read_b128 v[164:167], v150
	s_add_i32 s5, s94, s3
	s_add_i32 s6, s5, 0x80
	s_mov_b32 m0, s36
	ds_read_b128 v[168:171], v129
	ds_read_b128 v[172:175], v129 offset:1024
	ds_read_b128 v[176:179], v132
	ds_read_b128 v[180:183], v132 offset:1024
	ds_read_b128 v[184:187], v131
	ds_read_b128 v[188:191], v131 offset:1024
	ds_read_b128 v[192:195], v130
	ds_read_b128 v[196:199], v130 offset:1024
	buffer_load_dwordx4 v141, s[8:11], s6 offen lds
	s_mov_b32 m0, s61
	s_nop 0
	buffer_load_dwordx4 v142, s[8:11], s6 offen lds
	s_waitcnt lgkmcnt(8)
	s_barrier
	s_waitcnt lgkmcnt(0)
	v_mfma_f32_16x16x32_bf16 v[124:127], v[152:155], v[168:171], v[124:127]
	v_mfma_f32_16x16x32_bf16 v[120:123], v[160:163], v[168:171], v[120:123]
	v_mfma_f32_16x16x32_bf16 v[116:119], v[152:155], v[176:179], v[116:119]
	v_mfma_f32_16x16x32_bf16 v[112:115], v[160:163], v[176:179], v[112:115]
	v_mfma_f32_16x16x32_bf16 v[108:111], v[152:155], v[184:187], v[108:111]
	v_mfma_f32_16x16x32_bf16 v[104:107], v[160:163], v[184:187], v[104:107]
	v_mfma_f32_16x16x32_bf16 v[100:103], v[152:155], v[192:195], v[100:103]
	v_mfma_f32_16x16x32_bf16 v[96:99], v[160:163], v[192:195], v[96:99]
	v_mfma_f32_16x16x32_bf16 v[124:127], v[156:159], v[172:175], v[124:127]
	v_mfma_f32_16x16x32_bf16 v[120:123], v[164:167], v[172:175], v[120:123]
	v_mfma_f32_16x16x32_bf16 v[116:119], v[156:159], v[180:183], v[116:119]
	v_mfma_f32_16x16x32_bf16 v[112:115], v[164:167], v[180:183], v[112:115]
	v_mfma_f32_16x16x32_bf16 v[108:111], v[156:159], v[188:191], v[108:111]
	v_mfma_f32_16x16x32_bf16 v[104:107], v[164:167], v[188:191], v[104:107]
	v_mfma_f32_16x16x32_bf16 v[100:103], v[156:159], v[196:199], v[100:103]
	v_mfma_f32_16x16x32_bf16 v[96:99], v[164:167], v[196:199], v[96:99]
	s_barrier
	s_add_i32 s6, s96, s3
	s_add_i32 s7, s6, 0x100
	s_mov_b32 s14, s10
	s_mov_b32 s15, s11
	s_mov_b32 m0, s37
	ds_read_b128 v[200:203], v143
	ds_read_b128 v[204:207], v144
	ds_read_b128 v[208:211], v145
	ds_read_b128 v[212:215], v146
	buffer_load_dwordx4 v141, s[12:15], s7 offen lds
	s_mov_b32 m0, s48
	s_nop 0
	buffer_load_dwordx4 v142, s[12:15], s7 offen lds
	s_barrier
	s_waitcnt lgkmcnt(0)
	v_mfma_f32_16x16x32_bf16 v[92:95], v[200:203], v[168:171], v[92:95]
	v_mfma_f32_16x16x32_bf16 v[88:91], v[208:211], v[168:171], v[88:91]
	v_mfma_f32_16x16x32_bf16 v[80:83], v[200:203], v[176:179], v[80:83]
	v_mfma_f32_16x16x32_bf16 v[68:71], v[208:211], v[176:179], v[68:71]
	v_mfma_f32_16x16x32_bf16 v[60:63], v[200:203], v[184:187], v[60:63]
	v_mfma_f32_16x16x32_bf16 v[56:59], v[208:211], v[184:187], v[56:59]
	v_mfma_f32_16x16x32_bf16 v[52:55], v[200:203], v[192:195], v[52:55]
	v_mfma_f32_16x16x32_bf16 v[48:51], v[208:211], v[192:195], v[48:51]
	v_mfma_f32_16x16x32_bf16 v[92:95], v[204:207], v[172:175], v[92:95]
	v_mfma_f32_16x16x32_bf16 v[88:91], v[212:215], v[172:175], v[88:91]
	v_mfma_f32_16x16x32_bf16 v[80:83], v[204:207], v[180:183], v[80:83]
	v_mfma_f32_16x16x32_bf16 v[68:71], v[212:215], v[180:183], v[68:71]
	v_mfma_f32_16x16x32_bf16 v[60:63], v[204:207], v[188:191], v[60:63]
	v_mfma_f32_16x16x32_bf16 v[56:59], v[212:215], v[188:191], v[56:59]
	v_mfma_f32_16x16x32_bf16 v[52:55], v[204:207], v[196:199], v[52:55]
	v_mfma_f32_16x16x32_bf16 v[48:51], v[212:215], v[196:199], v[48:51]
	s_barrier
	s_add_i32 s7, s95, s3
	s_add_i32 s22, s7, 0x100
	s_mov_b32 m0, s35
	ds_read_b128 v[168:171], v129 offset:16384
	ds_read_b128 v[172:175], v129 offset:17408
	ds_read_b128 v[176:179], v132 offset:16384
	ds_read_b128 v[180:183], v132 offset:17408
	ds_read_b128 v[184:187], v131 offset:16384
	ds_read_b128 v[188:191], v131 offset:17408
	ds_read_b128 v[192:195], v130 offset:16384
	ds_read_b128 v[196:199], v130 offset:17408
	buffer_load_dwordx4 v141, s[8:11], s22 offen lds
	s_mov_b32 m0, s49
	s_nop 0
	buffer_load_dwordx4 v142, s[8:11], s22 offen lds
	s_barrier
	s_waitcnt lgkmcnt(0)
	v_mfma_f32_16x16x32_bf16 v[44:47], v[152:155], v[168:171], v[44:47]
	v_mfma_f32_16x16x32_bf16 v[40:43], v[160:163], v[168:171], v[40:43]
	v_mfma_f32_16x16x32_bf16 v[36:39], v[152:155], v[176:179], v[36:39]
	v_mfma_f32_16x16x32_bf16 v[32:35], v[160:163], v[176:179], v[32:35]
	v_mfma_f32_16x16x32_bf16 v[28:31], v[152:155], v[184:187], v[28:31]
	v_mfma_f32_16x16x32_bf16 v[24:27], v[160:163], v[184:187], v[24:27]
	v_mfma_f32_16x16x32_bf16 v[20:23], v[152:155], v[192:195], v[20:23]
	v_mfma_f32_16x16x32_bf16 v[16:19], v[160:163], v[192:195], v[16:19]
	v_mfma_f32_16x16x32_bf16 v[44:47], v[156:159], v[172:175], v[44:47]
	v_mfma_f32_16x16x32_bf16 v[40:43], v[164:167], v[172:175], v[40:43]
	v_mfma_f32_16x16x32_bf16 v[36:39], v[156:159], v[180:183], v[36:39]
	v_mfma_f32_16x16x32_bf16 v[32:35], v[164:167], v[180:183], v[32:35]
	v_mfma_f32_16x16x32_bf16 v[28:31], v[156:159], v[188:191], v[28:31]
	v_mfma_f32_16x16x32_bf16 v[24:27], v[164:167], v[188:191], v[24:27]
	v_mfma_f32_16x16x32_bf16 v[20:23], v[156:159], v[196:199], v[20:23]
	v_mfma_f32_16x16x32_bf16 v[16:19], v[164:167], v[196:199], v[16:19]
	s_barrier
	s_add_i32 s22, s97, s3
	s_add_i32 s23, s22, 0x100
	s_mov_b32 m0, s38
	s_nop 0
	buffer_load_dwordx4 v141, s[12:15], s23 offen lds
	s_mov_b32 m0, s54
	s_nop 0
	buffer_load_dwordx4 v142, s[12:15], s23 offen lds
	s_waitcnt vmcnt(6)
	s_barrier
; #define STAGE(P, RS, SOFF, OFF, kt) do { const int _so = (SOFF) + (kt) * (BK * 2); \
;     _Pragma("unroll") for (int _i = 0; _i < 2; ++_i) { \
;       __builtin_amdgcn_raw_ptr_buffer_load_lds(RS, (__attribute__((address_space(3))) void*)((P) + wave * 1024 + _i * 8192), 16, OFF[_i], _so, 0, 0); } } while (0)
; #define LDA(dst, b, h) _Pragma("unroll") for (int m = 0; m < 4; ++m) _Pragma("unroll") for (int k = 0; k < 2; ++k) \
;     dst[m][k] = *reinterpret_cast<const bf16x8*>(SA(b, h) + lds_byte(wr * 64 + m * 16 + fr, k * 32 + fq * 8))
; #define LDB(dst, b, h) _Pragma("unroll") for (int n = 0; n < 2; ++n) _Pragma("unroll") for (int k = 0; k < 2; ++k) \
;     dst[n][k] = *reinterpret_cast<const bf16x8*>(SB(b, h) + lds_byte(wc * 32 + n * 16 + fr, k * 32 + fq * 8))
; #define WAIT_V(n) asm volatile("s_waitcnt vmcnt(" #n ")" ::: "memory")
; #define WAIT_L(n) asm volatile("s_waitcnt lgkmcnt(" #n ")" ::: "memory")
; #define BAR __builtin_amdgcn_s_barrier()
; #define SCHED __builtin_amdgcn_sched_barrier(0)
;     ...
;       WAIT_V(6); BAR; MMA(1, 1, At, B1); BAR;
;       LDB(B0, 1, 0); SCHED; LDA(At, 1, 0); STAGE(SA(0, 1), rsA, sA1, offA, t + 2);
;       WAIT_L(8); BAR; WAIT_L(0); MMA(0, 0, At, B0); BAR; SCHED;
;       LDB(B1, 1, 1); STAGE(SB(1, 0), rsB, sB0, offB, t + 3);
;       BAR; WAIT_L(0); MMA(0, 1, At, B1); BAR;
;       LDA(At, 1, 1); STAGE(SA(1, 0), rsA, sA0, offA, t + 3);
;       BAR; WAIT_L(0); MMA(1, 0, At, B0); BAR; SCHED;
	v_mfma_f32_16x16x32_bf16 v[12:15], v[200:203], v[168:171], v[12:15]
	v_mfma_f32_16x16x32_bf16 v[8:11], v[208:211], v[168:171], v[8:11]
	v_mfma_f32_16x16x32_bf16 v[4:7], v[200:203], v[176:179], v[4:7]
	v_mfma_f32_16x16x32_bf16 v[0:3], v[208:211], v[176:179], v[0:3]
	v_mfma_f32_16x16x32_bf16 v[64:67], v[200:203], v[184:187], v[64:67]
	v_mfma_f32_16x16x32_bf16 v[72:75], v[208:211], v[184:187], v[72:75]
	v_mfma_f32_16x16x32_bf16 v[76:79], v[200:203], v[192:195], v[76:79]
	v_mfma_f32_16x16x32_bf16 v[84:87], v[208:211], v[192:195], v[84:87]
	v_mfma_f32_16x16x32_bf16 v[12:15], v[204:207], v[172:175], v[12:15]
	v_mfma_f32_16x16x32_bf16 v[8:11], v[212:215], v[172:175], v[8:11]
	v_mfma_f32_16x16x32_bf16 v[4:7], v[204:207], v[180:183], v[4:7]
	v_mfma_f32_16x16x32_bf16 v[0:3], v[212:215], v[180:183], v[0:3]
	v_mfma_f32_16x16x32_bf16 v[64:67], v[204:207], v[188:191], v[64:67]
	v_mfma_f32_16x16x32_bf16 v[72:75], v[212:215], v[188:191], v[72:75]
	v_mfma_f32_16x16x32_bf16 v[76:79], v[204:207], v[196:199], v[76:79]
	v_mfma_f32_16x16x32_bf16 v[84:87], v[212:215], v[196:199], v[84:87]
	s_barrier
	ds_read_b128 v[152:155], v137
	ds_read_b128 v[156:159], v138
	ds_read_b128 v[160:163], v139
	ds_read_b128 v[164:167], v140
	s_addk_i32 s5, 0x100
	s_mov_b32 m0, s39
	ds_read_b128 v[168:171], v129 offset:32768
	ds_read_b128 v[172:175], v129 offset:33792
	ds_read_b128 v[176:179], v132 offset:32768
	ds_read_b128 v[180:183], v132 offset:33792
	ds_read_b128 v[184:187], v131 offset:32768
	ds_read_b128 v[188:191], v131 offset:33792
	ds_read_b128 v[192:195], v130 offset:32768
	ds_read_b128 v[196:199], v130 offset:33792
	buffer_load_dwordx4 v141, s[8:11], s5 offen lds
	s_mov_b32 m0, s55
	s_nop 0
	buffer_load_dwordx4 v142, s[8:11], s5 offen lds
	s_waitcnt lgkmcnt(8)
	s_barrier
	s_waitcnt lgkmcnt(0)
	v_mfma_f32_16x16x32_bf16 v[124:127], v[152:155], v[168:171], v[124:127]
	v_mfma_f32_16x16x32_bf16 v[120:123], v[160:163], v[168:171], v[120:123]
	v_mfma_f32_16x16x32_bf16 v[116:119], v[152:155], v[176:179], v[116:119]
	v_mfma_f32_16x16x32_bf16 v[112:115], v[160:163], v[176:179], v[112:115]
	v_mfma_f32_16x16x32_bf16 v[108:111], v[152:155], v[184:187], v[108:111]
	v_mfma_f32_16x16x32_bf16 v[104:107], v[160:163], v[184:187], v[104:107]
	v_mfma_f32_16x16x32_bf16 v[100:103], v[152:155], v[192:195], v[100:103]
	v_mfma_f32_16x16x32_bf16 v[96:99], v[160:163], v[192:195], v[96:99]
	v_mfma_f32_16x16x32_bf16 v[124:127], v[156:159], v[172:175], v[124:127]
	v_mfma_f32_16x16x32_bf16 v[120:123], v[164:167], v[172:175], v[120:123]
	v_mfma_f32_16x16x32_bf16 v[116:119], v[156:159], v[180:183], v[116:119]
	v_mfma_f32_16x16x32_bf16 v[112:115], v[164:167], v[180:183], v[112:115]
	v_mfma_f32_16x16x32_bf16 v[108:111], v[156:159], v[188:191], v[108:111]
	v_mfma_f32_16x16x32_bf16 v[104:107], v[164:167], v[188:191], v[104:107]
	v_mfma_f32_16x16x32_bf16 v[100:103], v[156:159], v[196:199], v[100:103]
	v_mfma_f32_16x16x32_bf16 v[96:99], v[164:167], v[196:199], v[96:99]
	s_barrier
	s_addk_i32 s6, 0x180
	s_mov_b32 m0, s42
	ds_read_b128 v[200:203], v133
	ds_read_b128 v[204:207], v134
	ds_read_b128 v[208:211], v135
	ds_read_b128 v[212:215], v136
	buffer_load_dwordx4 v141, s[12:15], s6 offen lds
	s_mov_b32 m0, s58
	s_nop 0
	buffer_load_dwordx4 v142, s[12:15], s6 offen lds
	s_barrier
	s_waitcnt lgkmcnt(0)
	v_mfma_f32_16x16x32_bf16 v[92:95], v[200:203], v[168:171], v[92:95]
	v_mfma_f32_16x16x32_bf16 v[88:91], v[208:211], v[168:171], v[88:91]
	v_mfma_f32_16x16x32_bf16 v[80:83], v[200:203], v[176:179], v[80:83]
	v_mfma_f32_16x16x32_bf16 v[68:71], v[208:211], v[176:179], v[68:71]
	v_mfma_f32_16x16x32_bf16 v[60:63], v[200:203], v[184:187], v[60:63]
	v_mfma_f32_16x16x32_bf16 v[56:59], v[208:211], v[184:187], v[56:59]
	v_mfma_f32_16x16x32_bf16 v[52:55], v[200:203], v[192:195], v[52:55]
	v_mfma_f32_16x16x32_bf16 v[48:51], v[208:211], v[192:195], v[48:51]
	v_mfma_f32_16x16x32_bf16 v[92:95], v[204:207], v[172:175], v[92:95]
	v_mfma_f32_16x16x32_bf16 v[88:91], v[212:215], v[172:175], v[88:91]
	v_mfma_f32_16x16x32_bf16 v[80:83], v[204:207], v[180:183], v[80:83]
	v_mfma_f32_16x16x32_bf16 v[68:71], v[212:215], v[180:183], v[68:71]
	v_mfma_f32_16x16x32_bf16 v[60:63], v[204:207], v[188:191], v[60:63]
	v_mfma_f32_16x16x32_bf16 v[56:59], v[212:215], v[188:191], v[56:59]
	v_mfma_f32_16x16x32_bf16 v[52:55], v[204:207], v[196:199], v[52:55]
	v_mfma_f32_16x16x32_bf16 v[48:51], v[212:215], v[196:199], v[48:51]
	s_barrier
	s_addk_i32 s7, 0x180
	s_mov_b32 m0, s43
	ds_read_b128 v[168:171], v129 offset:49152
	ds_read_b128 v[172:175], v129 offset:50176
	ds_read_b128 v[176:179], v132 offset:49152
	ds_read_b128 v[180:183], v132 offset:50176
	ds_read_b128 v[184:187], v131 offset:49152
	ds_read_b128 v[188:191], v131 offset:50176
	ds_read_b128 v[192:195], v130 offset:49152
	ds_read_b128 v[196:199], v130 offset:50176
	buffer_load_dwordx4 v141, s[8:11], s7 offen lds
	s_mov_b32 m0, s59
	s_nop 0
	buffer_load_dwordx4 v142, s[8:11], s7 offen lds
	s_barrier
	s_waitcnt lgkmcnt(0)
	v_mfma_f32_16x16x32_bf16 v[44:47], v[152:155], v[168:171], v[44:47]
	v_mfma_f32_16x16x32_bf16 v[40:43], v[160:163], v[168:171], v[40:43]
	v_mfma_f32_16x16x32_bf16 v[36:39], v[152:155], v[176:179], v[36:39]
	v_mfma_f32_16x16x32_bf16 v[32:35], v[160:163], v[176:179], v[32:35]
	v_mfma_f32_16x16x32_bf16 v[28:31], v[152:155], v[184:187], v[28:31]
	v_mfma_f32_16x16x32_bf16 v[24:27], v[160:163], v[184:187], v[24:27]
	v_mfma_f32_16x16x32_bf16 v[20:23], v[152:155], v[192:195], v[20:23]
	v_mfma_f32_16x16x32_bf16 v[16:19], v[160:163], v[192:195], v[16:19]
	v_mfma_f32_16x16x32_bf16 v[44:47], v[156:159], v[172:175], v[44:47]
	v_mfma_f32_16x16x32_bf16 v[40:43], v[164:167], v[172:175], v[40:43]
	v_mfma_f32_16x16x32_bf16 v[36:39], v[156:159], v[180:183], v[36:39]
	v_mfma_f32_16x16x32_bf16 v[32:35], v[164:167], v[180:183], v[32:35]
	v_mfma_f32_16x16x32_bf16 v[28:31], v[156:159], v[188:191], v[28:31]
	v_mfma_f32_16x16x32_bf16 v[24:27], v[164:167], v[188:191], v[24:27]
	v_mfma_f32_16x16x32_bf16 v[20:23], v[156:159], v[196:199], v[20:23]
	v_mfma_f32_16x16x32_bf16 v[16:19], v[164:167], v[196:199], v[16:19]
	s_barrier
; #define STAGE(P, RS, SOFF, OFF, kt) do { const int _so = (SOFF) + (kt) * (BK * 2); \
;     _Pragma("unroll") for (int _i = 0; _i < 2; ++_i) { \
;       __builtin_amdgcn_raw_ptr_buffer_load_lds(RS, (__attribute__((address_space(3))) void*)((P) + wave * 1024 + _i * 8192), 16, OFF[_i], _so, 0, 0); } } while (0)
; #define LDA(dst, b, h) _Pragma("unroll") for (int m = 0; m < 4; ++m) _Pragma("unroll") for (int k = 0; k < 2; ++k) \
;     dst[m][k] = *reinterpret_cast<const bf16x8*>(SA(b, h) + lds_byte(wr * 64 + m * 16 + fr, k * 32 + fq * 8))
; #define LDB(dst, b, h) _Pragma("unroll") for (int n = 0; n < 2; ++n) _Pragma("unroll") for (int k = 0; k < 2; ++k) \
;     dst[n][k] = *reinterpret_cast<const bf16x8*>(SB(b, h) + lds_byte(wc * 32 + n * 16 + fr, k * 32 + fq * 8))
; #define WAIT_V(n) asm volatile("s_waitcnt vmcnt(" #n ")" ::: "memory")
; #define WAIT_L(n) asm volatile("s_waitcnt lgkmcnt(" #n ")" ::: "memory")
; #define BAR __builtin_amdgcn_s_barrier()
;     ...
;       STAGE(SB(1, 1), rsB, sB1, offB, t + 3);
;       WAIT_V(6); BAR; MMA(1, 1, At, B1); BAR;
;     }
;     { LDB(B0, 0, 0); LDA(At, 0, 0); STAGE(SA(1, 1), rsA, sA1, offA, nt - 1);
;       BAR; WAIT_L(0); MMA(0, 0, At, B0); BAR;
;       LDB(B1, 0, 1); BAR; WAIT_L(0); MMA(0, 1, At, B1); BAR;
;       LDA(At, 0, 1); WAIT_V(4); BAR; WAIT_L(0); MMA(1, 0, At, B0); MMA(1, 1, At, B1); BAR; }
	s_addk_i32 s22, 0x180
	s_mov_b32 m0, s44
	s_nop 0
	buffer_load_dwordx4 v141, s[12:15], s22 offen lds
	s_mov_b32 m0, s60
	s_nop 0
	buffer_load_dwordx4 v142, s[12:15], s22 offen lds
	s_add_i32 s1, s1, 2
	s_addk_i32 s3, 0x100
	s_cmp_gt_u32 s1, 11
	s_waitcnt vmcnt(6)
	s_barrier
	v_mfma_f32_16x16x32_bf16 v[12:15], v[200:203], v[168:171], v[12:15]
	v_mfma_f32_16x16x32_bf16 v[8:11], v[208:211], v[168:171], v[8:11]
	v_mfma_f32_16x16x32_bf16 v[4:7], v[200:203], v[176:179], v[4:7]
	v_mfma_f32_16x16x32_bf16 v[0:3], v[208:211], v[176:179], v[0:3]
	v_mfma_f32_16x16x32_bf16 v[64:67], v[200:203], v[184:187], v[64:67]
	v_mfma_f32_16x16x32_bf16 v[72:75], v[208:211], v[184:187], v[72:75]
	v_mfma_f32_16x16x32_bf16 v[76:79], v[200:203], v[192:195], v[76:79]
	v_mfma_f32_16x16x32_bf16 v[84:87], v[208:211], v[192:195], v[84:87]
	v_mfma_f32_16x16x32_bf16 v[12:15], v[204:207], v[172:175], v[12:15]
	v_mfma_f32_16x16x32_bf16 v[8:11], v[212:215], v[172:175], v[8:11]
	v_mfma_f32_16x16x32_bf16 v[4:7], v[204:207], v[180:183], v[4:7]
	v_mfma_f32_16x16x32_bf16 v[0:3], v[212:215], v[180:183], v[0:3]
	v_mfma_f32_16x16x32_bf16 v[64:67], v[204:207], v[188:191], v[64:67]
	v_mfma_f32_16x16x32_bf16 v[72:75], v[212:215], v[188:191], v[72:75]
	v_mfma_f32_16x16x32_bf16 v[76:79], v[204:207], v[196:199], v[76:79]
	v_mfma_f32_16x16x32_bf16 v[84:87], v[212:215], v[196:199], v[84:87]
	s_barrier
	s_cbranch_scc0 .LBB0_291
	s_add_i32 s1, s94, 0x780
	s_mov_b32 m0, s36
	ds_read_b128 v[152:155], v147
	ds_read_b128 v[156:159], v148
	ds_read_b128 v[160:163], v149
	ds_read_b128 v[148:151], v150
	ds_read_b128 v[164:167], v129
	ds_read_b128 v[168:171], v129 offset:1024
	ds_read_b128 v[172:175], v132
	ds_read_b128 v[176:179], v132 offset:1024
	ds_read_b128 v[180:183], v131
	ds_read_b128 v[184:187], v131 offset:1024
	ds_read_b128 v[188:191], v130
	ds_read_b128 v[192:195], v130 offset:1024
	buffer_load_dwordx4 v141, s[8:11], s1 offen lds
	s_mov_b32 m0, s61
	s_nop 0
	buffer_load_dwordx4 v142, s[8:11], s1 offen lds
	s_barrier
	s_waitcnt lgkmcnt(0)
	v_mfma_f32_16x16x32_bf16 v[124:127], v[152:155], v[164:167], v[124:127]
	v_mfma_f32_16x16x32_bf16 v[120:123], v[160:163], v[164:167], v[120:123]
	v_mfma_f32_16x16x32_bf16 v[116:119], v[152:155], v[172:175], v[116:119]
	v_mfma_f32_16x16x32_bf16 v[112:115], v[160:163], v[172:175], v[112:115]
	v_mfma_f32_16x16x32_bf16 v[108:111], v[152:155], v[180:183], v[108:111]
	v_mfma_f32_16x16x32_bf16 v[104:107], v[160:163], v[180:183], v[104:107]
	v_mfma_f32_16x16x32_bf16 v[100:103], v[152:155], v[188:191], v[100:103]
	v_mfma_f32_16x16x32_bf16 v[96:99], v[160:163], v[188:191], v[96:99]
	v_mfma_f32_16x16x32_bf16 v[124:127], v[156:159], v[168:171], v[124:127]
	v_mfma_f32_16x16x32_bf16 v[120:123], v[148:151], v[168:171], v[120:123]
	v_mfma_f32_16x16x32_bf16 v[116:119], v[156:159], v[176:179], v[116:119]
	v_mfma_f32_16x16x32_bf16 v[112:115], v[148:151], v[176:179], v[112:115]
	v_mfma_f32_16x16x32_bf16 v[108:111], v[156:159], v[184:187], v[108:111]
	v_mfma_f32_16x16x32_bf16 v[104:107], v[148:151], v[184:187], v[104:107]
	v_mfma_f32_16x16x32_bf16 v[100:103], v[156:159], v[192:195], v[100:103]
	v_mfma_f32_16x16x32_bf16 v[96:99], v[148:151], v[192:195], v[96:99]
	s_barrier
	ds_read_b128 v[196:199], v143
	ds_read_b128 v[200:203], v144
	ds_read_b128 v[142:145], v145
	ds_read_b128 v[204:207], v146
	s_barrier
	s_waitcnt lgkmcnt(0)
	v_mfma_f32_16x16x32_bf16 v[88:91], v[142:145], v[164:167], v[88:91]
	v_mfma_f32_16x16x32_bf16 v[80:83], v[196:199], v[172:175], v[80:83]
	v_mfma_f32_16x16x32_bf16 v[60:63], v[196:199], v[180:183], v[60:63]
	v_mfma_f32_16x16x32_bf16 v[56:59], v[142:145], v[180:183], v[56:59]
	v_mfma_f32_16x16x32_bf16 v[52:55], v[196:199], v[188:191], v[52:55]
	v_mfma_f32_16x16x32_bf16 v[48:51], v[142:145], v[188:191], v[48:51]
	v_mfma_f32_16x16x32_bf16 v[92:95], v[196:199], v[164:167], v[92:95]
	v_mfma_f32_16x16x32_bf16 v[68:71], v[142:145], v[172:175], v[68:71]
	v_mfma_f32_16x16x32_bf16 v[88:91], v[204:207], v[168:171], v[88:91]
	v_mfma_f32_16x16x32_bf16 v[80:83], v[200:203], v[176:179], v[80:83]
	v_mfma_f32_16x16x32_bf16 v[60:63], v[200:203], v[184:187], v[60:63]
	v_mfma_f32_16x16x32_bf16 v[56:59], v[204:207], v[184:187], v[56:59]
	v_mfma_f32_16x16x32_bf16 v[52:55], v[200:203], v[192:195], v[52:55]
	v_mfma_f32_16x16x32_bf16 v[48:51], v[204:207], v[192:195], v[48:51]
	v_mfma_f32_16x16x32_bf16 v[164:167], v[200:203], v[168:171], v[92:95]
	v_mfma_f32_16x16x32_bf16 v[168:171], v[204:207], v[176:179], v[68:71]
	s_barrier
	s_nop 0
	ds_read_b128 v[68:71], v129 offset:16384
	ds_read_b128 v[92:95], v129 offset:17408
	ds_read_b128 v[172:175], v132 offset:16384
	ds_read_b128 v[176:179], v132 offset:17408
	ds_read_b128 v[180:183], v131 offset:16384
	ds_read_b128 v[184:187], v131 offset:17408
	ds_read_b128 v[188:191], v130 offset:16384
	ds_read_b128 v[192:195], v130 offset:17408
	s_waitcnt vmcnt(4)
	s_barrier
; #define LDA(dst, b, h) _Pragma("unroll") for (int m = 0; m < 4; ++m) _Pragma("unroll") for (int k = 0; k < 2; ++k) \
;     dst[m][k] = *reinterpret_cast<const bf16x8*>(SA(b, h) + lds_byte(wr * 64 + m * 16 + fr, k * 32 + fq * 8))
; #define LDB(dst, b, h) _Pragma("unroll") for (int n = 0; n < 2; ++n) _Pragma("unroll") for (int k = 0; k < 2; ++k) \
;     dst[n][k] = *reinterpret_cast<const bf16x8*>(SB(b, h) + lds_byte(wc * 32 + n * 16 + fr, k * 32 + fq * 8))
; #define WAIT_V(n) asm volatile("s_waitcnt vmcnt(" #n ")" ::: "memory")
; #define WAIT_L(n) asm volatile("s_waitcnt lgkmcnt(" #n ")" ::: "memory")
; #define BAR __builtin_amdgcn_s_barrier()
;     ...
;       LDA(At, 0, 1); WAIT_V(4); BAR; WAIT_L(0); MMA(1, 0, At, B0); MMA(1, 1, At, B1); BAR; }
;     { LDB(B0, 1, 0); LDA(At, 1, 0); WAIT_V(2); BAR; WAIT_L(0); MMA(0, 0, At, B0); BAR;
	s_waitcnt lgkmcnt(0)
	v_mfma_f32_16x16x32_bf16 v[44:47], v[152:155], v[68:71], v[44:47]
	v_mfma_f32_16x16x32_bf16 v[40:43], v[160:163], v[68:71], v[40:43]
	v_mfma_f32_16x16x32_bf16 v[36:39], v[152:155], v[172:175], v[36:39]
	v_mfma_f32_16x16x32_bf16 v[32:35], v[160:163], v[172:175], v[32:35]
	v_mfma_f32_16x16x32_bf16 v[28:31], v[152:155], v[180:183], v[28:31]
	v_mfma_f32_16x16x32_bf16 v[24:27], v[160:163], v[180:183], v[24:27]
	v_mfma_f32_16x16x32_bf16 v[20:23], v[152:155], v[188:191], v[20:23]
	v_mfma_f32_16x16x32_bf16 v[16:19], v[160:163], v[188:191], v[16:19]
	v_mfma_f32_16x16x32_bf16 v[44:47], v[156:159], v[92:95], v[44:47]
	v_mfma_f32_16x16x32_bf16 v[40:43], v[148:151], v[92:95], v[40:43]
	v_mfma_f32_16x16x32_bf16 v[36:39], v[156:159], v[176:179], v[36:39]
	v_mfma_f32_16x16x32_bf16 v[32:35], v[148:151], v[176:179], v[32:35]
	v_mfma_f32_16x16x32_bf16 v[28:31], v[156:159], v[184:187], v[28:31]
	v_mfma_f32_16x16x32_bf16 v[24:27], v[148:151], v[184:187], v[24:27]
	v_mfma_f32_16x16x32_bf16 v[20:23], v[156:159], v[192:195], v[20:23]
	v_mfma_f32_16x16x32_bf16 v[16:19], v[148:151], v[192:195], v[16:19]
	v_mfma_f32_16x16x32_bf16 v[4:7], v[196:199], v[172:175], v[4:7]
	v_mfma_f32_16x16x32_bf16 v[0:3], v[142:145], v[172:175], v[0:3]
	v_mfma_f32_16x16x32_bf16 v[12:15], v[196:199], v[68:71], v[12:15]
	v_mfma_f32_16x16x32_bf16 v[8:11], v[142:145], v[68:71], v[8:11]
	v_mfma_f32_16x16x32_bf16 v[64:67], v[196:199], v[180:183], v[64:67]
	v_mfma_f32_16x16x32_bf16 v[68:71], v[142:145], v[180:183], v[72:75]
	v_mfma_f32_16x16x32_bf16 v[72:75], v[196:199], v[188:191], v[76:79]
	v_mfma_f32_16x16x32_bf16 v[76:79], v[142:145], v[188:191], v[84:87]
	v_mfma_f32_16x16x32_bf16 v[4:7], v[200:203], v[176:179], v[4:7]
	v_mfma_f32_16x16x32_bf16 v[0:3], v[204:207], v[176:179], v[0:3]
	v_mfma_f32_16x16x32_bf16 v[142:145], v[200:203], v[92:95], v[12:15]
	v_mfma_f32_16x16x32_bf16 v[146:149], v[204:207], v[92:95], v[8:11]
	v_mfma_f32_16x16x32_bf16 v[150:153], v[200:203], v[184:187], v[64:67]
	v_mfma_f32_16x16x32_bf16 v[154:157], v[204:207], v[184:187], v[68:71]
	v_mfma_f32_16x16x32_bf16 v[158:161], v[200:203], v[192:195], v[72:75]
	v_mfma_f32_16x16x32_bf16 v[172:175], v[204:207], v[192:195], v[76:79]
	s_barrier
	ds_read_b128 v[8:11], v137
	ds_read_b128 v[12:15], v138
	ds_read_b128 v[176:179], v139
	ds_read_b128 v[138:141], v140
	ds_read_b128 v[64:67], v129 offset:32768
	ds_read_b128 v[72:75], v129 offset:33792
	ds_read_b128 v[180:183], v132 offset:32768
	ds_read_b128 v[184:187], v132 offset:33792
	ds_read_b128 v[188:191], v131 offset:32768
	ds_read_b128 v[192:195], v131 offset:33792
	ds_read_b128 v[196:199], v130 offset:32768
	ds_read_b128 v[200:203], v130 offset:33792
	s_waitcnt vmcnt(2)
	s_barrier
	s_waitcnt lgkmcnt(0)
	v_mfma_f32_16x16x32_bf16 v[68:71], v[8:11], v[64:67], v[124:127]
	v_mfma_f32_16x16x32_bf16 v[76:79], v[176:179], v[64:67], v[120:123]
	v_mfma_f32_16x16x32_bf16 v[84:87], v[8:11], v[180:183], v[116:119]
	v_mfma_f32_16x16x32_bf16 v[92:95], v[176:179], v[180:183], v[112:115]
	v_mfma_f32_16x16x32_bf16 v[112:115], v[8:11], v[188:191], v[108:111]
	v_mfma_f32_16x16x32_bf16 v[104:107], v[176:179], v[188:191], v[104:107]
	v_mfma_f32_16x16x32_bf16 v[120:123], v[8:11], v[196:199], v[100:103]
	v_mfma_f32_16x16x32_bf16 v[96:99], v[176:179], v[196:199], v[96:99]
	v_mfma_f32_16x16x32_bf16 v[124:127], v[12:15], v[72:75], v[68:71]
	v_mfma_f32_16x16x32_bf16 v[116:119], v[138:141], v[72:75], v[76:79]
	v_mfma_f32_16x16x32_bf16 v[108:111], v[12:15], v[184:187], v[84:87]
	v_mfma_f32_16x16x32_bf16 v[100:103], v[138:141], v[184:187], v[92:95]
	v_mfma_f32_16x16x32_bf16 v[92:95], v[12:15], v[192:195], v[112:115]
	v_mfma_f32_16x16x32_bf16 v[84:87], v[138:141], v[192:195], v[104:107]
	v_mfma_f32_16x16x32_bf16 v[76:79], v[12:15], v[200:203], v[120:123]
	v_mfma_f32_16x16x32_bf16 v[68:71], v[138:141], v[200:203], v[96:99]
	s_barrier
; #define LDA(dst, b, h) _Pragma("unroll") for (int m = 0; m < 4; ++m) _Pragma("unroll") for (int k = 0; k < 2; ++k) \
;     dst[m][k] = *reinterpret_cast<const bf16x8*>(SA(b, h) + lds_byte(wr * 64 + m * 16 + fr, k * 32 + fq * 8))
; #define LDB(dst, b, h) _Pragma("unroll") for (int n = 0; n < 2; ++n) _Pragma("unroll") for (int k = 0; k < 2; ++k) \
;     dst[n][k] = *reinterpret_cast<const bf16x8*>(SB(b, h) + lds_byte(wc * 32 + n * 16 + fr, k * 32 + fq * 8))
; #define WAIT_V(n) asm volatile("s_waitcnt vmcnt(" #n ")" ::: "memory")
; #define WAIT_L(n) asm volatile("s_waitcnt lgkmcnt(" #n ")" ::: "memory")
; #define BAR __builtin_amdgcn_s_barrier()
;     ...
;       LDB(B1, 1, 1); WAIT_V(0); BAR; WAIT_L(0); MMA(0, 1, At, B1); BAR;
;       LDA(At, 1, 1); BAR; WAIT_L(0); MMA(1, 0, At, B0); MMA(1, 1, At, B1); BAR; }
;     if (wr == 0) BAR;
	ds_read_b128 v[204:207], v133
	ds_read_b128 v[208:211], v134
	ds_read_b128 v[212:215], v135
	ds_read_b128 v[134:137], v136
	s_waitcnt vmcnt(0)
	s_barrier
	s_waitcnt lgkmcnt(0)
	v_mfma_f32_16x16x32_bf16 v[96:99], v[204:207], v[64:67], v[164:167]
	v_mfma_f32_16x16x32_bf16 v[64:67], v[212:215], v[64:67], v[88:91]
	v_mfma_f32_16x16x32_bf16 v[80:83], v[204:207], v[180:183], v[80:83]
	v_mfma_f32_16x16x32_bf16 v[88:91], v[212:215], v[180:183], v[168:171]
	v_mfma_f32_16x16x32_bf16 v[60:63], v[204:207], v[188:191], v[60:63]
	v_mfma_f32_16x16x32_bf16 v[56:59], v[212:215], v[188:191], v[56:59]
	v_mfma_f32_16x16x32_bf16 v[52:55], v[204:207], v[196:199], v[52:55]
	v_mfma_f32_16x16x32_bf16 v[48:51], v[212:215], v[196:199], v[48:51]
	v_mfma_f32_16x16x32_bf16 v[120:123], v[208:211], v[72:75], v[96:99]
	v_mfma_f32_16x16x32_bf16 v[112:115], v[134:137], v[72:75], v[64:67]
	v_mfma_f32_16x16x32_bf16 v[104:107], v[208:211], v[184:187], v[80:83]
	v_mfma_f32_16x16x32_bf16 v[96:99], v[134:137], v[184:187], v[88:91]
	v_mfma_f32_16x16x32_bf16 v[88:91], v[208:211], v[192:195], v[60:63]
	v_mfma_f32_16x16x32_bf16 v[80:83], v[134:137], v[192:195], v[56:59]
	v_mfma_f32_16x16x32_bf16 v[72:75], v[208:211], v[200:203], v[52:55]
	v_mfma_f32_16x16x32_bf16 v[64:67], v[134:137], v[200:203], v[48:51]
	s_barrier
	s_nop 0
	ds_read_b128 v[48:51], v129 offset:49152
	ds_read_b128 v[162:165], v129 offset:50176
	ds_read_b128 v[52:55], v132 offset:49152
	ds_read_b128 v[166:169], v132 offset:50176
	ds_read_b128 v[180:183], v131 offset:49152
	ds_read_b128 v[184:187], v131 offset:50176
	ds_read_b128 v[188:191], v130 offset:49152
	ds_read_b128 v[130:133], v130 offset:50176
	s_barrier
	s_waitcnt lgkmcnt(0)
	v_mfma_f32_16x16x32_bf16 v[44:47], v[8:11], v[48:51], v[44:47]
	v_mfma_f32_16x16x32_bf16 v[40:43], v[176:179], v[48:51], v[40:43]
	v_mfma_f32_16x16x32_bf16 v[36:39], v[8:11], v[52:55], v[36:39]
	v_mfma_f32_16x16x32_bf16 v[32:35], v[176:179], v[52:55], v[32:35]
	v_mfma_f32_16x16x32_bf16 v[28:31], v[8:11], v[180:183], v[28:31]
	v_mfma_f32_16x16x32_bf16 v[24:27], v[176:179], v[180:183], v[24:27]
	v_mfma_f32_16x16x32_bf16 v[8:11], v[8:11], v[188:191], v[20:23]
	v_mfma_f32_16x16x32_bf16 v[16:19], v[176:179], v[188:191], v[16:19]
	v_mfma_f32_16x16x32_bf16 v[60:63], v[12:15], v[162:165], v[44:47]
	v_mfma_f32_16x16x32_bf16 v[56:59], v[138:141], v[162:165], v[40:43]
	v_mfma_f32_16x16x32_bf16 v[44:47], v[12:15], v[166:169], v[36:39]
	v_mfma_f32_16x16x32_bf16 v[40:43], v[138:141], v[166:169], v[32:35]
	v_mfma_f32_16x16x32_bf16 v[28:31], v[12:15], v[184:187], v[28:31]
	v_mfma_f32_16x16x32_bf16 v[24:27], v[138:141], v[184:187], v[24:27]
	v_mfma_f32_16x16x32_bf16 v[12:15], v[12:15], v[130:133], v[8:11]
	v_mfma_f32_16x16x32_bf16 v[8:11], v[138:141], v[130:133], v[16:19]
	v_mfma_f32_16x16x32_bf16 v[16:19], v[204:207], v[48:51], v[142:145]
	v_mfma_f32_16x16x32_bf16 v[20:23], v[212:215], v[48:51], v[146:149]
	v_mfma_f32_16x16x32_bf16 v[4:7], v[204:207], v[52:55], v[4:7]
	v_mfma_f32_16x16x32_bf16 v[0:3], v[212:215], v[52:55], v[0:3]
	v_mfma_f32_16x16x32_bf16 v[138:141], v[204:207], v[180:183], v[150:153]
	v_mfma_f32_16x16x32_bf16 v[142:145], v[212:215], v[180:183], v[154:157]
	v_mfma_f32_16x16x32_bf16 v[146:149], v[204:207], v[188:191], v[158:161]
	v_mfma_f32_16x16x32_bf16 v[150:153], v[212:215], v[188:191], v[172:175]
	v_mfma_f32_16x16x32_bf16 v[52:55], v[208:211], v[162:165], v[16:19]
	v_mfma_f32_16x16x32_bf16 v[48:51], v[134:137], v[162:165], v[20:23]
	v_mfma_f32_16x16x32_bf16 v[36:39], v[208:211], v[166:169], v[4:7]
	v_mfma_f32_16x16x32_bf16 v[32:35], v[134:137], v[166:169], v[0:3]
	v_mfma_f32_16x16x32_bf16 v[20:23], v[208:211], v[184:187], v[138:141]
	v_mfma_f32_16x16x32_bf16 v[16:19], v[134:137], v[184:187], v[142:145]
	v_mfma_f32_16x16x32_bf16 v[4:7], v[208:211], v[130:133], v[146:149]
	v_mfma_f32_16x16x32_bf16 v[0:3], v[134:137], v[130:133], v[150:153]
	v_cmp_gt_u32_e32 vcc, s46, v128
	s_barrier
	s_and_saveexec_b64 s[6:7], vcc
	s_cbranch_execz .LBB0_294
	s_barrier

; #define STAGE(P, RS, SOFF, OFF, kt) do { const int _so = (SOFF) + (kt) * (BK * 2); \
;     _Pragma("unroll") for (int _i = 0; _i < 2; ++_i) { \
;       __builtin_amdgcn_raw_ptr_buffer_load_lds(RS, (__attribute__((address_space(3))) void*)((P) + wave * 1024 + _i * 8192), 16, OFF[_i], _so, 0, 0); } } while (0)
; #define LDA(dst, b, h) _Pragma("unroll") for (int m = 0; m < 4; ++m) _Pragma("unroll") for (int k = 0; k < 2; ++k) \
;     dst[m][k] = *reinterpret_cast<const bf16x8*>(SA(b, h) + lds_byte(wr * 64 + m * 16 + fr, k * 32 + fq * 8))
; #define LDB(dst, b, h) _Pragma("unroll") for (int n = 0; n < 2; ++n) _Pragma("unroll") for (int k = 0; k < 2; ++k) \
;     dst[n][k] = *reinterpret_cast<const bf16x8*>(SB(b, h) + lds_byte(wc * 32 + n * 16 + fr, k * 32 + fq * 8))
; #define WAIT_V(n) asm volatile("s_waitcnt vmcnt(" #n ")" ::: "memory")
; #define WAIT_L(n) asm volatile("s_waitcnt lgkmcnt(" #n ")" ::: "memory")
; #define BAR __builtin_amdgcn_s_barrier()
; #define SCHED __builtin_amdgcn_sched_barrier(0)
;     ...
;       LDB(B0, 0, 0); SCHED; LDA(At, 0, 0); STAGE(SA(1, 1), rsA, sA1, offA, t + 1);
;       WAIT_L(8); BAR; WAIT_L(0); MMA(0, 0, At, B0); BAR; SCHED;
;       LDB(B1, 0, 1); STAGE(SB(0, 0), rsB, sB0, offB, t + 2);
;       BAR; WAIT_L(0); MMA(0, 1, At, B1); BAR;
;       LDA(At, 0, 1); STAGE(SA(0, 0), rsA, sA0, offA, t + 2);
;       BAR; WAIT_L(0); MMA(1, 0, At, B0); BAR; SCHED;
;       STAGE(SB(0, 1), rsB, sB1, offB, t + 2);
;       WAIT_V(6); BAR; MMA(1, 1, At, B1); BAR;
.LBB0_354:
	ds_read_b128 v[154:157], v149
	ds_read_b128 v[158:161], v150
	ds_read_b128 v[162:165], v151
	ds_read_b128 v[166:169], v152
	s_add_i32 s43, s37, s17
	s_add_i32 s10, s43, 0x80
	s_mov_b32 m0, s30
	ds_read_b128 v[170:173], v131
	ds_read_b128 v[174:177], v131 offset:1024
	ds_read_b128 v[178:181], v134
	ds_read_b128 v[182:185], v134 offset:1024
	ds_read_b128 v[186:189], v133
	ds_read_b128 v[190:193], v133 offset:1024
	ds_read_b128 v[194:197], v132
	ds_read_b128 v[198:201], v132 offset:1024
	buffer_load_dwordx4 v143, s[4:7], s10 offen lds
	s_mov_b32 m0, s31
	s_nop 0
	buffer_load_dwordx4 v144, s[4:7], s10 offen lds
	s_waitcnt lgkmcnt(8)
	s_barrier
	s_waitcnt lgkmcnt(0)
	v_mfma_f32_16x16x32_bf16 v[124:127], v[154:157], v[170:173], v[124:127]
	v_mfma_f32_16x16x32_bf16 v[120:123], v[162:165], v[170:173], v[120:123]
	v_mfma_f32_16x16x32_bf16 v[116:119], v[154:157], v[178:181], v[116:119]
	v_mfma_f32_16x16x32_bf16 v[112:115], v[162:165], v[178:181], v[112:115]
	v_mfma_f32_16x16x32_bf16 v[108:111], v[154:157], v[186:189], v[108:111]
	v_mfma_f32_16x16x32_bf16 v[104:107], v[162:165], v[186:189], v[104:107]
	v_mfma_f32_16x16x32_bf16 v[100:103], v[154:157], v[194:197], v[100:103]
	v_mfma_f32_16x16x32_bf16 v[96:99], v[162:165], v[194:197], v[96:99]
	v_mfma_f32_16x16x32_bf16 v[124:127], v[158:161], v[174:177], v[124:127]
	v_mfma_f32_16x16x32_bf16 v[120:123], v[166:169], v[174:177], v[120:123]
	v_mfma_f32_16x16x32_bf16 v[116:119], v[158:161], v[182:185], v[116:119]
	v_mfma_f32_16x16x32_bf16 v[112:115], v[166:169], v[182:185], v[112:115]
	v_mfma_f32_16x16x32_bf16 v[108:111], v[158:161], v[190:193], v[108:111]
	v_mfma_f32_16x16x32_bf16 v[104:107], v[166:169], v[190:193], v[104:107]
	v_mfma_f32_16x16x32_bf16 v[100:103], v[158:161], v[198:201], v[100:103]
	v_mfma_f32_16x16x32_bf16 v[96:99], v[166:169], v[198:201], v[96:99]
	s_barrier
	s_add_i32 s44, s39, s17
	s_add_i32 s45, s44, 0x100
	s_mov_b32 s10, s6
	s_mov_b32 s11, s7
	s_mov_b32 m0, s1
	ds_read_b128 v[202:205], v145
	ds_read_b128 v[206:209], v146
	ds_read_b128 v[210:213], v147
	ds_read_b128 v[214:217], v148
	buffer_load_dwordx4 v143, s[8:11], s45 offen lds
	s_mov_b32 m0, s3
	s_nop 0
	buffer_load_dwordx4 v144, s[8:11], s45 offen lds
	s_barrier
	s_waitcnt lgkmcnt(0)
	v_mfma_f32_16x16x32_bf16 v[92:95], v[202:205], v[170:173], v[92:95]
	v_mfma_f32_16x16x32_bf16 v[88:91], v[210:213], v[170:173], v[88:91]
	v_mfma_f32_16x16x32_bf16 v[84:87], v[202:205], v[178:181], v[84:87]
	v_mfma_f32_16x16x32_bf16 v[80:83], v[210:213], v[178:181], v[80:83]
	v_mfma_f32_16x16x32_bf16 v[76:79], v[202:205], v[186:189], v[76:79]
	v_mfma_f32_16x16x32_bf16 v[72:75], v[210:213], v[186:189], v[72:75]
	v_mfma_f32_16x16x32_bf16 v[68:71], v[202:205], v[194:197], v[68:71]
	v_mfma_f32_16x16x32_bf16 v[64:67], v[210:213], v[194:197], v[64:67]
	v_mfma_f32_16x16x32_bf16 v[92:95], v[206:209], v[174:177], v[92:95]
	v_mfma_f32_16x16x32_bf16 v[88:91], v[214:217], v[174:177], v[88:91]
	v_mfma_f32_16x16x32_bf16 v[84:87], v[206:209], v[182:185], v[84:87]
	v_mfma_f32_16x16x32_bf16 v[80:83], v[214:217], v[182:185], v[80:83]
	v_mfma_f32_16x16x32_bf16 v[76:79], v[206:209], v[190:193], v[76:79]
	v_mfma_f32_16x16x32_bf16 v[72:75], v[214:217], v[190:193], v[72:75]
	v_mfma_f32_16x16x32_bf16 v[68:71], v[206:209], v[198:201], v[68:71]
	v_mfma_f32_16x16x32_bf16 v[64:67], v[214:217], v[198:201], v[64:67]
	s_barrier
	s_add_i32 s45, s38, s17
	s_add_i32 s46, s45, 0x100
	s_mov_b32 m0, s0
	ds_read_b128 v[170:173], v131 offset:16384
	ds_read_b128 v[174:177], v131 offset:17408
	ds_read_b128 v[178:181], v134 offset:16384
	ds_read_b128 v[182:185], v134 offset:17408
	ds_read_b128 v[186:189], v133 offset:16384
	ds_read_b128 v[190:193], v133 offset:17408
	ds_read_b128 v[194:197], v132 offset:16384
	ds_read_b128 v[198:201], v132 offset:17408
	buffer_load_dwordx4 v143, s[4:7], s46 offen lds
	s_mov_b32 m0, s18
	s_nop 0
	buffer_load_dwordx4 v144, s[4:7], s46 offen lds
	s_barrier
	s_waitcnt lgkmcnt(0)
	v_mfma_f32_16x16x32_bf16 v[60:63], v[154:157], v[170:173], v[60:63]
	v_mfma_f32_16x16x32_bf16 v[56:59], v[162:165], v[170:173], v[56:59]
	v_mfma_f32_16x16x32_bf16 v[52:55], v[154:157], v[178:181], v[52:55]
	v_mfma_f32_16x16x32_bf16 v[48:51], v[162:165], v[178:181], v[48:51]
	v_mfma_f32_16x16x32_bf16 v[44:47], v[154:157], v[186:189], v[44:47]
	v_mfma_f32_16x16x32_bf16 v[40:43], v[162:165], v[186:189], v[40:43]
	v_mfma_f32_16x16x32_bf16 v[36:39], v[154:157], v[194:197], v[36:39]
	v_mfma_f32_16x16x32_bf16 v[32:35], v[162:165], v[194:197], v[32:35]
	v_mfma_f32_16x16x32_bf16 v[60:63], v[158:161], v[174:177], v[60:63]
	v_mfma_f32_16x16x32_bf16 v[56:59], v[166:169], v[174:177], v[56:59]
	v_mfma_f32_16x16x32_bf16 v[52:55], v[158:161], v[182:185], v[52:55]
	v_mfma_f32_16x16x32_bf16 v[48:51], v[166:169], v[182:185], v[48:51]
	v_mfma_f32_16x16x32_bf16 v[44:47], v[158:161], v[190:193], v[44:47]
	v_mfma_f32_16x16x32_bf16 v[40:43], v[166:169], v[190:193], v[40:43]
	v_mfma_f32_16x16x32_bf16 v[36:39], v[158:161], v[198:201], v[36:39]
	v_mfma_f32_16x16x32_bf16 v[32:35], v[166:169], v[198:201], v[32:35]
	s_barrier
	s_add_i32 s46, s40, s17
	s_add_i32 s47, s46, 0x100
	s_mov_b32 m0, s19
	s_nop 0
	buffer_load_dwordx4 v143, s[8:11], s47 offen lds
	s_mov_b32 m0, s20
	s_nop 0
	buffer_load_dwordx4 v144, s[8:11], s47 offen lds
	s_waitcnt vmcnt(6)
	s_barrier
; #define STAGE(P, RS, SOFF, OFF, kt) do { const int _so = (SOFF) + (kt) * (BK * 2); \
;     _Pragma("unroll") for (int _i = 0; _i < 2; ++_i) { \
;       __builtin_amdgcn_raw_ptr_buffer_load_lds(RS, (__attribute__((address_space(3))) void*)((P) + wave * 1024 + _i * 8192), 16, OFF[_i], _so, 0, 0); } } while (0)
; #define LDA(dst, b, h) _Pragma("unroll") for (int m = 0; m < 4; ++m) _Pragma("unroll") for (int k = 0; k < 2; ++k) \
;     dst[m][k] = *reinterpret_cast<const bf16x8*>(SA(b, h) + lds_byte(wr * 64 + m * 16 + fr, k * 32 + fq * 8))
; #define LDB(dst, b, h) _Pragma("unroll") for (int n = 0; n < 2; ++n) _Pragma("unroll") for (int k = 0; k < 2; ++k) \
;     dst[n][k] = *reinterpret_cast<const bf16x8*>(SB(b, h) + lds_byte(wc * 32 + n * 16 + fr, k * 32 + fq * 8))
; #define WAIT_V(n) asm volatile("s_waitcnt vmcnt(" #n ")" ::: "memory")
; #define WAIT_L(n) asm volatile("s_waitcnt lgkmcnt(" #n ")" ::: "memory")
; #define BAR __builtin_amdgcn_s_barrier()
; #define SCHED __builtin_amdgcn_sched_barrier(0)
;     ...
;       WAIT_V(6); BAR; MMA(1, 1, At, B1); BAR;
;       LDB(B0, 1, 0); SCHED; LDA(At, 1, 0); STAGE(SA(0, 1), rsA, sA1, offA, t + 2);
;       WAIT_L(8); BAR; WAIT_L(0); MMA(0, 0, At, B0); BAR; SCHED;
;       LDB(B1, 1, 1); STAGE(SB(1, 0), rsB, sB0, offB, t + 3);
;       BAR; WAIT_L(0); MMA(0, 1, At, B1); BAR;
;       LDA(At, 1, 1); STAGE(SA(1, 0), rsA, sA0, offA, t + 3);
;       BAR; WAIT_L(0); MMA(1, 0, At, B0); BAR; SCHED;
	v_mfma_f32_16x16x32_bf16 v[28:31], v[202:205], v[170:173], v[28:31]
	v_mfma_f32_16x16x32_bf16 v[24:27], v[210:213], v[170:173], v[24:27]
	v_mfma_f32_16x16x32_bf16 v[20:23], v[202:205], v[178:181], v[20:23]
	v_mfma_f32_16x16x32_bf16 v[16:19], v[210:213], v[178:181], v[16:19]
	v_mfma_f32_16x16x32_bf16 v[12:15], v[202:205], v[186:189], v[12:15]
	v_mfma_f32_16x16x32_bf16 v[8:11], v[210:213], v[186:189], v[8:11]
	v_mfma_f32_16x16x32_bf16 v[4:7], v[202:205], v[194:197], v[4:7]
	v_mfma_f32_16x16x32_bf16 v[0:3], v[210:213], v[194:197], v[0:3]
	v_mfma_f32_16x16x32_bf16 v[28:31], v[206:209], v[174:177], v[28:31]
	v_mfma_f32_16x16x32_bf16 v[24:27], v[214:217], v[174:177], v[24:27]
	v_mfma_f32_16x16x32_bf16 v[20:23], v[206:209], v[182:185], v[20:23]
	v_mfma_f32_16x16x32_bf16 v[16:19], v[214:217], v[182:185], v[16:19]
	v_mfma_f32_16x16x32_bf16 v[12:15], v[206:209], v[190:193], v[12:15]
	v_mfma_f32_16x16x32_bf16 v[8:11], v[214:217], v[190:193], v[8:11]
	v_mfma_f32_16x16x32_bf16 v[4:7], v[206:209], v[198:201], v[4:7]
	v_mfma_f32_16x16x32_bf16 v[0:3], v[214:217], v[198:201], v[0:3]
	s_barrier
	ds_read_b128 v[154:157], v139
	ds_read_b128 v[158:161], v140
	ds_read_b128 v[162:165], v141
	ds_read_b128 v[166:169], v142
	s_addk_i32 s43, 0x100
	s_mov_b32 m0, s21
	ds_read_b128 v[170:173], v131 offset:32768
	ds_read_b128 v[174:177], v131 offset:33792
	ds_read_b128 v[178:181], v134 offset:32768
	ds_read_b128 v[182:185], v134 offset:33792
	ds_read_b128 v[186:189], v133 offset:32768
	ds_read_b128 v[190:193], v133 offset:33792
	ds_read_b128 v[194:197], v132 offset:32768
	ds_read_b128 v[198:201], v132 offset:33792
	buffer_load_dwordx4 v143, s[4:7], s43 offen lds
	s_mov_b32 m0, s22
	s_nop 0
	buffer_load_dwordx4 v144, s[4:7], s43 offen lds
	s_waitcnt lgkmcnt(8)
	s_barrier
	s_waitcnt lgkmcnt(0)
	v_mfma_f32_16x16x32_bf16 v[124:127], v[154:157], v[170:173], v[124:127]
	v_mfma_f32_16x16x32_bf16 v[120:123], v[162:165], v[170:173], v[120:123]
	v_mfma_f32_16x16x32_bf16 v[116:119], v[154:157], v[178:181], v[116:119]
	v_mfma_f32_16x16x32_bf16 v[112:115], v[162:165], v[178:181], v[112:115]
	v_mfma_f32_16x16x32_bf16 v[108:111], v[154:157], v[186:189], v[108:111]
	v_mfma_f32_16x16x32_bf16 v[104:107], v[162:165], v[186:189], v[104:107]
	v_mfma_f32_16x16x32_bf16 v[100:103], v[154:157], v[194:197], v[100:103]
	v_mfma_f32_16x16x32_bf16 v[96:99], v[162:165], v[194:197], v[96:99]
	v_mfma_f32_16x16x32_bf16 v[124:127], v[158:161], v[174:177], v[124:127]
	v_mfma_f32_16x16x32_bf16 v[120:123], v[166:169], v[174:177], v[120:123]
	v_mfma_f32_16x16x32_bf16 v[116:119], v[158:161], v[182:185], v[116:119]
	v_mfma_f32_16x16x32_bf16 v[112:115], v[166:169], v[182:185], v[112:115]
	v_mfma_f32_16x16x32_bf16 v[108:111], v[158:161], v[190:193], v[108:111]
	v_mfma_f32_16x16x32_bf16 v[104:107], v[166:169], v[190:193], v[104:107]
	v_mfma_f32_16x16x32_bf16 v[100:103], v[158:161], v[198:201], v[100:103]
	v_mfma_f32_16x16x32_bf16 v[96:99], v[166:169], v[198:201], v[96:99]
	s_barrier
	s_addk_i32 s44, 0x180
	s_mov_b32 m0, s23
	ds_read_b128 v[202:205], v135
	ds_read_b128 v[206:209], v136
	ds_read_b128 v[210:213], v137
	ds_read_b128 v[214:217], v138
	buffer_load_dwordx4 v143, s[8:11], s44 offen lds
	s_mov_b32 m0, s24
	s_nop 0
	buffer_load_dwordx4 v144, s[8:11], s44 offen lds
	s_barrier
	s_waitcnt lgkmcnt(0)
	v_mfma_f32_16x16x32_bf16 v[92:95], v[202:205], v[170:173], v[92:95]
	v_mfma_f32_16x16x32_bf16 v[88:91], v[210:213], v[170:173], v[88:91]
	v_mfma_f32_16x16x32_bf16 v[84:87], v[202:205], v[178:181], v[84:87]
	v_mfma_f32_16x16x32_bf16 v[80:83], v[210:213], v[178:181], v[80:83]
	v_mfma_f32_16x16x32_bf16 v[76:79], v[202:205], v[186:189], v[76:79]
	v_mfma_f32_16x16x32_bf16 v[72:75], v[210:213], v[186:189], v[72:75]
	v_mfma_f32_16x16x32_bf16 v[68:71], v[202:205], v[194:197], v[68:71]
	v_mfma_f32_16x16x32_bf16 v[64:67], v[210:213], v[194:197], v[64:67]
	v_mfma_f32_16x16x32_bf16 v[92:95], v[206:209], v[174:177], v[92:95]
	v_mfma_f32_16x16x32_bf16 v[88:91], v[214:217], v[174:177], v[88:91]
	v_mfma_f32_16x16x32_bf16 v[84:87], v[206:209], v[182:185], v[84:87]
	v_mfma_f32_16x16x32_bf16 v[80:83], v[214:217], v[182:185], v[80:83]
	v_mfma_f32_16x16x32_bf16 v[76:79], v[206:209], v[190:193], v[76:79]
	v_mfma_f32_16x16x32_bf16 v[72:75], v[214:217], v[190:193], v[72:75]
	v_mfma_f32_16x16x32_bf16 v[68:71], v[206:209], v[198:201], v[68:71]
	v_mfma_f32_16x16x32_bf16 v[64:67], v[214:217], v[198:201], v[64:67]
	s_barrier
	s_addk_i32 s45, 0x180
	s_mov_b32 m0, s25
	ds_read_b128 v[170:173], v131 offset:49152
	ds_read_b128 v[174:177], v131 offset:50176
	ds_read_b128 v[178:181], v134 offset:49152
	ds_read_b128 v[182:185], v134 offset:50176
	ds_read_b128 v[186:189], v133 offset:49152
	ds_read_b128 v[190:193], v133 offset:50176
	ds_read_b128 v[194:197], v132 offset:49152
	ds_read_b128 v[198:201], v132 offset:50176
	buffer_load_dwordx4 v143, s[4:7], s45 offen lds
	s_mov_b32 m0, s26
	s_nop 0
	buffer_load_dwordx4 v144, s[4:7], s45 offen lds
	s_barrier
	s_waitcnt lgkmcnt(0)
	v_mfma_f32_16x16x32_bf16 v[60:63], v[154:157], v[170:173], v[60:63]
	v_mfma_f32_16x16x32_bf16 v[56:59], v[162:165], v[170:173], v[56:59]
	v_mfma_f32_16x16x32_bf16 v[52:55], v[154:157], v[178:181], v[52:55]
	v_mfma_f32_16x16x32_bf16 v[48:51], v[162:165], v[178:181], v[48:51]
	v_mfma_f32_16x16x32_bf16 v[44:47], v[154:157], v[186:189], v[44:47]
	v_mfma_f32_16x16x32_bf16 v[40:43], v[162:165], v[186:189], v[40:43]
	v_mfma_f32_16x16x32_bf16 v[36:39], v[154:157], v[194:197], v[36:39]
	v_mfma_f32_16x16x32_bf16 v[32:35], v[162:165], v[194:197], v[32:35]
	v_mfma_f32_16x16x32_bf16 v[60:63], v[158:161], v[174:177], v[60:63]
	v_mfma_f32_16x16x32_bf16 v[56:59], v[166:169], v[174:177], v[56:59]
	v_mfma_f32_16x16x32_bf16 v[52:55], v[158:161], v[182:185], v[52:55]
	v_mfma_f32_16x16x32_bf16 v[48:51], v[166:169], v[182:185], v[48:51]
	v_mfma_f32_16x16x32_bf16 v[44:47], v[158:161], v[190:193], v[44:47]
	v_mfma_f32_16x16x32_bf16 v[40:43], v[166:169], v[190:193], v[40:43]
	v_mfma_f32_16x16x32_bf16 v[36:39], v[158:161], v[198:201], v[36:39]
	v_mfma_f32_16x16x32_bf16 v[32:35], v[166:169], v[198:201], v[32:35]
	s_barrier
; #define STAGE(P, RS, SOFF, OFF, kt) do { const int _so = (SOFF) + (kt) * (BK * 2); \
;     _Pragma("unroll") for (int _i = 0; _i < 2; ++_i) { \
;       __builtin_amdgcn_raw_ptr_buffer_load_lds(RS, (__attribute__((address_space(3))) void*)((P) + wave * 1024 + _i * 8192), 16, OFF[_i], _so, 0, 0); } } while (0)
; #define LDA(dst, b, h) _Pragma("unroll") for (int m = 0; m < 4; ++m) _Pragma("unroll") for (int k = 0; k < 2; ++k) \
;     dst[m][k] = *reinterpret_cast<const bf16x8*>(SA(b, h) + lds_byte(wr * 64 + m * 16 + fr, k * 32 + fq * 8))
; #define LDB(dst, b, h) _Pragma("unroll") for (int n = 0; n < 2; ++n) _Pragma("unroll") for (int k = 0; k < 2; ++k) \
;     dst[n][k] = *reinterpret_cast<const bf16x8*>(SB(b, h) + lds_byte(wc * 32 + n * 16 + fr, k * 32 + fq * 8))
; #define WAIT_V(n) asm volatile("s_waitcnt vmcnt(" #n ")" ::: "memory")
; #define WAIT_L(n) asm volatile("s_waitcnt lgkmcnt(" #n ")" ::: "memory")
; #define BAR __builtin_amdgcn_s_barrier()
;     ...
;       STAGE(SB(1, 1), rsB, sB1, offB, t + 3);
;       WAIT_V(6); BAR; MMA(1, 1, At, B1); BAR;
;     }
;     { LDB(B0, 0, 0); LDA(At, 0, 0); STAGE(SA(1, 1), rsA, sA1, offA, nt - 1);
;       BAR; WAIT_L(0); MMA(0, 0, At, B0); BAR;
;       LDB(B1, 0, 1); BAR; WAIT_L(0); MMA(0, 1, At, B1); BAR;
;       LDA(At, 0, 1); WAIT_V(4); BAR; WAIT_L(0); MMA(1, 0, At, B0); MMA(1, 1, At, B1); BAR; }
	s_addk_i32 s46, 0x180
	s_mov_b32 m0, s27
	s_nop 0
	buffer_load_dwordx4 v143, s[8:11], s46 offen lds
	s_mov_b32 m0, s28
	s_nop 0
	buffer_load_dwordx4 v144, s[8:11], s46 offen lds
	s_add_i32 s16, s16, 2
	s_addk_i32 s17, 0x100
	s_cmp_gt_u32 s16, 27
	s_waitcnt vmcnt(6)
	s_barrier
	v_mfma_f32_16x16x32_bf16 v[28:31], v[202:205], v[170:173], v[28:31]
	v_mfma_f32_16x16x32_bf16 v[24:27], v[210:213], v[170:173], v[24:27]
	v_mfma_f32_16x16x32_bf16 v[20:23], v[202:205], v[178:181], v[20:23]
	v_mfma_f32_16x16x32_bf16 v[16:19], v[210:213], v[178:181], v[16:19]
	v_mfma_f32_16x16x32_bf16 v[12:15], v[202:205], v[186:189], v[12:15]
	v_mfma_f32_16x16x32_bf16 v[8:11], v[210:213], v[186:189], v[8:11]
	v_mfma_f32_16x16x32_bf16 v[4:7], v[202:205], v[194:197], v[4:7]
	v_mfma_f32_16x16x32_bf16 v[0:3], v[210:213], v[194:197], v[0:3]
	v_mfma_f32_16x16x32_bf16 v[28:31], v[206:209], v[174:177], v[28:31]
	v_mfma_f32_16x16x32_bf16 v[24:27], v[214:217], v[174:177], v[24:27]
	v_mfma_f32_16x16x32_bf16 v[20:23], v[206:209], v[182:185], v[20:23]
	v_mfma_f32_16x16x32_bf16 v[16:19], v[214:217], v[182:185], v[16:19]
	v_mfma_f32_16x16x32_bf16 v[12:15], v[206:209], v[190:193], v[12:15]
	v_mfma_f32_16x16x32_bf16 v[8:11], v[214:217], v[190:193], v[8:11]
	v_mfma_f32_16x16x32_bf16 v[4:7], v[206:209], v[198:201], v[4:7]
	v_mfma_f32_16x16x32_bf16 v[0:3], v[214:217], v[198:201], v[0:3]
	s_barrier
	s_cbranch_scc0 .LBB0_354
	s_add_i32 s10, s37, 0xf80
	s_mov_b32 m0, s30
	ds_read_b128 v[154:157], v149
	ds_read_b128 v[158:161], v150
	ds_read_b128 v[162:165], v151
	ds_read_b128 v[150:153], v152
	ds_read_b128 v[166:169], v131
	ds_read_b128 v[170:173], v131 offset:1024
	ds_read_b128 v[174:177], v134
	ds_read_b128 v[178:181], v134 offset:1024
	ds_read_b128 v[182:185], v133
	ds_read_b128 v[186:189], v133 offset:1024
	ds_read_b128 v[190:193], v132
	ds_read_b128 v[194:197], v132 offset:1024
	buffer_load_dwordx4 v143, s[4:7], s10 offen lds
	s_mov_b32 m0, s31
	s_nop 0
	buffer_load_dwordx4 v144, s[4:7], s10 offen lds
	s_barrier
	s_waitcnt lgkmcnt(0)
	v_mfma_f32_16x16x32_bf16 v[124:127], v[154:157], v[166:169], v[124:127]
	v_mfma_f32_16x16x32_bf16 v[120:123], v[162:165], v[166:169], v[120:123]
	v_mfma_f32_16x16x32_bf16 v[116:119], v[154:157], v[174:177], v[116:119]
	v_mfma_f32_16x16x32_bf16 v[112:115], v[162:165], v[174:177], v[112:115]
	v_mfma_f32_16x16x32_bf16 v[108:111], v[154:157], v[182:185], v[108:111]
	v_mfma_f32_16x16x32_bf16 v[104:107], v[162:165], v[182:185], v[104:107]
	v_mfma_f32_16x16x32_bf16 v[100:103], v[154:157], v[190:193], v[100:103]
	v_mfma_f32_16x16x32_bf16 v[96:99], v[162:165], v[190:193], v[96:99]
	v_mfma_f32_16x16x32_bf16 v[124:127], v[158:161], v[170:173], v[124:127]
	v_mfma_f32_16x16x32_bf16 v[120:123], v[150:153], v[170:173], v[120:123]
	v_mfma_f32_16x16x32_bf16 v[116:119], v[158:161], v[178:181], v[116:119]
	v_mfma_f32_16x16x32_bf16 v[112:115], v[150:153], v[178:181], v[112:115]
	v_mfma_f32_16x16x32_bf16 v[108:111], v[158:161], v[186:189], v[108:111]
	v_mfma_f32_16x16x32_bf16 v[104:107], v[150:153], v[186:189], v[104:107]
	v_mfma_f32_16x16x32_bf16 v[100:103], v[158:161], v[194:197], v[100:103]
	v_mfma_f32_16x16x32_bf16 v[96:99], v[150:153], v[194:197], v[96:99]
	s_barrier
	ds_read_b128 v[198:201], v145
	ds_read_b128 v[202:205], v146
	ds_read_b128 v[144:147], v147
	ds_read_b128 v[206:209], v148
	s_barrier
	s_waitcnt lgkmcnt(0)
	v_mfma_f32_16x16x32_bf16 v[92:95], v[198:201], v[166:169], v[92:95]
	v_mfma_f32_16x16x32_bf16 v[84:87], v[198:201], v[174:177], v[84:87]
	v_mfma_f32_16x16x32_bf16 v[76:79], v[198:201], v[182:185], v[76:79]
	v_mfma_f32_16x16x32_bf16 v[68:71], v[198:201], v[190:193], v[68:71]
	v_mfma_f32_16x16x32_bf16 v[88:91], v[144:147], v[166:169], v[88:91]
	v_mfma_f32_16x16x32_bf16 v[80:83], v[144:147], v[174:177], v[80:83]
	v_mfma_f32_16x16x32_bf16 v[72:75], v[144:147], v[182:185], v[72:75]
	v_mfma_f32_16x16x32_bf16 v[64:67], v[144:147], v[190:193], v[64:67]
	v_mfma_f32_16x16x32_bf16 v[92:95], v[202:205], v[170:173], v[92:95]
	v_mfma_f32_16x16x32_bf16 v[84:87], v[202:205], v[178:181], v[84:87]
	v_mfma_f32_16x16x32_bf16 v[76:79], v[202:205], v[186:189], v[76:79]
	v_mfma_f32_16x16x32_bf16 v[68:71], v[202:205], v[194:197], v[68:71]
	v_mfma_f32_16x16x32_bf16 v[166:169], v[206:209], v[170:173], v[88:91]
	v_mfma_f32_16x16x32_bf16 v[170:173], v[206:209], v[178:181], v[80:83]
	v_mfma_f32_16x16x32_bf16 v[174:177], v[206:209], v[186:189], v[72:75]
	v_mfma_f32_16x16x32_bf16 v[178:181], v[206:209], v[194:197], v[64:67]
	s_barrier
	s_nop 0
	ds_read_b128 v[64:67], v131 offset:16384
	ds_read_b128 v[72:75], v131 offset:17408
	ds_read_b128 v[80:83], v134 offset:16384
	ds_read_b128 v[88:91], v134 offset:17408
	ds_read_b128 v[182:185], v133 offset:16384
	ds_read_b128 v[186:189], v133 offset:17408
	ds_read_b128 v[190:193], v132 offset:16384
	ds_read_b128 v[194:197], v132 offset:17408
	s_waitcnt vmcnt(4)
	s_barrier
; #define LDA(dst, b, h) _Pragma("unroll") for (int m = 0; m < 4; ++m) _Pragma("unroll") for (int k = 0; k < 2; ++k) \
;     dst[m][k] = *reinterpret_cast<const bf16x8*>(SA(b, h) + lds_byte(wr * 64 + m * 16 + fr, k * 32 + fq * 8))
; #define LDB(dst, b, h) _Pragma("unroll") for (int n = 0; n < 2; ++n) _Pragma("unroll") for (int k = 0; k < 2; ++k) \
;     dst[n][k] = *reinterpret_cast<const bf16x8*>(SB(b, h) + lds_byte(wc * 32 + n * 16 + fr, k * 32 + fq * 8))
; #define WAIT_V(n) asm volatile("s_waitcnt vmcnt(" #n ")" ::: "memory")
; #define WAIT_L(n) asm volatile("s_waitcnt lgkmcnt(" #n ")" ::: "memory")
; #define BAR __builtin_amdgcn_s_barrier()
;     ...
;       LDA(At, 0, 1); WAIT_V(4); BAR; WAIT_L(0); MMA(1, 0, At, B0); MMA(1, 1, At, B1); BAR; }
;     { LDB(B0, 1, 0); LDA(At, 1, 0); WAIT_V(2); BAR; WAIT_L(0); MMA(0, 0, At, B0); BAR;
;       LDB(B1, 1, 1); WAIT_V(0); BAR; WAIT_L(0); MMA(0, 1, At, B1); BAR;
	s_waitcnt lgkmcnt(0)
	v_mfma_f32_16x16x32_bf16 v[60:63], v[154:157], v[64:67], v[60:63]
	v_mfma_f32_16x16x32_bf16 v[56:59], v[162:165], v[64:67], v[56:59]
	v_mfma_f32_16x16x32_bf16 v[52:55], v[154:157], v[80:83], v[52:55]
	v_mfma_f32_16x16x32_bf16 v[48:51], v[162:165], v[80:83], v[48:51]
	v_mfma_f32_16x16x32_bf16 v[44:47], v[154:157], v[182:185], v[44:47]
	v_mfma_f32_16x16x32_bf16 v[40:43], v[162:165], v[182:185], v[40:43]
	v_mfma_f32_16x16x32_bf16 v[36:39], v[154:157], v[190:193], v[36:39]
	v_mfma_f32_16x16x32_bf16 v[32:35], v[162:165], v[190:193], v[32:35]
	v_mfma_f32_16x16x32_bf16 v[60:63], v[158:161], v[72:75], v[60:63]
	v_mfma_f32_16x16x32_bf16 v[56:59], v[150:153], v[72:75], v[56:59]
	v_mfma_f32_16x16x32_bf16 v[52:55], v[158:161], v[88:91], v[52:55]
	v_mfma_f32_16x16x32_bf16 v[48:51], v[150:153], v[88:91], v[48:51]
	v_mfma_f32_16x16x32_bf16 v[44:47], v[158:161], v[186:189], v[44:47]
	v_mfma_f32_16x16x32_bf16 v[40:43], v[150:153], v[186:189], v[40:43]
	v_mfma_f32_16x16x32_bf16 v[36:39], v[158:161], v[194:197], v[36:39]
	v_mfma_f32_16x16x32_bf16 v[32:35], v[150:153], v[194:197], v[32:35]
	v_mfma_f32_16x16x32_bf16 v[28:31], v[198:201], v[64:67], v[28:31]
	v_mfma_f32_16x16x32_bf16 v[20:23], v[198:201], v[80:83], v[20:23]
	v_mfma_f32_16x16x32_bf16 v[12:15], v[198:201], v[182:185], v[12:15]
	v_mfma_f32_16x16x32_bf16 v[4:7], v[198:201], v[190:193], v[4:7]
	v_mfma_f32_16x16x32_bf16 v[24:27], v[144:147], v[64:67], v[24:27]
	v_mfma_f32_16x16x32_bf16 v[16:19], v[144:147], v[80:83], v[16:19]
	v_mfma_f32_16x16x32_bf16 v[8:11], v[144:147], v[182:185], v[8:11]
	v_mfma_f32_16x16x32_bf16 v[0:3], v[144:147], v[190:193], v[0:3]
	v_mfma_f32_16x16x32_bf16 v[28:31], v[202:205], v[72:75], v[28:31]
	v_mfma_f32_16x16x32_bf16 v[20:23], v[202:205], v[88:91], v[20:23]
	v_mfma_f32_16x16x32_bf16 v[12:15], v[202:205], v[186:189], v[12:15]
	v_mfma_f32_16x16x32_bf16 v[4:7], v[202:205], v[194:197], v[4:7]
	v_mfma_f32_16x16x32_bf16 v[144:147], v[206:209], v[72:75], v[24:27]
	v_mfma_f32_16x16x32_bf16 v[148:151], v[206:209], v[88:91], v[16:19]
	v_mfma_f32_16x16x32_bf16 v[152:155], v[206:209], v[186:189], v[8:11]
	v_mfma_f32_16x16x32_bf16 v[156:159], v[206:209], v[194:197], v[0:3]
	s_barrier
	s_nop 0
	ds_read_b128 v[0:3], v139
	ds_read_b128 v[8:11], v140
	ds_read_b128 v[16:19], v141
	ds_read_b128 v[140:143], v142
	ds_read_b128 v[24:27], v131 offset:32768
	ds_read_b128 v[160:163], v131 offset:33792
	ds_read_b128 v[182:185], v134 offset:32768
	ds_read_b128 v[186:189], v134 offset:33792
	ds_read_b128 v[190:193], v133 offset:32768
	ds_read_b128 v[194:197], v133 offset:33792
	ds_read_b128 v[198:201], v132 offset:32768
	ds_read_b128 v[202:205], v132 offset:33792
	s_waitcnt vmcnt(2)
	s_barrier
	s_waitcnt lgkmcnt(0)
	v_mfma_f32_16x16x32_bf16 v[64:67], v[0:3], v[24:27], v[124:127]
	v_mfma_f32_16x16x32_bf16 v[72:75], v[16:19], v[24:27], v[120:123]
	v_mfma_f32_16x16x32_bf16 v[80:83], v[0:3], v[182:185], v[116:119]
	v_mfma_f32_16x16x32_bf16 v[88:91], v[16:19], v[182:185], v[112:115]
	v_mfma_f32_16x16x32_bf16 v[108:111], v[0:3], v[190:193], v[108:111]
	v_mfma_f32_16x16x32_bf16 v[116:119], v[16:19], v[190:193], v[104:107]
	v_mfma_f32_16x16x32_bf16 v[100:103], v[0:3], v[198:201], v[100:103]
	v_mfma_f32_16x16x32_bf16 v[124:127], v[16:19], v[198:201], v[96:99]
	v_mfma_f32_16x16x32_bf16 v[120:123], v[8:11], v[160:163], v[64:67]
	v_mfma_f32_16x16x32_bf16 v[112:115], v[140:143], v[160:163], v[72:75]
	v_mfma_f32_16x16x32_bf16 v[104:107], v[8:11], v[186:189], v[80:83]
	v_mfma_f32_16x16x32_bf16 v[96:99], v[140:143], v[186:189], v[88:91]
	v_mfma_f32_16x16x32_bf16 v[88:91], v[8:11], v[194:197], v[108:111]
	v_mfma_f32_16x16x32_bf16 v[80:83], v[140:143], v[194:197], v[116:119]
	v_mfma_f32_16x16x32_bf16 v[72:75], v[8:11], v[202:205], v[100:103]
	v_mfma_f32_16x16x32_bf16 v[64:67], v[140:143], v[202:205], v[124:127]
	s_barrier
	ds_read_b128 v[206:209], v135
	ds_read_b128 v[210:213], v136
	ds_read_b128 v[214:217], v137
	ds_read_b128 v[136:139], v138
	s_waitcnt vmcnt(0)
	s_barrier
; #define LDA(dst, b, h) _Pragma("unroll") for (int m = 0; m < 4; ++m) _Pragma("unroll") for (int k = 0; k < 2; ++k) \
;     dst[m][k] = *reinterpret_cast<const bf16x8*>(SA(b, h) + lds_byte(wr * 64 + m * 16 + fr, k * 32 + fq * 8))
; #define LDB(dst, b, h) _Pragma("unroll") for (int n = 0; n < 2; ++n) _Pragma("unroll") for (int k = 0; k < 2; ++k) \
;     dst[n][k] = *reinterpret_cast<const bf16x8*>(SB(b, h) + lds_byte(wc * 32 + n * 16 + fr, k * 32 + fq * 8))
; #define WAIT_V(n) asm volatile("s_waitcnt vmcnt(" #n ")" ::: "memory")
; #define WAIT_L(n) asm volatile("s_waitcnt lgkmcnt(" #n ")" ::: "memory")
; #define BAR __builtin_amdgcn_s_barrier()
;     ...
;       LDB(B1, 1, 1); WAIT_V(0); BAR; WAIT_L(0); MMA(0, 1, At, B1); BAR;
;       LDA(At, 1, 1); BAR; WAIT_L(0); MMA(1, 0, At, B0); MMA(1, 1, At, B1); BAR; }
;     if (wr == 0) BAR;
	s_waitcnt lgkmcnt(0)
	v_mfma_f32_16x16x32_bf16 v[92:95], v[206:209], v[24:27], v[92:95]
	v_mfma_f32_16x16x32_bf16 v[24:27], v[214:217], v[24:27], v[166:169]
	v_mfma_f32_16x16x32_bf16 v[84:87], v[206:209], v[182:185], v[84:87]
	v_mfma_f32_16x16x32_bf16 v[100:103], v[214:217], v[182:185], v[170:173]
	v_mfma_f32_16x16x32_bf16 v[76:79], v[206:209], v[190:193], v[76:79]
	v_mfma_f32_16x16x32_bf16 v[164:167], v[214:217], v[190:193], v[174:177]
	v_mfma_f32_16x16x32_bf16 v[68:71], v[206:209], v[198:201], v[68:71]
	v_mfma_f32_16x16x32_bf16 v[168:171], v[214:217], v[198:201], v[178:181]
	v_mfma_f32_16x16x32_bf16 v[124:127], v[210:213], v[160:163], v[92:95]
	v_mfma_f32_16x16x32_bf16 v[116:119], v[136:139], v[160:163], v[24:27]
	v_mfma_f32_16x16x32_bf16 v[108:111], v[210:213], v[186:189], v[84:87]
	v_mfma_f32_16x16x32_bf16 v[100:103], v[136:139], v[186:189], v[100:103]
	v_mfma_f32_16x16x32_bf16 v[92:95], v[210:213], v[194:197], v[76:79]
	v_mfma_f32_16x16x32_bf16 v[84:87], v[136:139], v[194:197], v[164:167]
	v_mfma_f32_16x16x32_bf16 v[76:79], v[210:213], v[202:205], v[68:71]
	v_mfma_f32_16x16x32_bf16 v[68:71], v[136:139], v[202:205], v[168:171]
	s_barrier
	ds_read_b128 v[160:163], v131 offset:49152
	ds_read_b128 v[164:167], v131 offset:50176
	ds_read_b128 v[168:171], v134 offset:49152
	ds_read_b128 v[172:175], v134 offset:50176
	ds_read_b128 v[176:179], v133 offset:49152
	ds_read_b128 v[180:183], v133 offset:50176
	ds_read_b128 v[184:187], v132 offset:49152
	ds_read_b128 v[132:135], v132 offset:50176
	s_barrier
	s_waitcnt lgkmcnt(0)
	v_mfma_f32_16x16x32_bf16 v[24:27], v[0:3], v[160:163], v[60:63]
	v_mfma_f32_16x16x32_bf16 v[60:63], v[16:19], v[160:163], v[56:59]
	v_mfma_f32_16x16x32_bf16 v[52:55], v[0:3], v[168:171], v[52:55]
	v_mfma_f32_16x16x32_bf16 v[188:191], v[16:19], v[168:171], v[48:51]
	v_mfma_f32_16x16x32_bf16 v[44:47], v[0:3], v[176:179], v[44:47]
	v_mfma_f32_16x16x32_bf16 v[192:195], v[16:19], v[176:179], v[40:43]
	v_mfma_f32_16x16x32_bf16 v[0:3], v[0:3], v[184:187], v[36:39]
	v_mfma_f32_16x16x32_bf16 v[36:39], v[16:19], v[184:187], v[32:35]
	v_mfma_f32_16x16x32_bf16 v[56:59], v[8:11], v[164:167], v[24:27]
	v_mfma_f32_16x16x32_bf16 v[48:51], v[140:143], v[164:167], v[60:63]
	v_mfma_f32_16x16x32_bf16 v[40:43], v[8:11], v[172:175], v[52:55]
	v_mfma_f32_16x16x32_bf16 v[32:35], v[140:143], v[172:175], v[188:191]
	v_mfma_f32_16x16x32_bf16 v[24:27], v[8:11], v[180:183], v[44:47]
	v_mfma_f32_16x16x32_bf16 v[16:19], v[140:143], v[180:183], v[192:195]
	v_mfma_f32_16x16x32_bf16 v[8:11], v[8:11], v[132:135], v[0:3]
	v_mfma_f32_16x16x32_bf16 v[0:3], v[140:143], v[132:135], v[36:39]
	v_mfma_f32_16x16x32_bf16 v[28:31], v[206:209], v[160:163], v[28:31]
	v_mfma_f32_16x16x32_bf16 v[36:39], v[214:217], v[160:163], v[144:147]
	v_mfma_f32_16x16x32_bf16 v[20:23], v[206:209], v[168:171], v[20:23]
	v_mfma_f32_16x16x32_bf16 v[140:143], v[214:217], v[168:171], v[148:151]
	v_mfma_f32_16x16x32_bf16 v[12:15], v[206:209], v[176:179], v[12:15]
	v_mfma_f32_16x16x32_bf16 v[144:147], v[214:217], v[176:179], v[152:155]
	v_mfma_f32_16x16x32_bf16 v[4:7], v[206:209], v[184:187], v[4:7]
	v_mfma_f32_16x16x32_bf16 v[148:151], v[214:217], v[184:187], v[156:159]
	v_mfma_f32_16x16x32_bf16 v[60:63], v[210:213], v[164:167], v[28:31]
	v_mfma_f32_16x16x32_bf16 v[52:55], v[136:139], v[164:167], v[36:39]
	v_mfma_f32_16x16x32_bf16 v[44:47], v[210:213], v[172:175], v[20:23]
	v_mfma_f32_16x16x32_bf16 v[36:39], v[136:139], v[172:175], v[140:143]
	v_mfma_f32_16x16x32_bf16 v[28:31], v[210:213], v[180:183], v[12:15]
	v_mfma_f32_16x16x32_bf16 v[20:23], v[136:139], v[180:183], v[144:147]
	v_mfma_f32_16x16x32_bf16 v[12:15], v[210:213], v[132:135], v[4:7]
	v_mfma_f32_16x16x32_bf16 v[4:7], v[136:139], v[132:135], v[148:151]
	v_cmp_gt_u32_e32 vcc, s35, v130
	s_barrier
	s_and_saveexec_b64 s[10:11], vcc
	s_cbranch_execz .LBB0_357
	s_barrier

; #define STAGE(P, RS, SOFF, OFF, kt) do { const int _so = (SOFF) + (kt) * (BK * 2); \
;     _Pragma("unroll") for (int _i = 0; _i < 2; ++_i) { \
;       __builtin_amdgcn_raw_ptr_buffer_load_lds(RS, (__attribute__((address_space(3))) void*)((P) + wave * 1024 + _i * 8192), 16, OFF[_i], _so, 0, 0); } } while (0)
; #define LDA(dst, b, h) _Pragma("unroll") for (int m = 0; m < 4; ++m) _Pragma("unroll") for (int k = 0; k < 2; ++k) \
;     dst[m][k] = *reinterpret_cast<const bf16x8*>(SA(b, h) + lds_byte(wr * 64 + m * 16 + fr, k * 32 + fq * 8))
; #define LDB(dst, b, h) _Pragma("unroll") for (int n = 0; n < 2; ++n) _Pragma("unroll") for (int k = 0; k < 2; ++k) \
;     dst[n][k] = *reinterpret_cast<const bf16x8*>(SB(b, h) + lds_byte(wc * 32 + n * 16 + fr, k * 32 + fq * 8))
; #define WAIT_V(n) asm volatile("s_waitcnt vmcnt(" #n ")" ::: "memory")
; #define WAIT_L(n) asm volatile("s_waitcnt lgkmcnt(" #n ")" ::: "memory")
; #define BAR __builtin_amdgcn_s_barrier()
; #define SCHED __builtin_amdgcn_sched_barrier(0)
;     ...
;       LDB(B0, 0, 0); SCHED; LDA(At, 0, 0); STAGE(SA(1, 1), rsA, sA1, offA, t + 1);
;       WAIT_L(8); BAR; WAIT_L(0); MMA(0, 0, At, B0); BAR; SCHED;
;       LDB(B1, 0, 1); STAGE(SB(0, 0), rsB, sB0, offB, t + 2);
;       BAR; WAIT_L(0); MMA(0, 1, At, B1); BAR;
;       LDA(At, 0, 1); STAGE(SA(0, 0), rsA, sA0, offA, t + 2);
;       BAR; WAIT_L(0); MMA(1, 0, At, B0); BAR; SCHED;
;       STAGE(SB(0, 1), rsB, sB1, offB, t + 2);
;       WAIT_V(6); BAR; MMA(1, 1, At, B1); BAR;
.LBB0_392:
	ds_read_b128 v[152:155], v147
	ds_read_b128 v[156:159], v148
	ds_read_b128 v[160:163], v149
	ds_read_b128 v[164:167], v150
	s_add_i32 s5, s86, s3
	s_add_i32 s6, s5, 0x80
	s_mov_b32 m0, s36
	ds_read_b128 v[168:171], v129
	ds_read_b128 v[172:175], v129 offset:1024
	ds_read_b128 v[176:179], v132
	ds_read_b128 v[180:183], v132 offset:1024
	ds_read_b128 v[184:187], v131
	ds_read_b128 v[188:191], v131 offset:1024
	ds_read_b128 v[192:195], v130
	ds_read_b128 v[196:199], v130 offset:1024
	buffer_load_dwordx4 v141, s[8:11], s6 offen lds
	s_mov_b32 m0, s59
	s_nop 0
	buffer_load_dwordx4 v142, s[8:11], s6 offen lds
	s_waitcnt lgkmcnt(8)
	s_barrier
	s_waitcnt lgkmcnt(0)
	v_mfma_f32_16x16x32_bf16 v[124:127], v[152:155], v[168:171], v[124:127]
	v_mfma_f32_16x16x32_bf16 v[120:123], v[160:163], v[168:171], v[120:123]
	v_mfma_f32_16x16x32_bf16 v[116:119], v[152:155], v[176:179], v[116:119]
	v_mfma_f32_16x16x32_bf16 v[112:115], v[160:163], v[176:179], v[112:115]
	v_mfma_f32_16x16x32_bf16 v[108:111], v[152:155], v[184:187], v[108:111]
	v_mfma_f32_16x16x32_bf16 v[104:107], v[160:163], v[184:187], v[104:107]
	v_mfma_f32_16x16x32_bf16 v[100:103], v[152:155], v[192:195], v[100:103]
	v_mfma_f32_16x16x32_bf16 v[96:99], v[160:163], v[192:195], v[96:99]
	v_mfma_f32_16x16x32_bf16 v[124:127], v[156:159], v[172:175], v[124:127]
	v_mfma_f32_16x16x32_bf16 v[120:123], v[164:167], v[172:175], v[120:123]
	v_mfma_f32_16x16x32_bf16 v[116:119], v[156:159], v[180:183], v[116:119]
	v_mfma_f32_16x16x32_bf16 v[112:115], v[164:167], v[180:183], v[112:115]
	v_mfma_f32_16x16x32_bf16 v[108:111], v[156:159], v[188:191], v[108:111]
	v_mfma_f32_16x16x32_bf16 v[104:107], v[164:167], v[188:191], v[104:107]
	v_mfma_f32_16x16x32_bf16 v[100:103], v[156:159], v[196:199], v[100:103]
	v_mfma_f32_16x16x32_bf16 v[96:99], v[164:167], v[196:199], v[96:99]
	s_barrier
	s_add_i32 s6, s92, s3
	s_add_i32 s7, s6, 0x100
	s_mov_b32 s14, s10
	s_mov_b32 s15, s11
	s_mov_b32 m0, s37
	ds_read_b128 v[200:203], v143
	ds_read_b128 v[204:207], v144
	ds_read_b128 v[208:211], v145
	ds_read_b128 v[212:215], v146
	buffer_load_dwordx4 v141, s[12:15], s7 offen lds
	s_mov_b32 m0, s48
	s_nop 0
	buffer_load_dwordx4 v142, s[12:15], s7 offen lds
	s_barrier
	s_waitcnt lgkmcnt(0)
	v_mfma_f32_16x16x32_bf16 v[92:95], v[200:203], v[168:171], v[92:95]
	v_mfma_f32_16x16x32_bf16 v[88:91], v[208:211], v[168:171], v[88:91]
	v_mfma_f32_16x16x32_bf16 v[80:83], v[200:203], v[176:179], v[80:83]
	v_mfma_f32_16x16x32_bf16 v[68:71], v[208:211], v[176:179], v[68:71]
	v_mfma_f32_16x16x32_bf16 v[60:63], v[200:203], v[184:187], v[60:63]
	v_mfma_f32_16x16x32_bf16 v[56:59], v[208:211], v[184:187], v[56:59]
	v_mfma_f32_16x16x32_bf16 v[52:55], v[200:203], v[192:195], v[52:55]
	v_mfma_f32_16x16x32_bf16 v[48:51], v[208:211], v[192:195], v[48:51]
	v_mfma_f32_16x16x32_bf16 v[92:95], v[204:207], v[172:175], v[92:95]
	v_mfma_f32_16x16x32_bf16 v[88:91], v[212:215], v[172:175], v[88:91]
	v_mfma_f32_16x16x32_bf16 v[80:83], v[204:207], v[180:183], v[80:83]
	v_mfma_f32_16x16x32_bf16 v[68:71], v[212:215], v[180:183], v[68:71]
	v_mfma_f32_16x16x32_bf16 v[60:63], v[204:207], v[188:191], v[60:63]
	v_mfma_f32_16x16x32_bf16 v[56:59], v[212:215], v[188:191], v[56:59]
	v_mfma_f32_16x16x32_bf16 v[52:55], v[204:207], v[196:199], v[52:55]
	v_mfma_f32_16x16x32_bf16 v[48:51], v[212:215], v[196:199], v[48:51]
	s_barrier
	s_add_i32 s7, s87, s3
	s_add_i32 s22, s7, 0x100
	s_mov_b32 m0, s35
	ds_read_b128 v[168:171], v129 offset:16384
	ds_read_b128 v[172:175], v129 offset:17408
	ds_read_b128 v[176:179], v132 offset:16384
	ds_read_b128 v[180:183], v132 offset:17408
	ds_read_b128 v[184:187], v131 offset:16384
	ds_read_b128 v[188:191], v131 offset:17408
	ds_read_b128 v[192:195], v130 offset:16384
	ds_read_b128 v[196:199], v130 offset:17408
	buffer_load_dwordx4 v141, s[8:11], s22 offen lds
	s_mov_b32 m0, s49
	s_nop 0
	buffer_load_dwordx4 v142, s[8:11], s22 offen lds
	s_barrier
	s_waitcnt lgkmcnt(0)
	v_mfma_f32_16x16x32_bf16 v[44:47], v[152:155], v[168:171], v[44:47]
	v_mfma_f32_16x16x32_bf16 v[40:43], v[160:163], v[168:171], v[40:43]
	v_mfma_f32_16x16x32_bf16 v[36:39], v[152:155], v[176:179], v[36:39]
	v_mfma_f32_16x16x32_bf16 v[32:35], v[160:163], v[176:179], v[32:35]
	v_mfma_f32_16x16x32_bf16 v[28:31], v[152:155], v[184:187], v[28:31]
	v_mfma_f32_16x16x32_bf16 v[24:27], v[160:163], v[184:187], v[24:27]
	v_mfma_f32_16x16x32_bf16 v[20:23], v[152:155], v[192:195], v[20:23]
	v_mfma_f32_16x16x32_bf16 v[16:19], v[160:163], v[192:195], v[16:19]
	v_mfma_f32_16x16x32_bf16 v[44:47], v[156:159], v[172:175], v[44:47]
	v_mfma_f32_16x16x32_bf16 v[40:43], v[164:167], v[172:175], v[40:43]
	v_mfma_f32_16x16x32_bf16 v[36:39], v[156:159], v[180:183], v[36:39]
	v_mfma_f32_16x16x32_bf16 v[32:35], v[164:167], v[180:183], v[32:35]
	v_mfma_f32_16x16x32_bf16 v[28:31], v[156:159], v[188:191], v[28:31]
	v_mfma_f32_16x16x32_bf16 v[24:27], v[164:167], v[188:191], v[24:27]
	v_mfma_f32_16x16x32_bf16 v[20:23], v[156:159], v[196:199], v[20:23]
	v_mfma_f32_16x16x32_bf16 v[16:19], v[164:167], v[196:199], v[16:19]
	s_barrier
	s_add_i32 s22, s93, s3
	s_add_i32 s23, s22, 0x100
	s_mov_b32 m0, s38
	s_nop 0
	buffer_load_dwordx4 v141, s[12:15], s23 offen lds
	s_mov_b32 m0, s54
	s_nop 0
	buffer_load_dwordx4 v142, s[12:15], s23 offen lds
	s_waitcnt vmcnt(6)
	s_barrier
; #define STAGE(P, RS, SOFF, OFF, kt) do { const int _so = (SOFF) + (kt) * (BK * 2); \
;     _Pragma("unroll") for (int _i = 0; _i < 2; ++_i) { \
;       __builtin_amdgcn_raw_ptr_buffer_load_lds(RS, (__attribute__((address_space(3))) void*)((P) + wave * 1024 + _i * 8192), 16, OFF[_i], _so, 0, 0); } } while (0)
; #define LDA(dst, b, h) _Pragma("unroll") for (int m = 0; m < 4; ++m) _Pragma("unroll") for (int k = 0; k < 2; ++k) \
;     dst[m][k] = *reinterpret_cast<const bf16x8*>(SA(b, h) + lds_byte(wr * 64 + m * 16 + fr, k * 32 + fq * 8))
; #define LDB(dst, b, h) _Pragma("unroll") for (int n = 0; n < 2; ++n) _Pragma("unroll") for (int k = 0; k < 2; ++k) \
;     dst[n][k] = *reinterpret_cast<const bf16x8*>(SB(b, h) + lds_byte(wc * 32 + n * 16 + fr, k * 32 + fq * 8))
; #define WAIT_V(n) asm volatile("s_waitcnt vmcnt(" #n ")" ::: "memory")
; #define WAIT_L(n) asm volatile("s_waitcnt lgkmcnt(" #n ")" ::: "memory")
; #define BAR __builtin_amdgcn_s_barrier()
; #define SCHED __builtin_amdgcn_sched_barrier(0)
;     ...
;       WAIT_V(6); BAR; MMA(1, 1, At, B1); BAR;
;       LDB(B0, 1, 0); SCHED; LDA(At, 1, 0); STAGE(SA(0, 1), rsA, sA1, offA, t + 2);
;       WAIT_L(8); BAR; WAIT_L(0); MMA(0, 0, At, B0); BAR; SCHED;
;       LDB(B1, 1, 1); STAGE(SB(1, 0), rsB, sB0, offB, t + 3);
;       BAR; WAIT_L(0); MMA(0, 1, At, B1); BAR;
;       LDA(At, 1, 1); STAGE(SA(1, 0), rsA, sA0, offA, t + 3);
;       BAR; WAIT_L(0); MMA(1, 0, At, B0); BAR; SCHED;
	v_mfma_f32_16x16x32_bf16 v[12:15], v[200:203], v[168:171], v[12:15]
	v_mfma_f32_16x16x32_bf16 v[8:11], v[208:211], v[168:171], v[8:11]
	v_mfma_f32_16x16x32_bf16 v[4:7], v[200:203], v[176:179], v[4:7]
	v_mfma_f32_16x16x32_bf16 v[0:3], v[208:211], v[176:179], v[0:3]
	v_mfma_f32_16x16x32_bf16 v[64:67], v[200:203], v[184:187], v[64:67]
	v_mfma_f32_16x16x32_bf16 v[72:75], v[208:211], v[184:187], v[72:75]
	v_mfma_f32_16x16x32_bf16 v[76:79], v[200:203], v[192:195], v[76:79]
	v_mfma_f32_16x16x32_bf16 v[84:87], v[208:211], v[192:195], v[84:87]
	v_mfma_f32_16x16x32_bf16 v[12:15], v[204:207], v[172:175], v[12:15]
	v_mfma_f32_16x16x32_bf16 v[8:11], v[212:215], v[172:175], v[8:11]
	v_mfma_f32_16x16x32_bf16 v[4:7], v[204:207], v[180:183], v[4:7]
	v_mfma_f32_16x16x32_bf16 v[0:3], v[212:215], v[180:183], v[0:3]
	v_mfma_f32_16x16x32_bf16 v[64:67], v[204:207], v[188:191], v[64:67]
	v_mfma_f32_16x16x32_bf16 v[72:75], v[212:215], v[188:191], v[72:75]
	v_mfma_f32_16x16x32_bf16 v[76:79], v[204:207], v[196:199], v[76:79]
	v_mfma_f32_16x16x32_bf16 v[84:87], v[212:215], v[196:199], v[84:87]
	s_barrier
	ds_read_b128 v[152:155], v137
	ds_read_b128 v[156:159], v138
	ds_read_b128 v[160:163], v139
	ds_read_b128 v[164:167], v140
	s_addk_i32 s5, 0x100
	s_mov_b32 m0, s39
	ds_read_b128 v[168:171], v129 offset:32768
	ds_read_b128 v[172:175], v129 offset:33792
	ds_read_b128 v[176:179], v132 offset:32768
	ds_read_b128 v[180:183], v132 offset:33792
	ds_read_b128 v[184:187], v131 offset:32768
	ds_read_b128 v[188:191], v131 offset:33792
	ds_read_b128 v[192:195], v130 offset:32768
	ds_read_b128 v[196:199], v130 offset:33792
	buffer_load_dwordx4 v141, s[8:11], s5 offen lds
	s_mov_b32 m0, s55
	s_nop 0
	buffer_load_dwordx4 v142, s[8:11], s5 offen lds
	s_waitcnt lgkmcnt(8)
	s_barrier
	s_waitcnt lgkmcnt(0)
	v_mfma_f32_16x16x32_bf16 v[124:127], v[152:155], v[168:171], v[124:127]
	v_mfma_f32_16x16x32_bf16 v[120:123], v[160:163], v[168:171], v[120:123]
	v_mfma_f32_16x16x32_bf16 v[116:119], v[152:155], v[176:179], v[116:119]
	v_mfma_f32_16x16x32_bf16 v[112:115], v[160:163], v[176:179], v[112:115]
	v_mfma_f32_16x16x32_bf16 v[108:111], v[152:155], v[184:187], v[108:111]
	v_mfma_f32_16x16x32_bf16 v[104:107], v[160:163], v[184:187], v[104:107]
	v_mfma_f32_16x16x32_bf16 v[100:103], v[152:155], v[192:195], v[100:103]
	v_mfma_f32_16x16x32_bf16 v[96:99], v[160:163], v[192:195], v[96:99]
	v_mfma_f32_16x16x32_bf16 v[124:127], v[156:159], v[172:175], v[124:127]
	v_mfma_f32_16x16x32_bf16 v[120:123], v[164:167], v[172:175], v[120:123]
	v_mfma_f32_16x16x32_bf16 v[116:119], v[156:159], v[180:183], v[116:119]
	v_mfma_f32_16x16x32_bf16 v[112:115], v[164:167], v[180:183], v[112:115]
	v_mfma_f32_16x16x32_bf16 v[108:111], v[156:159], v[188:191], v[108:111]
	v_mfma_f32_16x16x32_bf16 v[104:107], v[164:167], v[188:191], v[104:107]
	v_mfma_f32_16x16x32_bf16 v[100:103], v[156:159], v[196:199], v[100:103]
	v_mfma_f32_16x16x32_bf16 v[96:99], v[164:167], v[196:199], v[96:99]
	s_barrier
	s_addk_i32 s6, 0x180
	s_mov_b32 m0, s42
	ds_read_b128 v[200:203], v133
	ds_read_b128 v[204:207], v134
	ds_read_b128 v[208:211], v135
	ds_read_b128 v[212:215], v136
	buffer_load_dwordx4 v141, s[12:15], s6 offen lds
	s_mov_b32 m0, s56
	s_nop 0
	buffer_load_dwordx4 v142, s[12:15], s6 offen lds
	s_barrier
	s_waitcnt lgkmcnt(0)
	v_mfma_f32_16x16x32_bf16 v[92:95], v[200:203], v[168:171], v[92:95]
	v_mfma_f32_16x16x32_bf16 v[88:91], v[208:211], v[168:171], v[88:91]
	v_mfma_f32_16x16x32_bf16 v[80:83], v[200:203], v[176:179], v[80:83]
	v_mfma_f32_16x16x32_bf16 v[68:71], v[208:211], v[176:179], v[68:71]
	v_mfma_f32_16x16x32_bf16 v[60:63], v[200:203], v[184:187], v[60:63]
	v_mfma_f32_16x16x32_bf16 v[56:59], v[208:211], v[184:187], v[56:59]
	v_mfma_f32_16x16x32_bf16 v[52:55], v[200:203], v[192:195], v[52:55]
	v_mfma_f32_16x16x32_bf16 v[48:51], v[208:211], v[192:195], v[48:51]
	v_mfma_f32_16x16x32_bf16 v[92:95], v[204:207], v[172:175], v[92:95]
	v_mfma_f32_16x16x32_bf16 v[88:91], v[212:215], v[172:175], v[88:91]
	v_mfma_f32_16x16x32_bf16 v[80:83], v[204:207], v[180:183], v[80:83]
	v_mfma_f32_16x16x32_bf16 v[68:71], v[212:215], v[180:183], v[68:71]
	v_mfma_f32_16x16x32_bf16 v[60:63], v[204:207], v[188:191], v[60:63]
	v_mfma_f32_16x16x32_bf16 v[56:59], v[212:215], v[188:191], v[56:59]
	v_mfma_f32_16x16x32_bf16 v[52:55], v[204:207], v[196:199], v[52:55]
	v_mfma_f32_16x16x32_bf16 v[48:51], v[212:215], v[196:199], v[48:51]
	s_barrier
	s_addk_i32 s7, 0x180
	s_mov_b32 m0, s43
	ds_read_b128 v[168:171], v129 offset:49152
	ds_read_b128 v[172:175], v129 offset:50176
	ds_read_b128 v[176:179], v132 offset:49152
	ds_read_b128 v[180:183], v132 offset:50176
	ds_read_b128 v[184:187], v131 offset:49152
	ds_read_b128 v[188:191], v131 offset:50176
	ds_read_b128 v[192:195], v130 offset:49152
	ds_read_b128 v[196:199], v130 offset:50176
	buffer_load_dwordx4 v141, s[8:11], s7 offen lds
	s_mov_b32 m0, s57
	s_nop 0
	buffer_load_dwordx4 v142, s[8:11], s7 offen lds
	s_barrier
	s_waitcnt lgkmcnt(0)
	v_mfma_f32_16x16x32_bf16 v[44:47], v[152:155], v[168:171], v[44:47]
	v_mfma_f32_16x16x32_bf16 v[40:43], v[160:163], v[168:171], v[40:43]
	v_mfma_f32_16x16x32_bf16 v[36:39], v[152:155], v[176:179], v[36:39]
	v_mfma_f32_16x16x32_bf16 v[32:35], v[160:163], v[176:179], v[32:35]
	v_mfma_f32_16x16x32_bf16 v[28:31], v[152:155], v[184:187], v[28:31]
	v_mfma_f32_16x16x32_bf16 v[24:27], v[160:163], v[184:187], v[24:27]
	v_mfma_f32_16x16x32_bf16 v[20:23], v[152:155], v[192:195], v[20:23]
	v_mfma_f32_16x16x32_bf16 v[16:19], v[160:163], v[192:195], v[16:19]
	v_mfma_f32_16x16x32_bf16 v[44:47], v[156:159], v[172:175], v[44:47]
	v_mfma_f32_16x16x32_bf16 v[40:43], v[164:167], v[172:175], v[40:43]
	v_mfma_f32_16x16x32_bf16 v[36:39], v[156:159], v[180:183], v[36:39]
	v_mfma_f32_16x16x32_bf16 v[32:35], v[164:167], v[180:183], v[32:35]
	v_mfma_f32_16x16x32_bf16 v[28:31], v[156:159], v[188:191], v[28:31]
	v_mfma_f32_16x16x32_bf16 v[24:27], v[164:167], v[188:191], v[24:27]
	v_mfma_f32_16x16x32_bf16 v[20:23], v[156:159], v[196:199], v[20:23]
	v_mfma_f32_16x16x32_bf16 v[16:19], v[164:167], v[196:199], v[16:19]
	s_barrier
; #define STAGE(P, RS, SOFF, OFF, kt) do { const int _so = (SOFF) + (kt) * (BK * 2); \
;     _Pragma("unroll") for (int _i = 0; _i < 2; ++_i) { \
;       __builtin_amdgcn_raw_ptr_buffer_load_lds(RS, (__attribute__((address_space(3))) void*)((P) + wave * 1024 + _i * 8192), 16, OFF[_i], _so, 0, 0); } } while (0)
; #define LDA(dst, b, h) _Pragma("unroll") for (int m = 0; m < 4; ++m) _Pragma("unroll") for (int k = 0; k < 2; ++k) \
;     dst[m][k] = *reinterpret_cast<const bf16x8*>(SA(b, h) + lds_byte(wr * 64 + m * 16 + fr, k * 32 + fq * 8))
; #define LDB(dst, b, h) _Pragma("unroll") for (int n = 0; n < 2; ++n) _Pragma("unroll") for (int k = 0; k < 2; ++k) \
;     dst[n][k] = *reinterpret_cast<const bf16x8*>(SB(b, h) + lds_byte(wc * 32 + n * 16 + fr, k * 32 + fq * 8))
; #define WAIT_V(n) asm volatile("s_waitcnt vmcnt(" #n ")" ::: "memory")
; #define WAIT_L(n) asm volatile("s_waitcnt lgkmcnt(" #n ")" ::: "memory")
; #define BAR __builtin_amdgcn_s_barrier()
;     ...
;       STAGE(SB(1, 1), rsB, sB1, offB, t + 3);
;       WAIT_V(6); BAR; MMA(1, 1, At, B1); BAR;
;     }
;     { LDB(B0, 0, 0); LDA(At, 0, 0); STAGE(SA(1, 1), rsA, sA1, offA, nt - 1);
;       BAR; WAIT_L(0); MMA(0, 0, At, B0); BAR;
;       LDB(B1, 0, 1); BAR; WAIT_L(0); MMA(0, 1, At, B1); BAR;
;       LDA(At, 0, 1); WAIT_V(4); BAR; WAIT_L(0); MMA(1, 0, At, B0); MMA(1, 1, At, B1); BAR; }
	s_addk_i32 s22, 0x180
	s_mov_b32 m0, s44
	s_nop 0
	buffer_load_dwordx4 v141, s[12:15], s22 offen lds
	s_mov_b32 m0, s58
	s_nop 0
	buffer_load_dwordx4 v142, s[12:15], s22 offen lds
	s_add_i32 s1, s1, 2
	s_addk_i32 s3, 0x100
	s_cmp_gt_u32 s1, 59
	s_waitcnt vmcnt(6)
	s_barrier
	v_mfma_f32_16x16x32_bf16 v[12:15], v[200:203], v[168:171], v[12:15]
	v_mfma_f32_16x16x32_bf16 v[8:11], v[208:211], v[168:171], v[8:11]
	v_mfma_f32_16x16x32_bf16 v[4:7], v[200:203], v[176:179], v[4:7]
	v_mfma_f32_16x16x32_bf16 v[0:3], v[208:211], v[176:179], v[0:3]
	v_mfma_f32_16x16x32_bf16 v[64:67], v[200:203], v[184:187], v[64:67]
	v_mfma_f32_16x16x32_bf16 v[72:75], v[208:211], v[184:187], v[72:75]
	v_mfma_f32_16x16x32_bf16 v[76:79], v[200:203], v[192:195], v[76:79]
	v_mfma_f32_16x16x32_bf16 v[84:87], v[208:211], v[192:195], v[84:87]
	v_mfma_f32_16x16x32_bf16 v[12:15], v[204:207], v[172:175], v[12:15]
	v_mfma_f32_16x16x32_bf16 v[8:11], v[212:215], v[172:175], v[8:11]
	v_mfma_f32_16x16x32_bf16 v[4:7], v[204:207], v[180:183], v[4:7]
	v_mfma_f32_16x16x32_bf16 v[0:3], v[212:215], v[180:183], v[0:3]
	v_mfma_f32_16x16x32_bf16 v[64:67], v[204:207], v[188:191], v[64:67]
	v_mfma_f32_16x16x32_bf16 v[72:75], v[212:215], v[188:191], v[72:75]
	v_mfma_f32_16x16x32_bf16 v[76:79], v[204:207], v[196:199], v[76:79]
	v_mfma_f32_16x16x32_bf16 v[84:87], v[212:215], v[196:199], v[84:87]
	s_barrier
	s_cbranch_scc0 .LBB0_392
	s_add_i32 s1, s86, 0x1f80
	s_mov_b32 m0, s36
	ds_read_b128 v[152:155], v147
	ds_read_b128 v[156:159], v148
	ds_read_b128 v[160:163], v149
	ds_read_b128 v[148:151], v150
	ds_read_b128 v[164:167], v129
	ds_read_b128 v[168:171], v129 offset:1024
	ds_read_b128 v[172:175], v132
	ds_read_b128 v[176:179], v132 offset:1024
	ds_read_b128 v[180:183], v131
	ds_read_b128 v[184:187], v131 offset:1024
	ds_read_b128 v[188:191], v130
	ds_read_b128 v[192:195], v130 offset:1024
	buffer_load_dwordx4 v141, s[8:11], s1 offen lds
	s_mov_b32 m0, s59
	s_nop 0
	buffer_load_dwordx4 v142, s[8:11], s1 offen lds
	s_barrier
	s_waitcnt lgkmcnt(0)
	v_mfma_f32_16x16x32_bf16 v[124:127], v[152:155], v[164:167], v[124:127]
	v_mfma_f32_16x16x32_bf16 v[120:123], v[160:163], v[164:167], v[120:123]
	v_mfma_f32_16x16x32_bf16 v[116:119], v[152:155], v[172:175], v[116:119]
	v_mfma_f32_16x16x32_bf16 v[112:115], v[160:163], v[172:175], v[112:115]
	v_mfma_f32_16x16x32_bf16 v[108:111], v[152:155], v[180:183], v[108:111]
	v_mfma_f32_16x16x32_bf16 v[104:107], v[160:163], v[180:183], v[104:107]
	v_mfma_f32_16x16x32_bf16 v[100:103], v[152:155], v[188:191], v[100:103]
	v_mfma_f32_16x16x32_bf16 v[96:99], v[160:163], v[188:191], v[96:99]
	v_mfma_f32_16x16x32_bf16 v[124:127], v[156:159], v[168:171], v[124:127]
	v_mfma_f32_16x16x32_bf16 v[120:123], v[148:151], v[168:171], v[120:123]
	v_mfma_f32_16x16x32_bf16 v[116:119], v[156:159], v[176:179], v[116:119]
	v_mfma_f32_16x16x32_bf16 v[112:115], v[148:151], v[176:179], v[112:115]
	v_mfma_f32_16x16x32_bf16 v[108:111], v[156:159], v[184:187], v[108:111]
	v_mfma_f32_16x16x32_bf16 v[104:107], v[148:151], v[184:187], v[104:107]
	v_mfma_f32_16x16x32_bf16 v[100:103], v[156:159], v[192:195], v[100:103]
	v_mfma_f32_16x16x32_bf16 v[96:99], v[148:151], v[192:195], v[96:99]
	s_barrier
	ds_read_b128 v[196:199], v143
	ds_read_b128 v[200:203], v144
	ds_read_b128 v[142:145], v145
	ds_read_b128 v[204:207], v146
	s_barrier
	s_waitcnt lgkmcnt(0)
	v_mfma_f32_16x16x32_bf16 v[80:83], v[196:199], v[172:175], v[80:83]
	v_mfma_f32_16x16x32_bf16 v[68:71], v[142:145], v[172:175], v[68:71]
	v_mfma_f32_16x16x32_bf16 v[60:63], v[196:199], v[180:183], v[60:63]
	v_mfma_f32_16x16x32_bf16 v[56:59], v[142:145], v[180:183], v[56:59]
	v_mfma_f32_16x16x32_bf16 v[52:55], v[196:199], v[188:191], v[52:55]
	v_mfma_f32_16x16x32_bf16 v[48:51], v[142:145], v[188:191], v[48:51]
	v_mfma_f32_16x16x32_bf16 v[92:95], v[196:199], v[164:167], v[92:95]
	v_mfma_f32_16x16x32_bf16 v[88:91], v[142:145], v[164:167], v[88:91]
	v_mfma_f32_16x16x32_bf16 v[80:83], v[200:203], v[176:179], v[80:83]
	v_mfma_f32_16x16x32_bf16 v[68:71], v[204:207], v[176:179], v[68:71]
	v_mfma_f32_16x16x32_bf16 v[60:63], v[200:203], v[184:187], v[60:63]
	v_mfma_f32_16x16x32_bf16 v[56:59], v[204:207], v[184:187], v[56:59]
	v_mfma_f32_16x16x32_bf16 v[52:55], v[200:203], v[192:195], v[52:55]
	v_mfma_f32_16x16x32_bf16 v[48:51], v[204:207], v[192:195], v[48:51]
	v_mfma_f32_16x16x32_bf16 v[164:167], v[200:203], v[168:171], v[92:95]
	v_mfma_f32_16x16x32_bf16 v[168:171], v[204:207], v[168:171], v[88:91]
	s_barrier
	s_nop 0
	ds_read_b128 v[88:91], v129 offset:16384
	ds_read_b128 v[92:95], v129 offset:17408
	ds_read_b128 v[172:175], v132 offset:16384
	ds_read_b128 v[176:179], v132 offset:17408
	ds_read_b128 v[180:183], v131 offset:16384
	ds_read_b128 v[184:187], v131 offset:17408
	ds_read_b128 v[188:191], v130 offset:16384
	ds_read_b128 v[192:195], v130 offset:17408
	s_waitcnt vmcnt(4)
	s_barrier
; #define LDA(dst, b, h) _Pragma("unroll") for (int m = 0; m < 4; ++m) _Pragma("unroll") for (int k = 0; k < 2; ++k) \
;     dst[m][k] = *reinterpret_cast<const bf16x8*>(SA(b, h) + lds_byte(wr * 64 + m * 16 + fr, k * 32 + fq * 8))
; #define LDB(dst, b, h) _Pragma("unroll") for (int n = 0; n < 2; ++n) _Pragma("unroll") for (int k = 0; k < 2; ++k) \
;     dst[n][k] = *reinterpret_cast<const bf16x8*>(SB(b, h) + lds_byte(wc * 32 + n * 16 + fr, k * 32 + fq * 8))
; #define WAIT_V(n) asm volatile("s_waitcnt vmcnt(" #n ")" ::: "memory")
; #define WAIT_L(n) asm volatile("s_waitcnt lgkmcnt(" #n ")" ::: "memory")
; #define BAR __builtin_amdgcn_s_barrier()
;     ...
;       LDA(At, 0, 1); WAIT_V(4); BAR; WAIT_L(0); MMA(1, 0, At, B0); MMA(1, 1, At, B1); BAR; }
;     { LDB(B0, 1, 0); LDA(At, 1, 0); WAIT_V(2); BAR; WAIT_L(0); MMA(0, 0, At, B0); BAR;
	s_waitcnt lgkmcnt(0)
	v_mfma_f32_16x16x32_bf16 v[44:47], v[152:155], v[88:91], v[44:47]
	v_mfma_f32_16x16x32_bf16 v[40:43], v[160:163], v[88:91], v[40:43]
	v_mfma_f32_16x16x32_bf16 v[36:39], v[152:155], v[172:175], v[36:39]
	v_mfma_f32_16x16x32_bf16 v[32:35], v[160:163], v[172:175], v[32:35]
	v_mfma_f32_16x16x32_bf16 v[28:31], v[152:155], v[180:183], v[28:31]
	v_mfma_f32_16x16x32_bf16 v[24:27], v[160:163], v[180:183], v[24:27]
	v_mfma_f32_16x16x32_bf16 v[20:23], v[152:155], v[188:191], v[20:23]
	v_mfma_f32_16x16x32_bf16 v[16:19], v[160:163], v[188:191], v[16:19]
	v_mfma_f32_16x16x32_bf16 v[44:47], v[156:159], v[92:95], v[44:47]
	v_mfma_f32_16x16x32_bf16 v[40:43], v[148:151], v[92:95], v[40:43]
	v_mfma_f32_16x16x32_bf16 v[36:39], v[156:159], v[176:179], v[36:39]
	v_mfma_f32_16x16x32_bf16 v[32:35], v[148:151], v[176:179], v[32:35]
	v_mfma_f32_16x16x32_bf16 v[28:31], v[156:159], v[184:187], v[28:31]
	v_mfma_f32_16x16x32_bf16 v[24:27], v[148:151], v[184:187], v[24:27]
	v_mfma_f32_16x16x32_bf16 v[20:23], v[156:159], v[192:195], v[20:23]
	v_mfma_f32_16x16x32_bf16 v[16:19], v[148:151], v[192:195], v[16:19]
	v_mfma_f32_16x16x32_bf16 v[4:7], v[196:199], v[172:175], v[4:7]
	v_mfma_f32_16x16x32_bf16 v[0:3], v[142:145], v[172:175], v[0:3]
	v_mfma_f32_16x16x32_bf16 v[12:15], v[196:199], v[88:91], v[12:15]
	v_mfma_f32_16x16x32_bf16 v[8:11], v[142:145], v[88:91], v[8:11]
	v_mfma_f32_16x16x32_bf16 v[64:67], v[196:199], v[180:183], v[64:67]
	v_mfma_f32_16x16x32_bf16 v[72:75], v[142:145], v[180:183], v[72:75]
	v_mfma_f32_16x16x32_bf16 v[76:79], v[196:199], v[188:191], v[76:79]
	v_mfma_f32_16x16x32_bf16 v[84:87], v[142:145], v[188:191], v[84:87]
	v_mfma_f32_16x16x32_bf16 v[4:7], v[200:203], v[176:179], v[4:7]
	v_mfma_f32_16x16x32_bf16 v[0:3], v[204:207], v[176:179], v[0:3]
	v_mfma_f32_16x16x32_bf16 v[142:145], v[200:203], v[92:95], v[12:15]
	v_mfma_f32_16x16x32_bf16 v[146:149], v[204:207], v[92:95], v[8:11]
	v_mfma_f32_16x16x32_bf16 v[150:153], v[200:203], v[184:187], v[64:67]
	v_mfma_f32_16x16x32_bf16 v[154:157], v[204:207], v[184:187], v[72:75]
	v_mfma_f32_16x16x32_bf16 v[158:161], v[200:203], v[192:195], v[76:79]
	v_mfma_f32_16x16x32_bf16 v[172:175], v[204:207], v[192:195], v[84:87]
	s_barrier
	ds_read_b128 v[8:11], v137
	ds_read_b128 v[12:15], v138
	ds_read_b128 v[176:179], v139
	ds_read_b128 v[138:141], v140
	ds_read_b128 v[64:67], v129 offset:32768
	ds_read_b128 v[84:87], v129 offset:33792
	ds_read_b128 v[180:183], v132 offset:32768
	ds_read_b128 v[184:187], v132 offset:33792
	ds_read_b128 v[188:191], v131 offset:32768
	ds_read_b128 v[192:195], v131 offset:33792
	ds_read_b128 v[196:199], v130 offset:32768
	ds_read_b128 v[200:203], v130 offset:33792
	s_waitcnt vmcnt(2)
	s_barrier
	s_waitcnt lgkmcnt(0)
	v_mfma_f32_16x16x32_bf16 v[72:75], v[8:11], v[64:67], v[124:127]
	v_mfma_f32_16x16x32_bf16 v[76:79], v[176:179], v[64:67], v[120:123]
	v_mfma_f32_16x16x32_bf16 v[88:91], v[8:11], v[180:183], v[116:119]
	v_mfma_f32_16x16x32_bf16 v[92:95], v[176:179], v[180:183], v[112:115]
	v_mfma_f32_16x16x32_bf16 v[112:115], v[8:11], v[188:191], v[108:111]
	v_mfma_f32_16x16x32_bf16 v[120:123], v[176:179], v[188:191], v[104:107]
	v_mfma_f32_16x16x32_bf16 v[100:103], v[8:11], v[196:199], v[100:103]
	v_mfma_f32_16x16x32_bf16 v[96:99], v[176:179], v[196:199], v[96:99]
	v_mfma_f32_16x16x32_bf16 v[124:127], v[12:15], v[84:87], v[72:75]
	v_mfma_f32_16x16x32_bf16 v[116:119], v[138:141], v[84:87], v[76:79]
	v_mfma_f32_16x16x32_bf16 v[108:111], v[12:15], v[184:187], v[88:91]
	v_mfma_f32_16x16x32_bf16 v[104:107], v[138:141], v[184:187], v[92:95]
	v_mfma_f32_16x16x32_bf16 v[92:95], v[12:15], v[192:195], v[112:115]
	v_mfma_f32_16x16x32_bf16 v[88:91], v[138:141], v[192:195], v[120:123]
	v_mfma_f32_16x16x32_bf16 v[76:79], v[12:15], v[200:203], v[100:103]
	v_mfma_f32_16x16x32_bf16 v[72:75], v[138:141], v[200:203], v[96:99]
	s_barrier
; #define LDA(dst, b, h) _Pragma("unroll") for (int m = 0; m < 4; ++m) _Pragma("unroll") for (int k = 0; k < 2; ++k) \
;     dst[m][k] = *reinterpret_cast<const bf16x8*>(SA(b, h) + lds_byte(wr * 64 + m * 16 + fr, k * 32 + fq * 8))
; #define LDB(dst, b, h) _Pragma("unroll") for (int n = 0; n < 2; ++n) _Pragma("unroll") for (int k = 0; k < 2; ++k) \
;     dst[n][k] = *reinterpret_cast<const bf16x8*>(SB(b, h) + lds_byte(wc * 32 + n * 16 + fr, k * 32 + fq * 8))
; #define WAIT_V(n) asm volatile("s_waitcnt vmcnt(" #n ")" ::: "memory")
; #define WAIT_L(n) asm volatile("s_waitcnt lgkmcnt(" #n ")" ::: "memory")
; #define BAR __builtin_amdgcn_s_barrier()
;     ...
;     { LDB(B0, 1, 0); LDA(At, 1, 0); WAIT_V(2); BAR; WAIT_L(0); MMA(0, 0, At, B0); BAR;
;       LDB(B1, 1, 1); WAIT_V(0); BAR; WAIT_L(0); MMA(0, 1, At, B1); BAR;
;       LDA(At, 1, 1); BAR; WAIT_L(0); MMA(1, 0, At, B0); MMA(1, 1, At, B1); BAR; }
;     if (wr == 0) BAR;
	ds_read_b128 v[204:207], v133
	ds_read_b128 v[208:211], v134
	ds_read_b128 v[212:215], v135
	ds_read_b128 v[134:137], v136
	s_waitcnt vmcnt(0)
	s_barrier
	s_waitcnt lgkmcnt(0)
	v_mfma_f32_16x16x32_bf16 v[96:99], v[204:207], v[64:67], v[164:167]
	v_mfma_f32_16x16x32_bf16 v[64:67], v[212:215], v[64:67], v[168:171]
	v_mfma_f32_16x16x32_bf16 v[80:83], v[204:207], v[180:183], v[80:83]
	v_mfma_f32_16x16x32_bf16 v[68:71], v[212:215], v[180:183], v[68:71]
	v_mfma_f32_16x16x32_bf16 v[60:63], v[204:207], v[188:191], v[60:63]
	v_mfma_f32_16x16x32_bf16 v[56:59], v[212:215], v[188:191], v[56:59]
	v_mfma_f32_16x16x32_bf16 v[52:55], v[204:207], v[196:199], v[52:55]
	v_mfma_f32_16x16x32_bf16 v[48:51], v[212:215], v[196:199], v[48:51]
	v_mfma_f32_16x16x32_bf16 v[120:123], v[208:211], v[84:87], v[96:99]
	v_mfma_f32_16x16x32_bf16 v[112:115], v[134:137], v[84:87], v[64:67]
	v_mfma_f32_16x16x32_bf16 v[100:103], v[208:211], v[184:187], v[80:83]
	v_mfma_f32_16x16x32_bf16 v[96:99], v[134:137], v[184:187], v[68:71]
	v_mfma_f32_16x16x32_bf16 v[84:87], v[208:211], v[192:195], v[60:63]
	v_mfma_f32_16x16x32_bf16 v[80:83], v[134:137], v[192:195], v[56:59]
	v_mfma_f32_16x16x32_bf16 v[68:71], v[208:211], v[200:203], v[52:55]
	v_mfma_f32_16x16x32_bf16 v[64:67], v[134:137], v[200:203], v[48:51]
	s_barrier
	s_nop 0
	ds_read_b128 v[48:51], v129 offset:49152
	ds_read_b128 v[162:165], v129 offset:50176
	ds_read_b128 v[52:55], v132 offset:49152
	ds_read_b128 v[166:169], v132 offset:50176
	ds_read_b128 v[180:183], v131 offset:49152
	ds_read_b128 v[184:187], v131 offset:50176
	ds_read_b128 v[188:191], v130 offset:49152
	ds_read_b128 v[130:133], v130 offset:50176
	s_barrier
	s_waitcnt lgkmcnt(0)
	v_mfma_f32_16x16x32_bf16 v[44:47], v[8:11], v[48:51], v[44:47]
	v_mfma_f32_16x16x32_bf16 v[40:43], v[176:179], v[48:51], v[40:43]
	v_mfma_f32_16x16x32_bf16 v[36:39], v[8:11], v[52:55], v[36:39]
	v_mfma_f32_16x16x32_bf16 v[32:35], v[176:179], v[52:55], v[32:35]
	v_mfma_f32_16x16x32_bf16 v[28:31], v[8:11], v[180:183], v[28:31]
	v_mfma_f32_16x16x32_bf16 v[24:27], v[176:179], v[180:183], v[24:27]
	v_mfma_f32_16x16x32_bf16 v[8:11], v[8:11], v[188:191], v[20:23]
	v_mfma_f32_16x16x32_bf16 v[16:19], v[176:179], v[188:191], v[16:19]
	v_mfma_f32_16x16x32_bf16 v[60:63], v[12:15], v[162:165], v[44:47]
	v_mfma_f32_16x16x32_bf16 v[56:59], v[138:141], v[162:165], v[40:43]
	v_mfma_f32_16x16x32_bf16 v[44:47], v[12:15], v[166:169], v[36:39]
	v_mfma_f32_16x16x32_bf16 v[40:43], v[138:141], v[166:169], v[32:35]
	v_mfma_f32_16x16x32_bf16 v[28:31], v[12:15], v[184:187], v[28:31]
	v_mfma_f32_16x16x32_bf16 v[24:27], v[138:141], v[184:187], v[24:27]
	v_mfma_f32_16x16x32_bf16 v[12:15], v[12:15], v[130:133], v[8:11]
	v_mfma_f32_16x16x32_bf16 v[8:11], v[138:141], v[130:133], v[16:19]
	v_mfma_f32_16x16x32_bf16 v[16:19], v[204:207], v[48:51], v[142:145]
	v_mfma_f32_16x16x32_bf16 v[20:23], v[212:215], v[48:51], v[146:149]
	v_mfma_f32_16x16x32_bf16 v[4:7], v[204:207], v[52:55], v[4:7]
	v_mfma_f32_16x16x32_bf16 v[0:3], v[212:215], v[52:55], v[0:3]
	v_mfma_f32_16x16x32_bf16 v[138:141], v[204:207], v[180:183], v[150:153]
	v_mfma_f32_16x16x32_bf16 v[142:145], v[212:215], v[180:183], v[154:157]
	v_mfma_f32_16x16x32_bf16 v[146:149], v[204:207], v[188:191], v[158:161]
	v_mfma_f32_16x16x32_bf16 v[150:153], v[212:215], v[188:191], v[172:175]
	v_mfma_f32_16x16x32_bf16 v[52:55], v[208:211], v[162:165], v[16:19]
	v_mfma_f32_16x16x32_bf16 v[48:51], v[134:137], v[162:165], v[20:23]
	v_mfma_f32_16x16x32_bf16 v[36:39], v[208:211], v[166:169], v[4:7]
	v_mfma_f32_16x16x32_bf16 v[32:35], v[134:137], v[166:169], v[0:3]
	v_mfma_f32_16x16x32_bf16 v[20:23], v[208:211], v[184:187], v[138:141]
	v_mfma_f32_16x16x32_bf16 v[16:19], v[134:137], v[184:187], v[142:145]
	v_mfma_f32_16x16x32_bf16 v[4:7], v[208:211], v[130:133], v[146:149]
	v_mfma_f32_16x16x32_bf16 v[0:3], v[134:137], v[130:133], v[150:153]
	v_cmp_gt_u32_e32 vcc, s40, v128
	s_barrier
	s_and_saveexec_b64 s[6:7], vcc
	s_cbranch_execz .LBB0_395
	s_barrier

; #define STAGE(P, RS, SOFF, OFF, kt) do { const int _so = (SOFF) + (kt) * (BK * 2); \
;     _Pragma("unroll") for (int _i = 0; _i < 2; ++_i) { \
;       __builtin_amdgcn_raw_ptr_buffer_load_lds(RS, (__attribute__((address_space(3))) void*)((P) + wave * 1024 + _i * 8192), 16, OFF[_i], _so, 0, 0); } } while (0)
; #define LDA(dst, b, h) _Pragma("unroll") for (int m = 0; m < 4; ++m) _Pragma("unroll") for (int k = 0; k < 2; ++k) \
;     dst[m][k] = *reinterpret_cast<const bf16x8*>(SA(b, h) + lds_byte(wr * 64 + m * 16 + fr, k * 32 + fq * 8))
; #define LDB(dst, b, h) _Pragma("unroll") for (int n = 0; n < 2; ++n) _Pragma("unroll") for (int k = 0; k < 2; ++k) \
;     dst[n][k] = *reinterpret_cast<const bf16x8*>(SB(b, h) + lds_byte(wc * 32 + n * 16 + fr, k * 32 + fq * 8))
; #define WAIT_V(n) asm volatile("s_waitcnt vmcnt(" #n ")" ::: "memory")
; #define WAIT_L(n) asm volatile("s_waitcnt lgkmcnt(" #n ")" ::: "memory")
; #define BAR __builtin_amdgcn_s_barrier()
; #define SCHED __builtin_amdgcn_sched_barrier(0)
;     ...
;       LDB(B0, 0, 0); SCHED; LDA(At, 0, 0); STAGE(SA(1, 1), rsA, sA1, offA, t + 1);
;       WAIT_L(8); BAR; WAIT_L(0); MMA(0, 0, At, B0); BAR; SCHED;
;       LDB(B1, 0, 1); STAGE(SB(0, 0), rsB, sB0, offB, t + 2);
;       BAR; WAIT_L(0); MMA(0, 1, At, B1); BAR;
;       LDA(At, 0, 1); STAGE(SA(0, 0), rsA, sA0, offA, t + 2);
;       BAR; WAIT_L(0); MMA(1, 0, At, B0); BAR; SCHED;
;       STAGE(SB(0, 1), rsB, sB1, offB, t + 2);
;       WAIT_V(6); BAR; MMA(1, 1, At, B1); BAR;
.LBB0_494:
	ds_read_b128 v[152:155], v147
	ds_read_b128 v[156:159], v148
	ds_read_b128 v[160:163], v149
	ds_read_b128 v[164:167], v150
	s_add_i32 s5, s82, s3
	s_add_i32 s6, s5, 0x80
	s_mov_b32 m0, s36
	ds_read_b128 v[168:171], v129
	ds_read_b128 v[172:175], v129 offset:1024
	ds_read_b128 v[176:179], v132
	ds_read_b128 v[180:183], v132 offset:1024
	ds_read_b128 v[184:187], v131
	ds_read_b128 v[188:191], v131 offset:1024
	ds_read_b128 v[192:195], v130
	ds_read_b128 v[196:199], v130 offset:1024
	buffer_load_dwordx4 v141, s[8:11], s6 offen lds
	s_mov_b32 m0, s59
	s_nop 0
	buffer_load_dwordx4 v142, s[8:11], s6 offen lds
	s_waitcnt lgkmcnt(8)
	s_barrier
	s_waitcnt lgkmcnt(0)
	v_mfma_f32_16x16x32_bf16 v[124:127], v[152:155], v[168:171], v[124:127]
	v_mfma_f32_16x16x32_bf16 v[120:123], v[160:163], v[168:171], v[120:123]
	v_mfma_f32_16x16x32_bf16 v[116:119], v[152:155], v[176:179], v[116:119]
	v_mfma_f32_16x16x32_bf16 v[112:115], v[160:163], v[176:179], v[112:115]
	v_mfma_f32_16x16x32_bf16 v[108:111], v[152:155], v[184:187], v[108:111]
	v_mfma_f32_16x16x32_bf16 v[104:107], v[160:163], v[184:187], v[104:107]
	v_mfma_f32_16x16x32_bf16 v[100:103], v[152:155], v[192:195], v[100:103]
	v_mfma_f32_16x16x32_bf16 v[96:99], v[160:163], v[192:195], v[96:99]
	v_mfma_f32_16x16x32_bf16 v[124:127], v[156:159], v[172:175], v[124:127]
	v_mfma_f32_16x16x32_bf16 v[120:123], v[164:167], v[172:175], v[120:123]
	v_mfma_f32_16x16x32_bf16 v[116:119], v[156:159], v[180:183], v[116:119]
	v_mfma_f32_16x16x32_bf16 v[112:115], v[164:167], v[180:183], v[112:115]
	v_mfma_f32_16x16x32_bf16 v[108:111], v[156:159], v[188:191], v[108:111]
	v_mfma_f32_16x16x32_bf16 v[104:107], v[164:167], v[188:191], v[104:107]
	v_mfma_f32_16x16x32_bf16 v[100:103], v[156:159], v[196:199], v[100:103]
	v_mfma_f32_16x16x32_bf16 v[96:99], v[164:167], v[196:199], v[96:99]
	s_barrier
	s_add_i32 s6, s84, s3
	s_add_i32 s7, s6, 0x100
	s_mov_b32 s14, s10
	s_mov_b32 s15, s11
	s_mov_b32 m0, s37
	ds_read_b128 v[200:203], v143
	ds_read_b128 v[204:207], v144
	ds_read_b128 v[208:211], v145
	ds_read_b128 v[212:215], v146
	buffer_load_dwordx4 v141, s[12:15], s7 offen lds
	s_mov_b32 m0, s70
	s_nop 0
	buffer_load_dwordx4 v142, s[12:15], s7 offen lds
	s_barrier
	s_waitcnt lgkmcnt(0)
	v_mfma_f32_16x16x32_bf16 v[92:95], v[200:203], v[168:171], v[92:95]
	v_mfma_f32_16x16x32_bf16 v[88:91], v[208:211], v[168:171], v[88:91]
	v_mfma_f32_16x16x32_bf16 v[80:83], v[200:203], v[176:179], v[80:83]
	v_mfma_f32_16x16x32_bf16 v[68:71], v[208:211], v[176:179], v[68:71]
	v_mfma_f32_16x16x32_bf16 v[60:63], v[200:203], v[184:187], v[60:63]
	v_mfma_f32_16x16x32_bf16 v[56:59], v[208:211], v[184:187], v[56:59]
	v_mfma_f32_16x16x32_bf16 v[52:55], v[200:203], v[192:195], v[52:55]
	v_mfma_f32_16x16x32_bf16 v[48:51], v[208:211], v[192:195], v[48:51]
	v_mfma_f32_16x16x32_bf16 v[92:95], v[204:207], v[172:175], v[92:95]
	v_mfma_f32_16x16x32_bf16 v[88:91], v[212:215], v[172:175], v[88:91]
	v_mfma_f32_16x16x32_bf16 v[80:83], v[204:207], v[180:183], v[80:83]
	v_mfma_f32_16x16x32_bf16 v[68:71], v[212:215], v[180:183], v[68:71]
	v_mfma_f32_16x16x32_bf16 v[60:63], v[204:207], v[188:191], v[60:63]
	v_mfma_f32_16x16x32_bf16 v[56:59], v[212:215], v[188:191], v[56:59]
	v_mfma_f32_16x16x32_bf16 v[52:55], v[204:207], v[196:199], v[52:55]
	v_mfma_f32_16x16x32_bf16 v[48:51], v[212:215], v[196:199], v[48:51]
	s_barrier
	s_add_i32 s7, s83, s3
	s_add_i32 s22, s7, 0x100
	s_mov_b32 m0, s35
	ds_read_b128 v[168:171], v129 offset:16384
	ds_read_b128 v[172:175], v129 offset:17408
	ds_read_b128 v[176:179], v132 offset:16384
	ds_read_b128 v[180:183], v132 offset:17408
	ds_read_b128 v[184:187], v131 offset:16384
	ds_read_b128 v[188:191], v131 offset:17408
	ds_read_b128 v[192:195], v130 offset:16384
	ds_read_b128 v[196:199], v130 offset:17408
	buffer_load_dwordx4 v141, s[8:11], s22 offen lds
	s_mov_b32 m0, s95
	s_nop 0
	buffer_load_dwordx4 v142, s[8:11], s22 offen lds
	s_barrier
	s_waitcnt lgkmcnt(0)
	v_mfma_f32_16x16x32_bf16 v[44:47], v[152:155], v[168:171], v[44:47]
	v_mfma_f32_16x16x32_bf16 v[40:43], v[160:163], v[168:171], v[40:43]
	v_mfma_f32_16x16x32_bf16 v[36:39], v[152:155], v[176:179], v[36:39]
	v_mfma_f32_16x16x32_bf16 v[32:35], v[160:163], v[176:179], v[32:35]
	v_mfma_f32_16x16x32_bf16 v[28:31], v[152:155], v[184:187], v[28:31]
	v_mfma_f32_16x16x32_bf16 v[24:27], v[160:163], v[184:187], v[24:27]
	v_mfma_f32_16x16x32_bf16 v[20:23], v[152:155], v[192:195], v[20:23]
	v_mfma_f32_16x16x32_bf16 v[16:19], v[160:163], v[192:195], v[16:19]
	v_mfma_f32_16x16x32_bf16 v[44:47], v[156:159], v[172:175], v[44:47]
	v_mfma_f32_16x16x32_bf16 v[40:43], v[164:167], v[172:175], v[40:43]
	v_mfma_f32_16x16x32_bf16 v[36:39], v[156:159], v[180:183], v[36:39]
	v_mfma_f32_16x16x32_bf16 v[32:35], v[164:167], v[180:183], v[32:35]
	v_mfma_f32_16x16x32_bf16 v[28:31], v[156:159], v[188:191], v[28:31]
	v_mfma_f32_16x16x32_bf16 v[24:27], v[164:167], v[188:191], v[24:27]
	v_mfma_f32_16x16x32_bf16 v[20:23], v[156:159], v[196:199], v[20:23]
	v_mfma_f32_16x16x32_bf16 v[16:19], v[164:167], v[196:199], v[16:19]
	s_barrier
	s_add_i32 s22, s85, s3
	s_add_i32 s23, s22, 0x100
	s_mov_b32 m0, s38
	s_nop 0
	buffer_load_dwordx4 v141, s[12:15], s23 offen lds
	s_mov_b32 m0, s71
	s_nop 0
	buffer_load_dwordx4 v142, s[12:15], s23 offen lds
	s_waitcnt vmcnt(6)
	s_barrier
; #define STAGE(P, RS, SOFF, OFF, kt) do { const int _so = (SOFF) + (kt) * (BK * 2); \
;     _Pragma("unroll") for (int _i = 0; _i < 2; ++_i) { \
;       __builtin_amdgcn_raw_ptr_buffer_load_lds(RS, (__attribute__((address_space(3))) void*)((P) + wave * 1024 + _i * 8192), 16, OFF[_i], _so, 0, 0); } } while (0)
; #define LDA(dst, b, h) _Pragma("unroll") for (int m = 0; m < 4; ++m) _Pragma("unroll") for (int k = 0; k < 2; ++k) \
;     dst[m][k] = *reinterpret_cast<const bf16x8*>(SA(b, h) + lds_byte(wr * 64 + m * 16 + fr, k * 32 + fq * 8))
; #define LDB(dst, b, h) _Pragma("unroll") for (int n = 0; n < 2; ++n) _Pragma("unroll") for (int k = 0; k < 2; ++k) \
;     dst[n][k] = *reinterpret_cast<const bf16x8*>(SB(b, h) + lds_byte(wc * 32 + n * 16 + fr, k * 32 + fq * 8))
; #define WAIT_V(n) asm volatile("s_waitcnt vmcnt(" #n ")" ::: "memory")
; #define WAIT_L(n) asm volatile("s_waitcnt lgkmcnt(" #n ")" ::: "memory")
; #define BAR __builtin_amdgcn_s_barrier()
; #define SCHED __builtin_amdgcn_sched_barrier(0)
;     ...
;       WAIT_V(6); BAR; MMA(1, 1, At, B1); BAR;
;       LDB(B0, 1, 0); SCHED; LDA(At, 1, 0); STAGE(SA(0, 1), rsA, sA1, offA, t + 2);
;       WAIT_L(8); BAR; WAIT_L(0); MMA(0, 0, At, B0); BAR; SCHED;
;       LDB(B1, 1, 1); STAGE(SB(1, 0), rsB, sB0, offB, t + 3);
;       BAR; WAIT_L(0); MMA(0, 1, At, B1); BAR;
;       LDA(At, 1, 1); STAGE(SA(1, 0), rsA, sA0, offA, t + 3);
;       BAR; WAIT_L(0); MMA(1, 0, At, B0); BAR; SCHED;
	v_mfma_f32_16x16x32_bf16 v[12:15], v[200:203], v[168:171], v[12:15]
	v_mfma_f32_16x16x32_bf16 v[8:11], v[208:211], v[168:171], v[8:11]
	v_mfma_f32_16x16x32_bf16 v[4:7], v[200:203], v[176:179], v[4:7]
	v_mfma_f32_16x16x32_bf16 v[0:3], v[208:211], v[176:179], v[0:3]
	v_mfma_f32_16x16x32_bf16 v[64:67], v[200:203], v[184:187], v[64:67]
	v_mfma_f32_16x16x32_bf16 v[72:75], v[208:211], v[184:187], v[72:75]
	v_mfma_f32_16x16x32_bf16 v[76:79], v[200:203], v[192:195], v[76:79]
	v_mfma_f32_16x16x32_bf16 v[84:87], v[208:211], v[192:195], v[84:87]
	v_mfma_f32_16x16x32_bf16 v[12:15], v[204:207], v[172:175], v[12:15]
	v_mfma_f32_16x16x32_bf16 v[8:11], v[212:215], v[172:175], v[8:11]
	v_mfma_f32_16x16x32_bf16 v[4:7], v[204:207], v[180:183], v[4:7]
	v_mfma_f32_16x16x32_bf16 v[0:3], v[212:215], v[180:183], v[0:3]
	v_mfma_f32_16x16x32_bf16 v[64:67], v[204:207], v[188:191], v[64:67]
	v_mfma_f32_16x16x32_bf16 v[72:75], v[212:215], v[188:191], v[72:75]
	v_mfma_f32_16x16x32_bf16 v[76:79], v[204:207], v[196:199], v[76:79]
	v_mfma_f32_16x16x32_bf16 v[84:87], v[212:215], v[196:199], v[84:87]
	s_barrier
	ds_read_b128 v[152:155], v137
	ds_read_b128 v[156:159], v138
	ds_read_b128 v[160:163], v139
	ds_read_b128 v[164:167], v140
	s_addk_i32 s5, 0x100
	s_mov_b32 m0, s39
	ds_read_b128 v[168:171], v129 offset:32768
	ds_read_b128 v[172:175], v129 offset:33792
	ds_read_b128 v[176:179], v132 offset:32768
	ds_read_b128 v[180:183], v132 offset:33792
	ds_read_b128 v[184:187], v131 offset:32768
	ds_read_b128 v[188:191], v131 offset:33792
	ds_read_b128 v[192:195], v130 offset:32768
	ds_read_b128 v[196:199], v130 offset:33792
	buffer_load_dwordx4 v141, s[8:11], s5 offen lds
	s_mov_b32 m0, s97
	s_nop 0
	buffer_load_dwordx4 v142, s[8:11], s5 offen lds
	s_waitcnt lgkmcnt(8)
	s_barrier
	s_waitcnt lgkmcnt(0)
	v_mfma_f32_16x16x32_bf16 v[124:127], v[152:155], v[168:171], v[124:127]
	v_mfma_f32_16x16x32_bf16 v[120:123], v[160:163], v[168:171], v[120:123]
	v_mfma_f32_16x16x32_bf16 v[116:119], v[152:155], v[176:179], v[116:119]
	v_mfma_f32_16x16x32_bf16 v[112:115], v[160:163], v[176:179], v[112:115]
	v_mfma_f32_16x16x32_bf16 v[108:111], v[152:155], v[184:187], v[108:111]
	v_mfma_f32_16x16x32_bf16 v[104:107], v[160:163], v[184:187], v[104:107]
	v_mfma_f32_16x16x32_bf16 v[100:103], v[152:155], v[192:195], v[100:103]
	v_mfma_f32_16x16x32_bf16 v[96:99], v[160:163], v[192:195], v[96:99]
	v_mfma_f32_16x16x32_bf16 v[124:127], v[156:159], v[172:175], v[124:127]
	v_mfma_f32_16x16x32_bf16 v[120:123], v[164:167], v[172:175], v[120:123]
	v_mfma_f32_16x16x32_bf16 v[116:119], v[156:159], v[180:183], v[116:119]
	v_mfma_f32_16x16x32_bf16 v[112:115], v[164:167], v[180:183], v[112:115]
	v_mfma_f32_16x16x32_bf16 v[108:111], v[156:159], v[188:191], v[108:111]
	v_mfma_f32_16x16x32_bf16 v[104:107], v[164:167], v[188:191], v[104:107]
	v_mfma_f32_16x16x32_bf16 v[100:103], v[156:159], v[196:199], v[100:103]
	v_mfma_f32_16x16x32_bf16 v[96:99], v[164:167], v[196:199], v[96:99]
	s_barrier
	s_addk_i32 s6, 0x180
	s_mov_b32 m0, s92
	ds_read_b128 v[200:203], v133
	ds_read_b128 v[204:207], v134
	ds_read_b128 v[208:211], v135
	ds_read_b128 v[212:215], v136
	buffer_load_dwordx4 v141, s[12:15], s6 offen lds
	s_mov_b32 m0, s56
	s_nop 0
	buffer_load_dwordx4 v142, s[12:15], s6 offen lds
	s_barrier
	s_waitcnt lgkmcnt(0)
	v_mfma_f32_16x16x32_bf16 v[92:95], v[200:203], v[168:171], v[92:95]
	v_mfma_f32_16x16x32_bf16 v[88:91], v[208:211], v[168:171], v[88:91]
	v_mfma_f32_16x16x32_bf16 v[80:83], v[200:203], v[176:179], v[80:83]
	v_mfma_f32_16x16x32_bf16 v[68:71], v[208:211], v[176:179], v[68:71]
	v_mfma_f32_16x16x32_bf16 v[60:63], v[200:203], v[184:187], v[60:63]
	v_mfma_f32_16x16x32_bf16 v[56:59], v[208:211], v[184:187], v[56:59]
	v_mfma_f32_16x16x32_bf16 v[52:55], v[200:203], v[192:195], v[52:55]
	v_mfma_f32_16x16x32_bf16 v[48:51], v[208:211], v[192:195], v[48:51]
	v_mfma_f32_16x16x32_bf16 v[92:95], v[204:207], v[172:175], v[92:95]
	v_mfma_f32_16x16x32_bf16 v[88:91], v[212:215], v[172:175], v[88:91]
	v_mfma_f32_16x16x32_bf16 v[80:83], v[204:207], v[180:183], v[80:83]
	v_mfma_f32_16x16x32_bf16 v[68:71], v[212:215], v[180:183], v[68:71]
	v_mfma_f32_16x16x32_bf16 v[60:63], v[204:207], v[188:191], v[60:63]
	v_mfma_f32_16x16x32_bf16 v[56:59], v[212:215], v[188:191], v[56:59]
	v_mfma_f32_16x16x32_bf16 v[52:55], v[204:207], v[196:199], v[52:55]
	v_mfma_f32_16x16x32_bf16 v[48:51], v[212:215], v[196:199], v[48:51]
	s_barrier
	s_addk_i32 s7, 0x180
	s_mov_b32 m0, s93
	ds_read_b128 v[168:171], v129 offset:49152
	ds_read_b128 v[172:175], v129 offset:50176
	ds_read_b128 v[176:179], v132 offset:49152
	ds_read_b128 v[180:183], v132 offset:50176
	ds_read_b128 v[184:187], v131 offset:49152
	ds_read_b128 v[188:191], v131 offset:50176
	ds_read_b128 v[192:195], v130 offset:49152
	ds_read_b128 v[196:199], v130 offset:50176
	buffer_load_dwordx4 v141, s[8:11], s7 offen lds
	s_mov_b32 m0, s57
	s_nop 0
	buffer_load_dwordx4 v142, s[8:11], s7 offen lds
	s_barrier
	s_waitcnt lgkmcnt(0)
	v_mfma_f32_16x16x32_bf16 v[44:47], v[152:155], v[168:171], v[44:47]
	v_mfma_f32_16x16x32_bf16 v[40:43], v[160:163], v[168:171], v[40:43]
	v_mfma_f32_16x16x32_bf16 v[36:39], v[152:155], v[176:179], v[36:39]
	v_mfma_f32_16x16x32_bf16 v[32:35], v[160:163], v[176:179], v[32:35]
	v_mfma_f32_16x16x32_bf16 v[28:31], v[152:155], v[184:187], v[28:31]
	v_mfma_f32_16x16x32_bf16 v[24:27], v[160:163], v[184:187], v[24:27]
	v_mfma_f32_16x16x32_bf16 v[20:23], v[152:155], v[192:195], v[20:23]
	v_mfma_f32_16x16x32_bf16 v[16:19], v[160:163], v[192:195], v[16:19]
	v_mfma_f32_16x16x32_bf16 v[44:47], v[156:159], v[172:175], v[44:47]
	v_mfma_f32_16x16x32_bf16 v[40:43], v[164:167], v[172:175], v[40:43]
	v_mfma_f32_16x16x32_bf16 v[36:39], v[156:159], v[180:183], v[36:39]
	v_mfma_f32_16x16x32_bf16 v[32:35], v[164:167], v[180:183], v[32:35]
	v_mfma_f32_16x16x32_bf16 v[28:31], v[156:159], v[188:191], v[28:31]
	v_mfma_f32_16x16x32_bf16 v[24:27], v[164:167], v[188:191], v[24:27]
	v_mfma_f32_16x16x32_bf16 v[20:23], v[156:159], v[196:199], v[20:23]
	v_mfma_f32_16x16x32_bf16 v[16:19], v[164:167], v[196:199], v[16:19]
	s_barrier
; #define STAGE(P, RS, SOFF, OFF, kt) do { const int _so = (SOFF) + (kt) * (BK * 2); \
;     _Pragma("unroll") for (int _i = 0; _i < 2; ++_i) { \
;       __builtin_amdgcn_raw_ptr_buffer_load_lds(RS, (__attribute__((address_space(3))) void*)((P) + wave * 1024 + _i * 8192), 16, OFF[_i], _so, 0, 0); } } while (0)
; #define LDA(dst, b, h) _Pragma("unroll") for (int m = 0; m < 4; ++m) _Pragma("unroll") for (int k = 0; k < 2; ++k) \
;     dst[m][k] = *reinterpret_cast<const bf16x8*>(SA(b, h) + lds_byte(wr * 64 + m * 16 + fr, k * 32 + fq * 8))
; #define LDB(dst, b, h) _Pragma("unroll") for (int n = 0; n < 2; ++n) _Pragma("unroll") for (int k = 0; k < 2; ++k) \
;     dst[n][k] = *reinterpret_cast<const bf16x8*>(SB(b, h) + lds_byte(wc * 32 + n * 16 + fr, k * 32 + fq * 8))
; #define WAIT_V(n) asm volatile("s_waitcnt vmcnt(" #n ")" ::: "memory")
; #define WAIT_L(n) asm volatile("s_waitcnt lgkmcnt(" #n ")" ::: "memory")
; #define BAR __builtin_amdgcn_s_barrier()
;     ...
;       STAGE(SB(1, 1), rsB, sB1, offB, t + 3);
;       WAIT_V(6); BAR; MMA(1, 1, At, B1); BAR;
;     }
;     { LDB(B0, 0, 0); LDA(At, 0, 0); STAGE(SA(1, 1), rsA, sA1, offA, nt - 1);
;       BAR; WAIT_L(0); MMA(0, 0, At, B0); BAR;
;       LDB(B1, 0, 1); BAR; WAIT_L(0); MMA(0, 1, At, B1); BAR;
;       LDA(At, 0, 1); WAIT_V(4); BAR; WAIT_L(0); MMA(1, 0, At, B0); MMA(1, 1, At, B1); BAR; }
;     { LDB(B0, 1, 0); LDA(At, 1, 0); WAIT_V(2); BAR; WAIT_L(0); MMA(0, 0, At, B0); BAR;
	s_addk_i32 s22, 0x180
	s_mov_b32 m0, s94
	s_nop 0
	buffer_load_dwordx4 v141, s[12:15], s22 offen lds
	s_mov_b32 m0, s58
	s_nop 0
	buffer_load_dwordx4 v142, s[12:15], s22 offen lds
	s_add_i32 s1, s1, 2
	s_addk_i32 s3, 0x100
	s_cmp_gt_u32 s1, 59
	s_waitcnt vmcnt(6)
	s_barrier
	v_mfma_f32_16x16x32_bf16 v[12:15], v[200:203], v[168:171], v[12:15]
	v_mfma_f32_16x16x32_bf16 v[8:11], v[208:211], v[168:171], v[8:11]
	v_mfma_f32_16x16x32_bf16 v[4:7], v[200:203], v[176:179], v[4:7]
	v_mfma_f32_16x16x32_bf16 v[0:3], v[208:211], v[176:179], v[0:3]
	v_mfma_f32_16x16x32_bf16 v[64:67], v[200:203], v[184:187], v[64:67]
	v_mfma_f32_16x16x32_bf16 v[72:75], v[208:211], v[184:187], v[72:75]
	v_mfma_f32_16x16x32_bf16 v[76:79], v[200:203], v[192:195], v[76:79]
	v_mfma_f32_16x16x32_bf16 v[84:87], v[208:211], v[192:195], v[84:87]
	v_mfma_f32_16x16x32_bf16 v[12:15], v[204:207], v[172:175], v[12:15]
	v_mfma_f32_16x16x32_bf16 v[8:11], v[212:215], v[172:175], v[8:11]
	v_mfma_f32_16x16x32_bf16 v[4:7], v[204:207], v[180:183], v[4:7]
	v_mfma_f32_16x16x32_bf16 v[0:3], v[212:215], v[180:183], v[0:3]
	v_mfma_f32_16x16x32_bf16 v[64:67], v[204:207], v[188:191], v[64:67]
	v_mfma_f32_16x16x32_bf16 v[72:75], v[212:215], v[188:191], v[72:75]
	v_mfma_f32_16x16x32_bf16 v[76:79], v[204:207], v[196:199], v[76:79]
	v_mfma_f32_16x16x32_bf16 v[84:87], v[212:215], v[196:199], v[84:87]
	s_barrier
	s_cbranch_scc0 .LBB0_494
	s_add_i32 s1, s82, 0x1f80
	s_mov_b32 m0, s36
	ds_read_b128 v[152:155], v147
	ds_read_b128 v[156:159], v148
	ds_read_b128 v[160:163], v149
	ds_read_b128 v[148:151], v150
	ds_read_b128 v[164:167], v129
	ds_read_b128 v[168:171], v129 offset:1024
	ds_read_b128 v[172:175], v132
	ds_read_b128 v[176:179], v132 offset:1024
	ds_read_b128 v[180:183], v131
	ds_read_b128 v[184:187], v131 offset:1024
	ds_read_b128 v[188:191], v130
	ds_read_b128 v[192:195], v130 offset:1024
	buffer_load_dwordx4 v141, s[8:11], s1 offen lds
	s_mov_b32 m0, s59
	s_nop 0
	buffer_load_dwordx4 v142, s[8:11], s1 offen lds
	s_barrier
	s_waitcnt lgkmcnt(0)
	v_mfma_f32_16x16x32_bf16 v[124:127], v[152:155], v[164:167], v[124:127]
	v_mfma_f32_16x16x32_bf16 v[120:123], v[160:163], v[164:167], v[120:123]
	v_mfma_f32_16x16x32_bf16 v[116:119], v[152:155], v[172:175], v[116:119]
	v_mfma_f32_16x16x32_bf16 v[112:115], v[160:163], v[172:175], v[112:115]
	v_mfma_f32_16x16x32_bf16 v[108:111], v[152:155], v[180:183], v[108:111]
	v_mfma_f32_16x16x32_bf16 v[104:107], v[160:163], v[180:183], v[104:107]
	v_mfma_f32_16x16x32_bf16 v[100:103], v[152:155], v[188:191], v[100:103]
	v_mfma_f32_16x16x32_bf16 v[96:99], v[160:163], v[188:191], v[96:99]
	v_mfma_f32_16x16x32_bf16 v[124:127], v[156:159], v[168:171], v[124:127]
	v_mfma_f32_16x16x32_bf16 v[120:123], v[148:151], v[168:171], v[120:123]
	v_mfma_f32_16x16x32_bf16 v[116:119], v[156:159], v[176:179], v[116:119]
	v_mfma_f32_16x16x32_bf16 v[112:115], v[148:151], v[176:179], v[112:115]
	v_mfma_f32_16x16x32_bf16 v[108:111], v[156:159], v[184:187], v[108:111]
	v_mfma_f32_16x16x32_bf16 v[104:107], v[148:151], v[184:187], v[104:107]
	v_mfma_f32_16x16x32_bf16 v[100:103], v[156:159], v[192:195], v[100:103]
	v_mfma_f32_16x16x32_bf16 v[96:99], v[148:151], v[192:195], v[96:99]
	s_barrier
	ds_read_b128 v[196:199], v143
	ds_read_b128 v[200:203], v144
	ds_read_b128 v[142:145], v145
	ds_read_b128 v[204:207], v146
	s_barrier
	s_waitcnt lgkmcnt(0)
	v_mfma_f32_16x16x32_bf16 v[80:83], v[196:199], v[172:175], v[80:83]
	v_mfma_f32_16x16x32_bf16 v[68:71], v[142:145], v[172:175], v[68:71]
	v_mfma_f32_16x16x32_bf16 v[60:63], v[196:199], v[180:183], v[60:63]
	v_mfma_f32_16x16x32_bf16 v[56:59], v[142:145], v[180:183], v[56:59]
	v_mfma_f32_16x16x32_bf16 v[52:55], v[196:199], v[188:191], v[52:55]
	v_mfma_f32_16x16x32_bf16 v[48:51], v[142:145], v[188:191], v[48:51]
	v_mfma_f32_16x16x32_bf16 v[92:95], v[196:199], v[164:167], v[92:95]
	v_mfma_f32_16x16x32_bf16 v[88:91], v[142:145], v[164:167], v[88:91]
	v_mfma_f32_16x16x32_bf16 v[80:83], v[200:203], v[176:179], v[80:83]
	v_mfma_f32_16x16x32_bf16 v[68:71], v[204:207], v[176:179], v[68:71]
	v_mfma_f32_16x16x32_bf16 v[60:63], v[200:203], v[184:187], v[60:63]
	v_mfma_f32_16x16x32_bf16 v[56:59], v[204:207], v[184:187], v[56:59]
	v_mfma_f32_16x16x32_bf16 v[52:55], v[200:203], v[192:195], v[52:55]
	v_mfma_f32_16x16x32_bf16 v[48:51], v[204:207], v[192:195], v[48:51]
	v_mfma_f32_16x16x32_bf16 v[164:167], v[200:203], v[168:171], v[92:95]
	v_mfma_f32_16x16x32_bf16 v[168:171], v[204:207], v[168:171], v[88:91]
	s_barrier
	s_nop 0
	ds_read_b128 v[88:91], v129 offset:16384
	ds_read_b128 v[92:95], v129 offset:17408
	ds_read_b128 v[172:175], v132 offset:16384
	ds_read_b128 v[176:179], v132 offset:17408
	ds_read_b128 v[180:183], v131 offset:16384
	ds_read_b128 v[184:187], v131 offset:17408
	ds_read_b128 v[188:191], v130 offset:16384
	ds_read_b128 v[192:195], v130 offset:17408
	s_waitcnt vmcnt(4)
	s_barrier
; #define LDA(dst, b, h) _Pragma("unroll") for (int m = 0; m < 4; ++m) _Pragma("unroll") for (int k = 0; k < 2; ++k) \
;     dst[m][k] = *reinterpret_cast<const bf16x8*>(SA(b, h) + lds_byte(wr * 64 + m * 16 + fr, k * 32 + fq * 8))
; #define LDB(dst, b, h) _Pragma("unroll") for (int n = 0; n < 2; ++n) _Pragma("unroll") for (int k = 0; k < 2; ++k) \
;     dst[n][k] = *reinterpret_cast<const bf16x8*>(SB(b, h) + lds_byte(wc * 32 + n * 16 + fr, k * 32 + fq * 8))
; #define WAIT_V(n) asm volatile("s_waitcnt vmcnt(" #n ")" ::: "memory")
; #define WAIT_L(n) asm volatile("s_waitcnt lgkmcnt(" #n ")" ::: "memory")
; #define BAR __builtin_amdgcn_s_barrier()
;     ...
;       LDA(At, 0, 1); WAIT_V(4); BAR; WAIT_L(0); MMA(1, 0, At, B0); MMA(1, 1, At, B1); BAR; }
;     { LDB(B0, 1, 0); LDA(At, 1, 0); WAIT_V(2); BAR; WAIT_L(0); MMA(0, 0, At, B0); BAR;
	s_waitcnt lgkmcnt(0)
	v_mfma_f32_16x16x32_bf16 v[44:47], v[152:155], v[88:91], v[44:47]
	v_mfma_f32_16x16x32_bf16 v[40:43], v[160:163], v[88:91], v[40:43]
	v_mfma_f32_16x16x32_bf16 v[36:39], v[152:155], v[172:175], v[36:39]
	v_mfma_f32_16x16x32_bf16 v[32:35], v[160:163], v[172:175], v[32:35]
	v_mfma_f32_16x16x32_bf16 v[28:31], v[152:155], v[180:183], v[28:31]
	v_mfma_f32_16x16x32_bf16 v[24:27], v[160:163], v[180:183], v[24:27]
	v_mfma_f32_16x16x32_bf16 v[20:23], v[152:155], v[188:191], v[20:23]
	v_mfma_f32_16x16x32_bf16 v[16:19], v[160:163], v[188:191], v[16:19]
	v_mfma_f32_16x16x32_bf16 v[44:47], v[156:159], v[92:95], v[44:47]
	v_mfma_f32_16x16x32_bf16 v[40:43], v[148:151], v[92:95], v[40:43]
	v_mfma_f32_16x16x32_bf16 v[36:39], v[156:159], v[176:179], v[36:39]
	v_mfma_f32_16x16x32_bf16 v[32:35], v[148:151], v[176:179], v[32:35]
	v_mfma_f32_16x16x32_bf16 v[28:31], v[156:159], v[184:187], v[28:31]
	v_mfma_f32_16x16x32_bf16 v[24:27], v[148:151], v[184:187], v[24:27]
	v_mfma_f32_16x16x32_bf16 v[20:23], v[156:159], v[192:195], v[20:23]
	v_mfma_f32_16x16x32_bf16 v[16:19], v[148:151], v[192:195], v[16:19]
	v_mfma_f32_16x16x32_bf16 v[4:7], v[196:199], v[172:175], v[4:7]
	v_mfma_f32_16x16x32_bf16 v[0:3], v[142:145], v[172:175], v[0:3]
	v_mfma_f32_16x16x32_bf16 v[12:15], v[196:199], v[88:91], v[12:15]
	v_mfma_f32_16x16x32_bf16 v[8:11], v[142:145], v[88:91], v[8:11]
	v_mfma_f32_16x16x32_bf16 v[64:67], v[196:199], v[180:183], v[64:67]
	v_mfma_f32_16x16x32_bf16 v[72:75], v[142:145], v[180:183], v[72:75]
	v_mfma_f32_16x16x32_bf16 v[76:79], v[196:199], v[188:191], v[76:79]
	v_mfma_f32_16x16x32_bf16 v[84:87], v[142:145], v[188:191], v[84:87]
	v_mfma_f32_16x16x32_bf16 v[4:7], v[200:203], v[176:179], v[4:7]
	v_mfma_f32_16x16x32_bf16 v[0:3], v[204:207], v[176:179], v[0:3]
	v_mfma_f32_16x16x32_bf16 v[142:145], v[200:203], v[92:95], v[12:15]
	v_mfma_f32_16x16x32_bf16 v[146:149], v[204:207], v[92:95], v[8:11]
	v_mfma_f32_16x16x32_bf16 v[150:153], v[200:203], v[184:187], v[64:67]
	v_mfma_f32_16x16x32_bf16 v[154:157], v[204:207], v[184:187], v[72:75]
	v_mfma_f32_16x16x32_bf16 v[158:161], v[200:203], v[192:195], v[76:79]
	v_mfma_f32_16x16x32_bf16 v[172:175], v[204:207], v[192:195], v[84:87]
	s_barrier
	ds_read_b128 v[8:11], v137
	ds_read_b128 v[12:15], v138
	ds_read_b128 v[176:179], v139
	ds_read_b128 v[138:141], v140
	ds_read_b128 v[64:67], v129 offset:32768
	ds_read_b128 v[84:87], v129 offset:33792
	ds_read_b128 v[180:183], v132 offset:32768
	ds_read_b128 v[184:187], v132 offset:33792
	ds_read_b128 v[188:191], v131 offset:32768
	ds_read_b128 v[192:195], v131 offset:33792
	ds_read_b128 v[196:199], v130 offset:32768
	ds_read_b128 v[200:203], v130 offset:33792
	s_waitcnt vmcnt(2)
	s_barrier
	s_waitcnt lgkmcnt(0)
	v_mfma_f32_16x16x32_bf16 v[72:75], v[8:11], v[64:67], v[124:127]
	v_mfma_f32_16x16x32_bf16 v[76:79], v[176:179], v[64:67], v[120:123]
	v_mfma_f32_16x16x32_bf16 v[88:91], v[8:11], v[180:183], v[116:119]
	v_mfma_f32_16x16x32_bf16 v[92:95], v[176:179], v[180:183], v[112:115]
	v_mfma_f32_16x16x32_bf16 v[112:115], v[8:11], v[188:191], v[108:111]
	v_mfma_f32_16x16x32_bf16 v[120:123], v[176:179], v[188:191], v[104:107]
	v_mfma_f32_16x16x32_bf16 v[100:103], v[8:11], v[196:199], v[100:103]
	v_mfma_f32_16x16x32_bf16 v[96:99], v[176:179], v[196:199], v[96:99]
	v_mfma_f32_16x16x32_bf16 v[124:127], v[12:15], v[84:87], v[72:75]
	v_mfma_f32_16x16x32_bf16 v[116:119], v[138:141], v[84:87], v[76:79]
	v_mfma_f32_16x16x32_bf16 v[108:111], v[12:15], v[184:187], v[88:91]
	v_mfma_f32_16x16x32_bf16 v[104:107], v[138:141], v[184:187], v[92:95]
	v_mfma_f32_16x16x32_bf16 v[92:95], v[12:15], v[192:195], v[112:115]
	v_mfma_f32_16x16x32_bf16 v[88:91], v[138:141], v[192:195], v[120:123]
	v_mfma_f32_16x16x32_bf16 v[76:79], v[12:15], v[200:203], v[100:103]
	v_mfma_f32_16x16x32_bf16 v[72:75], v[138:141], v[200:203], v[96:99]
	s_barrier
; #define LDA(dst, b, h) _Pragma("unroll") for (int m = 0; m < 4; ++m) _Pragma("unroll") for (int k = 0; k < 2; ++k) \
;     dst[m][k] = *reinterpret_cast<const bf16x8*>(SA(b, h) + lds_byte(wr * 64 + m * 16 + fr, k * 32 + fq * 8))
; #define LDB(dst, b, h) _Pragma("unroll") for (int n = 0; n < 2; ++n) _Pragma("unroll") for (int k = 0; k < 2; ++k) \
;     dst[n][k] = *reinterpret_cast<const bf16x8*>(SB(b, h) + lds_byte(wc * 32 + n * 16 + fr, k * 32 + fq * 8))
; #define WAIT_V(n) asm volatile("s_waitcnt vmcnt(" #n ")" ::: "memory")
; #define WAIT_L(n) asm volatile("s_waitcnt lgkmcnt(" #n ")" ::: "memory")
; #define BAR __builtin_amdgcn_s_barrier()
;     ...
;       LDB(B1, 1, 1); WAIT_V(0); BAR; WAIT_L(0); MMA(0, 1, At, B1); BAR;
;       LDA(At, 1, 1); BAR; WAIT_L(0); MMA(1, 0, At, B0); MMA(1, 1, At, B1); BAR; }
;     if (wr == 0) BAR;
	ds_read_b128 v[204:207], v133
	ds_read_b128 v[208:211], v134
	ds_read_b128 v[212:215], v135
	ds_read_b128 v[134:137], v136
	s_waitcnt vmcnt(0)
	s_barrier
	s_waitcnt lgkmcnt(0)
	v_mfma_f32_16x16x32_bf16 v[96:99], v[204:207], v[64:67], v[164:167]
	v_mfma_f32_16x16x32_bf16 v[64:67], v[212:215], v[64:67], v[168:171]
	v_mfma_f32_16x16x32_bf16 v[80:83], v[204:207], v[180:183], v[80:83]
	v_mfma_f32_16x16x32_bf16 v[68:71], v[212:215], v[180:183], v[68:71]
	v_mfma_f32_16x16x32_bf16 v[60:63], v[204:207], v[188:191], v[60:63]
	v_mfma_f32_16x16x32_bf16 v[56:59], v[212:215], v[188:191], v[56:59]
	v_mfma_f32_16x16x32_bf16 v[52:55], v[204:207], v[196:199], v[52:55]
	v_mfma_f32_16x16x32_bf16 v[48:51], v[212:215], v[196:199], v[48:51]
	v_mfma_f32_16x16x32_bf16 v[120:123], v[208:211], v[84:87], v[96:99]
	v_mfma_f32_16x16x32_bf16 v[112:115], v[134:137], v[84:87], v[64:67]
	v_mfma_f32_16x16x32_bf16 v[100:103], v[208:211], v[184:187], v[80:83]
	v_mfma_f32_16x16x32_bf16 v[96:99], v[134:137], v[184:187], v[68:71]
	v_mfma_f32_16x16x32_bf16 v[84:87], v[208:211], v[192:195], v[60:63]
	v_mfma_f32_16x16x32_bf16 v[80:83], v[134:137], v[192:195], v[56:59]
	v_mfma_f32_16x16x32_bf16 v[68:71], v[208:211], v[200:203], v[52:55]
	v_mfma_f32_16x16x32_bf16 v[64:67], v[134:137], v[200:203], v[48:51]
	s_barrier
	s_nop 0
	ds_read_b128 v[48:51], v129 offset:49152
	ds_read_b128 v[162:165], v129 offset:50176
	ds_read_b128 v[52:55], v132 offset:49152
	ds_read_b128 v[166:169], v132 offset:50176
	ds_read_b128 v[180:183], v131 offset:49152
	ds_read_b128 v[184:187], v131 offset:50176
	ds_read_b128 v[188:191], v130 offset:49152
	ds_read_b128 v[130:133], v130 offset:50176
	s_barrier
	s_waitcnt lgkmcnt(0)
	v_mfma_f32_16x16x32_bf16 v[44:47], v[8:11], v[48:51], v[44:47]
	v_mfma_f32_16x16x32_bf16 v[40:43], v[176:179], v[48:51], v[40:43]
	v_mfma_f32_16x16x32_bf16 v[36:39], v[8:11], v[52:55], v[36:39]
	v_mfma_f32_16x16x32_bf16 v[32:35], v[176:179], v[52:55], v[32:35]
	v_mfma_f32_16x16x32_bf16 v[28:31], v[8:11], v[180:183], v[28:31]
	v_mfma_f32_16x16x32_bf16 v[24:27], v[176:179], v[180:183], v[24:27]
	v_mfma_f32_16x16x32_bf16 v[8:11], v[8:11], v[188:191], v[20:23]
	v_mfma_f32_16x16x32_bf16 v[16:19], v[176:179], v[188:191], v[16:19]
	v_mfma_f32_16x16x32_bf16 v[60:63], v[12:15], v[162:165], v[44:47]
	v_mfma_f32_16x16x32_bf16 v[56:59], v[138:141], v[162:165], v[40:43]
	v_mfma_f32_16x16x32_bf16 v[44:47], v[12:15], v[166:169], v[36:39]
	v_mfma_f32_16x16x32_bf16 v[40:43], v[138:141], v[166:169], v[32:35]
	v_mfma_f32_16x16x32_bf16 v[28:31], v[12:15], v[184:187], v[28:31]
	v_mfma_f32_16x16x32_bf16 v[24:27], v[138:141], v[184:187], v[24:27]
	v_mfma_f32_16x16x32_bf16 v[12:15], v[12:15], v[130:133], v[8:11]
	v_mfma_f32_16x16x32_bf16 v[8:11], v[138:141], v[130:133], v[16:19]
	v_mfma_f32_16x16x32_bf16 v[16:19], v[204:207], v[48:51], v[142:145]
	v_mfma_f32_16x16x32_bf16 v[20:23], v[212:215], v[48:51], v[146:149]
	v_mfma_f32_16x16x32_bf16 v[4:7], v[204:207], v[52:55], v[4:7]
	v_mfma_f32_16x16x32_bf16 v[0:3], v[212:215], v[52:55], v[0:3]
	v_mfma_f32_16x16x32_bf16 v[138:141], v[204:207], v[180:183], v[150:153]
	v_mfma_f32_16x16x32_bf16 v[142:145], v[212:215], v[180:183], v[154:157]
	v_mfma_f32_16x16x32_bf16 v[146:149], v[204:207], v[188:191], v[158:161]
	v_mfma_f32_16x16x32_bf16 v[150:153], v[212:215], v[188:191], v[172:175]
	v_mfma_f32_16x16x32_bf16 v[52:55], v[208:211], v[162:165], v[16:19]
	v_mfma_f32_16x16x32_bf16 v[48:51], v[134:137], v[162:165], v[20:23]
	v_mfma_f32_16x16x32_bf16 v[36:39], v[208:211], v[166:169], v[4:7]
	v_mfma_f32_16x16x32_bf16 v[32:35], v[134:137], v[166:169], v[0:3]
	v_mfma_f32_16x16x32_bf16 v[20:23], v[208:211], v[184:187], v[138:141]
	v_mfma_f32_16x16x32_bf16 v[16:19], v[134:137], v[184:187], v[142:145]
	v_mfma_f32_16x16x32_bf16 v[4:7], v[208:211], v[130:133], v[146:149]
	v_mfma_f32_16x16x32_bf16 v[0:3], v[134:137], v[130:133], v[150:153]
	v_cmp_gt_u32_e32 vcc, s76, v128
	s_barrier
	s_and_saveexec_b64 s[6:7], vcc
	s_cbranch_execz .LBB0_497
	s_barrier

; #define STAGE(P, RS, SOFF, OFF, kt) do { const int _so = (SOFF) + (kt) * (BK * 2); \
;     _Pragma("unroll") for (int _i = 0; _i < 2; ++_i) { \
;       __builtin_amdgcn_raw_ptr_buffer_load_lds(RS, (__attribute__((address_space(3))) void*)((P) + wave * 1024 + _i * 8192), 16, OFF[_i], _so, 0, 0); } } while (0)
; #define LDA(dst, b, h) _Pragma("unroll") for (int m = 0; m < 4; ++m) _Pragma("unroll") for (int k = 0; k < 2; ++k) \
;     dst[m][k] = *reinterpret_cast<const bf16x8*>(SA(b, h) + lds_byte(wr * 64 + m * 16 + fr, k * 32 + fq * 8))
; #define LDB(dst, b, h) _Pragma("unroll") for (int n = 0; n < 2; ++n) _Pragma("unroll") for (int k = 0; k < 2; ++k) \
;     dst[n][k] = *reinterpret_cast<const bf16x8*>(SB(b, h) + lds_byte(wc * 32 + n * 16 + fr, k * 32 + fq * 8))
; #define WAIT_V(n) asm volatile("s_waitcnt vmcnt(" #n ")" ::: "memory")
; #define WAIT_L(n) asm volatile("s_waitcnt lgkmcnt(" #n ")" ::: "memory")
; #define BAR __builtin_amdgcn_s_barrier()
; #define SCHED __builtin_amdgcn_sched_barrier(0)
;     ...
;       LDB(B0, 0, 0); SCHED; LDA(At, 0, 0); STAGE(SA(1, 1), rsA, sA1, offA, t + 1);
;       WAIT_L(8); BAR; WAIT_L(0); MMA(0, 0, At, B0); BAR; SCHED;
;       LDB(B1, 0, 1); STAGE(SB(0, 0), rsB, sB0, offB, t + 2);
;       BAR; WAIT_L(0); MMA(0, 1, At, B1); BAR;
;       LDA(At, 0, 1); STAGE(SA(0, 0), rsA, sA0, offA, t + 2);
;       BAR; WAIT_L(0); MMA(1, 0, At, B0); BAR; SCHED;
;       STAGE(SB(0, 1), rsB, sB1, offB, t + 2);
;       WAIT_V(6); BAR; MMA(1, 1, At, B1); BAR;
.LBB0_556:
	ds_read_b128 v[154:157], v149
	ds_read_b128 v[158:161], v150
	ds_read_b128 v[162:165], v151
	ds_read_b128 v[166:169], v152
	s_add_i32 s43, s37, s17
	s_add_i32 s10, s43, 0x80
	s_mov_b32 m0, s30
	ds_read_b128 v[170:173], v131
	ds_read_b128 v[174:177], v131 offset:1024
	ds_read_b128 v[178:181], v134
	ds_read_b128 v[182:185], v134 offset:1024
	ds_read_b128 v[186:189], v133
	ds_read_b128 v[190:193], v133 offset:1024
	ds_read_b128 v[194:197], v132
	ds_read_b128 v[198:201], v132 offset:1024
	buffer_load_dwordx4 v143, s[4:7], s10 offen lds
	s_mov_b32 m0, s31
	s_nop 0
	buffer_load_dwordx4 v144, s[4:7], s10 offen lds
	s_waitcnt lgkmcnt(8)
	s_barrier
	s_waitcnt lgkmcnt(0)
	v_mfma_f32_16x16x32_bf16 v[124:127], v[154:157], v[170:173], v[124:127]
	v_mfma_f32_16x16x32_bf16 v[120:123], v[162:165], v[170:173], v[120:123]
	v_mfma_f32_16x16x32_bf16 v[116:119], v[154:157], v[178:181], v[116:119]
	v_mfma_f32_16x16x32_bf16 v[112:115], v[162:165], v[178:181], v[112:115]
	v_mfma_f32_16x16x32_bf16 v[108:111], v[154:157], v[186:189], v[108:111]
	v_mfma_f32_16x16x32_bf16 v[104:107], v[162:165], v[186:189], v[104:107]
	v_mfma_f32_16x16x32_bf16 v[100:103], v[154:157], v[194:197], v[100:103]
	v_mfma_f32_16x16x32_bf16 v[96:99], v[162:165], v[194:197], v[96:99]
	v_mfma_f32_16x16x32_bf16 v[124:127], v[158:161], v[174:177], v[124:127]
	v_mfma_f32_16x16x32_bf16 v[120:123], v[166:169], v[174:177], v[120:123]
	v_mfma_f32_16x16x32_bf16 v[116:119], v[158:161], v[182:185], v[116:119]
	v_mfma_f32_16x16x32_bf16 v[112:115], v[166:169], v[182:185], v[112:115]
	v_mfma_f32_16x16x32_bf16 v[108:111], v[158:161], v[190:193], v[108:111]
	v_mfma_f32_16x16x32_bf16 v[104:107], v[166:169], v[190:193], v[104:107]
	v_mfma_f32_16x16x32_bf16 v[100:103], v[158:161], v[198:201], v[100:103]
	v_mfma_f32_16x16x32_bf16 v[96:99], v[166:169], v[198:201], v[96:99]
	s_barrier
	s_add_i32 s44, s39, s17
	s_add_i32 s45, s44, 0x100
	s_mov_b32 s10, s6
	s_mov_b32 s11, s7
	s_mov_b32 m0, s1
	ds_read_b128 v[202:205], v145
	ds_read_b128 v[206:209], v146
	ds_read_b128 v[210:213], v147
	ds_read_b128 v[214:217], v148
	buffer_load_dwordx4 v143, s[8:11], s45 offen lds
	s_mov_b32 m0, s3
	s_nop 0
	buffer_load_dwordx4 v144, s[8:11], s45 offen lds
	s_barrier
	s_waitcnt lgkmcnt(0)
	v_mfma_f32_16x16x32_bf16 v[92:95], v[202:205], v[170:173], v[92:95]
	v_mfma_f32_16x16x32_bf16 v[88:91], v[210:213], v[170:173], v[88:91]
	v_mfma_f32_16x16x32_bf16 v[84:87], v[202:205], v[178:181], v[84:87]
	v_mfma_f32_16x16x32_bf16 v[80:83], v[210:213], v[178:181], v[80:83]
	v_mfma_f32_16x16x32_bf16 v[76:79], v[202:205], v[186:189], v[76:79]
	v_mfma_f32_16x16x32_bf16 v[72:75], v[210:213], v[186:189], v[72:75]
	v_mfma_f32_16x16x32_bf16 v[68:71], v[202:205], v[194:197], v[68:71]
	v_mfma_f32_16x16x32_bf16 v[64:67], v[210:213], v[194:197], v[64:67]
	v_mfma_f32_16x16x32_bf16 v[92:95], v[206:209], v[174:177], v[92:95]
	v_mfma_f32_16x16x32_bf16 v[88:91], v[214:217], v[174:177], v[88:91]
	v_mfma_f32_16x16x32_bf16 v[84:87], v[206:209], v[182:185], v[84:87]
	v_mfma_f32_16x16x32_bf16 v[80:83], v[214:217], v[182:185], v[80:83]
	v_mfma_f32_16x16x32_bf16 v[76:79], v[206:209], v[190:193], v[76:79]
	v_mfma_f32_16x16x32_bf16 v[72:75], v[214:217], v[190:193], v[72:75]
	v_mfma_f32_16x16x32_bf16 v[68:71], v[206:209], v[198:201], v[68:71]
	v_mfma_f32_16x16x32_bf16 v[64:67], v[214:217], v[198:201], v[64:67]
	s_barrier
	s_add_i32 s45, s38, s17
	s_add_i32 s46, s45, 0x100
	s_mov_b32 m0, s0
	ds_read_b128 v[170:173], v131 offset:16384
	ds_read_b128 v[174:177], v131 offset:17408
	ds_read_b128 v[178:181], v134 offset:16384
	ds_read_b128 v[182:185], v134 offset:17408
	ds_read_b128 v[186:189], v133 offset:16384
	ds_read_b128 v[190:193], v133 offset:17408
	ds_read_b128 v[194:197], v132 offset:16384
	ds_read_b128 v[198:201], v132 offset:17408
	buffer_load_dwordx4 v143, s[4:7], s46 offen lds
	s_mov_b32 m0, s18
	s_nop 0
	buffer_load_dwordx4 v144, s[4:7], s46 offen lds
	s_barrier
	s_waitcnt lgkmcnt(0)
	v_mfma_f32_16x16x32_bf16 v[60:63], v[154:157], v[170:173], v[60:63]
	v_mfma_f32_16x16x32_bf16 v[56:59], v[162:165], v[170:173], v[56:59]
	v_mfma_f32_16x16x32_bf16 v[52:55], v[154:157], v[178:181], v[52:55]
	v_mfma_f32_16x16x32_bf16 v[48:51], v[162:165], v[178:181], v[48:51]
	v_mfma_f32_16x16x32_bf16 v[44:47], v[154:157], v[186:189], v[44:47]
	v_mfma_f32_16x16x32_bf16 v[40:43], v[162:165], v[186:189], v[40:43]
	v_mfma_f32_16x16x32_bf16 v[36:39], v[154:157], v[194:197], v[36:39]
	v_mfma_f32_16x16x32_bf16 v[32:35], v[162:165], v[194:197], v[32:35]
	v_mfma_f32_16x16x32_bf16 v[60:63], v[158:161], v[174:177], v[60:63]
	v_mfma_f32_16x16x32_bf16 v[56:59], v[166:169], v[174:177], v[56:59]
	v_mfma_f32_16x16x32_bf16 v[52:55], v[158:161], v[182:185], v[52:55]
	v_mfma_f32_16x16x32_bf16 v[48:51], v[166:169], v[182:185], v[48:51]
	v_mfma_f32_16x16x32_bf16 v[44:47], v[158:161], v[190:193], v[44:47]
	v_mfma_f32_16x16x32_bf16 v[40:43], v[166:169], v[190:193], v[40:43]
	v_mfma_f32_16x16x32_bf16 v[36:39], v[158:161], v[198:201], v[36:39]
	v_mfma_f32_16x16x32_bf16 v[32:35], v[166:169], v[198:201], v[32:35]
	s_barrier
	s_add_i32 s46, s40, s17
	s_add_i32 s47, s46, 0x100
	s_mov_b32 m0, s19
	s_nop 0
	buffer_load_dwordx4 v143, s[8:11], s47 offen lds
	s_mov_b32 m0, s20
	s_nop 0
	buffer_load_dwordx4 v144, s[8:11], s47 offen lds
	s_waitcnt vmcnt(6)
	s_barrier
; #define STAGE(P, RS, SOFF, OFF, kt) do { const int _so = (SOFF) + (kt) * (BK * 2); \
;     _Pragma("unroll") for (int _i = 0; _i < 2; ++_i) { \
;       __builtin_amdgcn_raw_ptr_buffer_load_lds(RS, (__attribute__((address_space(3))) void*)((P) + wave * 1024 + _i * 8192), 16, OFF[_i], _so, 0, 0); } } while (0)
; #define LDA(dst, b, h) _Pragma("unroll") for (int m = 0; m < 4; ++m) _Pragma("unroll") for (int k = 0; k < 2; ++k) \
;     dst[m][k] = *reinterpret_cast<const bf16x8*>(SA(b, h) + lds_byte(wr * 64 + m * 16 + fr, k * 32 + fq * 8))
; #define LDB(dst, b, h) _Pragma("unroll") for (int n = 0; n < 2; ++n) _Pragma("unroll") for (int k = 0; k < 2; ++k) \
;     dst[n][k] = *reinterpret_cast<const bf16x8*>(SB(b, h) + lds_byte(wc * 32 + n * 16 + fr, k * 32 + fq * 8))
; #define WAIT_V(n) asm volatile("s_waitcnt vmcnt(" #n ")" ::: "memory")
; #define WAIT_L(n) asm volatile("s_waitcnt lgkmcnt(" #n ")" ::: "memory")
; #define BAR __builtin_amdgcn_s_barrier()
; #define SCHED __builtin_amdgcn_sched_barrier(0)
;     ...
;       WAIT_V(6); BAR; MMA(1, 1, At, B1); BAR;
;       LDB(B0, 1, 0); SCHED; LDA(At, 1, 0); STAGE(SA(0, 1), rsA, sA1, offA, t + 2);
;       WAIT_L(8); BAR; WAIT_L(0); MMA(0, 0, At, B0); BAR; SCHED;
;       LDB(B1, 1, 1); STAGE(SB(1, 0), rsB, sB0, offB, t + 3);
;       BAR; WAIT_L(0); MMA(0, 1, At, B1); BAR;
;       LDA(At, 1, 1); STAGE(SA(1, 0), rsA, sA0, offA, t + 3);
;       BAR; WAIT_L(0); MMA(1, 0, At, B0); BAR; SCHED;
	v_mfma_f32_16x16x32_bf16 v[28:31], v[202:205], v[170:173], v[28:31]
	v_mfma_f32_16x16x32_bf16 v[24:27], v[210:213], v[170:173], v[24:27]
	v_mfma_f32_16x16x32_bf16 v[20:23], v[202:205], v[178:181], v[20:23]
	v_mfma_f32_16x16x32_bf16 v[16:19], v[210:213], v[178:181], v[16:19]
	v_mfma_f32_16x16x32_bf16 v[12:15], v[202:205], v[186:189], v[12:15]
	v_mfma_f32_16x16x32_bf16 v[8:11], v[210:213], v[186:189], v[8:11]
	v_mfma_f32_16x16x32_bf16 v[4:7], v[202:205], v[194:197], v[4:7]
	v_mfma_f32_16x16x32_bf16 v[0:3], v[210:213], v[194:197], v[0:3]
	v_mfma_f32_16x16x32_bf16 v[28:31], v[206:209], v[174:177], v[28:31]
	v_mfma_f32_16x16x32_bf16 v[24:27], v[214:217], v[174:177], v[24:27]
	v_mfma_f32_16x16x32_bf16 v[20:23], v[206:209], v[182:185], v[20:23]
	v_mfma_f32_16x16x32_bf16 v[16:19], v[214:217], v[182:185], v[16:19]
	v_mfma_f32_16x16x32_bf16 v[12:15], v[206:209], v[190:193], v[12:15]
	v_mfma_f32_16x16x32_bf16 v[8:11], v[214:217], v[190:193], v[8:11]
	v_mfma_f32_16x16x32_bf16 v[4:7], v[206:209], v[198:201], v[4:7]
	v_mfma_f32_16x16x32_bf16 v[0:3], v[214:217], v[198:201], v[0:3]
	s_barrier
	ds_read_b128 v[154:157], v139
	ds_read_b128 v[158:161], v140
	ds_read_b128 v[162:165], v141
	ds_read_b128 v[166:169], v142
	s_addk_i32 s43, 0x100
	s_mov_b32 m0, s21
	ds_read_b128 v[170:173], v131 offset:32768
	ds_read_b128 v[174:177], v131 offset:33792
	ds_read_b128 v[178:181], v134 offset:32768
	ds_read_b128 v[182:185], v134 offset:33792
	ds_read_b128 v[186:189], v133 offset:32768
	ds_read_b128 v[190:193], v133 offset:33792
	ds_read_b128 v[194:197], v132 offset:32768
	ds_read_b128 v[198:201], v132 offset:33792
	buffer_load_dwordx4 v143, s[4:7], s43 offen lds
	s_mov_b32 m0, s22
	s_nop 0
	buffer_load_dwordx4 v144, s[4:7], s43 offen lds
	s_waitcnt lgkmcnt(8)
	s_barrier
	s_waitcnt lgkmcnt(0)
	v_mfma_f32_16x16x32_bf16 v[124:127], v[154:157], v[170:173], v[124:127]
	v_mfma_f32_16x16x32_bf16 v[120:123], v[162:165], v[170:173], v[120:123]
	v_mfma_f32_16x16x32_bf16 v[116:119], v[154:157], v[178:181], v[116:119]
	v_mfma_f32_16x16x32_bf16 v[112:115], v[162:165], v[178:181], v[112:115]
	v_mfma_f32_16x16x32_bf16 v[108:111], v[154:157], v[186:189], v[108:111]
	v_mfma_f32_16x16x32_bf16 v[104:107], v[162:165], v[186:189], v[104:107]
	v_mfma_f32_16x16x32_bf16 v[100:103], v[154:157], v[194:197], v[100:103]
	v_mfma_f32_16x16x32_bf16 v[96:99], v[162:165], v[194:197], v[96:99]
	v_mfma_f32_16x16x32_bf16 v[124:127], v[158:161], v[174:177], v[124:127]
	v_mfma_f32_16x16x32_bf16 v[120:123], v[166:169], v[174:177], v[120:123]
	v_mfma_f32_16x16x32_bf16 v[116:119], v[158:161], v[182:185], v[116:119]
	v_mfma_f32_16x16x32_bf16 v[112:115], v[166:169], v[182:185], v[112:115]
	v_mfma_f32_16x16x32_bf16 v[108:111], v[158:161], v[190:193], v[108:111]
	v_mfma_f32_16x16x32_bf16 v[104:107], v[166:169], v[190:193], v[104:107]
	v_mfma_f32_16x16x32_bf16 v[100:103], v[158:161], v[198:201], v[100:103]
	v_mfma_f32_16x16x32_bf16 v[96:99], v[166:169], v[198:201], v[96:99]
	s_barrier
	s_addk_i32 s44, 0x180
	s_mov_b32 m0, s23
	ds_read_b128 v[202:205], v135
	ds_read_b128 v[206:209], v136
	ds_read_b128 v[210:213], v137
	ds_read_b128 v[214:217], v138
	buffer_load_dwordx4 v143, s[8:11], s44 offen lds
	s_mov_b32 m0, s24
	s_nop 0
	buffer_load_dwordx4 v144, s[8:11], s44 offen lds
	s_barrier
	s_waitcnt lgkmcnt(0)
	v_mfma_f32_16x16x32_bf16 v[92:95], v[202:205], v[170:173], v[92:95]
	v_mfma_f32_16x16x32_bf16 v[88:91], v[210:213], v[170:173], v[88:91]
	v_mfma_f32_16x16x32_bf16 v[84:87], v[202:205], v[178:181], v[84:87]
	v_mfma_f32_16x16x32_bf16 v[80:83], v[210:213], v[178:181], v[80:83]
	v_mfma_f32_16x16x32_bf16 v[76:79], v[202:205], v[186:189], v[76:79]
	v_mfma_f32_16x16x32_bf16 v[72:75], v[210:213], v[186:189], v[72:75]
	v_mfma_f32_16x16x32_bf16 v[68:71], v[202:205], v[194:197], v[68:71]
	v_mfma_f32_16x16x32_bf16 v[64:67], v[210:213], v[194:197], v[64:67]
	v_mfma_f32_16x16x32_bf16 v[92:95], v[206:209], v[174:177], v[92:95]
	v_mfma_f32_16x16x32_bf16 v[88:91], v[214:217], v[174:177], v[88:91]
	v_mfma_f32_16x16x32_bf16 v[84:87], v[206:209], v[182:185], v[84:87]
	v_mfma_f32_16x16x32_bf16 v[80:83], v[214:217], v[182:185], v[80:83]
	v_mfma_f32_16x16x32_bf16 v[76:79], v[206:209], v[190:193], v[76:79]
	v_mfma_f32_16x16x32_bf16 v[72:75], v[214:217], v[190:193], v[72:75]
	v_mfma_f32_16x16x32_bf16 v[68:71], v[206:209], v[198:201], v[68:71]
	v_mfma_f32_16x16x32_bf16 v[64:67], v[214:217], v[198:201], v[64:67]
	s_barrier
	s_addk_i32 s45, 0x180
	s_mov_b32 m0, s25
	ds_read_b128 v[170:173], v131 offset:49152
	ds_read_b128 v[174:177], v131 offset:50176
	ds_read_b128 v[178:181], v134 offset:49152
	ds_read_b128 v[182:185], v134 offset:50176
	ds_read_b128 v[186:189], v133 offset:49152
	ds_read_b128 v[190:193], v133 offset:50176
	ds_read_b128 v[194:197], v132 offset:49152
	ds_read_b128 v[198:201], v132 offset:50176
	buffer_load_dwordx4 v143, s[4:7], s45 offen lds
	s_mov_b32 m0, s26
	s_nop 0
	buffer_load_dwordx4 v144, s[4:7], s45 offen lds
	s_barrier
	s_waitcnt lgkmcnt(0)
	v_mfma_f32_16x16x32_bf16 v[60:63], v[154:157], v[170:173], v[60:63]
	v_mfma_f32_16x16x32_bf16 v[56:59], v[162:165], v[170:173], v[56:59]
	v_mfma_f32_16x16x32_bf16 v[52:55], v[154:157], v[178:181], v[52:55]
	v_mfma_f32_16x16x32_bf16 v[48:51], v[162:165], v[178:181], v[48:51]
	v_mfma_f32_16x16x32_bf16 v[44:47], v[154:157], v[186:189], v[44:47]
	v_mfma_f32_16x16x32_bf16 v[40:43], v[162:165], v[186:189], v[40:43]
	v_mfma_f32_16x16x32_bf16 v[36:39], v[154:157], v[194:197], v[36:39]
	v_mfma_f32_16x16x32_bf16 v[32:35], v[162:165], v[194:197], v[32:35]
	v_mfma_f32_16x16x32_bf16 v[60:63], v[158:161], v[174:177], v[60:63]
	v_mfma_f32_16x16x32_bf16 v[56:59], v[166:169], v[174:177], v[56:59]
	v_mfma_f32_16x16x32_bf16 v[52:55], v[158:161], v[182:185], v[52:55]
	v_mfma_f32_16x16x32_bf16 v[48:51], v[166:169], v[182:185], v[48:51]
	v_mfma_f32_16x16x32_bf16 v[44:47], v[158:161], v[190:193], v[44:47]
	v_mfma_f32_16x16x32_bf16 v[40:43], v[166:169], v[190:193], v[40:43]
	v_mfma_f32_16x16x32_bf16 v[36:39], v[158:161], v[198:201], v[36:39]
	v_mfma_f32_16x16x32_bf16 v[32:35], v[166:169], v[198:201], v[32:35]
	s_barrier
; #define STAGE(P, RS, SOFF, OFF, kt) do { const int _so = (SOFF) + (kt) * (BK * 2); \
;     _Pragma("unroll") for (int _i = 0; _i < 2; ++_i) { \
;       __builtin_amdgcn_raw_ptr_buffer_load_lds(RS, (__attribute__((address_space(3))) void*)((P) + wave * 1024 + _i * 8192), 16, OFF[_i], _so, 0, 0); } } while (0)
; #define LDA(dst, b, h) _Pragma("unroll") for (int m = 0; m < 4; ++m) _Pragma("unroll") for (int k = 0; k < 2; ++k) \
;     dst[m][k] = *reinterpret_cast<const bf16x8*>(SA(b, h) + lds_byte(wr * 64 + m * 16 + fr, k * 32 + fq * 8))
; #define LDB(dst, b, h) _Pragma("unroll") for (int n = 0; n < 2; ++n) _Pragma("unroll") for (int k = 0; k < 2; ++k) \
;     dst[n][k] = *reinterpret_cast<const bf16x8*>(SB(b, h) + lds_byte(wc * 32 + n * 16 + fr, k * 32 + fq * 8))
; #define WAIT_V(n) asm volatile("s_waitcnt vmcnt(" #n ")" ::: "memory")
; #define WAIT_L(n) asm volatile("s_waitcnt lgkmcnt(" #n ")" ::: "memory")
; #define BAR __builtin_amdgcn_s_barrier()
;     ...
;       STAGE(SB(1, 1), rsB, sB1, offB, t + 3);
;       WAIT_V(6); BAR; MMA(1, 1, At, B1); BAR;
;     }
;     { LDB(B0, 0, 0); LDA(At, 0, 0); STAGE(SA(1, 1), rsA, sA1, offA, nt - 1);
;       BAR; WAIT_L(0); MMA(0, 0, At, B0); BAR;
;       LDB(B1, 0, 1); BAR; WAIT_L(0); MMA(0, 1, At, B1); BAR;
;       LDA(At, 0, 1); WAIT_V(4); BAR; WAIT_L(0); MMA(1, 0, At, B0); MMA(1, 1, At, B1); BAR; }
;     { LDB(B0, 1, 0); LDA(At, 1, 0); WAIT_V(2); BAR; WAIT_L(0); MMA(0, 0, At, B0); BAR;
	s_addk_i32 s46, 0x180
	s_mov_b32 m0, s27
	s_nop 0
	buffer_load_dwordx4 v143, s[8:11], s46 offen lds
	s_mov_b32 m0, s28
	s_nop 0
	buffer_load_dwordx4 v144, s[8:11], s46 offen lds
	s_add_i32 s16, s16, 2
	s_addk_i32 s17, 0x100
	s_cmp_gt_u32 s16, 27
	s_waitcnt vmcnt(6)
	s_barrier
	v_mfma_f32_16x16x32_bf16 v[28:31], v[202:205], v[170:173], v[28:31]
	v_mfma_f32_16x16x32_bf16 v[24:27], v[210:213], v[170:173], v[24:27]
	v_mfma_f32_16x16x32_bf16 v[20:23], v[202:205], v[178:181], v[20:23]
	v_mfma_f32_16x16x32_bf16 v[16:19], v[210:213], v[178:181], v[16:19]
	v_mfma_f32_16x16x32_bf16 v[12:15], v[202:205], v[186:189], v[12:15]
	v_mfma_f32_16x16x32_bf16 v[8:11], v[210:213], v[186:189], v[8:11]
	v_mfma_f32_16x16x32_bf16 v[4:7], v[202:205], v[194:197], v[4:7]
	v_mfma_f32_16x16x32_bf16 v[0:3], v[210:213], v[194:197], v[0:3]
	v_mfma_f32_16x16x32_bf16 v[28:31], v[206:209], v[174:177], v[28:31]
	v_mfma_f32_16x16x32_bf16 v[24:27], v[214:217], v[174:177], v[24:27]
	v_mfma_f32_16x16x32_bf16 v[20:23], v[206:209], v[182:185], v[20:23]
	v_mfma_f32_16x16x32_bf16 v[16:19], v[214:217], v[182:185], v[16:19]
	v_mfma_f32_16x16x32_bf16 v[12:15], v[206:209], v[190:193], v[12:15]
	v_mfma_f32_16x16x32_bf16 v[8:11], v[214:217], v[190:193], v[8:11]
	v_mfma_f32_16x16x32_bf16 v[4:7], v[206:209], v[198:201], v[4:7]
	v_mfma_f32_16x16x32_bf16 v[0:3], v[214:217], v[198:201], v[0:3]
	s_barrier
	s_cbranch_scc0 .LBB0_556
	s_add_i32 s10, s37, 0xf80
	s_mov_b32 m0, s30
	ds_read_b128 v[154:157], v149
	ds_read_b128 v[158:161], v150
	ds_read_b128 v[162:165], v151
	ds_read_b128 v[150:153], v152
	ds_read_b128 v[166:169], v131
	ds_read_b128 v[170:173], v131 offset:1024
	ds_read_b128 v[174:177], v134
	ds_read_b128 v[178:181], v134 offset:1024
	ds_read_b128 v[182:185], v133
	ds_read_b128 v[186:189], v133 offset:1024
	ds_read_b128 v[190:193], v132
	ds_read_b128 v[194:197], v132 offset:1024
	buffer_load_dwordx4 v143, s[4:7], s10 offen lds
	s_mov_b32 m0, s31
	s_nop 0
	buffer_load_dwordx4 v144, s[4:7], s10 offen lds
	s_barrier
	s_waitcnt lgkmcnt(0)
	v_mfma_f32_16x16x32_bf16 v[124:127], v[154:157], v[166:169], v[124:127]
	v_mfma_f32_16x16x32_bf16 v[120:123], v[162:165], v[166:169], v[120:123]
	v_mfma_f32_16x16x32_bf16 v[116:119], v[154:157], v[174:177], v[116:119]
	v_mfma_f32_16x16x32_bf16 v[112:115], v[162:165], v[174:177], v[112:115]
	v_mfma_f32_16x16x32_bf16 v[108:111], v[154:157], v[182:185], v[108:111]
	v_mfma_f32_16x16x32_bf16 v[104:107], v[162:165], v[182:185], v[104:107]
	v_mfma_f32_16x16x32_bf16 v[100:103], v[154:157], v[190:193], v[100:103]
	v_mfma_f32_16x16x32_bf16 v[96:99], v[162:165], v[190:193], v[96:99]
	v_mfma_f32_16x16x32_bf16 v[124:127], v[158:161], v[170:173], v[124:127]
	v_mfma_f32_16x16x32_bf16 v[120:123], v[150:153], v[170:173], v[120:123]
	v_mfma_f32_16x16x32_bf16 v[116:119], v[158:161], v[178:181], v[116:119]
	v_mfma_f32_16x16x32_bf16 v[112:115], v[150:153], v[178:181], v[112:115]
	v_mfma_f32_16x16x32_bf16 v[108:111], v[158:161], v[186:189], v[108:111]
	v_mfma_f32_16x16x32_bf16 v[104:107], v[150:153], v[186:189], v[104:107]
	v_mfma_f32_16x16x32_bf16 v[100:103], v[158:161], v[194:197], v[100:103]
	v_mfma_f32_16x16x32_bf16 v[96:99], v[150:153], v[194:197], v[96:99]
	s_barrier
	ds_read_b128 v[198:201], v145
	ds_read_b128 v[202:205], v146
	ds_read_b128 v[144:147], v147
	ds_read_b128 v[206:209], v148
	s_barrier
	s_waitcnt lgkmcnt(0)
	v_mfma_f32_16x16x32_bf16 v[92:95], v[198:201], v[166:169], v[92:95]
	v_mfma_f32_16x16x32_bf16 v[88:91], v[144:147], v[166:169], v[88:91]
	v_mfma_f32_16x16x32_bf16 v[84:87], v[198:201], v[174:177], v[84:87]
	v_mfma_f32_16x16x32_bf16 v[80:83], v[144:147], v[174:177], v[80:83]
	v_mfma_f32_16x16x32_bf16 v[76:79], v[198:201], v[182:185], v[76:79]
	v_mfma_f32_16x16x32_bf16 v[72:75], v[144:147], v[182:185], v[72:75]
	v_mfma_f32_16x16x32_bf16 v[68:71], v[198:201], v[190:193], v[68:71]
	v_mfma_f32_16x16x32_bf16 v[64:67], v[144:147], v[190:193], v[64:67]
	v_mfma_f32_16x16x32_bf16 v[92:95], v[202:205], v[170:173], v[92:95]
	v_mfma_f32_16x16x32_bf16 v[88:91], v[206:209], v[170:173], v[88:91]
	v_mfma_f32_16x16x32_bf16 v[84:87], v[202:205], v[178:181], v[84:87]
	v_mfma_f32_16x16x32_bf16 v[80:83], v[206:209], v[178:181], v[80:83]
	v_mfma_f32_16x16x32_bf16 v[76:79], v[202:205], v[186:189], v[76:79]
	v_mfma_f32_16x16x32_bf16 v[72:75], v[206:209], v[186:189], v[72:75]
	v_mfma_f32_16x16x32_bf16 v[68:71], v[202:205], v[194:197], v[68:71]
	v_mfma_f32_16x16x32_bf16 v[64:67], v[206:209], v[194:197], v[64:67]
	s_barrier
	ds_read_b128 v[166:169], v131 offset:16384
	ds_read_b128 v[170:173], v131 offset:17408
	ds_read_b128 v[174:177], v134 offset:16384
	ds_read_b128 v[178:181], v134 offset:17408
	ds_read_b128 v[182:185], v133 offset:16384
	ds_read_b128 v[186:189], v133 offset:17408
	ds_read_b128 v[190:193], v132 offset:16384
	ds_read_b128 v[194:197], v132 offset:17408
	s_waitcnt vmcnt(4)
	s_barrier
; #define LDA(dst, b, h) _Pragma("unroll") for (int m = 0; m < 4; ++m) _Pragma("unroll") for (int k = 0; k < 2; ++k) \
;     dst[m][k] = *reinterpret_cast<const bf16x8*>(SA(b, h) + lds_byte(wr * 64 + m * 16 + fr, k * 32 + fq * 8))
; #define LDB(dst, b, h) _Pragma("unroll") for (int n = 0; n < 2; ++n) _Pragma("unroll") for (int k = 0; k < 2; ++k) \
;     dst[n][k] = *reinterpret_cast<const bf16x8*>(SB(b, h) + lds_byte(wc * 32 + n * 16 + fr, k * 32 + fq * 8))
; #define WAIT_V(n) asm volatile("s_waitcnt vmcnt(" #n ")" ::: "memory")
; #define WAIT_L(n) asm volatile("s_waitcnt lgkmcnt(" #n ")" ::: "memory")
; #define BAR __builtin_amdgcn_s_barrier()
;     ...
;       LDA(At, 0, 1); WAIT_V(4); BAR; WAIT_L(0); MMA(1, 0, At, B0); MMA(1, 1, At, B1); BAR; }
;     { LDB(B0, 1, 0); LDA(At, 1, 0); WAIT_V(2); BAR; WAIT_L(0); MMA(0, 0, At, B0); BAR;
	s_waitcnt lgkmcnt(0)
	v_mfma_f32_16x16x32_bf16 v[60:63], v[154:157], v[166:169], v[60:63]
	v_mfma_f32_16x16x32_bf16 v[56:59], v[162:165], v[166:169], v[56:59]
	v_mfma_f32_16x16x32_bf16 v[52:55], v[154:157], v[174:177], v[52:55]
	v_mfma_f32_16x16x32_bf16 v[48:51], v[162:165], v[174:177], v[48:51]
	v_mfma_f32_16x16x32_bf16 v[44:47], v[154:157], v[182:185], v[44:47]
	v_mfma_f32_16x16x32_bf16 v[40:43], v[162:165], v[182:185], v[40:43]
	v_mfma_f32_16x16x32_bf16 v[36:39], v[154:157], v[190:193], v[36:39]
	v_mfma_f32_16x16x32_bf16 v[32:35], v[162:165], v[190:193], v[32:35]
	v_mfma_f32_16x16x32_bf16 v[60:63], v[158:161], v[170:173], v[60:63]
	v_mfma_f32_16x16x32_bf16 v[56:59], v[150:153], v[170:173], v[56:59]
	v_mfma_f32_16x16x32_bf16 v[52:55], v[158:161], v[178:181], v[52:55]
	v_mfma_f32_16x16x32_bf16 v[48:51], v[150:153], v[178:181], v[48:51]
	v_mfma_f32_16x16x32_bf16 v[44:47], v[158:161], v[186:189], v[44:47]
	v_mfma_f32_16x16x32_bf16 v[40:43], v[150:153], v[186:189], v[40:43]
	v_mfma_f32_16x16x32_bf16 v[36:39], v[158:161], v[194:197], v[36:39]
	v_mfma_f32_16x16x32_bf16 v[32:35], v[150:153], v[194:197], v[32:35]
	v_mfma_f32_16x16x32_bf16 v[28:31], v[198:201], v[166:169], v[28:31]
	v_mfma_f32_16x16x32_bf16 v[24:27], v[144:147], v[166:169], v[24:27]
	v_mfma_f32_16x16x32_bf16 v[20:23], v[198:201], v[174:177], v[20:23]
	v_mfma_f32_16x16x32_bf16 v[16:19], v[144:147], v[174:177], v[16:19]
	v_mfma_f32_16x16x32_bf16 v[12:15], v[198:201], v[182:185], v[12:15]
	v_mfma_f32_16x16x32_bf16 v[8:11], v[144:147], v[182:185], v[8:11]
	v_mfma_f32_16x16x32_bf16 v[4:7], v[198:201], v[190:193], v[4:7]
	v_mfma_f32_16x16x32_bf16 v[0:3], v[144:147], v[190:193], v[0:3]
	v_mfma_f32_16x16x32_bf16 v[28:31], v[202:205], v[170:173], v[28:31]
	v_mfma_f32_16x16x32_bf16 v[24:27], v[206:209], v[170:173], v[24:27]
	v_mfma_f32_16x16x32_bf16 v[20:23], v[202:205], v[178:181], v[20:23]
	v_mfma_f32_16x16x32_bf16 v[16:19], v[206:209], v[178:181], v[16:19]
	v_mfma_f32_16x16x32_bf16 v[12:15], v[202:205], v[186:189], v[12:15]
	v_mfma_f32_16x16x32_bf16 v[8:11], v[206:209], v[186:189], v[8:11]
	v_mfma_f32_16x16x32_bf16 v[4:7], v[202:205], v[194:197], v[4:7]
	v_mfma_f32_16x16x32_bf16 v[0:3], v[206:209], v[194:197], v[0:3]
	s_barrier
	ds_read_b128 v[144:147], v139
	ds_read_b128 v[148:151], v140
	ds_read_b128 v[152:155], v141
	ds_read_b128 v[140:143], v142
	ds_read_b128 v[156:159], v131 offset:32768
	ds_read_b128 v[160:163], v131 offset:33792
	ds_read_b128 v[164:167], v134 offset:32768
	ds_read_b128 v[168:171], v134 offset:33792
	ds_read_b128 v[172:175], v133 offset:32768
	ds_read_b128 v[176:179], v133 offset:33792
	ds_read_b128 v[180:183], v132 offset:32768
	ds_read_b128 v[184:187], v132 offset:33792
	s_waitcnt vmcnt(2)
	s_barrier
	s_waitcnt lgkmcnt(0)
	v_mfma_f32_16x16x32_bf16 v[124:127], v[144:147], v[156:159], v[124:127]
	v_mfma_f32_16x16x32_bf16 v[120:123], v[152:155], v[156:159], v[120:123]
	v_mfma_f32_16x16x32_bf16 v[116:119], v[144:147], v[164:167], v[116:119]
	v_mfma_f32_16x16x32_bf16 v[112:115], v[152:155], v[164:167], v[112:115]
	v_mfma_f32_16x16x32_bf16 v[108:111], v[144:147], v[172:175], v[108:111]
	v_mfma_f32_16x16x32_bf16 v[104:107], v[152:155], v[172:175], v[104:107]
	v_mfma_f32_16x16x32_bf16 v[100:103], v[144:147], v[180:183], v[100:103]
	v_mfma_f32_16x16x32_bf16 v[96:99], v[152:155], v[180:183], v[96:99]
	v_mfma_f32_16x16x32_bf16 v[124:127], v[148:151], v[160:163], v[124:127]
	v_mfma_f32_16x16x32_bf16 v[120:123], v[140:143], v[160:163], v[120:123]
	v_mfma_f32_16x16x32_bf16 v[116:119], v[148:151], v[168:171], v[116:119]
	v_mfma_f32_16x16x32_bf16 v[112:115], v[140:143], v[168:171], v[112:115]
	v_mfma_f32_16x16x32_bf16 v[108:111], v[148:151], v[176:179], v[108:111]
	v_mfma_f32_16x16x32_bf16 v[104:107], v[140:143], v[176:179], v[104:107]
	v_mfma_f32_16x16x32_bf16 v[100:103], v[148:151], v[184:187], v[100:103]
	v_mfma_f32_16x16x32_bf16 v[96:99], v[140:143], v[184:187], v[96:99]
	s_barrier
; #define LDA(dst, b, h) _Pragma("unroll") for (int m = 0; m < 4; ++m) _Pragma("unroll") for (int k = 0; k < 2; ++k) \
;     dst[m][k] = *reinterpret_cast<const bf16x8*>(SA(b, h) + lds_byte(wr * 64 + m * 16 + fr, k * 32 + fq * 8))
; #define LDB(dst, b, h) _Pragma("unroll") for (int n = 0; n < 2; ++n) _Pragma("unroll") for (int k = 0; k < 2; ++k) \
;     dst[n][k] = *reinterpret_cast<const bf16x8*>(SB(b, h) + lds_byte(wc * 32 + n * 16 + fr, k * 32 + fq * 8))
; #define WAIT_V(n) asm volatile("s_waitcnt vmcnt(" #n ")" ::: "memory")
; #define WAIT_L(n) asm volatile("s_waitcnt lgkmcnt(" #n ")" ::: "memory")
; #define BAR __builtin_amdgcn_s_barrier()
;     ...
;       LDB(B1, 1, 1); WAIT_V(0); BAR; WAIT_L(0); MMA(0, 1, At, B1); BAR;
;       LDA(At, 1, 1); BAR; WAIT_L(0); MMA(1, 0, At, B0); MMA(1, 1, At, B1); BAR; }
;     if (wr == 0) BAR;
	ds_read_b128 v[188:191], v135
	ds_read_b128 v[192:195], v136
	ds_read_b128 v[196:199], v137
	ds_read_b128 v[136:139], v138
	s_waitcnt vmcnt(0)
	s_barrier
	s_waitcnt lgkmcnt(0)
	v_mfma_f32_16x16x32_bf16 v[92:95], v[188:191], v[156:159], v[92:95]
	v_mfma_f32_16x16x32_bf16 v[88:91], v[196:199], v[156:159], v[88:91]
	v_mfma_f32_16x16x32_bf16 v[84:87], v[188:191], v[164:167], v[84:87]
	v_mfma_f32_16x16x32_bf16 v[80:83], v[196:199], v[164:167], v[80:83]
	v_mfma_f32_16x16x32_bf16 v[76:79], v[188:191], v[172:175], v[76:79]
	v_mfma_f32_16x16x32_bf16 v[72:75], v[196:199], v[172:175], v[72:75]
	v_mfma_f32_16x16x32_bf16 v[68:71], v[188:191], v[180:183], v[68:71]
	v_mfma_f32_16x16x32_bf16 v[64:67], v[196:199], v[180:183], v[64:67]
	v_mfma_f32_16x16x32_bf16 v[92:95], v[192:195], v[160:163], v[92:95]
	v_mfma_f32_16x16x32_bf16 v[88:91], v[136:139], v[160:163], v[88:91]
	v_mfma_f32_16x16x32_bf16 v[84:87], v[192:195], v[168:171], v[84:87]
	v_mfma_f32_16x16x32_bf16 v[80:83], v[136:139], v[168:171], v[80:83]
	v_mfma_f32_16x16x32_bf16 v[76:79], v[192:195], v[176:179], v[76:79]
	v_mfma_f32_16x16x32_bf16 v[72:75], v[136:139], v[176:179], v[72:75]
	v_mfma_f32_16x16x32_bf16 v[68:71], v[192:195], v[184:187], v[68:71]
	v_mfma_f32_16x16x32_bf16 v[64:67], v[136:139], v[184:187], v[64:67]
	s_barrier
	ds_read_b128 v[156:159], v131 offset:49152
	ds_read_b128 v[160:163], v131 offset:50176
	ds_read_b128 v[164:167], v134 offset:49152
	ds_read_b128 v[168:171], v134 offset:50176
	ds_read_b128 v[172:175], v133 offset:49152
	ds_read_b128 v[176:179], v133 offset:50176
	ds_read_b128 v[180:183], v132 offset:49152
	ds_read_b128 v[132:135], v132 offset:50176
	s_barrier
	s_waitcnt lgkmcnt(0)
	v_mfma_f32_16x16x32_bf16 v[60:63], v[144:147], v[156:159], v[60:63]
	v_mfma_f32_16x16x32_bf16 v[56:59], v[152:155], v[156:159], v[56:59]
	v_mfma_f32_16x16x32_bf16 v[52:55], v[144:147], v[164:167], v[52:55]
	v_mfma_f32_16x16x32_bf16 v[48:51], v[152:155], v[164:167], v[48:51]
	v_mfma_f32_16x16x32_bf16 v[44:47], v[144:147], v[172:175], v[44:47]
	v_mfma_f32_16x16x32_bf16 v[40:43], v[152:155], v[172:175], v[40:43]
	v_mfma_f32_16x16x32_bf16 v[36:39], v[144:147], v[180:183], v[36:39]
	v_mfma_f32_16x16x32_bf16 v[32:35], v[152:155], v[180:183], v[32:35]
	v_mfma_f32_16x16x32_bf16 v[60:63], v[148:151], v[160:163], v[60:63]
	v_mfma_f32_16x16x32_bf16 v[56:59], v[140:143], v[160:163], v[56:59]
	v_mfma_f32_16x16x32_bf16 v[52:55], v[148:151], v[168:171], v[52:55]
	v_mfma_f32_16x16x32_bf16 v[48:51], v[140:143], v[168:171], v[48:51]
	v_mfma_f32_16x16x32_bf16 v[44:47], v[148:151], v[176:179], v[44:47]
	v_mfma_f32_16x16x32_bf16 v[40:43], v[140:143], v[176:179], v[40:43]
	v_mfma_f32_16x16x32_bf16 v[36:39], v[148:151], v[132:135], v[36:39]
	v_mfma_f32_16x16x32_bf16 v[32:35], v[140:143], v[132:135], v[32:35]
	v_mfma_f32_16x16x32_bf16 v[28:31], v[188:191], v[156:159], v[28:31]
	v_mfma_f32_16x16x32_bf16 v[24:27], v[196:199], v[156:159], v[24:27]
	v_mfma_f32_16x16x32_bf16 v[20:23], v[188:191], v[164:167], v[20:23]
	v_mfma_f32_16x16x32_bf16 v[16:19], v[196:199], v[164:167], v[16:19]
	v_mfma_f32_16x16x32_bf16 v[12:15], v[188:191], v[172:175], v[12:15]
	v_mfma_f32_16x16x32_bf16 v[8:11], v[196:199], v[172:175], v[8:11]
	v_mfma_f32_16x16x32_bf16 v[4:7], v[188:191], v[180:183], v[4:7]
	v_mfma_f32_16x16x32_bf16 v[0:3], v[196:199], v[180:183], v[0:3]
	v_mfma_f32_16x16x32_bf16 v[28:31], v[192:195], v[160:163], v[28:31]
	v_mfma_f32_16x16x32_bf16 v[24:27], v[136:139], v[160:163], v[24:27]
	v_mfma_f32_16x16x32_bf16 v[20:23], v[192:195], v[168:171], v[20:23]
	v_mfma_f32_16x16x32_bf16 v[16:19], v[136:139], v[168:171], v[16:19]
	v_mfma_f32_16x16x32_bf16 v[12:15], v[192:195], v[176:179], v[12:15]
	v_mfma_f32_16x16x32_bf16 v[8:11], v[136:139], v[176:179], v[8:11]
	v_mfma_f32_16x16x32_bf16 v[4:7], v[192:195], v[132:135], v[4:7]
	v_mfma_f32_16x16x32_bf16 v[0:3], v[136:139], v[132:135], v[0:3]
	v_cmp_gt_u32_e32 vcc, s35, v130
	s_barrier
	s_and_saveexec_b64 s[10:11], vcc
	s_cbranch_execz .LBB0_559
	s_barrier

; #define STAGE(P, RS, SOFF, OFF, kt) do { const int _so = (SOFF) + (kt) * (BK * 2); \
;     _Pragma("unroll") for (int _i = 0; _i < 2; ++_i) { \
;       __builtin_amdgcn_raw_ptr_buffer_load_lds(RS, (__attribute__((address_space(3))) void*)((P) + wave * 1024 + _i * 8192), 16, OFF[_i], _so, 0, 0); } } while (0)
; #define LDA(dst, b, h) _Pragma("unroll") for (int m = 0; m < 4; ++m) _Pragma("unroll") for (int k = 0; k < 2; ++k) \
;     dst[m][k] = *reinterpret_cast<const bf16x8*>(SA(b, h) + lds_byte(wr * 64 + m * 16 + fr, k * 32 + fq * 8))
; #define LDB(dst, b, h) _Pragma("unroll") for (int n = 0; n < 2; ++n) _Pragma("unroll") for (int k = 0; k < 2; ++k) \
;     dst[n][k] = *reinterpret_cast<const bf16x8*>(SB(b, h) + lds_byte(wc * 32 + n * 16 + fr, k * 32 + fq * 8))
; #define WAIT_V(n) asm volatile("s_waitcnt vmcnt(" #n ")" ::: "memory")
; #define WAIT_L(n) asm volatile("s_waitcnt lgkmcnt(" #n ")" ::: "memory")
; #define BAR __builtin_amdgcn_s_barrier()
; #define SCHED __builtin_amdgcn_sched_barrier(0)
;     ...
;       LDB(B0, 0, 0); SCHED; LDA(At, 0, 0); STAGE(SA(1, 1), rsA, sA1, offA, t + 1);
;       WAIT_L(8); BAR; WAIT_L(0); MMA(0, 0, At, B0); BAR; SCHED;
;       LDB(B1, 0, 1); STAGE(SB(0, 0), rsB, sB0, offB, t + 2);
;       BAR; WAIT_L(0); MMA(0, 1, At, B1); BAR;
;       LDA(At, 0, 1); STAGE(SA(0, 0), rsA, sA0, offA, t + 2);
;       BAR; WAIT_L(0); MMA(1, 0, At, B0); BAR; SCHED;
;       STAGE(SB(0, 1), rsB, sB1, offB, t + 2);
;       WAIT_V(6); BAR; MMA(1, 1, At, B1); BAR;
.LBB0_657:
	ds_read_b128 v[152:155], v147
	ds_read_b128 v[156:159], v148
	ds_read_b128 v[160:163], v149
	ds_read_b128 v[164:167], v150
	s_add_i32 s5, s81, s3
	s_add_i32 s6, s5, 0x80
	s_mov_b32 m0, s39
	ds_read_b128 v[168:171], v129
	ds_read_b128 v[172:175], v129 offset:1024
	ds_read_b128 v[176:179], v132
	ds_read_b128 v[180:183], v132 offset:1024
	ds_read_b128 v[184:187], v131
	ds_read_b128 v[188:191], v131 offset:1024
	ds_read_b128 v[192:195], v130
	ds_read_b128 v[196:199], v130 offset:1024
	buffer_load_dwordx4 v141, s[8:11], s6 offen lds
	s_mov_b32 m0, s58
	s_nop 0
	buffer_load_dwordx4 v142, s[8:11], s6 offen lds
	s_waitcnt lgkmcnt(8)
	s_barrier
	s_waitcnt lgkmcnt(0)
	v_mfma_f32_16x16x32_bf16 v[124:127], v[152:155], v[168:171], v[124:127]
	v_mfma_f32_16x16x32_bf16 v[120:123], v[160:163], v[168:171], v[120:123]
	v_mfma_f32_16x16x32_bf16 v[116:119], v[152:155], v[176:179], v[116:119]
	v_mfma_f32_16x16x32_bf16 v[112:115], v[160:163], v[176:179], v[112:115]
	v_mfma_f32_16x16x32_bf16 v[108:111], v[152:155], v[184:187], v[108:111]
	v_mfma_f32_16x16x32_bf16 v[104:107], v[160:163], v[184:187], v[104:107]
	v_mfma_f32_16x16x32_bf16 v[100:103], v[152:155], v[192:195], v[100:103]
	v_mfma_f32_16x16x32_bf16 v[96:99], v[160:163], v[192:195], v[96:99]
	v_mfma_f32_16x16x32_bf16 v[124:127], v[156:159], v[172:175], v[124:127]
	v_mfma_f32_16x16x32_bf16 v[120:123], v[164:167], v[172:175], v[120:123]
	v_mfma_f32_16x16x32_bf16 v[116:119], v[156:159], v[180:183], v[116:119]
	v_mfma_f32_16x16x32_bf16 v[112:115], v[164:167], v[180:183], v[112:115]
	v_mfma_f32_16x16x32_bf16 v[108:111], v[156:159], v[188:191], v[108:111]
	v_mfma_f32_16x16x32_bf16 v[104:107], v[164:167], v[188:191], v[104:107]
	v_mfma_f32_16x16x32_bf16 v[100:103], v[156:159], v[196:199], v[100:103]
	v_mfma_f32_16x16x32_bf16 v[96:99], v[164:167], v[196:199], v[96:99]
	s_barrier
	s_add_i32 s6, s83, s3
	s_add_i32 s7, s6, 0x100
	s_mov_b32 s14, s10
	s_mov_b32 s15, s11
	s_mov_b32 m0, s85
	ds_read_b128 v[200:203], v143
	ds_read_b128 v[204:207], v144
	ds_read_b128 v[208:211], v145
	ds_read_b128 v[212:215], v146
	buffer_load_dwordx4 v141, s[12:15], s7 offen lds
	s_mov_b32 m0, s75
	s_nop 0
	buffer_load_dwordx4 v142, s[12:15], s7 offen lds
	s_barrier
	s_waitcnt lgkmcnt(0)
	v_mfma_f32_16x16x32_bf16 v[92:95], v[200:203], v[168:171], v[92:95]
	v_mfma_f32_16x16x32_bf16 v[88:91], v[208:211], v[168:171], v[88:91]
	v_mfma_f32_16x16x32_bf16 v[80:83], v[200:203], v[176:179], v[80:83]
	v_mfma_f32_16x16x32_bf16 v[68:71], v[208:211], v[176:179], v[68:71]
	v_mfma_f32_16x16x32_bf16 v[60:63], v[200:203], v[184:187], v[60:63]
	v_mfma_f32_16x16x32_bf16 v[56:59], v[208:211], v[184:187], v[56:59]
	v_mfma_f32_16x16x32_bf16 v[52:55], v[200:203], v[192:195], v[52:55]
	v_mfma_f32_16x16x32_bf16 v[48:51], v[208:211], v[192:195], v[48:51]
	v_mfma_f32_16x16x32_bf16 v[92:95], v[204:207], v[172:175], v[92:95]
	v_mfma_f32_16x16x32_bf16 v[88:91], v[212:215], v[172:175], v[88:91]
	v_mfma_f32_16x16x32_bf16 v[80:83], v[204:207], v[180:183], v[80:83]
	v_mfma_f32_16x16x32_bf16 v[68:71], v[212:215], v[180:183], v[68:71]
	v_mfma_f32_16x16x32_bf16 v[60:63], v[204:207], v[188:191], v[60:63]
	v_mfma_f32_16x16x32_bf16 v[56:59], v[212:215], v[188:191], v[56:59]
	v_mfma_f32_16x16x32_bf16 v[52:55], v[204:207], v[196:199], v[52:55]
	v_mfma_f32_16x16x32_bf16 v[48:51], v[212:215], v[196:199], v[48:51]
	s_barrier
	s_add_i32 s7, s82, s3
	s_add_i32 s22, s7, 0x100
	s_mov_b32 m0, s38
	ds_read_b128 v[168:171], v129 offset:16384
	ds_read_b128 v[172:175], v129 offset:17408
	ds_read_b128 v[176:179], v132 offset:16384
	ds_read_b128 v[180:183], v132 offset:17408
	ds_read_b128 v[184:187], v131 offset:16384
	ds_read_b128 v[188:191], v131 offset:17408
	ds_read_b128 v[192:195], v130 offset:16384
	ds_read_b128 v[196:199], v130 offset:17408
	buffer_load_dwordx4 v141, s[8:11], s22 offen lds
	s_mov_b32 m0, s95
	s_nop 0
	buffer_load_dwordx4 v142, s[8:11], s22 offen lds
	s_barrier
	s_waitcnt lgkmcnt(0)
	v_mfma_f32_16x16x32_bf16 v[44:47], v[152:155], v[168:171], v[44:47]
	v_mfma_f32_16x16x32_bf16 v[40:43], v[160:163], v[168:171], v[40:43]
	v_mfma_f32_16x16x32_bf16 v[36:39], v[152:155], v[176:179], v[36:39]
	v_mfma_f32_16x16x32_bf16 v[32:35], v[160:163], v[176:179], v[32:35]
	v_mfma_f32_16x16x32_bf16 v[28:31], v[152:155], v[184:187], v[28:31]
	v_mfma_f32_16x16x32_bf16 v[24:27], v[160:163], v[184:187], v[24:27]
	v_mfma_f32_16x16x32_bf16 v[20:23], v[152:155], v[192:195], v[20:23]
	v_mfma_f32_16x16x32_bf16 v[16:19], v[160:163], v[192:195], v[16:19]
	v_mfma_f32_16x16x32_bf16 v[44:47], v[156:159], v[172:175], v[44:47]
	v_mfma_f32_16x16x32_bf16 v[40:43], v[164:167], v[172:175], v[40:43]
	v_mfma_f32_16x16x32_bf16 v[36:39], v[156:159], v[180:183], v[36:39]
	v_mfma_f32_16x16x32_bf16 v[32:35], v[164:167], v[180:183], v[32:35]
	v_mfma_f32_16x16x32_bf16 v[28:31], v[156:159], v[188:191], v[28:31]
	v_mfma_f32_16x16x32_bf16 v[24:27], v[164:167], v[188:191], v[24:27]
	v_mfma_f32_16x16x32_bf16 v[20:23], v[156:159], v[196:199], v[20:23]
	v_mfma_f32_16x16x32_bf16 v[16:19], v[164:167], v[196:199], v[16:19]
	s_barrier
	s_add_i32 s22, s84, s3
	s_add_i32 s23, s22, 0x100
	s_mov_b32 m0, s86
	s_nop 0
	buffer_load_dwordx4 v141, s[12:15], s23 offen lds
	s_mov_b32 m0, s28
	s_nop 0
	buffer_load_dwordx4 v142, s[12:15], s23 offen lds
	s_waitcnt vmcnt(6)
	s_barrier
; #define STAGE(P, RS, SOFF, OFF, kt) do { const int _so = (SOFF) + (kt) * (BK * 2); \
;     _Pragma("unroll") for (int _i = 0; _i < 2; ++_i) { \
;       __builtin_amdgcn_raw_ptr_buffer_load_lds(RS, (__attribute__((address_space(3))) void*)((P) + wave * 1024 + _i * 8192), 16, OFF[_i], _so, 0, 0); } } while (0)
; #define LDA(dst, b, h) _Pragma("unroll") for (int m = 0; m < 4; ++m) _Pragma("unroll") for (int k = 0; k < 2; ++k) \
;     dst[m][k] = *reinterpret_cast<const bf16x8*>(SA(b, h) + lds_byte(wr * 64 + m * 16 + fr, k * 32 + fq * 8))
; #define LDB(dst, b, h) _Pragma("unroll") for (int n = 0; n < 2; ++n) _Pragma("unroll") for (int k = 0; k < 2; ++k) \
;     dst[n][k] = *reinterpret_cast<const bf16x8*>(SB(b, h) + lds_byte(wc * 32 + n * 16 + fr, k * 32 + fq * 8))
; #define WAIT_V(n) asm volatile("s_waitcnt vmcnt(" #n ")" ::: "memory")
; #define WAIT_L(n) asm volatile("s_waitcnt lgkmcnt(" #n ")" ::: "memory")
; #define BAR __builtin_amdgcn_s_barrier()
; #define SCHED __builtin_amdgcn_sched_barrier(0)
;     ...
;       WAIT_V(6); BAR; MMA(1, 1, At, B1); BAR;
;       LDB(B0, 1, 0); SCHED; LDA(At, 1, 0); STAGE(SA(0, 1), rsA, sA1, offA, t + 2);
;       WAIT_L(8); BAR; WAIT_L(0); MMA(0, 0, At, B0); BAR; SCHED;
;       LDB(B1, 1, 1); STAGE(SB(1, 0), rsB, sB0, offB, t + 3);
;       BAR; WAIT_L(0); MMA(0, 1, At, B1); BAR;
;       LDA(At, 1, 1); STAGE(SA(1, 0), rsA, sA0, offA, t + 3);
;       BAR; WAIT_L(0); MMA(1, 0, At, B0); BAR; SCHED;
	v_mfma_f32_16x16x32_bf16 v[12:15], v[200:203], v[168:171], v[12:15]
	v_mfma_f32_16x16x32_bf16 v[8:11], v[208:211], v[168:171], v[8:11]
	v_mfma_f32_16x16x32_bf16 v[4:7], v[200:203], v[176:179], v[4:7]
	v_mfma_f32_16x16x32_bf16 v[0:3], v[208:211], v[176:179], v[0:3]
	v_mfma_f32_16x16x32_bf16 v[64:67], v[200:203], v[184:187], v[64:67]
	v_mfma_f32_16x16x32_bf16 v[72:75], v[208:211], v[184:187], v[72:75]
	v_mfma_f32_16x16x32_bf16 v[76:79], v[200:203], v[192:195], v[76:79]
	v_mfma_f32_16x16x32_bf16 v[84:87], v[208:211], v[192:195], v[84:87]
	v_mfma_f32_16x16x32_bf16 v[12:15], v[204:207], v[172:175], v[12:15]
	v_mfma_f32_16x16x32_bf16 v[8:11], v[212:215], v[172:175], v[8:11]
	v_mfma_f32_16x16x32_bf16 v[4:7], v[204:207], v[180:183], v[4:7]
	v_mfma_f32_16x16x32_bf16 v[0:3], v[212:215], v[180:183], v[0:3]
	v_mfma_f32_16x16x32_bf16 v[64:67], v[204:207], v[188:191], v[64:67]
	v_mfma_f32_16x16x32_bf16 v[72:75], v[212:215], v[188:191], v[72:75]
	v_mfma_f32_16x16x32_bf16 v[76:79], v[204:207], v[196:199], v[76:79]
	v_mfma_f32_16x16x32_bf16 v[84:87], v[212:215], v[196:199], v[84:87]
	s_barrier
	ds_read_b128 v[152:155], v137
	ds_read_b128 v[156:159], v138
	ds_read_b128 v[160:163], v139
	ds_read_b128 v[164:167], v140
	s_addk_i32 s5, 0x100
	s_mov_b32 m0, s87
	ds_read_b128 v[168:171], v129 offset:32768
	ds_read_b128 v[172:175], v129 offset:33792
	ds_read_b128 v[176:179], v132 offset:32768
	ds_read_b128 v[180:183], v132 offset:33792
	ds_read_b128 v[184:187], v131 offset:32768
	ds_read_b128 v[188:191], v131 offset:33792
	ds_read_b128 v[192:195], v130 offset:32768
	ds_read_b128 v[196:199], v130 offset:33792
	buffer_load_dwordx4 v141, s[8:11], s5 offen lds
	s_mov_b32 m0, s97
	s_nop 0
	buffer_load_dwordx4 v142, s[8:11], s5 offen lds
	s_waitcnt lgkmcnt(8)
	s_barrier
	s_waitcnt lgkmcnt(0)
	v_mfma_f32_16x16x32_bf16 v[124:127], v[152:155], v[168:171], v[124:127]
	v_mfma_f32_16x16x32_bf16 v[120:123], v[160:163], v[168:171], v[120:123]
	v_mfma_f32_16x16x32_bf16 v[116:119], v[152:155], v[176:179], v[116:119]
	v_mfma_f32_16x16x32_bf16 v[112:115], v[160:163], v[176:179], v[112:115]
	v_mfma_f32_16x16x32_bf16 v[108:111], v[152:155], v[184:187], v[108:111]
	v_mfma_f32_16x16x32_bf16 v[104:107], v[160:163], v[184:187], v[104:107]
	v_mfma_f32_16x16x32_bf16 v[100:103], v[152:155], v[192:195], v[100:103]
	v_mfma_f32_16x16x32_bf16 v[96:99], v[160:163], v[192:195], v[96:99]
	v_mfma_f32_16x16x32_bf16 v[124:127], v[156:159], v[172:175], v[124:127]
	v_mfma_f32_16x16x32_bf16 v[120:123], v[164:167], v[172:175], v[120:123]
	v_mfma_f32_16x16x32_bf16 v[116:119], v[156:159], v[180:183], v[116:119]
	v_mfma_f32_16x16x32_bf16 v[112:115], v[164:167], v[180:183], v[112:115]
	v_mfma_f32_16x16x32_bf16 v[108:111], v[156:159], v[188:191], v[108:111]
	v_mfma_f32_16x16x32_bf16 v[104:107], v[164:167], v[188:191], v[104:107]
	v_mfma_f32_16x16x32_bf16 v[100:103], v[156:159], v[196:199], v[100:103]
	v_mfma_f32_16x16x32_bf16 v[96:99], v[164:167], v[196:199], v[96:99]
	s_barrier
	s_addk_i32 s6, 0x180
	s_mov_b32 m0, s92
	ds_read_b128 v[200:203], v133
	ds_read_b128 v[204:207], v134
	ds_read_b128 v[208:211], v135
	ds_read_b128 v[212:215], v136
	buffer_load_dwordx4 v141, s[12:15], s6 offen lds
	s_mov_b32 m0, s29
	s_nop 0
	buffer_load_dwordx4 v142, s[12:15], s6 offen lds
	s_barrier
	s_waitcnt lgkmcnt(0)
	v_mfma_f32_16x16x32_bf16 v[92:95], v[200:203], v[168:171], v[92:95]
	v_mfma_f32_16x16x32_bf16 v[88:91], v[208:211], v[168:171], v[88:91]
	v_mfma_f32_16x16x32_bf16 v[80:83], v[200:203], v[176:179], v[80:83]
	v_mfma_f32_16x16x32_bf16 v[68:71], v[208:211], v[176:179], v[68:71]
	v_mfma_f32_16x16x32_bf16 v[60:63], v[200:203], v[184:187], v[60:63]
	v_mfma_f32_16x16x32_bf16 v[56:59], v[208:211], v[184:187], v[56:59]
	v_mfma_f32_16x16x32_bf16 v[52:55], v[200:203], v[192:195], v[52:55]
	v_mfma_f32_16x16x32_bf16 v[48:51], v[208:211], v[192:195], v[48:51]
	v_mfma_f32_16x16x32_bf16 v[92:95], v[204:207], v[172:175], v[92:95]
	v_mfma_f32_16x16x32_bf16 v[88:91], v[212:215], v[172:175], v[88:91]
	v_mfma_f32_16x16x32_bf16 v[80:83], v[204:207], v[180:183], v[80:83]
	v_mfma_f32_16x16x32_bf16 v[68:71], v[212:215], v[180:183], v[68:71]
	v_mfma_f32_16x16x32_bf16 v[60:63], v[204:207], v[188:191], v[60:63]
	v_mfma_f32_16x16x32_bf16 v[56:59], v[212:215], v[188:191], v[56:59]
	v_mfma_f32_16x16x32_bf16 v[52:55], v[204:207], v[196:199], v[52:55]
	v_mfma_f32_16x16x32_bf16 v[48:51], v[212:215], v[196:199], v[48:51]
	s_barrier
	s_addk_i32 s7, 0x180
	s_mov_b32 m0, s93
	ds_read_b128 v[168:171], v129 offset:49152
	ds_read_b128 v[172:175], v129 offset:50176
	ds_read_b128 v[176:179], v132 offset:49152
	ds_read_b128 v[180:183], v132 offset:50176
	ds_read_b128 v[184:187], v131 offset:49152
	ds_read_b128 v[188:191], v131 offset:50176
	ds_read_b128 v[192:195], v130 offset:49152
	ds_read_b128 v[196:199], v130 offset:50176
	buffer_load_dwordx4 v141, s[8:11], s7 offen lds
	s_mov_b32 m0, s56
	s_nop 0
	buffer_load_dwordx4 v142, s[8:11], s7 offen lds
	s_barrier
	s_waitcnt lgkmcnt(0)
	v_mfma_f32_16x16x32_bf16 v[44:47], v[152:155], v[168:171], v[44:47]
	v_mfma_f32_16x16x32_bf16 v[40:43], v[160:163], v[168:171], v[40:43]
	v_mfma_f32_16x16x32_bf16 v[36:39], v[152:155], v[176:179], v[36:39]
	v_mfma_f32_16x16x32_bf16 v[32:35], v[160:163], v[176:179], v[32:35]
	v_mfma_f32_16x16x32_bf16 v[28:31], v[152:155], v[184:187], v[28:31]
	v_mfma_f32_16x16x32_bf16 v[24:27], v[160:163], v[184:187], v[24:27]
	v_mfma_f32_16x16x32_bf16 v[20:23], v[152:155], v[192:195], v[20:23]
	v_mfma_f32_16x16x32_bf16 v[16:19], v[160:163], v[192:195], v[16:19]
	v_mfma_f32_16x16x32_bf16 v[44:47], v[156:159], v[172:175], v[44:47]
	v_mfma_f32_16x16x32_bf16 v[40:43], v[164:167], v[172:175], v[40:43]
	v_mfma_f32_16x16x32_bf16 v[36:39], v[156:159], v[180:183], v[36:39]
	v_mfma_f32_16x16x32_bf16 v[32:35], v[164:167], v[180:183], v[32:35]
	v_mfma_f32_16x16x32_bf16 v[28:31], v[156:159], v[188:191], v[28:31]
	v_mfma_f32_16x16x32_bf16 v[24:27], v[164:167], v[188:191], v[24:27]
	v_mfma_f32_16x16x32_bf16 v[20:23], v[156:159], v[196:199], v[20:23]
	v_mfma_f32_16x16x32_bf16 v[16:19], v[164:167], v[196:199], v[16:19]
	s_barrier
; #define STAGE(P, RS, SOFF, OFF, kt) do { const int _so = (SOFF) + (kt) * (BK * 2); \
;     _Pragma("unroll") for (int _i = 0; _i < 2; ++_i) { \
;       __builtin_amdgcn_raw_ptr_buffer_load_lds(RS, (__attribute__((address_space(3))) void*)((P) + wave * 1024 + _i * 8192), 16, OFF[_i], _so, 0, 0); } } while (0)
; #define LDA(dst, b, h) _Pragma("unroll") for (int m = 0; m < 4; ++m) _Pragma("unroll") for (int k = 0; k < 2; ++k) \
;     dst[m][k] = *reinterpret_cast<const bf16x8*>(SA(b, h) + lds_byte(wr * 64 + m * 16 + fr, k * 32 + fq * 8))
; #define LDB(dst, b, h) _Pragma("unroll") for (int n = 0; n < 2; ++n) _Pragma("unroll") for (int k = 0; k < 2; ++k) \
;     dst[n][k] = *reinterpret_cast<const bf16x8*>(SB(b, h) + lds_byte(wc * 32 + n * 16 + fr, k * 32 + fq * 8))
; #define WAIT_V(n) asm volatile("s_waitcnt vmcnt(" #n ")" ::: "memory")
; #define WAIT_L(n) asm volatile("s_waitcnt lgkmcnt(" #n ")" ::: "memory")
; #define BAR __builtin_amdgcn_s_barrier()
;     ...
;       STAGE(SB(1, 1), rsB, sB1, offB, t + 3);
;       WAIT_V(6); BAR; MMA(1, 1, At, B1); BAR;
;     }
;     { LDB(B0, 0, 0); LDA(At, 0, 0); STAGE(SA(1, 1), rsA, sA1, offA, nt - 1);
;       BAR; WAIT_L(0); MMA(0, 0, At, B0); BAR;
;       LDB(B1, 0, 1); BAR; WAIT_L(0); MMA(0, 1, At, B1); BAR;
;       LDA(At, 0, 1); WAIT_V(4); BAR; WAIT_L(0); MMA(1, 0, At, B0); MMA(1, 1, At, B1); BAR; }
;     { LDB(B0, 1, 0); LDA(At, 1, 0); WAIT_V(2); BAR; WAIT_L(0); MMA(0, 0, At, B0); BAR;
	s_addk_i32 s22, 0x180
	s_mov_b32 m0, s94
	s_nop 0
	buffer_load_dwordx4 v141, s[12:15], s22 offen lds
	s_mov_b32 m0, s57
	s_nop 0
	buffer_load_dwordx4 v142, s[12:15], s22 offen lds
	s_add_i32 s1, s1, 2
	s_addk_i32 s3, 0x100
	s_cmp_gt_u32 s1, 27
	s_waitcnt vmcnt(6)
	s_barrier
	v_mfma_f32_16x16x32_bf16 v[12:15], v[200:203], v[168:171], v[12:15]
	v_mfma_f32_16x16x32_bf16 v[8:11], v[208:211], v[168:171], v[8:11]
	v_mfma_f32_16x16x32_bf16 v[4:7], v[200:203], v[176:179], v[4:7]
	v_mfma_f32_16x16x32_bf16 v[0:3], v[208:211], v[176:179], v[0:3]
	v_mfma_f32_16x16x32_bf16 v[64:67], v[200:203], v[184:187], v[64:67]
	v_mfma_f32_16x16x32_bf16 v[72:75], v[208:211], v[184:187], v[72:75]
	v_mfma_f32_16x16x32_bf16 v[76:79], v[200:203], v[192:195], v[76:79]
	v_mfma_f32_16x16x32_bf16 v[84:87], v[208:211], v[192:195], v[84:87]
	v_mfma_f32_16x16x32_bf16 v[12:15], v[204:207], v[172:175], v[12:15]
	v_mfma_f32_16x16x32_bf16 v[8:11], v[212:215], v[172:175], v[8:11]
	v_mfma_f32_16x16x32_bf16 v[4:7], v[204:207], v[180:183], v[4:7]
	v_mfma_f32_16x16x32_bf16 v[0:3], v[212:215], v[180:183], v[0:3]
	v_mfma_f32_16x16x32_bf16 v[64:67], v[204:207], v[188:191], v[64:67]
	v_mfma_f32_16x16x32_bf16 v[72:75], v[212:215], v[188:191], v[72:75]
	v_mfma_f32_16x16x32_bf16 v[76:79], v[204:207], v[196:199], v[76:79]
	v_mfma_f32_16x16x32_bf16 v[84:87], v[212:215], v[196:199], v[84:87]
	s_barrier
	s_cbranch_scc0 .LBB0_657
	s_add_i32 s1, s81, 0xf80
	s_mov_b32 m0, s39
	ds_read_b128 v[152:155], v147
	ds_read_b128 v[156:159], v148
	ds_read_b128 v[160:163], v149
	ds_read_b128 v[148:151], v150
	ds_read_b128 v[164:167], v129
	ds_read_b128 v[168:171], v129 offset:1024
	ds_read_b128 v[172:175], v132
	ds_read_b128 v[176:179], v132 offset:1024
	ds_read_b128 v[180:183], v131
	ds_read_b128 v[184:187], v131 offset:1024
	ds_read_b128 v[188:191], v130
	ds_read_b128 v[192:195], v130 offset:1024
	buffer_load_dwordx4 v141, s[8:11], s1 offen lds
	s_mov_b32 m0, s58
	s_nop 0
	buffer_load_dwordx4 v142, s[8:11], s1 offen lds
	s_barrier
	s_waitcnt lgkmcnt(0)
	v_mfma_f32_16x16x32_bf16 v[124:127], v[152:155], v[164:167], v[124:127]
	v_mfma_f32_16x16x32_bf16 v[120:123], v[160:163], v[164:167], v[120:123]
	v_mfma_f32_16x16x32_bf16 v[116:119], v[152:155], v[172:175], v[116:119]
	v_mfma_f32_16x16x32_bf16 v[112:115], v[160:163], v[172:175], v[112:115]
	v_mfma_f32_16x16x32_bf16 v[108:111], v[152:155], v[180:183], v[108:111]
	v_mfma_f32_16x16x32_bf16 v[104:107], v[160:163], v[180:183], v[104:107]
	v_mfma_f32_16x16x32_bf16 v[100:103], v[152:155], v[188:191], v[100:103]
	v_mfma_f32_16x16x32_bf16 v[96:99], v[160:163], v[188:191], v[96:99]
	v_mfma_f32_16x16x32_bf16 v[124:127], v[156:159], v[168:171], v[124:127]
	v_mfma_f32_16x16x32_bf16 v[120:123], v[148:151], v[168:171], v[120:123]
	v_mfma_f32_16x16x32_bf16 v[116:119], v[156:159], v[176:179], v[116:119]
	v_mfma_f32_16x16x32_bf16 v[112:115], v[148:151], v[176:179], v[112:115]
	v_mfma_f32_16x16x32_bf16 v[108:111], v[156:159], v[184:187], v[108:111]
	v_mfma_f32_16x16x32_bf16 v[104:107], v[148:151], v[184:187], v[104:107]
	v_mfma_f32_16x16x32_bf16 v[100:103], v[156:159], v[192:195], v[100:103]
	v_mfma_f32_16x16x32_bf16 v[96:99], v[148:151], v[192:195], v[96:99]
	s_barrier
	ds_read_b128 v[196:199], v143
	ds_read_b128 v[200:203], v144
	ds_read_b128 v[142:145], v145
	ds_read_b128 v[204:207], v146
	s_barrier
	s_waitcnt lgkmcnt(0)
	v_mfma_f32_16x16x32_bf16 v[88:91], v[142:145], v[164:167], v[88:91]
	v_mfma_f32_16x16x32_bf16 v[80:83], v[196:199], v[172:175], v[80:83]
	v_mfma_f32_16x16x32_bf16 v[60:63], v[196:199], v[180:183], v[60:63]
	v_mfma_f32_16x16x32_bf16 v[56:59], v[142:145], v[180:183], v[56:59]
	v_mfma_f32_16x16x32_bf16 v[52:55], v[196:199], v[188:191], v[52:55]
	v_mfma_f32_16x16x32_bf16 v[48:51], v[142:145], v[188:191], v[48:51]
	v_mfma_f32_16x16x32_bf16 v[92:95], v[196:199], v[164:167], v[92:95]
	v_mfma_f32_16x16x32_bf16 v[68:71], v[142:145], v[172:175], v[68:71]
	v_mfma_f32_16x16x32_bf16 v[88:91], v[204:207], v[168:171], v[88:91]
	v_mfma_f32_16x16x32_bf16 v[80:83], v[200:203], v[176:179], v[80:83]
	v_mfma_f32_16x16x32_bf16 v[60:63], v[200:203], v[184:187], v[60:63]
	v_mfma_f32_16x16x32_bf16 v[56:59], v[204:207], v[184:187], v[56:59]
	v_mfma_f32_16x16x32_bf16 v[52:55], v[200:203], v[192:195], v[52:55]
	v_mfma_f32_16x16x32_bf16 v[48:51], v[204:207], v[192:195], v[48:51]
	v_mfma_f32_16x16x32_bf16 v[164:167], v[200:203], v[168:171], v[92:95]
	v_mfma_f32_16x16x32_bf16 v[168:171], v[204:207], v[176:179], v[68:71]
	s_barrier
	s_nop 0
	ds_read_b128 v[68:71], v129 offset:16384
	ds_read_b128 v[92:95], v129 offset:17408
	ds_read_b128 v[172:175], v132 offset:16384
	ds_read_b128 v[176:179], v132 offset:17408
	ds_read_b128 v[180:183], v131 offset:16384
	ds_read_b128 v[184:187], v131 offset:17408
	ds_read_b128 v[188:191], v130 offset:16384
	ds_read_b128 v[192:195], v130 offset:17408
	s_waitcnt vmcnt(4)
	s_barrier
; #define LDA(dst, b, h) _Pragma("unroll") for (int m = 0; m < 4; ++m) _Pragma("unroll") for (int k = 0; k < 2; ++k) \
;     dst[m][k] = *reinterpret_cast<const bf16x8*>(SA(b, h) + lds_byte(wr * 64 + m * 16 + fr, k * 32 + fq * 8))
; #define LDB(dst, b, h) _Pragma("unroll") for (int n = 0; n < 2; ++n) _Pragma("unroll") for (int k = 0; k < 2; ++k) \
;     dst[n][k] = *reinterpret_cast<const bf16x8*>(SB(b, h) + lds_byte(wc * 32 + n * 16 + fr, k * 32 + fq * 8))
; #define WAIT_V(n) asm volatile("s_waitcnt vmcnt(" #n ")" ::: "memory")
; #define WAIT_L(n) asm volatile("s_waitcnt lgkmcnt(" #n ")" ::: "memory")
; #define BAR __builtin_amdgcn_s_barrier()
;     ...
;       LDA(At, 0, 1); WAIT_V(4); BAR; WAIT_L(0); MMA(1, 0, At, B0); MMA(1, 1, At, B1); BAR; }
;     { LDB(B0, 1, 0); LDA(At, 1, 0); WAIT_V(2); BAR; WAIT_L(0); MMA(0, 0, At, B0); BAR;
	s_waitcnt lgkmcnt(0)
	v_mfma_f32_16x16x32_bf16 v[44:47], v[152:155], v[68:71], v[44:47]
	v_mfma_f32_16x16x32_bf16 v[40:43], v[160:163], v[68:71], v[40:43]
	v_mfma_f32_16x16x32_bf16 v[36:39], v[152:155], v[172:175], v[36:39]
	v_mfma_f32_16x16x32_bf16 v[32:35], v[160:163], v[172:175], v[32:35]
	v_mfma_f32_16x16x32_bf16 v[28:31], v[152:155], v[180:183], v[28:31]
	v_mfma_f32_16x16x32_bf16 v[24:27], v[160:163], v[180:183], v[24:27]
	v_mfma_f32_16x16x32_bf16 v[20:23], v[152:155], v[188:191], v[20:23]
	v_mfma_f32_16x16x32_bf16 v[16:19], v[160:163], v[188:191], v[16:19]
	v_mfma_f32_16x16x32_bf16 v[44:47], v[156:159], v[92:95], v[44:47]
	v_mfma_f32_16x16x32_bf16 v[40:43], v[148:151], v[92:95], v[40:43]
	v_mfma_f32_16x16x32_bf16 v[36:39], v[156:159], v[176:179], v[36:39]
	v_mfma_f32_16x16x32_bf16 v[32:35], v[148:151], v[176:179], v[32:35]
	v_mfma_f32_16x16x32_bf16 v[28:31], v[156:159], v[184:187], v[28:31]
	v_mfma_f32_16x16x32_bf16 v[24:27], v[148:151], v[184:187], v[24:27]
	v_mfma_f32_16x16x32_bf16 v[20:23], v[156:159], v[192:195], v[20:23]
	v_mfma_f32_16x16x32_bf16 v[16:19], v[148:151], v[192:195], v[16:19]
	v_mfma_f32_16x16x32_bf16 v[4:7], v[196:199], v[172:175], v[4:7]
	v_mfma_f32_16x16x32_bf16 v[0:3], v[142:145], v[172:175], v[0:3]
	v_mfma_f32_16x16x32_bf16 v[12:15], v[196:199], v[68:71], v[12:15]
	v_mfma_f32_16x16x32_bf16 v[8:11], v[142:145], v[68:71], v[8:11]
	v_mfma_f32_16x16x32_bf16 v[64:67], v[196:199], v[180:183], v[64:67]
	v_mfma_f32_16x16x32_bf16 v[68:71], v[142:145], v[180:183], v[72:75]
	v_mfma_f32_16x16x32_bf16 v[72:75], v[196:199], v[188:191], v[76:79]
	v_mfma_f32_16x16x32_bf16 v[76:79], v[142:145], v[188:191], v[84:87]
	v_mfma_f32_16x16x32_bf16 v[4:7], v[200:203], v[176:179], v[4:7]
	v_mfma_f32_16x16x32_bf16 v[0:3], v[204:207], v[176:179], v[0:3]
	v_mfma_f32_16x16x32_bf16 v[142:145], v[200:203], v[92:95], v[12:15]
	v_mfma_f32_16x16x32_bf16 v[146:149], v[204:207], v[92:95], v[8:11]
	v_mfma_f32_16x16x32_bf16 v[150:153], v[200:203], v[184:187], v[64:67]
	v_mfma_f32_16x16x32_bf16 v[154:157], v[204:207], v[184:187], v[68:71]
	v_mfma_f32_16x16x32_bf16 v[158:161], v[200:203], v[192:195], v[72:75]
	v_mfma_f32_16x16x32_bf16 v[172:175], v[204:207], v[192:195], v[76:79]
	s_barrier
	ds_read_b128 v[8:11], v137
	ds_read_b128 v[12:15], v138
	ds_read_b128 v[176:179], v139
	ds_read_b128 v[138:141], v140
	ds_read_b128 v[64:67], v129 offset:32768
	ds_read_b128 v[72:75], v129 offset:33792
	ds_read_b128 v[180:183], v132 offset:32768
	ds_read_b128 v[184:187], v132 offset:33792
	ds_read_b128 v[188:191], v131 offset:32768
	ds_read_b128 v[192:195], v131 offset:33792
	ds_read_b128 v[196:199], v130 offset:32768
	ds_read_b128 v[200:203], v130 offset:33792
	s_waitcnt vmcnt(2)
	s_barrier
	s_waitcnt lgkmcnt(0)
	v_mfma_f32_16x16x32_bf16 v[68:71], v[8:11], v[64:67], v[124:127]
	v_mfma_f32_16x16x32_bf16 v[76:79], v[176:179], v[64:67], v[120:123]
	v_mfma_f32_16x16x32_bf16 v[84:87], v[8:11], v[180:183], v[116:119]
	v_mfma_f32_16x16x32_bf16 v[92:95], v[176:179], v[180:183], v[112:115]
	v_mfma_f32_16x16x32_bf16 v[112:115], v[8:11], v[188:191], v[108:111]
	v_mfma_f32_16x16x32_bf16 v[104:107], v[176:179], v[188:191], v[104:107]
	v_mfma_f32_16x16x32_bf16 v[120:123], v[8:11], v[196:199], v[100:103]
	v_mfma_f32_16x16x32_bf16 v[96:99], v[176:179], v[196:199], v[96:99]
	v_mfma_f32_16x16x32_bf16 v[124:127], v[12:15], v[72:75], v[68:71]
	v_mfma_f32_16x16x32_bf16 v[116:119], v[138:141], v[72:75], v[76:79]
	v_mfma_f32_16x16x32_bf16 v[108:111], v[12:15], v[184:187], v[84:87]
	v_mfma_f32_16x16x32_bf16 v[100:103], v[138:141], v[184:187], v[92:95]
	v_mfma_f32_16x16x32_bf16 v[92:95], v[12:15], v[192:195], v[112:115]
	v_mfma_f32_16x16x32_bf16 v[84:87], v[138:141], v[192:195], v[104:107]
	v_mfma_f32_16x16x32_bf16 v[76:79], v[12:15], v[200:203], v[120:123]
	v_mfma_f32_16x16x32_bf16 v[68:71], v[138:141], v[200:203], v[96:99]
	s_barrier
; #define LDA(dst, b, h) _Pragma("unroll") for (int m = 0; m < 4; ++m) _Pragma("unroll") for (int k = 0; k < 2; ++k) \
;     dst[m][k] = *reinterpret_cast<const bf16x8*>(SA(b, h) + lds_byte(wr * 64 + m * 16 + fr, k * 32 + fq * 8))
; #define LDB(dst, b, h) _Pragma("unroll") for (int n = 0; n < 2; ++n) _Pragma("unroll") for (int k = 0; k < 2; ++k) \
;     dst[n][k] = *reinterpret_cast<const bf16x8*>(SB(b, h) + lds_byte(wc * 32 + n * 16 + fr, k * 32 + fq * 8))
; #define WAIT_V(n) asm volatile("s_waitcnt vmcnt(" #n ")" ::: "memory")
; #define WAIT_L(n) asm volatile("s_waitcnt lgkmcnt(" #n ")" ::: "memory")
; #define BAR __builtin_amdgcn_s_barrier()
;     ...
;       LDB(B1, 1, 1); WAIT_V(0); BAR; WAIT_L(0); MMA(0, 1, At, B1); BAR;
;       LDA(At, 1, 1); BAR; WAIT_L(0); MMA(1, 0, At, B0); MMA(1, 1, At, B1); BAR; }
;     if (wr == 0) BAR;
	ds_read_b128 v[204:207], v133
	ds_read_b128 v[208:211], v134
	ds_read_b128 v[212:215], v135
	ds_read_b128 v[134:137], v136
	s_waitcnt vmcnt(0)
	s_barrier
	s_waitcnt lgkmcnt(0)
	v_mfma_f32_16x16x32_bf16 v[96:99], v[204:207], v[64:67], v[164:167]
	v_mfma_f32_16x16x32_bf16 v[64:67], v[212:215], v[64:67], v[88:91]
	v_mfma_f32_16x16x32_bf16 v[80:83], v[204:207], v[180:183], v[80:83]
	v_mfma_f32_16x16x32_bf16 v[88:91], v[212:215], v[180:183], v[168:171]
	v_mfma_f32_16x16x32_bf16 v[60:63], v[204:207], v[188:191], v[60:63]
	v_mfma_f32_16x16x32_bf16 v[56:59], v[212:215], v[188:191], v[56:59]
	v_mfma_f32_16x16x32_bf16 v[52:55], v[204:207], v[196:199], v[52:55]
	v_mfma_f32_16x16x32_bf16 v[48:51], v[212:215], v[196:199], v[48:51]
	v_mfma_f32_16x16x32_bf16 v[120:123], v[208:211], v[72:75], v[96:99]
	v_mfma_f32_16x16x32_bf16 v[112:115], v[134:137], v[72:75], v[64:67]
	v_mfma_f32_16x16x32_bf16 v[104:107], v[208:211], v[184:187], v[80:83]
	v_mfma_f32_16x16x32_bf16 v[96:99], v[134:137], v[184:187], v[88:91]
	v_mfma_f32_16x16x32_bf16 v[88:91], v[208:211], v[192:195], v[60:63]
	v_mfma_f32_16x16x32_bf16 v[80:83], v[134:137], v[192:195], v[56:59]
	v_mfma_f32_16x16x32_bf16 v[72:75], v[208:211], v[200:203], v[52:55]
	v_mfma_f32_16x16x32_bf16 v[64:67], v[134:137], v[200:203], v[48:51]
	s_barrier
	s_nop 0
	ds_read_b128 v[48:51], v129 offset:49152
	ds_read_b128 v[162:165], v129 offset:50176
	ds_read_b128 v[52:55], v132 offset:49152
	ds_read_b128 v[166:169], v132 offset:50176
	ds_read_b128 v[180:183], v131 offset:49152
	ds_read_b128 v[184:187], v131 offset:50176
	ds_read_b128 v[188:191], v130 offset:49152
	ds_read_b128 v[130:133], v130 offset:50176
	s_barrier
	s_waitcnt lgkmcnt(0)
	v_mfma_f32_16x16x32_bf16 v[44:47], v[8:11], v[48:51], v[44:47]
	v_mfma_f32_16x16x32_bf16 v[40:43], v[176:179], v[48:51], v[40:43]
	v_mfma_f32_16x16x32_bf16 v[36:39], v[8:11], v[52:55], v[36:39]
	v_mfma_f32_16x16x32_bf16 v[32:35], v[176:179], v[52:55], v[32:35]
	v_mfma_f32_16x16x32_bf16 v[28:31], v[8:11], v[180:183], v[28:31]
	v_mfma_f32_16x16x32_bf16 v[24:27], v[176:179], v[180:183], v[24:27]
	v_mfma_f32_16x16x32_bf16 v[8:11], v[8:11], v[188:191], v[20:23]
	v_mfma_f32_16x16x32_bf16 v[16:19], v[176:179], v[188:191], v[16:19]
	v_mfma_f32_16x16x32_bf16 v[60:63], v[12:15], v[162:165], v[44:47]
	v_mfma_f32_16x16x32_bf16 v[56:59], v[138:141], v[162:165], v[40:43]
	v_mfma_f32_16x16x32_bf16 v[44:47], v[12:15], v[166:169], v[36:39]
	v_mfma_f32_16x16x32_bf16 v[40:43], v[138:141], v[166:169], v[32:35]
	v_mfma_f32_16x16x32_bf16 v[28:31], v[12:15], v[184:187], v[28:31]
	v_mfma_f32_16x16x32_bf16 v[24:27], v[138:141], v[184:187], v[24:27]
	v_mfma_f32_16x16x32_bf16 v[12:15], v[12:15], v[130:133], v[8:11]
	v_mfma_f32_16x16x32_bf16 v[8:11], v[138:141], v[130:133], v[16:19]
	v_mfma_f32_16x16x32_bf16 v[16:19], v[204:207], v[48:51], v[142:145]
	v_mfma_f32_16x16x32_bf16 v[20:23], v[212:215], v[48:51], v[146:149]
	v_mfma_f32_16x16x32_bf16 v[4:7], v[204:207], v[52:55], v[4:7]
	v_mfma_f32_16x16x32_bf16 v[0:3], v[212:215], v[52:55], v[0:3]
	v_mfma_f32_16x16x32_bf16 v[138:141], v[204:207], v[180:183], v[150:153]
	v_mfma_f32_16x16x32_bf16 v[142:145], v[212:215], v[180:183], v[154:157]
	v_mfma_f32_16x16x32_bf16 v[146:149], v[204:207], v[188:191], v[158:161]
	v_mfma_f32_16x16x32_bf16 v[150:153], v[212:215], v[188:191], v[172:175]
	v_mfma_f32_16x16x32_bf16 v[52:55], v[208:211], v[162:165], v[16:19]
	v_mfma_f32_16x16x32_bf16 v[48:51], v[134:137], v[162:165], v[20:23]
	v_mfma_f32_16x16x32_bf16 v[36:39], v[208:211], v[166:169], v[4:7]
	v_mfma_f32_16x16x32_bf16 v[32:35], v[134:137], v[166:169], v[0:3]
	v_mfma_f32_16x16x32_bf16 v[20:23], v[208:211], v[184:187], v[138:141]
	v_mfma_f32_16x16x32_bf16 v[16:19], v[134:137], v[184:187], v[142:145]
	v_mfma_f32_16x16x32_bf16 v[4:7], v[208:211], v[130:133], v[146:149]
	v_mfma_f32_16x16x32_bf16 v[0:3], v[134:137], v[130:133], v[150:153]
	v_cmp_gt_u32_e32 vcc, s73, v128
	s_barrier
	s_and_saveexec_b64 s[6:7], vcc
	s_cbranch_execz .LBB0_660
	s_barrier

; #define STAGE(P, RS, SOFF, OFF, kt) do { const int _so = (SOFF) + (kt) * (BK * 2); \
;     _Pragma("unroll") for (int _i = 0; _i < 2; ++_i) { \
;       __builtin_amdgcn_raw_ptr_buffer_load_lds(RS, (__attribute__((address_space(3))) void*)((P) + wave * 1024 + _i * 8192), 16, OFF[_i], _so, 0, 0); } } while (0)
; #define LDA(dst, b, h) _Pragma("unroll") for (int m = 0; m < 4; ++m) _Pragma("unroll") for (int k = 0; k < 2; ++k) \
;     dst[m][k] = *reinterpret_cast<const bf16x8*>(SA(b, h) + lds_byte(wr * 64 + m * 16 + fr, k * 32 + fq * 8))
; #define LDB(dst, b, h) _Pragma("unroll") for (int n = 0; n < 2; ++n) _Pragma("unroll") for (int k = 0; k < 2; ++k) \
;     dst[n][k] = *reinterpret_cast<const bf16x8*>(SB(b, h) + lds_byte(wc * 32 + n * 16 + fr, k * 32 + fq * 8))
; #define WAIT_V(n) asm volatile("s_waitcnt vmcnt(" #n ")" ::: "memory")
; #define WAIT_L(n) asm volatile("s_waitcnt lgkmcnt(" #n ")" ::: "memory")
; #define BAR __builtin_amdgcn_s_barrier()
; #define SCHED __builtin_amdgcn_sched_barrier(0)
;     ...
;       LDB(B0, 0, 0); SCHED; LDA(At, 0, 0); STAGE(SA(1, 1), rsA, sA1, offA, t + 1);
;       WAIT_L(8); BAR; WAIT_L(0); MMA(0, 0, At, B0); BAR; SCHED;
;       LDB(B1, 0, 1); STAGE(SB(0, 0), rsB, sB0, offB, t + 2);
;       BAR; WAIT_L(0); MMA(0, 1, At, B1); BAR;
;       LDA(At, 0, 1); STAGE(SA(0, 0), rsA, sA0, offA, t + 2);
;       BAR; WAIT_L(0); MMA(1, 0, At, B0); BAR; SCHED;
;       STAGE(SB(0, 1), rsB, sB1, offB, t + 2);
;       WAIT_V(6); BAR; MMA(1, 1, At, B1); BAR;
.LBB0_757:
	ds_read_b128 v[152:155], v147
	ds_read_b128 v[156:159], v148
	ds_read_b128 v[160:163], v149
	ds_read_b128 v[164:167], v150
	s_add_i32 s6, s85, s5
	s_add_i32 s7, s6, 0x80
	s_mov_b32 m0, s39
	ds_read_b128 v[168:171], v129
	ds_read_b128 v[172:175], v129 offset:1024
	ds_read_b128 v[176:179], v132
	ds_read_b128 v[180:183], v132 offset:1024
	ds_read_b128 v[184:187], v131
	ds_read_b128 v[188:191], v131 offset:1024
	ds_read_b128 v[192:195], v130
	ds_read_b128 v[196:199], v130 offset:1024
	buffer_load_dwordx4 v141, s[8:11], s7 offen lds
	s_mov_b32 m0, s56
	s_nop 0
	buffer_load_dwordx4 v142, s[8:11], s7 offen lds
	s_waitcnt lgkmcnt(8)
	s_barrier
	s_waitcnt lgkmcnt(0)
	v_mfma_f32_16x16x32_bf16 v[124:127], v[152:155], v[168:171], v[124:127]
	v_mfma_f32_16x16x32_bf16 v[120:123], v[160:163], v[168:171], v[120:123]
	v_mfma_f32_16x16x32_bf16 v[116:119], v[152:155], v[176:179], v[116:119]
	v_mfma_f32_16x16x32_bf16 v[112:115], v[160:163], v[176:179], v[112:115]
	v_mfma_f32_16x16x32_bf16 v[108:111], v[152:155], v[184:187], v[108:111]
	v_mfma_f32_16x16x32_bf16 v[104:107], v[160:163], v[184:187], v[104:107]
	v_mfma_f32_16x16x32_bf16 v[100:103], v[152:155], v[192:195], v[100:103]
	v_mfma_f32_16x16x32_bf16 v[96:99], v[160:163], v[192:195], v[96:99]
	v_mfma_f32_16x16x32_bf16 v[124:127], v[156:159], v[172:175], v[124:127]
	v_mfma_f32_16x16x32_bf16 v[120:123], v[164:167], v[172:175], v[120:123]
	v_mfma_f32_16x16x32_bf16 v[116:119], v[156:159], v[180:183], v[116:119]
	v_mfma_f32_16x16x32_bf16 v[112:115], v[164:167], v[180:183], v[112:115]
	v_mfma_f32_16x16x32_bf16 v[108:111], v[156:159], v[188:191], v[108:111]
	v_mfma_f32_16x16x32_bf16 v[104:107], v[164:167], v[188:191], v[104:107]
	v_mfma_f32_16x16x32_bf16 v[100:103], v[156:159], v[196:199], v[100:103]
	v_mfma_f32_16x16x32_bf16 v[96:99], v[164:167], v[196:199], v[96:99]
	s_barrier
	s_add_i32 s7, s87, s5
	s_add_i32 s23, s7, 0x100
	s_mov_b32 s14, s10
	s_mov_b32 s15, s11
	s_mov_b32 m0, s42
	ds_read_b128 v[200:203], v143
	ds_read_b128 v[204:207], v144
	ds_read_b128 v[208:211], v145
	ds_read_b128 v[212:215], v146
	buffer_load_dwordx4 v141, s[12:15], s23 offen lds
	s_mov_b32 m0, s49
	s_nop 0
	buffer_load_dwordx4 v142, s[12:15], s23 offen lds
	s_barrier
	s_waitcnt lgkmcnt(0)
	v_mfma_f32_16x16x32_bf16 v[92:95], v[200:203], v[168:171], v[92:95]
	v_mfma_f32_16x16x32_bf16 v[88:91], v[208:211], v[168:171], v[88:91]
	v_mfma_f32_16x16x32_bf16 v[80:83], v[200:203], v[176:179], v[80:83]
	v_mfma_f32_16x16x32_bf16 v[68:71], v[208:211], v[176:179], v[68:71]
	v_mfma_f32_16x16x32_bf16 v[60:63], v[200:203], v[184:187], v[60:63]
	v_mfma_f32_16x16x32_bf16 v[56:59], v[208:211], v[184:187], v[56:59]
	v_mfma_f32_16x16x32_bf16 v[52:55], v[200:203], v[192:195], v[52:55]
	v_mfma_f32_16x16x32_bf16 v[48:51], v[208:211], v[192:195], v[48:51]
	v_mfma_f32_16x16x32_bf16 v[92:95], v[204:207], v[172:175], v[92:95]
	v_mfma_f32_16x16x32_bf16 v[88:91], v[212:215], v[172:175], v[88:91]
	v_mfma_f32_16x16x32_bf16 v[80:83], v[204:207], v[180:183], v[80:83]
	v_mfma_f32_16x16x32_bf16 v[68:71], v[212:215], v[180:183], v[68:71]
	v_mfma_f32_16x16x32_bf16 v[60:63], v[204:207], v[188:191], v[60:63]
	v_mfma_f32_16x16x32_bf16 v[56:59], v[212:215], v[188:191], v[56:59]
	v_mfma_f32_16x16x32_bf16 v[52:55], v[204:207], v[196:199], v[52:55]
	v_mfma_f32_16x16x32_bf16 v[48:51], v[212:215], v[196:199], v[48:51]
	s_barrier
	s_add_i32 s23, s86, s5
	s_add_i32 s26, s23, 0x100
	s_mov_b32 m0, s33
	ds_read_b128 v[168:171], v129 offset:16384
	ds_read_b128 v[172:175], v129 offset:17408
	ds_read_b128 v[176:179], v132 offset:16384
	ds_read_b128 v[180:183], v132 offset:17408
	ds_read_b128 v[184:187], v131 offset:16384
	ds_read_b128 v[188:191], v131 offset:17408
	ds_read_b128 v[192:195], v130 offset:16384
	ds_read_b128 v[196:199], v130 offset:17408
	buffer_load_dwordx4 v141, s[8:11], s26 offen lds
	s_mov_b32 m0, s50
	s_nop 0
	buffer_load_dwordx4 v142, s[8:11], s26 offen lds
	s_barrier
	s_waitcnt lgkmcnt(0)
	v_mfma_f32_16x16x32_bf16 v[44:47], v[152:155], v[168:171], v[44:47]
	v_mfma_f32_16x16x32_bf16 v[40:43], v[160:163], v[168:171], v[40:43]
	v_mfma_f32_16x16x32_bf16 v[36:39], v[152:155], v[176:179], v[36:39]
	v_mfma_f32_16x16x32_bf16 v[32:35], v[160:163], v[176:179], v[32:35]
	v_mfma_f32_16x16x32_bf16 v[28:31], v[152:155], v[184:187], v[28:31]
	v_mfma_f32_16x16x32_bf16 v[24:27], v[160:163], v[184:187], v[24:27]
	v_mfma_f32_16x16x32_bf16 v[20:23], v[152:155], v[192:195], v[20:23]
	v_mfma_f32_16x16x32_bf16 v[16:19], v[160:163], v[192:195], v[16:19]
	v_mfma_f32_16x16x32_bf16 v[44:47], v[156:159], v[172:175], v[44:47]
	v_mfma_f32_16x16x32_bf16 v[40:43], v[164:167], v[172:175], v[40:43]
	v_mfma_f32_16x16x32_bf16 v[36:39], v[156:159], v[180:183], v[36:39]
	v_mfma_f32_16x16x32_bf16 v[32:35], v[164:167], v[180:183], v[32:35]
	v_mfma_f32_16x16x32_bf16 v[28:31], v[156:159], v[188:191], v[28:31]
	v_mfma_f32_16x16x32_bf16 v[24:27], v[164:167], v[188:191], v[24:27]
	v_mfma_f32_16x16x32_bf16 v[20:23], v[156:159], v[196:199], v[20:23]
	v_mfma_f32_16x16x32_bf16 v[16:19], v[164:167], v[196:199], v[16:19]
	s_barrier
	s_add_i32 s26, s90, s5
	s_add_i32 s27, s26, 0x100
	s_mov_b32 m0, s43
	s_nop 0
	buffer_load_dwordx4 v141, s[12:15], s27 offen lds
	s_mov_b32 m0, s51
	s_nop 0
	buffer_load_dwordx4 v142, s[12:15], s27 offen lds
	s_waitcnt vmcnt(6)
	s_barrier
; #define STAGE(P, RS, SOFF, OFF, kt) do { const int _so = (SOFF) + (kt) * (BK * 2); \
;     _Pragma("unroll") for (int _i = 0; _i < 2; ++_i) { \
;       __builtin_amdgcn_raw_ptr_buffer_load_lds(RS, (__attribute__((address_space(3))) void*)((P) + wave * 1024 + _i * 8192), 16, OFF[_i], _so, 0, 0); } } while (0)
; #define LDA(dst, b, h) _Pragma("unroll") for (int m = 0; m < 4; ++m) _Pragma("unroll") for (int k = 0; k < 2; ++k) \
;     dst[m][k] = *reinterpret_cast<const bf16x8*>(SA(b, h) + lds_byte(wr * 64 + m * 16 + fr, k * 32 + fq * 8))
; #define LDB(dst, b, h) _Pragma("unroll") for (int n = 0; n < 2; ++n) _Pragma("unroll") for (int k = 0; k < 2; ++k) \
;     dst[n][k] = *reinterpret_cast<const bf16x8*>(SB(b, h) + lds_byte(wc * 32 + n * 16 + fr, k * 32 + fq * 8))
; #define WAIT_V(n) asm volatile("s_waitcnt vmcnt(" #n ")" ::: "memory")
; #define WAIT_L(n) asm volatile("s_waitcnt lgkmcnt(" #n ")" ::: "memory")
; #define BAR __builtin_amdgcn_s_barrier()
; #define SCHED __builtin_amdgcn_sched_barrier(0)
;     ...
;       WAIT_V(6); BAR; MMA(1, 1, At, B1); BAR;
;       LDB(B0, 1, 0); SCHED; LDA(At, 1, 0); STAGE(SA(0, 1), rsA, sA1, offA, t + 2);
;       WAIT_L(8); BAR; WAIT_L(0); MMA(0, 0, At, B0); BAR; SCHED;
;       LDB(B1, 1, 1); STAGE(SB(1, 0), rsB, sB0, offB, t + 3);
;       BAR; WAIT_L(0); MMA(0, 1, At, B1); BAR;
;       LDA(At, 1, 1); STAGE(SA(1, 0), rsA, sA0, offA, t + 3);
;       BAR; WAIT_L(0); MMA(1, 0, At, B0); BAR; SCHED;
	v_mfma_f32_16x16x32_bf16 v[12:15], v[200:203], v[168:171], v[12:15]
	v_mfma_f32_16x16x32_bf16 v[8:11], v[208:211], v[168:171], v[8:11]
	v_mfma_f32_16x16x32_bf16 v[4:7], v[200:203], v[176:179], v[4:7]
	v_mfma_f32_16x16x32_bf16 v[0:3], v[208:211], v[176:179], v[0:3]
	v_mfma_f32_16x16x32_bf16 v[64:67], v[200:203], v[184:187], v[64:67]
	v_mfma_f32_16x16x32_bf16 v[72:75], v[208:211], v[184:187], v[72:75]
	v_mfma_f32_16x16x32_bf16 v[76:79], v[200:203], v[192:195], v[76:79]
	v_mfma_f32_16x16x32_bf16 v[84:87], v[208:211], v[192:195], v[84:87]
	v_mfma_f32_16x16x32_bf16 v[12:15], v[204:207], v[172:175], v[12:15]
	v_mfma_f32_16x16x32_bf16 v[8:11], v[212:215], v[172:175], v[8:11]
	v_mfma_f32_16x16x32_bf16 v[4:7], v[204:207], v[180:183], v[4:7]
	v_mfma_f32_16x16x32_bf16 v[0:3], v[212:215], v[180:183], v[0:3]
	v_mfma_f32_16x16x32_bf16 v[64:67], v[204:207], v[188:191], v[64:67]
	v_mfma_f32_16x16x32_bf16 v[72:75], v[212:215], v[188:191], v[72:75]
	v_mfma_f32_16x16x32_bf16 v[76:79], v[204:207], v[196:199], v[76:79]
	v_mfma_f32_16x16x32_bf16 v[84:87], v[212:215], v[196:199], v[84:87]
	s_barrier
	ds_read_b128 v[152:155], v137
	ds_read_b128 v[156:159], v138
	ds_read_b128 v[160:163], v139
	ds_read_b128 v[164:167], v140
	s_addk_i32 s6, 0x100
	s_mov_b32 m0, s44
	ds_read_b128 v[168:171], v129 offset:32768
	ds_read_b128 v[172:175], v129 offset:33792
	ds_read_b128 v[176:179], v132 offset:32768
	ds_read_b128 v[180:183], v132 offset:33792
	ds_read_b128 v[184:187], v131 offset:32768
	ds_read_b128 v[188:191], v131 offset:33792
	ds_read_b128 v[192:195], v130 offset:32768
	ds_read_b128 v[196:199], v130 offset:33792
	buffer_load_dwordx4 v141, s[8:11], s6 offen lds
	s_mov_b32 m0, s52
	s_nop 0
	buffer_load_dwordx4 v142, s[8:11], s6 offen lds
	s_waitcnt lgkmcnt(8)
	s_barrier
	s_waitcnt lgkmcnt(0)
	v_mfma_f32_16x16x32_bf16 v[124:127], v[152:155], v[168:171], v[124:127]
	v_mfma_f32_16x16x32_bf16 v[120:123], v[160:163], v[168:171], v[120:123]
	v_mfma_f32_16x16x32_bf16 v[116:119], v[152:155], v[176:179], v[116:119]
	v_mfma_f32_16x16x32_bf16 v[112:115], v[160:163], v[176:179], v[112:115]
	v_mfma_f32_16x16x32_bf16 v[108:111], v[152:155], v[184:187], v[108:111]
	v_mfma_f32_16x16x32_bf16 v[104:107], v[160:163], v[184:187], v[104:107]
	v_mfma_f32_16x16x32_bf16 v[100:103], v[152:155], v[192:195], v[100:103]
	v_mfma_f32_16x16x32_bf16 v[96:99], v[160:163], v[192:195], v[96:99]
	v_mfma_f32_16x16x32_bf16 v[124:127], v[156:159], v[172:175], v[124:127]
	v_mfma_f32_16x16x32_bf16 v[120:123], v[164:167], v[172:175], v[120:123]
	v_mfma_f32_16x16x32_bf16 v[116:119], v[156:159], v[180:183], v[116:119]
	v_mfma_f32_16x16x32_bf16 v[112:115], v[164:167], v[180:183], v[112:115]
	v_mfma_f32_16x16x32_bf16 v[108:111], v[156:159], v[188:191], v[108:111]
	v_mfma_f32_16x16x32_bf16 v[104:107], v[164:167], v[188:191], v[104:107]
	v_mfma_f32_16x16x32_bf16 v[100:103], v[156:159], v[196:199], v[100:103]
	v_mfma_f32_16x16x32_bf16 v[96:99], v[164:167], v[196:199], v[96:99]
	s_barrier
	s_addk_i32 s7, 0x180
	s_mov_b32 m0, s45
	ds_read_b128 v[200:203], v133
	ds_read_b128 v[204:207], v134
	ds_read_b128 v[208:211], v135
	ds_read_b128 v[212:215], v136
	buffer_load_dwordx4 v141, s[12:15], s7 offen lds
	s_mov_b32 m0, s53
	s_nop 0
	buffer_load_dwordx4 v142, s[12:15], s7 offen lds
	s_barrier
	s_waitcnt lgkmcnt(0)
	v_mfma_f32_16x16x32_bf16 v[92:95], v[200:203], v[168:171], v[92:95]
	v_mfma_f32_16x16x32_bf16 v[88:91], v[208:211], v[168:171], v[88:91]
	v_mfma_f32_16x16x32_bf16 v[80:83], v[200:203], v[176:179], v[80:83]
	v_mfma_f32_16x16x32_bf16 v[68:71], v[208:211], v[176:179], v[68:71]
	v_mfma_f32_16x16x32_bf16 v[60:63], v[200:203], v[184:187], v[60:63]
	v_mfma_f32_16x16x32_bf16 v[56:59], v[208:211], v[184:187], v[56:59]
	v_mfma_f32_16x16x32_bf16 v[52:55], v[200:203], v[192:195], v[52:55]
	v_mfma_f32_16x16x32_bf16 v[48:51], v[208:211], v[192:195], v[48:51]
	v_mfma_f32_16x16x32_bf16 v[92:95], v[204:207], v[172:175], v[92:95]
	v_mfma_f32_16x16x32_bf16 v[88:91], v[212:215], v[172:175], v[88:91]
	v_mfma_f32_16x16x32_bf16 v[80:83], v[204:207], v[180:183], v[80:83]
	v_mfma_f32_16x16x32_bf16 v[68:71], v[212:215], v[180:183], v[68:71]
	v_mfma_f32_16x16x32_bf16 v[60:63], v[204:207], v[188:191], v[60:63]
	v_mfma_f32_16x16x32_bf16 v[56:59], v[212:215], v[188:191], v[56:59]
	v_mfma_f32_16x16x32_bf16 v[52:55], v[204:207], v[196:199], v[52:55]
	v_mfma_f32_16x16x32_bf16 v[48:51], v[212:215], v[196:199], v[48:51]
	s_barrier
	s_addk_i32 s23, 0x180
	s_mov_b32 m0, s46
	ds_read_b128 v[168:171], v129 offset:49152
	ds_read_b128 v[172:175], v129 offset:50176
	ds_read_b128 v[176:179], v132 offset:49152
	ds_read_b128 v[180:183], v132 offset:50176
	ds_read_b128 v[184:187], v131 offset:49152
	ds_read_b128 v[188:191], v131 offset:50176
	ds_read_b128 v[192:195], v130 offset:49152
	ds_read_b128 v[196:199], v130 offset:50176
	buffer_load_dwordx4 v141, s[8:11], s23 offen lds
	s_mov_b32 m0, s54
	s_nop 0
	buffer_load_dwordx4 v142, s[8:11], s23 offen lds
	s_barrier
	s_waitcnt lgkmcnt(0)
	v_mfma_f32_16x16x32_bf16 v[44:47], v[152:155], v[168:171], v[44:47]
	v_mfma_f32_16x16x32_bf16 v[40:43], v[160:163], v[168:171], v[40:43]
	v_mfma_f32_16x16x32_bf16 v[36:39], v[152:155], v[176:179], v[36:39]
	v_mfma_f32_16x16x32_bf16 v[32:35], v[160:163], v[176:179], v[32:35]
	v_mfma_f32_16x16x32_bf16 v[28:31], v[152:155], v[184:187], v[28:31]
	v_mfma_f32_16x16x32_bf16 v[24:27], v[160:163], v[184:187], v[24:27]
	v_mfma_f32_16x16x32_bf16 v[20:23], v[152:155], v[192:195], v[20:23]
	v_mfma_f32_16x16x32_bf16 v[16:19], v[160:163], v[192:195], v[16:19]
	v_mfma_f32_16x16x32_bf16 v[44:47], v[156:159], v[172:175], v[44:47]
	v_mfma_f32_16x16x32_bf16 v[40:43], v[164:167], v[172:175], v[40:43]
	v_mfma_f32_16x16x32_bf16 v[36:39], v[156:159], v[180:183], v[36:39]
	v_mfma_f32_16x16x32_bf16 v[32:35], v[164:167], v[180:183], v[32:35]
	v_mfma_f32_16x16x32_bf16 v[28:31], v[156:159], v[188:191], v[28:31]
	v_mfma_f32_16x16x32_bf16 v[24:27], v[164:167], v[188:191], v[24:27]
	v_mfma_f32_16x16x32_bf16 v[20:23], v[156:159], v[196:199], v[20:23]
	v_mfma_f32_16x16x32_bf16 v[16:19], v[164:167], v[196:199], v[16:19]
	s_barrier
; #define STAGE(P, RS, SOFF, OFF, kt) do { const int _so = (SOFF) + (kt) * (BK * 2); \
;     _Pragma("unroll") for (int _i = 0; _i < 2; ++_i) { \
;       __builtin_amdgcn_raw_ptr_buffer_load_lds(RS, (__attribute__((address_space(3))) void*)((P) + wave * 1024 + _i * 8192), 16, OFF[_i], _so, 0, 0); } } while (0)
; #define LDA(dst, b, h) _Pragma("unroll") for (int m = 0; m < 4; ++m) _Pragma("unroll") for (int k = 0; k < 2; ++k) \
;     dst[m][k] = *reinterpret_cast<const bf16x8*>(SA(b, h) + lds_byte(wr * 64 + m * 16 + fr, k * 32 + fq * 8))
; #define LDB(dst, b, h) _Pragma("unroll") for (int n = 0; n < 2; ++n) _Pragma("unroll") for (int k = 0; k < 2; ++k) \
;     dst[n][k] = *reinterpret_cast<const bf16x8*>(SB(b, h) + lds_byte(wc * 32 + n * 16 + fr, k * 32 + fq * 8))
; #define WAIT_V(n) asm volatile("s_waitcnt vmcnt(" #n ")" ::: "memory")
; #define WAIT_L(n) asm volatile("s_waitcnt lgkmcnt(" #n ")" ::: "memory")
; #define BAR __builtin_amdgcn_s_barrier()
;     ...
;       STAGE(SB(1, 1), rsB, sB1, offB, t + 3);
;       WAIT_V(6); BAR; MMA(1, 1, At, B1); BAR;
;     }
;     { LDB(B0, 0, 0); LDA(At, 0, 0); STAGE(SA(1, 1), rsA, sA1, offA, nt - 1);
;       BAR; WAIT_L(0); MMA(0, 0, At, B0); BAR;
;       LDB(B1, 0, 1); BAR; WAIT_L(0); MMA(0, 1, At, B1); BAR;
;       LDA(At, 0, 1); WAIT_V(4); BAR; WAIT_L(0); MMA(1, 0, At, B0); MMA(1, 1, At, B1); BAR; }
;     { LDB(B0, 1, 0); LDA(At, 1, 0); WAIT_V(2); BAR; WAIT_L(0); MMA(0, 0, At, B0); BAR;
	s_addk_i32 s26, 0x180
	s_mov_b32 m0, s47
	s_nop 0
	buffer_load_dwordx4 v141, s[12:15], s26 offen lds
	s_mov_b32 m0, s55
	s_nop 0
	buffer_load_dwordx4 v142, s[12:15], s26 offen lds
	s_add_i32 s4, s4, 2
	s_addk_i32 s5, 0x100
	s_cmp_gt_u32 s4, 59
	s_waitcnt vmcnt(6)
	s_barrier
	v_mfma_f32_16x16x32_bf16 v[12:15], v[200:203], v[168:171], v[12:15]
	v_mfma_f32_16x16x32_bf16 v[8:11], v[208:211], v[168:171], v[8:11]
	v_mfma_f32_16x16x32_bf16 v[4:7], v[200:203], v[176:179], v[4:7]
	v_mfma_f32_16x16x32_bf16 v[0:3], v[208:211], v[176:179], v[0:3]
	v_mfma_f32_16x16x32_bf16 v[64:67], v[200:203], v[184:187], v[64:67]
	v_mfma_f32_16x16x32_bf16 v[72:75], v[208:211], v[184:187], v[72:75]
	v_mfma_f32_16x16x32_bf16 v[76:79], v[200:203], v[192:195], v[76:79]
	v_mfma_f32_16x16x32_bf16 v[84:87], v[208:211], v[192:195], v[84:87]
	v_mfma_f32_16x16x32_bf16 v[12:15], v[204:207], v[172:175], v[12:15]
	v_mfma_f32_16x16x32_bf16 v[8:11], v[212:215], v[172:175], v[8:11]
	v_mfma_f32_16x16x32_bf16 v[4:7], v[204:207], v[180:183], v[4:7]
	v_mfma_f32_16x16x32_bf16 v[0:3], v[212:215], v[180:183], v[0:3]
	v_mfma_f32_16x16x32_bf16 v[64:67], v[204:207], v[188:191], v[64:67]
	v_mfma_f32_16x16x32_bf16 v[72:75], v[212:215], v[188:191], v[72:75]
	v_mfma_f32_16x16x32_bf16 v[76:79], v[204:207], v[196:199], v[76:79]
	v_mfma_f32_16x16x32_bf16 v[84:87], v[212:215], v[196:199], v[84:87]
	s_barrier
	s_cbranch_scc0 .LBB0_757
	s_add_i32 s4, s85, 0x1f80
	s_mov_b32 m0, s39
	ds_read_b128 v[152:155], v147
	ds_read_b128 v[156:159], v148
	ds_read_b128 v[160:163], v149
	ds_read_b128 v[148:151], v150
	ds_read_b128 v[164:167], v129
	ds_read_b128 v[168:171], v129 offset:1024
	ds_read_b128 v[172:175], v132
	ds_read_b128 v[176:179], v132 offset:1024
	ds_read_b128 v[180:183], v131
	ds_read_b128 v[184:187], v131 offset:1024
	ds_read_b128 v[188:191], v130
	ds_read_b128 v[192:195], v130 offset:1024
	buffer_load_dwordx4 v141, s[8:11], s4 offen lds
	s_mov_b32 m0, s56
	s_nop 0
	buffer_load_dwordx4 v142, s[8:11], s4 offen lds
	s_barrier
	s_waitcnt lgkmcnt(0)
	v_mfma_f32_16x16x32_bf16 v[124:127], v[152:155], v[164:167], v[124:127]
	v_mfma_f32_16x16x32_bf16 v[120:123], v[160:163], v[164:167], v[120:123]
	v_mfma_f32_16x16x32_bf16 v[116:119], v[152:155], v[172:175], v[116:119]
	v_mfma_f32_16x16x32_bf16 v[112:115], v[160:163], v[172:175], v[112:115]
	v_mfma_f32_16x16x32_bf16 v[108:111], v[152:155], v[180:183], v[108:111]
	v_mfma_f32_16x16x32_bf16 v[104:107], v[160:163], v[180:183], v[104:107]
	v_mfma_f32_16x16x32_bf16 v[100:103], v[152:155], v[188:191], v[100:103]
	v_mfma_f32_16x16x32_bf16 v[96:99], v[160:163], v[188:191], v[96:99]
	v_mfma_f32_16x16x32_bf16 v[124:127], v[156:159], v[168:171], v[124:127]
	v_mfma_f32_16x16x32_bf16 v[120:123], v[148:151], v[168:171], v[120:123]
	v_mfma_f32_16x16x32_bf16 v[116:119], v[156:159], v[176:179], v[116:119]
	v_mfma_f32_16x16x32_bf16 v[112:115], v[148:151], v[176:179], v[112:115]
	v_mfma_f32_16x16x32_bf16 v[108:111], v[156:159], v[184:187], v[108:111]
	v_mfma_f32_16x16x32_bf16 v[104:107], v[148:151], v[184:187], v[104:107]
	v_mfma_f32_16x16x32_bf16 v[100:103], v[156:159], v[192:195], v[100:103]
	v_mfma_f32_16x16x32_bf16 v[96:99], v[148:151], v[192:195], v[96:99]
	s_barrier
	ds_read_b128 v[196:199], v143
	ds_read_b128 v[200:203], v144
	ds_read_b128 v[142:145], v145
	ds_read_b128 v[204:207], v146
	s_barrier
	s_waitcnt lgkmcnt(0)
	v_mfma_f32_16x16x32_bf16 v[88:91], v[142:145], v[164:167], v[88:91]
	v_mfma_f32_16x16x32_bf16 v[80:83], v[196:199], v[172:175], v[80:83]
	v_mfma_f32_16x16x32_bf16 v[60:63], v[196:199], v[180:183], v[60:63]
	v_mfma_f32_16x16x32_bf16 v[56:59], v[142:145], v[180:183], v[56:59]
	v_mfma_f32_16x16x32_bf16 v[52:55], v[196:199], v[188:191], v[52:55]
	v_mfma_f32_16x16x32_bf16 v[48:51], v[142:145], v[188:191], v[48:51]
	v_mfma_f32_16x16x32_bf16 v[92:95], v[196:199], v[164:167], v[92:95]
	v_mfma_f32_16x16x32_bf16 v[68:71], v[142:145], v[172:175], v[68:71]
	v_mfma_f32_16x16x32_bf16 v[88:91], v[204:207], v[168:171], v[88:91]
	v_mfma_f32_16x16x32_bf16 v[80:83], v[200:203], v[176:179], v[80:83]
	v_mfma_f32_16x16x32_bf16 v[60:63], v[200:203], v[184:187], v[60:63]
	v_mfma_f32_16x16x32_bf16 v[56:59], v[204:207], v[184:187], v[56:59]
	v_mfma_f32_16x16x32_bf16 v[52:55], v[200:203], v[192:195], v[52:55]
	v_mfma_f32_16x16x32_bf16 v[48:51], v[204:207], v[192:195], v[48:51]
	v_mfma_f32_16x16x32_bf16 v[164:167], v[200:203], v[168:171], v[92:95]
	v_mfma_f32_16x16x32_bf16 v[168:171], v[204:207], v[176:179], v[68:71]
	s_barrier
	s_nop 0
	ds_read_b128 v[68:71], v129 offset:16384
	ds_read_b128 v[92:95], v129 offset:17408
	ds_read_b128 v[172:175], v132 offset:16384
	ds_read_b128 v[176:179], v132 offset:17408
	ds_read_b128 v[180:183], v131 offset:16384
	ds_read_b128 v[184:187], v131 offset:17408
	ds_read_b128 v[188:191], v130 offset:16384
	ds_read_b128 v[192:195], v130 offset:17408
	s_waitcnt vmcnt(4)
	s_barrier
; #define LDA(dst, b, h) _Pragma("unroll") for (int m = 0; m < 4; ++m) _Pragma("unroll") for (int k = 0; k < 2; ++k) \
;     dst[m][k] = *reinterpret_cast<const bf16x8*>(SA(b, h) + lds_byte(wr * 64 + m * 16 + fr, k * 32 + fq * 8))
; #define LDB(dst, b, h) _Pragma("unroll") for (int n = 0; n < 2; ++n) _Pragma("unroll") for (int k = 0; k < 2; ++k) \
;     dst[n][k] = *reinterpret_cast<const bf16x8*>(SB(b, h) + lds_byte(wc * 32 + n * 16 + fr, k * 32 + fq * 8))
; #define WAIT_V(n) asm volatile("s_waitcnt vmcnt(" #n ")" ::: "memory")
; #define WAIT_L(n) asm volatile("s_waitcnt lgkmcnt(" #n ")" ::: "memory")
; #define BAR __builtin_amdgcn_s_barrier()
;     ...
;       LDA(At, 0, 1); WAIT_V(4); BAR; WAIT_L(0); MMA(1, 0, At, B0); MMA(1, 1, At, B1); BAR; }
;     { LDB(B0, 1, 0); LDA(At, 1, 0); WAIT_V(2); BAR; WAIT_L(0); MMA(0, 0, At, B0); BAR;
	s_waitcnt lgkmcnt(0)
	v_mfma_f32_16x16x32_bf16 v[44:47], v[152:155], v[68:71], v[44:47]
	v_mfma_f32_16x16x32_bf16 v[40:43], v[160:163], v[68:71], v[40:43]
	v_mfma_f32_16x16x32_bf16 v[36:39], v[152:155], v[172:175], v[36:39]
	v_mfma_f32_16x16x32_bf16 v[32:35], v[160:163], v[172:175], v[32:35]
	v_mfma_f32_16x16x32_bf16 v[28:31], v[152:155], v[180:183], v[28:31]
	v_mfma_f32_16x16x32_bf16 v[24:27], v[160:163], v[180:183], v[24:27]
	v_mfma_f32_16x16x32_bf16 v[20:23], v[152:155], v[188:191], v[20:23]
	v_mfma_f32_16x16x32_bf16 v[16:19], v[160:163], v[188:191], v[16:19]
	v_mfma_f32_16x16x32_bf16 v[44:47], v[156:159], v[92:95], v[44:47]
	v_mfma_f32_16x16x32_bf16 v[40:43], v[148:151], v[92:95], v[40:43]
	v_mfma_f32_16x16x32_bf16 v[36:39], v[156:159], v[176:179], v[36:39]
	v_mfma_f32_16x16x32_bf16 v[32:35], v[148:151], v[176:179], v[32:35]
	v_mfma_f32_16x16x32_bf16 v[28:31], v[156:159], v[184:187], v[28:31]
	v_mfma_f32_16x16x32_bf16 v[24:27], v[148:151], v[184:187], v[24:27]
	v_mfma_f32_16x16x32_bf16 v[20:23], v[156:159], v[192:195], v[20:23]
	v_mfma_f32_16x16x32_bf16 v[16:19], v[148:151], v[192:195], v[16:19]
	v_mfma_f32_16x16x32_bf16 v[4:7], v[196:199], v[172:175], v[4:7]
	v_mfma_f32_16x16x32_bf16 v[0:3], v[142:145], v[172:175], v[0:3]
	v_mfma_f32_16x16x32_bf16 v[12:15], v[196:199], v[68:71], v[12:15]
	v_mfma_f32_16x16x32_bf16 v[8:11], v[142:145], v[68:71], v[8:11]
	v_mfma_f32_16x16x32_bf16 v[64:67], v[196:199], v[180:183], v[64:67]
	v_mfma_f32_16x16x32_bf16 v[68:71], v[142:145], v[180:183], v[72:75]
	v_mfma_f32_16x16x32_bf16 v[72:75], v[196:199], v[188:191], v[76:79]
	v_mfma_f32_16x16x32_bf16 v[76:79], v[142:145], v[188:191], v[84:87]
	v_mfma_f32_16x16x32_bf16 v[4:7], v[200:203], v[176:179], v[4:7]
	v_mfma_f32_16x16x32_bf16 v[0:3], v[204:207], v[176:179], v[0:3]
	v_mfma_f32_16x16x32_bf16 v[142:145], v[200:203], v[92:95], v[12:15]
	v_mfma_f32_16x16x32_bf16 v[146:149], v[204:207], v[92:95], v[8:11]
	v_mfma_f32_16x16x32_bf16 v[150:153], v[200:203], v[184:187], v[64:67]
	v_mfma_f32_16x16x32_bf16 v[154:157], v[204:207], v[184:187], v[68:71]
	v_mfma_f32_16x16x32_bf16 v[158:161], v[200:203], v[192:195], v[72:75]
	v_mfma_f32_16x16x32_bf16 v[172:175], v[204:207], v[192:195], v[76:79]
	s_barrier
	ds_read_b128 v[8:11], v137
	ds_read_b128 v[12:15], v138
	ds_read_b128 v[176:179], v139
	ds_read_b128 v[138:141], v140
	ds_read_b128 v[64:67], v129 offset:32768
	ds_read_b128 v[72:75], v129 offset:33792
	ds_read_b128 v[180:183], v132 offset:32768
	ds_read_b128 v[184:187], v132 offset:33792
	ds_read_b128 v[188:191], v131 offset:32768
	ds_read_b128 v[192:195], v131 offset:33792
	ds_read_b128 v[196:199], v130 offset:32768
	ds_read_b128 v[200:203], v130 offset:33792
	s_waitcnt vmcnt(2)
	s_barrier
	s_waitcnt lgkmcnt(0)
	v_mfma_f32_16x16x32_bf16 v[68:71], v[8:11], v[64:67], v[124:127]
	v_mfma_f32_16x16x32_bf16 v[76:79], v[176:179], v[64:67], v[120:123]
	v_mfma_f32_16x16x32_bf16 v[84:87], v[8:11], v[180:183], v[116:119]
	v_mfma_f32_16x16x32_bf16 v[92:95], v[176:179], v[180:183], v[112:115]
	v_mfma_f32_16x16x32_bf16 v[112:115], v[8:11], v[188:191], v[108:111]
	v_mfma_f32_16x16x32_bf16 v[104:107], v[176:179], v[188:191], v[104:107]
	v_mfma_f32_16x16x32_bf16 v[120:123], v[8:11], v[196:199], v[100:103]
	v_mfma_f32_16x16x32_bf16 v[96:99], v[176:179], v[196:199], v[96:99]
	v_mfma_f32_16x16x32_bf16 v[124:127], v[12:15], v[72:75], v[68:71]
	v_mfma_f32_16x16x32_bf16 v[116:119], v[138:141], v[72:75], v[76:79]
	v_mfma_f32_16x16x32_bf16 v[108:111], v[12:15], v[184:187], v[84:87]
	v_mfma_f32_16x16x32_bf16 v[100:103], v[138:141], v[184:187], v[92:95]
	v_mfma_f32_16x16x32_bf16 v[92:95], v[12:15], v[192:195], v[112:115]
	v_mfma_f32_16x16x32_bf16 v[84:87], v[138:141], v[192:195], v[104:107]
	v_mfma_f32_16x16x32_bf16 v[76:79], v[12:15], v[200:203], v[120:123]
	v_mfma_f32_16x16x32_bf16 v[68:71], v[138:141], v[200:203], v[96:99]
	s_barrier
; #define LDA(dst, b, h) _Pragma("unroll") for (int m = 0; m < 4; ++m) _Pragma("unroll") for (int k = 0; k < 2; ++k) \
;     dst[m][k] = *reinterpret_cast<const bf16x8*>(SA(b, h) + lds_byte(wr * 64 + m * 16 + fr, k * 32 + fq * 8))
; #define LDB(dst, b, h) _Pragma("unroll") for (int n = 0; n < 2; ++n) _Pragma("unroll") for (int k = 0; k < 2; ++k) \
;     dst[n][k] = *reinterpret_cast<const bf16x8*>(SB(b, h) + lds_byte(wc * 32 + n * 16 + fr, k * 32 + fq * 8))
; #define WAIT_V(n) asm volatile("s_waitcnt vmcnt(" #n ")" ::: "memory")
; #define WAIT_L(n) asm volatile("s_waitcnt lgkmcnt(" #n ")" ::: "memory")
; #define BAR __builtin_amdgcn_s_barrier()
;     ...
;       LDB(B1, 1, 1); WAIT_V(0); BAR; WAIT_L(0); MMA(0, 1, At, B1); BAR;
;       LDA(At, 1, 1); BAR; WAIT_L(0); MMA(1, 0, At, B0); MMA(1, 1, At, B1); BAR; }
;     if (wr == 0) BAR;
	ds_read_b128 v[204:207], v133
	ds_read_b128 v[208:211], v134
	ds_read_b128 v[212:215], v135
	ds_read_b128 v[134:137], v136
	s_waitcnt vmcnt(0)
	s_barrier
	s_waitcnt lgkmcnt(0)
	v_mfma_f32_16x16x32_bf16 v[96:99], v[204:207], v[64:67], v[164:167]
	v_mfma_f32_16x16x32_bf16 v[64:67], v[212:215], v[64:67], v[88:91]
	v_mfma_f32_16x16x32_bf16 v[80:83], v[204:207], v[180:183], v[80:83]
	v_mfma_f32_16x16x32_bf16 v[88:91], v[212:215], v[180:183], v[168:171]
	v_mfma_f32_16x16x32_bf16 v[60:63], v[204:207], v[188:191], v[60:63]
	v_mfma_f32_16x16x32_bf16 v[56:59], v[212:215], v[188:191], v[56:59]
	v_mfma_f32_16x16x32_bf16 v[52:55], v[204:207], v[196:199], v[52:55]
	v_mfma_f32_16x16x32_bf16 v[48:51], v[212:215], v[196:199], v[48:51]
	v_mfma_f32_16x16x32_bf16 v[120:123], v[208:211], v[72:75], v[96:99]
	v_mfma_f32_16x16x32_bf16 v[112:115], v[134:137], v[72:75], v[64:67]
	v_mfma_f32_16x16x32_bf16 v[104:107], v[208:211], v[184:187], v[80:83]
	v_mfma_f32_16x16x32_bf16 v[96:99], v[134:137], v[184:187], v[88:91]
	v_mfma_f32_16x16x32_bf16 v[88:91], v[208:211], v[192:195], v[60:63]
	v_mfma_f32_16x16x32_bf16 v[80:83], v[134:137], v[192:195], v[56:59]
	v_mfma_f32_16x16x32_bf16 v[72:75], v[208:211], v[200:203], v[52:55]
	v_mfma_f32_16x16x32_bf16 v[64:67], v[134:137], v[200:203], v[48:51]
	s_barrier
	s_nop 0
	ds_read_b128 v[48:51], v129 offset:49152
	ds_read_b128 v[162:165], v129 offset:50176
	ds_read_b128 v[52:55], v132 offset:49152
	ds_read_b128 v[166:169], v132 offset:50176
	ds_read_b128 v[180:183], v131 offset:49152
	ds_read_b128 v[184:187], v131 offset:50176
	ds_read_b128 v[188:191], v130 offset:49152
	ds_read_b128 v[130:133], v130 offset:50176
	s_barrier
	s_waitcnt lgkmcnt(0)
	v_mfma_f32_16x16x32_bf16 v[44:47], v[8:11], v[48:51], v[44:47]
	v_mfma_f32_16x16x32_bf16 v[40:43], v[176:179], v[48:51], v[40:43]
	v_mfma_f32_16x16x32_bf16 v[36:39], v[8:11], v[52:55], v[36:39]
	v_mfma_f32_16x16x32_bf16 v[32:35], v[176:179], v[52:55], v[32:35]
	v_mfma_f32_16x16x32_bf16 v[28:31], v[8:11], v[180:183], v[28:31]
	v_mfma_f32_16x16x32_bf16 v[24:27], v[176:179], v[180:183], v[24:27]
	v_mfma_f32_16x16x32_bf16 v[8:11], v[8:11], v[188:191], v[20:23]
	v_mfma_f32_16x16x32_bf16 v[16:19], v[176:179], v[188:191], v[16:19]
	v_mfma_f32_16x16x32_bf16 v[60:63], v[12:15], v[162:165], v[44:47]
	v_mfma_f32_16x16x32_bf16 v[56:59], v[138:141], v[162:165], v[40:43]
	v_mfma_f32_16x16x32_bf16 v[44:47], v[12:15], v[166:169], v[36:39]
	v_mfma_f32_16x16x32_bf16 v[40:43], v[138:141], v[166:169], v[32:35]
	v_mfma_f32_16x16x32_bf16 v[28:31], v[12:15], v[184:187], v[28:31]
	v_mfma_f32_16x16x32_bf16 v[24:27], v[138:141], v[184:187], v[24:27]
	v_mfma_f32_16x16x32_bf16 v[12:15], v[12:15], v[130:133], v[8:11]
	v_mfma_f32_16x16x32_bf16 v[8:11], v[138:141], v[130:133], v[16:19]
	v_mfma_f32_16x16x32_bf16 v[16:19], v[204:207], v[48:51], v[142:145]
	v_mfma_f32_16x16x32_bf16 v[20:23], v[212:215], v[48:51], v[146:149]
	v_mfma_f32_16x16x32_bf16 v[4:7], v[204:207], v[52:55], v[4:7]
	v_mfma_f32_16x16x32_bf16 v[0:3], v[212:215], v[52:55], v[0:3]
	v_mfma_f32_16x16x32_bf16 v[138:141], v[204:207], v[180:183], v[150:153]
	v_mfma_f32_16x16x32_bf16 v[142:145], v[212:215], v[180:183], v[154:157]
	v_mfma_f32_16x16x32_bf16 v[146:149], v[204:207], v[188:191], v[158:161]
	v_mfma_f32_16x16x32_bf16 v[150:153], v[212:215], v[188:191], v[172:175]
	v_mfma_f32_16x16x32_bf16 v[52:55], v[208:211], v[162:165], v[16:19]
	v_mfma_f32_16x16x32_bf16 v[48:51], v[134:137], v[162:165], v[20:23]
	v_mfma_f32_16x16x32_bf16 v[36:39], v[208:211], v[166:169], v[4:7]
	v_mfma_f32_16x16x32_bf16 v[32:35], v[134:137], v[166:169], v[0:3]
	v_mfma_f32_16x16x32_bf16 v[20:23], v[208:211], v[184:187], v[138:141]
	v_mfma_f32_16x16x32_bf16 v[16:19], v[134:137], v[184:187], v[142:145]
	v_mfma_f32_16x16x32_bf16 v[4:7], v[208:211], v[130:133], v[146:149]
	v_mfma_f32_16x16x32_bf16 v[0:3], v[134:137], v[130:133], v[150:153]
	v_cmp_gt_u32_e32 vcc, s74, v128
	s_barrier
	s_and_saveexec_b64 s[4:5], vcc
	s_cbranch_execz .LBB0_760
	s_barrier
